# c27: c16 + stacked neutral-or-better edits: no mid-segment priority yield, satisfied in-segment waits dropped with MFMAs 8-byte aligned, SwiGLU epilogue address chains folded into store immediates
# baseline (speedup 1.0000x reference)
.LBB0_343:
	s_ashr_i32 s11, s10, 31
	s_lshl_b64 s[12:13], s[10:11], 20
	s_add_u32 s12, s26, s12
	s_addc_u32 s13, s27, s13
	s_and_b64 s[14:15], s[2:3], exec
	s_cselect_b32 s11, s13, s21
	s_cselect_b32 s75, s12, s20
	s_ashr_i32 s9, s8, 31
	s_lshl_b64 s[14:15], s[8:9], 20
	s_add_u32 s14, s28, s14
	s_addc_u32 s15, s29, s15
	s_and_b64 s[22:23], s[2:3], exec
	s_cselect_b32 s9, s15, s19
	s_cselect_b32 s76, s14, s18
	s_add_u32 s77, s18, 0x100
	s_addc_u32 s78, s19, 0
	s_add_u32 s18, s20, 0x80080
	s_addc_u32 s19, s21, 0
	s_add_u32 s79, s20, 0x100
	s_addc_u32 s80, s21, 0
	s_mov_b32 s81, -2
	ds_read_b128 v[148:151], v143
	ds_read_b128 v[152:155], v143 offset:1024
	ds_read_b128 v[156:159], v143 offset:2048
	ds_read_b128 v[160:163], v143 offset:3072
	ds_read_b128 v[164:167], v144
	ds_read_b128 v[168:171], v144 offset:1024
	ds_read_b128 v[172:175], v144 offset:2048
	ds_read_b128 v[176:179], v144 offset:3072
	s_cmp_eq_u32 s81, 28
	s_cselect_b32 s21, s9, s78
	s_cselect_b32 s20, s76, s77
	s_cselect_b32 s23, s11, s80
	s_cselect_b32 s22, s75, s79
	ds_read_b128 v[180:183], v145
	ds_read_b128 v[184:187], v145 offset:1024
	ds_read_b128 v[188:191], v145 offset:2048
	ds_read_b128 v[192:195], v145 offset:3072
	ds_read_b128 v[196:199], v145 offset:4096
	ds_read_b128 v[200:203], v145 offset:5120
	ds_read_b128 v[204:207], v145 offset:6144
	ds_read_b128 v[208:211], v145 offset:7168
	s_add_u32 s82, s18, 0xfff80000
	s_addc_u32 s83, s19, -1
	s_mov_b32 s86, m0
	s_mov_b32 m0, s64
	s_nop 0
	global_load_lds_dwordx4 v138, s[82:83]
	s_mov_b32 m0, s86
	s_nop 0
	s_mov_b32 s86, m0
	s_mov_b32 m0, s67
	s_nop 0
	global_load_lds_dwordx4 v140, s[82:83]
	s_mov_b32 m0, s86
	s_mov_b32 s82, m0
	s_mov_b32 m0, s65
	s_nop 0
	global_load_lds_dwordx4 v138, s[18:19]
	s_mov_b32 m0, s82
	s_nop 0
	s_mov_b32 s82, m0
	s_mov_b32 m0, s73
	s_nop 0
	global_load_lds_dwordx4 v140, s[18:19]
	s_mov_b32 m0, s82
	s_waitcnt vmcnt(8)
	s_waitcnt lgkmcnt(0)
	s_barrier
	s_setprio 1
	.p2align 3
	v_mfma_f32_16x16x32_bf16 v[126:129], v[148:151], v[180:183], 0
	v_mfma_f32_16x16x32_bf16 v[126:129], v[152:155], v[184:187], v[126:129]
	v_mfma_f32_16x16x32_bf16 v[122:125], v[156:159], v[180:183], 0
	v_mfma_f32_16x16x32_bf16 v[122:125], v[160:163], v[184:187], v[122:125]
	v_mfma_f32_16x16x32_bf16 v[106:109], v[156:159], v[188:191], 0
	v_mfma_f32_16x16x32_bf16 v[106:109], v[160:163], v[192:195], v[106:109]
	v_mfma_f32_16x16x32_bf16 v[110:113], v[148:151], v[188:191], 0
	v_mfma_f32_16x16x32_bf16 v[110:113], v[152:155], v[192:195], v[110:113]
	v_mfma_f32_16x16x32_bf16 v[94:97], v[148:151], v[196:199], 0
	v_mfma_f32_16x16x32_bf16 v[94:97], v[152:155], v[200:203], v[94:97]
	v_mfma_f32_16x16x32_bf16 v[90:93], v[156:159], v[196:199], 0
	v_mfma_f32_16x16x32_bf16 v[90:93], v[160:163], v[200:203], v[90:93]
	v_mfma_f32_16x16x32_bf16 v[74:77], v[156:159], v[204:207], 0
	v_mfma_f32_16x16x32_bf16 v[74:77], v[160:163], v[208:211], v[74:77]
	v_mfma_f32_16x16x32_bf16 v[78:81], v[148:151], v[204:207], 0
	v_mfma_f32_16x16x32_bf16 v[78:81], v[152:155], v[208:211], v[78:81]
	v_mfma_f32_16x16x32_bf16 v[118:121], v[164:167], v[180:183], 0
	v_mfma_f32_16x16x32_bf16 v[118:121], v[168:171], v[184:187], v[118:121]
	v_mfma_f32_16x16x32_bf16 v[114:117], v[172:175], v[180:183], 0
	v_mfma_f32_16x16x32_bf16 v[114:117], v[176:179], v[184:187], v[114:117]
	v_mfma_f32_16x16x32_bf16 v[98:101], v[172:175], v[188:191], 0
	v_mfma_f32_16x16x32_bf16 v[98:101], v[176:179], v[192:195], v[98:101]
	v_mfma_f32_16x16x32_bf16 v[102:105], v[164:167], v[188:191], 0
	v_mfma_f32_16x16x32_bf16 v[102:105], v[168:171], v[192:195], v[102:105]
	v_mfma_f32_16x16x32_bf16 v[86:89], v[164:167], v[196:199], 0
	v_mfma_f32_16x16x32_bf16 v[86:89], v[168:171], v[200:203], v[86:89]
	v_mfma_f32_16x16x32_bf16 v[82:85], v[172:175], v[196:199], 0
	v_mfma_f32_16x16x32_bf16 v[82:85], v[176:179], v[200:203], v[82:85]
	v_mfma_f32_16x16x32_bf16 v[66:69], v[172:175], v[204:207], 0
	v_mfma_f32_16x16x32_bf16 v[66:69], v[176:179], v[208:211], v[66:69]
	s_setprio 2
	s_barrier
	v_mfma_f32_16x16x32_bf16 v[70:73], v[164:167], v[204:207], 0
	v_mfma_f32_16x16x32_bf16 v[70:73], v[168:171], v[208:211], v[70:73]
	s_setprio 0
	ds_read_b128 v[180:183], v145 offset:16384
	ds_read_b128 v[184:187], v145 offset:17408
	ds_read_b128 v[188:191], v145 offset:18432
	ds_read_b128 v[192:195], v145 offset:19456
	ds_read_b128 v[196:199], v145 offset:20480
	ds_read_b128 v[200:203], v145 offset:21504
	ds_read_b128 v[204:207], v145 offset:22528
	ds_read_b128 v[208:211], v145 offset:23552
	s_mov_b32 s82, m0
	s_mov_b32 m0, s35
	s_nop 0
	global_load_lds_dwordx4 v139, s[20:21]
	s_mov_b32 m0, s82
	s_nop 0
	s_mov_b32 s82, m0
	s_mov_b32 m0, s36
	s_nop 0
	global_load_lds_dwordx4 v141, s[20:21]
	s_mov_b32 m0, s82
	s_add_u32 s82, s20, 0x80000
	s_addc_u32 s83, s21, 0
	s_mov_b32 s86, m0
	s_mov_b32 m0, s37
	s_nop 0
	global_load_lds_dwordx4 v139, s[82:83]
	s_mov_b32 m0, s86
	s_nop 0
	s_mov_b32 s86, m0
	s_mov_b32 m0, s42
	s_nop 0
	global_load_lds_dwordx4 v141, s[82:83]
	s_mov_b32 m0, s86
	s_waitcnt vmcnt(4)
	s_waitcnt lgkmcnt(0)
	s_barrier
	s_setprio 1
	.p2align 3
	v_mfma_f32_16x16x32_bf16 v[62:65], v[148:151], v[180:183], 0
	v_mfma_f32_16x16x32_bf16 v[62:65], v[152:155], v[184:187], v[62:65]
	v_mfma_f32_16x16x32_bf16 v[58:61], v[156:159], v[180:183], 0
	v_mfma_f32_16x16x32_bf16 v[58:61], v[160:163], v[184:187], v[58:61]
	v_mfma_f32_16x16x32_bf16 v[42:45], v[156:159], v[188:191], 0
	v_mfma_f32_16x16x32_bf16 v[42:45], v[160:163], v[192:195], v[42:45]
	v_mfma_f32_16x16x32_bf16 v[46:49], v[148:151], v[188:191], 0
	v_mfma_f32_16x16x32_bf16 v[46:49], v[152:155], v[192:195], v[46:49]
	v_mfma_f32_16x16x32_bf16 v[30:33], v[148:151], v[196:199], 0
	v_mfma_f32_16x16x32_bf16 v[30:33], v[152:155], v[200:203], v[30:33]
	v_mfma_f32_16x16x32_bf16 v[26:29], v[156:159], v[196:199], 0
	v_mfma_f32_16x16x32_bf16 v[26:29], v[160:163], v[200:203], v[26:29]
	v_mfma_f32_16x16x32_bf16 v[10:13], v[156:159], v[204:207], 0
	v_mfma_f32_16x16x32_bf16 v[10:13], v[160:163], v[208:211], v[10:13]
	v_mfma_f32_16x16x32_bf16 v[14:17], v[148:151], v[204:207], 0
	v_mfma_f32_16x16x32_bf16 v[14:17], v[152:155], v[208:211], v[14:17]
	v_mfma_f32_16x16x32_bf16 v[54:57], v[164:167], v[180:183], 0
	v_mfma_f32_16x16x32_bf16 v[54:57], v[168:171], v[184:187], v[54:57]
	v_mfma_f32_16x16x32_bf16 v[50:53], v[172:175], v[180:183], 0
	v_mfma_f32_16x16x32_bf16 v[50:53], v[176:179], v[184:187], v[50:53]
	v_mfma_f32_16x16x32_bf16 v[34:37], v[172:175], v[188:191], 0
	v_mfma_f32_16x16x32_bf16 v[34:37], v[176:179], v[192:195], v[34:37]
	v_mfma_f32_16x16x32_bf16 v[38:41], v[164:167], v[188:191], 0
	v_mfma_f32_16x16x32_bf16 v[38:41], v[168:171], v[192:195], v[38:41]
	v_mfma_f32_16x16x32_bf16 v[22:25], v[164:167], v[196:199], 0
	v_mfma_f32_16x16x32_bf16 v[22:25], v[168:171], v[200:203], v[22:25]
	v_mfma_f32_16x16x32_bf16 v[18:21], v[172:175], v[196:199], 0
	v_mfma_f32_16x16x32_bf16 v[18:21], v[176:179], v[200:203], v[18:21]
	v_mfma_f32_16x16x32_bf16 v[2:5], v[172:175], v[204:207], 0
	v_mfma_f32_16x16x32_bf16 v[2:5], v[176:179], v[208:211], v[2:5]
	s_setprio 2
	s_barrier
	v_mfma_f32_16x16x32_bf16 v[6:9], v[164:167], v[204:207], 0
	v_mfma_f32_16x16x32_bf16 v[6:9], v[168:171], v[208:211], v[6:9]
	s_setprio 0
	ds_read_b128 v[148:151], v146
	ds_read_b128 v[152:155], v146 offset:1024
	ds_read_b128 v[156:159], v146 offset:2048
	ds_read_b128 v[160:163], v146 offset:3072
	ds_read_b128 v[164:167], v147
	ds_read_b128 v[168:171], v147 offset:1024
	ds_read_b128 v[172:175], v147 offset:2048
	ds_read_b128 v[176:179], v147 offset:3072
	ds_read_b128 v[180:183], v145 offset:32768
	ds_read_b128 v[184:187], v145 offset:33792
	ds_read_b128 v[188:191], v145 offset:34816
	ds_read_b128 v[192:195], v145 offset:35840
	ds_read_b128 v[196:199], v145 offset:36864
	ds_read_b128 v[200:203], v145 offset:37888
	ds_read_b128 v[204:207], v145 offset:38912
	ds_read_b128 v[208:211], v145 offset:39936
	s_mov_b32 s82, m0
	s_mov_b32 m0, s31
	s_nop 0
	global_load_lds_dwordx4 v138, s[22:23]
	s_mov_b32 m0, s82
	s_nop 0
	s_mov_b32 s82, m0
	s_mov_b32 m0, s43
	s_nop 0
	global_load_lds_dwordx4 v140, s[22:23]
	s_mov_b32 m0, s82
	s_add_u32 s22, s22, 0x80000
	s_addc_u32 s23, s23, 0
	s_mov_b32 s82, m0
	s_mov_b32 m0, s46
	s_nop 0
	global_load_lds_dwordx4 v138, s[22:23]
	s_mov_b32 m0, s82
	s_nop 0
	s_mov_b32 s82, m0
	s_mov_b32 m0, s47
	s_nop 0
	global_load_lds_dwordx4 v140, s[22:23]
	s_mov_b32 m0, s82
	s_waitcnt vmcnt(8)
	s_waitcnt lgkmcnt(0)
	s_barrier
	s_setprio 1
	.p2align 3
	v_mfma_f32_16x16x32_bf16 v[126:129], v[148:151], v[180:183], v[126:129]
	v_mfma_f32_16x16x32_bf16 v[126:129], v[152:155], v[184:187], v[126:129]
	v_mfma_f32_16x16x32_bf16 v[122:125], v[156:159], v[180:183], v[122:125]
	v_mfma_f32_16x16x32_bf16 v[122:125], v[160:163], v[184:187], v[122:125]
	v_mfma_f32_16x16x32_bf16 v[106:109], v[156:159], v[188:191], v[106:109]
	v_mfma_f32_16x16x32_bf16 v[106:109], v[160:163], v[192:195], v[106:109]
	v_mfma_f32_16x16x32_bf16 v[110:113], v[148:151], v[188:191], v[110:113]
	v_mfma_f32_16x16x32_bf16 v[110:113], v[152:155], v[192:195], v[110:113]
	v_mfma_f32_16x16x32_bf16 v[94:97], v[148:151], v[196:199], v[94:97]
	v_mfma_f32_16x16x32_bf16 v[94:97], v[152:155], v[200:203], v[94:97]
	v_mfma_f32_16x16x32_bf16 v[90:93], v[156:159], v[196:199], v[90:93]
	v_mfma_f32_16x16x32_bf16 v[90:93], v[160:163], v[200:203], v[90:93]
	v_mfma_f32_16x16x32_bf16 v[74:77], v[156:159], v[204:207], v[74:77]
	v_mfma_f32_16x16x32_bf16 v[74:77], v[160:163], v[208:211], v[74:77]
	v_mfma_f32_16x16x32_bf16 v[78:81], v[148:151], v[204:207], v[78:81]
	v_mfma_f32_16x16x32_bf16 v[78:81], v[152:155], v[208:211], v[78:81]
	v_mfma_f32_16x16x32_bf16 v[118:121], v[164:167], v[180:183], v[118:121]
	v_mfma_f32_16x16x32_bf16 v[118:121], v[168:171], v[184:187], v[118:121]
	v_mfma_f32_16x16x32_bf16 v[114:117], v[172:175], v[180:183], v[114:117]
	v_mfma_f32_16x16x32_bf16 v[114:117], v[176:179], v[184:187], v[114:117]
	v_mfma_f32_16x16x32_bf16 v[98:101], v[172:175], v[188:191], v[98:101]
	v_mfma_f32_16x16x32_bf16 v[98:101], v[176:179], v[192:195], v[98:101]
	v_mfma_f32_16x16x32_bf16 v[102:105], v[164:167], v[188:191], v[102:105]
	v_mfma_f32_16x16x32_bf16 v[102:105], v[168:171], v[192:195], v[102:105]
	v_mfma_f32_16x16x32_bf16 v[86:89], v[164:167], v[196:199], v[86:89]
	v_mfma_f32_16x16x32_bf16 v[86:89], v[168:171], v[200:203], v[86:89]
	v_mfma_f32_16x16x32_bf16 v[82:85], v[172:175], v[196:199], v[82:85]
	v_mfma_f32_16x16x32_bf16 v[82:85], v[176:179], v[200:203], v[82:85]
	v_mfma_f32_16x16x32_bf16 v[66:69], v[172:175], v[204:207], v[66:69]
	v_mfma_f32_16x16x32_bf16 v[66:69], v[176:179], v[208:211], v[66:69]
	s_setprio 2
	s_barrier
	v_mfma_f32_16x16x32_bf16 v[70:73], v[164:167], v[204:207], v[70:73]
	v_mfma_f32_16x16x32_bf16 v[70:73], v[168:171], v[208:211], v[70:73]
	s_setprio 0
	ds_read_b128 v[180:183], v145 offset:49152
	ds_read_b128 v[184:187], v145 offset:50176
	ds_read_b128 v[188:191], v145 offset:51200
	ds_read_b128 v[192:195], v145 offset:52224
	ds_read_b128 v[196:199], v145 offset:53248
	ds_read_b128 v[200:203], v145 offset:54272
	ds_read_b128 v[204:207], v145 offset:55296
	ds_read_b128 v[208:211], v145 offset:56320
	s_add_u32 s22, s20, 0x80
	s_addc_u32 s23, s21, 0
	s_mov_b32 s82, m0
	s_mov_b32 m0, s48
	s_nop 0
	global_load_lds_dwordx4 v139, s[22:23]
	s_mov_b32 m0, s82
	s_add_u32 s20, s20, 0x80080
	s_mov_b32 s82, m0
	s_mov_b32 m0, s49
	s_nop 0
	global_load_lds_dwordx4 v141, s[22:23]
	s_mov_b32 m0, s82
	s_addc_u32 s21, s21, 0
	s_mov_b32 s22, m0
	s_mov_b32 m0, s56
	s_nop 0
	global_load_lds_dwordx4 v139, s[20:21]
	s_mov_b32 m0, s22
	s_nop 0
	s_mov_b32 s22, m0
	s_mov_b32 m0, s57
	s_nop 0
	global_load_lds_dwordx4 v141, s[20:21]
	s_mov_b32 m0, s22
	s_waitcnt vmcnt(4)
	s_waitcnt lgkmcnt(0)
	s_barrier
	s_setprio 1
	.p2align 3
	v_mfma_f32_16x16x32_bf16 v[62:65], v[148:151], v[180:183], v[62:65]
	v_mfma_f32_16x16x32_bf16 v[62:65], v[152:155], v[184:187], v[62:65]
	v_mfma_f32_16x16x32_bf16 v[58:61], v[156:159], v[180:183], v[58:61]
	v_mfma_f32_16x16x32_bf16 v[58:61], v[160:163], v[184:187], v[58:61]
	v_mfma_f32_16x16x32_bf16 v[42:45], v[156:159], v[188:191], v[42:45]
	v_mfma_f32_16x16x32_bf16 v[42:45], v[160:163], v[192:195], v[42:45]
	v_mfma_f32_16x16x32_bf16 v[46:49], v[148:151], v[188:191], v[46:49]
	v_mfma_f32_16x16x32_bf16 v[46:49], v[152:155], v[192:195], v[46:49]
	v_mfma_f32_16x16x32_bf16 v[30:33], v[148:151], v[196:199], v[30:33]
	v_mfma_f32_16x16x32_bf16 v[30:33], v[152:155], v[200:203], v[30:33]
	v_mfma_f32_16x16x32_bf16 v[26:29], v[156:159], v[196:199], v[26:29]
	v_mfma_f32_16x16x32_bf16 v[26:29], v[160:163], v[200:203], v[26:29]
	v_mfma_f32_16x16x32_bf16 v[10:13], v[156:159], v[204:207], v[10:13]
	v_mfma_f32_16x16x32_bf16 v[10:13], v[160:163], v[208:211], v[10:13]
	v_mfma_f32_16x16x32_bf16 v[14:17], v[148:151], v[204:207], v[14:17]
	v_mfma_f32_16x16x32_bf16 v[14:17], v[152:155], v[208:211], v[14:17]
	v_mfma_f32_16x16x32_bf16 v[54:57], v[164:167], v[180:183], v[54:57]
	v_mfma_f32_16x16x32_bf16 v[54:57], v[168:171], v[184:187], v[54:57]
	v_mfma_f32_16x16x32_bf16 v[50:53], v[172:175], v[180:183], v[50:53]
	v_mfma_f32_16x16x32_bf16 v[50:53], v[176:179], v[184:187], v[50:53]
	v_mfma_f32_16x16x32_bf16 v[34:37], v[172:175], v[188:191], v[34:37]
	v_mfma_f32_16x16x32_bf16 v[34:37], v[176:179], v[192:195], v[34:37]
	v_mfma_f32_16x16x32_bf16 v[38:41], v[164:167], v[188:191], v[38:41]
	v_mfma_f32_16x16x32_bf16 v[38:41], v[168:171], v[192:195], v[38:41]
	v_mfma_f32_16x16x32_bf16 v[22:25], v[164:167], v[196:199], v[22:25]
	v_mfma_f32_16x16x32_bf16 v[22:25], v[168:171], v[200:203], v[22:25]
	v_mfma_f32_16x16x32_bf16 v[18:21], v[172:175], v[196:199], v[18:21]
	v_mfma_f32_16x16x32_bf16 v[18:21], v[176:179], v[200:203], v[18:21]
	v_mfma_f32_16x16x32_bf16 v[2:5], v[172:175], v[204:207], v[2:5]
	v_mfma_f32_16x16x32_bf16 v[2:5], v[176:179], v[208:211], v[2:5]
	s_setprio 2
	s_barrier
	v_mfma_f32_16x16x32_bf16 v[6:9], v[164:167], v[204:207], v[6:9]
	v_mfma_f32_16x16x32_bf16 v[6:9], v[168:171], v[208:211], v[6:9]
	s_setprio 0
	s_add_i32 s81, s81, 2
	s_add_u32 s77, s77, 0x100
	s_addc_u32 s78, s78, 0
	s_add_u32 s18, s18, 0x100
	s_addc_u32 s19, s19, 0
	s_add_u32 s79, s79, 0x100
	s_addc_u32 s80, s80, 0
	s_cmp_gt_u32 s81, 29
	.p2align 6
.LBB0_344:
	ds_read_b128 v[148:151], v143
	ds_read_b128 v[152:155], v143 offset:1024
	ds_read_b128 v[156:159], v143 offset:2048
	ds_read_b128 v[160:163], v143 offset:3072
	ds_read_b128 v[164:167], v144
	ds_read_b128 v[168:171], v144 offset:1024
	ds_read_b128 v[172:175], v144 offset:2048
	ds_read_b128 v[176:179], v144 offset:3072
	s_cmp_eq_u32 s81, 28
	s_cselect_b32 s21, s9, s78
	s_cselect_b32 s20, s76, s77
	s_cselect_b32 s23, s11, s80
	s_cselect_b32 s22, s75, s79
	ds_read_b128 v[180:183], v145
	ds_read_b128 v[184:187], v145 offset:1024
	ds_read_b128 v[188:191], v145 offset:2048
	ds_read_b128 v[192:195], v145 offset:3072
	ds_read_b128 v[196:199], v145 offset:4096
	ds_read_b128 v[200:203], v145 offset:5120
	ds_read_b128 v[204:207], v145 offset:6144
	ds_read_b128 v[208:211], v145 offset:7168
	s_add_u32 s82, s18, 0xfff80000
	s_addc_u32 s83, s19, -1
	s_mov_b32 s86, m0
	s_mov_b32 m0, s64
	s_nop 0
	global_load_lds_dwordx4 v138, s[82:83]
	s_mov_b32 m0, s86
	s_nop 0
	s_mov_b32 s86, m0
	s_mov_b32 m0, s67
	s_nop 0
	global_load_lds_dwordx4 v140, s[82:83]
	s_mov_b32 m0, s86
	s_mov_b32 s82, m0
	s_mov_b32 m0, s65
	s_nop 0
	global_load_lds_dwordx4 v138, s[18:19]
	s_mov_b32 m0, s82
	s_nop 0
	s_mov_b32 s82, m0
	s_mov_b32 m0, s73
	s_nop 0
	global_load_lds_dwordx4 v140, s[18:19]
	s_mov_b32 m0, s82
	s_waitcnt vmcnt(8)
	s_waitcnt lgkmcnt(0)
	s_barrier
	s_setprio 1
	.p2align 3
	v_mfma_f32_16x16x32_bf16 v[126:129], v[148:151], v[180:183], v[126:129]
	v_mfma_f32_16x16x32_bf16 v[126:129], v[152:155], v[184:187], v[126:129]
	v_mfma_f32_16x16x32_bf16 v[122:125], v[156:159], v[180:183], v[122:125]
	v_mfma_f32_16x16x32_bf16 v[122:125], v[160:163], v[184:187], v[122:125]
	v_mfma_f32_16x16x32_bf16 v[106:109], v[156:159], v[188:191], v[106:109]
	v_mfma_f32_16x16x32_bf16 v[106:109], v[160:163], v[192:195], v[106:109]
	v_mfma_f32_16x16x32_bf16 v[110:113], v[148:151], v[188:191], v[110:113]
	v_mfma_f32_16x16x32_bf16 v[110:113], v[152:155], v[192:195], v[110:113]
	v_mfma_f32_16x16x32_bf16 v[94:97], v[148:151], v[196:199], v[94:97]
	v_mfma_f32_16x16x32_bf16 v[94:97], v[152:155], v[200:203], v[94:97]
	v_mfma_f32_16x16x32_bf16 v[90:93], v[156:159], v[196:199], v[90:93]
	v_mfma_f32_16x16x32_bf16 v[90:93], v[160:163], v[200:203], v[90:93]
	v_mfma_f32_16x16x32_bf16 v[74:77], v[156:159], v[204:207], v[74:77]
	v_mfma_f32_16x16x32_bf16 v[74:77], v[160:163], v[208:211], v[74:77]
	v_mfma_f32_16x16x32_bf16 v[78:81], v[148:151], v[204:207], v[78:81]
	v_mfma_f32_16x16x32_bf16 v[78:81], v[152:155], v[208:211], v[78:81]
	v_mfma_f32_16x16x32_bf16 v[118:121], v[164:167], v[180:183], v[118:121]
	v_mfma_f32_16x16x32_bf16 v[118:121], v[168:171], v[184:187], v[118:121]
	v_mfma_f32_16x16x32_bf16 v[114:117], v[172:175], v[180:183], v[114:117]
	v_mfma_f32_16x16x32_bf16 v[114:117], v[176:179], v[184:187], v[114:117]
	v_mfma_f32_16x16x32_bf16 v[98:101], v[172:175], v[188:191], v[98:101]
	v_mfma_f32_16x16x32_bf16 v[98:101], v[176:179], v[192:195], v[98:101]
	v_mfma_f32_16x16x32_bf16 v[102:105], v[164:167], v[188:191], v[102:105]
	v_mfma_f32_16x16x32_bf16 v[102:105], v[168:171], v[192:195], v[102:105]
	v_mfma_f32_16x16x32_bf16 v[86:89], v[164:167], v[196:199], v[86:89]
	v_mfma_f32_16x16x32_bf16 v[86:89], v[168:171], v[200:203], v[86:89]
	v_mfma_f32_16x16x32_bf16 v[82:85], v[172:175], v[196:199], v[82:85]
	v_mfma_f32_16x16x32_bf16 v[82:85], v[176:179], v[200:203], v[82:85]
	v_mfma_f32_16x16x32_bf16 v[66:69], v[172:175], v[204:207], v[66:69]
	v_mfma_f32_16x16x32_bf16 v[66:69], v[176:179], v[208:211], v[66:69]
	s_setprio 2
	s_barrier
	v_mfma_f32_16x16x32_bf16 v[70:73], v[164:167], v[204:207], v[70:73]
	v_mfma_f32_16x16x32_bf16 v[70:73], v[168:171], v[208:211], v[70:73]
	s_setprio 0
	ds_read_b128 v[180:183], v145 offset:16384
	ds_read_b128 v[184:187], v145 offset:17408
	ds_read_b128 v[188:191], v145 offset:18432
	ds_read_b128 v[192:195], v145 offset:19456
	ds_read_b128 v[196:199], v145 offset:20480
	ds_read_b128 v[200:203], v145 offset:21504
	ds_read_b128 v[204:207], v145 offset:22528
	ds_read_b128 v[208:211], v145 offset:23552
	s_mov_b32 s82, m0
	s_mov_b32 m0, s35
	s_nop 0
	global_load_lds_dwordx4 v139, s[20:21]
	s_mov_b32 m0, s82
	s_nop 0
	s_mov_b32 s82, m0
	s_mov_b32 m0, s36
	s_nop 0
	global_load_lds_dwordx4 v141, s[20:21]
	s_mov_b32 m0, s82
	s_add_u32 s82, s20, 0x80000
	s_addc_u32 s83, s21, 0
	s_mov_b32 s86, m0
	s_mov_b32 m0, s37
	s_nop 0
	global_load_lds_dwordx4 v139, s[82:83]
	s_mov_b32 m0, s86
	s_nop 0
	s_mov_b32 s86, m0
	s_mov_b32 m0, s42
	s_nop 0
	global_load_lds_dwordx4 v141, s[82:83]
	s_mov_b32 m0, s86
	s_waitcnt vmcnt(4)
	s_waitcnt lgkmcnt(0)
	s_barrier
	s_setprio 1
	.p2align 3
	v_mfma_f32_16x16x32_bf16 v[62:65], v[148:151], v[180:183], v[62:65]
	v_mfma_f32_16x16x32_bf16 v[62:65], v[152:155], v[184:187], v[62:65]
	v_mfma_f32_16x16x32_bf16 v[58:61], v[156:159], v[180:183], v[58:61]
	v_mfma_f32_16x16x32_bf16 v[58:61], v[160:163], v[184:187], v[58:61]
	v_mfma_f32_16x16x32_bf16 v[42:45], v[156:159], v[188:191], v[42:45]
	v_mfma_f32_16x16x32_bf16 v[42:45], v[160:163], v[192:195], v[42:45]
	v_mfma_f32_16x16x32_bf16 v[46:49], v[148:151], v[188:191], v[46:49]
	v_mfma_f32_16x16x32_bf16 v[46:49], v[152:155], v[192:195], v[46:49]
	v_mfma_f32_16x16x32_bf16 v[30:33], v[148:151], v[196:199], v[30:33]
	v_mfma_f32_16x16x32_bf16 v[30:33], v[152:155], v[200:203], v[30:33]
	v_mfma_f32_16x16x32_bf16 v[26:29], v[156:159], v[196:199], v[26:29]
	v_mfma_f32_16x16x32_bf16 v[26:29], v[160:163], v[200:203], v[26:29]
	v_mfma_f32_16x16x32_bf16 v[10:13], v[156:159], v[204:207], v[10:13]
	v_mfma_f32_16x16x32_bf16 v[10:13], v[160:163], v[208:211], v[10:13]
	v_mfma_f32_16x16x32_bf16 v[14:17], v[148:151], v[204:207], v[14:17]
	v_mfma_f32_16x16x32_bf16 v[14:17], v[152:155], v[208:211], v[14:17]
	v_mfma_f32_16x16x32_bf16 v[54:57], v[164:167], v[180:183], v[54:57]
	v_mfma_f32_16x16x32_bf16 v[54:57], v[168:171], v[184:187], v[54:57]
	v_mfma_f32_16x16x32_bf16 v[50:53], v[172:175], v[180:183], v[50:53]
	v_mfma_f32_16x16x32_bf16 v[50:53], v[176:179], v[184:187], v[50:53]
	v_mfma_f32_16x16x32_bf16 v[34:37], v[172:175], v[188:191], v[34:37]
	v_mfma_f32_16x16x32_bf16 v[34:37], v[176:179], v[192:195], v[34:37]
	v_mfma_f32_16x16x32_bf16 v[38:41], v[164:167], v[188:191], v[38:41]
	v_mfma_f32_16x16x32_bf16 v[38:41], v[168:171], v[192:195], v[38:41]
	v_mfma_f32_16x16x32_bf16 v[22:25], v[164:167], v[196:199], v[22:25]
	v_mfma_f32_16x16x32_bf16 v[22:25], v[168:171], v[200:203], v[22:25]
	v_mfma_f32_16x16x32_bf16 v[18:21], v[172:175], v[196:199], v[18:21]
	v_mfma_f32_16x16x32_bf16 v[18:21], v[176:179], v[200:203], v[18:21]
	v_mfma_f32_16x16x32_bf16 v[2:5], v[172:175], v[204:207], v[2:5]
	v_mfma_f32_16x16x32_bf16 v[2:5], v[176:179], v[208:211], v[2:5]
	s_setprio 2
	s_barrier
	v_mfma_f32_16x16x32_bf16 v[6:9], v[164:167], v[204:207], v[6:9]
	v_mfma_f32_16x16x32_bf16 v[6:9], v[168:171], v[208:211], v[6:9]
	s_setprio 0
	ds_read_b128 v[148:151], v146
	ds_read_b128 v[152:155], v146 offset:1024
	ds_read_b128 v[156:159], v146 offset:2048
	ds_read_b128 v[160:163], v146 offset:3072
	ds_read_b128 v[164:167], v147
	ds_read_b128 v[168:171], v147 offset:1024
	ds_read_b128 v[172:175], v147 offset:2048
	ds_read_b128 v[176:179], v147 offset:3072
	ds_read_b128 v[180:183], v145 offset:32768
	ds_read_b128 v[184:187], v145 offset:33792
	ds_read_b128 v[188:191], v145 offset:34816
	ds_read_b128 v[192:195], v145 offset:35840
	ds_read_b128 v[196:199], v145 offset:36864
	ds_read_b128 v[200:203], v145 offset:37888
	ds_read_b128 v[204:207], v145 offset:38912
	ds_read_b128 v[208:211], v145 offset:39936
	s_mov_b32 s82, m0
	s_mov_b32 m0, s31
	s_nop 0
	global_load_lds_dwordx4 v138, s[22:23]
	s_mov_b32 m0, s82
	s_nop 0
	s_mov_b32 s82, m0
	s_mov_b32 m0, s43
	s_nop 0
	global_load_lds_dwordx4 v140, s[22:23]
	s_mov_b32 m0, s82
	s_add_u32 s22, s22, 0x80000
	s_addc_u32 s23, s23, 0
	s_mov_b32 s82, m0
	s_mov_b32 m0, s46
	s_nop 0
	global_load_lds_dwordx4 v138, s[22:23]
	s_mov_b32 m0, s82
	s_nop 0
	s_mov_b32 s82, m0
	s_mov_b32 m0, s47
	s_nop 0
	global_load_lds_dwordx4 v140, s[22:23]
	s_mov_b32 m0, s82
	s_waitcnt vmcnt(8)
	s_waitcnt lgkmcnt(0)
	s_barrier
	s_setprio 1
	.p2align 3
	v_mfma_f32_16x16x32_bf16 v[126:129], v[148:151], v[180:183], v[126:129]
	v_mfma_f32_16x16x32_bf16 v[126:129], v[152:155], v[184:187], v[126:129]
	v_mfma_f32_16x16x32_bf16 v[122:125], v[156:159], v[180:183], v[122:125]
	v_mfma_f32_16x16x32_bf16 v[122:125], v[160:163], v[184:187], v[122:125]
	v_mfma_f32_16x16x32_bf16 v[106:109], v[156:159], v[188:191], v[106:109]
	v_mfma_f32_16x16x32_bf16 v[106:109], v[160:163], v[192:195], v[106:109]
	v_mfma_f32_16x16x32_bf16 v[110:113], v[148:151], v[188:191], v[110:113]
	v_mfma_f32_16x16x32_bf16 v[110:113], v[152:155], v[192:195], v[110:113]
	v_mfma_f32_16x16x32_bf16 v[94:97], v[148:151], v[196:199], v[94:97]
	v_mfma_f32_16x16x32_bf16 v[94:97], v[152:155], v[200:203], v[94:97]
	v_mfma_f32_16x16x32_bf16 v[90:93], v[156:159], v[196:199], v[90:93]
	v_mfma_f32_16x16x32_bf16 v[90:93], v[160:163], v[200:203], v[90:93]
	v_mfma_f32_16x16x32_bf16 v[74:77], v[156:159], v[204:207], v[74:77]
	v_mfma_f32_16x16x32_bf16 v[74:77], v[160:163], v[208:211], v[74:77]
	v_mfma_f32_16x16x32_bf16 v[78:81], v[148:151], v[204:207], v[78:81]
	v_mfma_f32_16x16x32_bf16 v[78:81], v[152:155], v[208:211], v[78:81]
	v_mfma_f32_16x16x32_bf16 v[118:121], v[164:167], v[180:183], v[118:121]
	v_mfma_f32_16x16x32_bf16 v[118:121], v[168:171], v[184:187], v[118:121]
	v_mfma_f32_16x16x32_bf16 v[114:117], v[172:175], v[180:183], v[114:117]
	v_mfma_f32_16x16x32_bf16 v[114:117], v[176:179], v[184:187], v[114:117]
	v_mfma_f32_16x16x32_bf16 v[98:101], v[172:175], v[188:191], v[98:101]
	v_mfma_f32_16x16x32_bf16 v[98:101], v[176:179], v[192:195], v[98:101]
	v_mfma_f32_16x16x32_bf16 v[102:105], v[164:167], v[188:191], v[102:105]
	v_mfma_f32_16x16x32_bf16 v[102:105], v[168:171], v[192:195], v[102:105]
	v_mfma_f32_16x16x32_bf16 v[86:89], v[164:167], v[196:199], v[86:89]
	v_mfma_f32_16x16x32_bf16 v[86:89], v[168:171], v[200:203], v[86:89]
	v_mfma_f32_16x16x32_bf16 v[82:85], v[172:175], v[196:199], v[82:85]
	v_mfma_f32_16x16x32_bf16 v[82:85], v[176:179], v[200:203], v[82:85]
	v_mfma_f32_16x16x32_bf16 v[66:69], v[172:175], v[204:207], v[66:69]
	v_mfma_f32_16x16x32_bf16 v[66:69], v[176:179], v[208:211], v[66:69]
	s_setprio 2
	s_barrier
	v_mfma_f32_16x16x32_bf16 v[70:73], v[164:167], v[204:207], v[70:73]
	v_mfma_f32_16x16x32_bf16 v[70:73], v[168:171], v[208:211], v[70:73]
	s_setprio 0
	ds_read_b128 v[180:183], v145 offset:49152
	ds_read_b128 v[184:187], v145 offset:50176
	ds_read_b128 v[188:191], v145 offset:51200
	ds_read_b128 v[192:195], v145 offset:52224
	ds_read_b128 v[196:199], v145 offset:53248
	ds_read_b128 v[200:203], v145 offset:54272
	ds_read_b128 v[204:207], v145 offset:55296
	ds_read_b128 v[208:211], v145 offset:56320
	s_add_u32 s22, s20, 0x80
	s_addc_u32 s23, s21, 0
	s_mov_b32 s82, m0
	s_mov_b32 m0, s48
	s_nop 0
	global_load_lds_dwordx4 v139, s[22:23]
	s_mov_b32 m0, s82
	s_add_u32 s20, s20, 0x80080
	s_mov_b32 s82, m0
	s_mov_b32 m0, s49
	s_nop 0
	global_load_lds_dwordx4 v141, s[22:23]
	s_mov_b32 m0, s82
	s_addc_u32 s21, s21, 0
	s_mov_b32 s22, m0
	s_mov_b32 m0, s56
	s_nop 0
	global_load_lds_dwordx4 v139, s[20:21]
	s_mov_b32 m0, s22
	s_nop 0
	s_mov_b32 s22, m0
	s_mov_b32 m0, s57
	s_nop 0
	global_load_lds_dwordx4 v141, s[20:21]
	s_mov_b32 m0, s22
	s_waitcnt vmcnt(4)
	s_waitcnt lgkmcnt(0)
	s_barrier
	s_setprio 1
	.p2align 3
	v_mfma_f32_16x16x32_bf16 v[62:65], v[148:151], v[180:183], v[62:65]
	v_mfma_f32_16x16x32_bf16 v[62:65], v[152:155], v[184:187], v[62:65]
	v_mfma_f32_16x16x32_bf16 v[58:61], v[156:159], v[180:183], v[58:61]
	v_mfma_f32_16x16x32_bf16 v[58:61], v[160:163], v[184:187], v[58:61]
	v_mfma_f32_16x16x32_bf16 v[42:45], v[156:159], v[188:191], v[42:45]
	v_mfma_f32_16x16x32_bf16 v[42:45], v[160:163], v[192:195], v[42:45]
	v_mfma_f32_16x16x32_bf16 v[46:49], v[148:151], v[188:191], v[46:49]
	v_mfma_f32_16x16x32_bf16 v[46:49], v[152:155], v[192:195], v[46:49]
	v_mfma_f32_16x16x32_bf16 v[30:33], v[148:151], v[196:199], v[30:33]
	v_mfma_f32_16x16x32_bf16 v[30:33], v[152:155], v[200:203], v[30:33]
	v_mfma_f32_16x16x32_bf16 v[26:29], v[156:159], v[196:199], v[26:29]
	v_mfma_f32_16x16x32_bf16 v[26:29], v[160:163], v[200:203], v[26:29]
	v_mfma_f32_16x16x32_bf16 v[10:13], v[156:159], v[204:207], v[10:13]
	v_mfma_f32_16x16x32_bf16 v[10:13], v[160:163], v[208:211], v[10:13]
	v_mfma_f32_16x16x32_bf16 v[14:17], v[148:151], v[204:207], v[14:17]
	v_mfma_f32_16x16x32_bf16 v[14:17], v[152:155], v[208:211], v[14:17]
	v_mfma_f32_16x16x32_bf16 v[54:57], v[164:167], v[180:183], v[54:57]
	v_mfma_f32_16x16x32_bf16 v[54:57], v[168:171], v[184:187], v[54:57]
	v_mfma_f32_16x16x32_bf16 v[50:53], v[172:175], v[180:183], v[50:53]
	v_mfma_f32_16x16x32_bf16 v[50:53], v[176:179], v[184:187], v[50:53]
	v_mfma_f32_16x16x32_bf16 v[34:37], v[172:175], v[188:191], v[34:37]
	v_mfma_f32_16x16x32_bf16 v[34:37], v[176:179], v[192:195], v[34:37]
	v_mfma_f32_16x16x32_bf16 v[38:41], v[164:167], v[188:191], v[38:41]
	v_mfma_f32_16x16x32_bf16 v[38:41], v[168:171], v[192:195], v[38:41]
	v_mfma_f32_16x16x32_bf16 v[22:25], v[164:167], v[196:199], v[22:25]
	v_mfma_f32_16x16x32_bf16 v[22:25], v[168:171], v[200:203], v[22:25]
	v_mfma_f32_16x16x32_bf16 v[18:21], v[172:175], v[196:199], v[18:21]
	v_mfma_f32_16x16x32_bf16 v[18:21], v[176:179], v[200:203], v[18:21]
	v_mfma_f32_16x16x32_bf16 v[2:5], v[172:175], v[204:207], v[2:5]
	v_mfma_f32_16x16x32_bf16 v[2:5], v[176:179], v[208:211], v[2:5]
	s_setprio 2
	s_barrier
	v_mfma_f32_16x16x32_bf16 v[6:9], v[164:167], v[204:207], v[6:9]
	v_mfma_f32_16x16x32_bf16 v[6:9], v[168:171], v[208:211], v[6:9]
	s_setprio 0
	s_add_i32 s81, s81, 2
	s_add_u32 s77, s77, 0x100
	s_addc_u32 s78, s78, 0
	s_add_u32 s18, s18, 0x100
	s_addc_u32 s19, s19, 0
	s_add_u32 s79, s79, 0x100
	s_addc_u32 s80, s80, 0
	s_cmp_gt_u32 s81, 29
	s_cbranch_scc0 .LBB0_344
	s_and_b64 vcc, exec, s[6:7]
	s_cbranch_vccz .LBB0_347
	s_barrier

.LBB0_472:
	s_ashr_i32 s13, s12, 31
	s_lshl_b64 s[14:15], s[12:13], 15
	s_add_u32 s14, s28, s14
	s_addc_u32 s15, s29, s15
	s_and_b64 s[16:17], s[2:3], exec
	s_cselect_b32 s13, s15, s23
	s_cselect_b32 s76, s14, s22
	s_ashr_i32 s11, s10, 31
	s_lshl_b64 s[16:17], s[10:11], 15
	s_add_u32 s16, s30, s16
	s_addc_u32 s17, s31, s17
	s_and_b64 s[24:25], s[2:3], exec
	s_cselect_b32 s11, s17, s21
	s_cselect_b32 s77, s16, s20
	s_add_u32 s78, s20, 0x80000
	s_addc_u32 s79, s21, 0
	s_add_u32 s20, s22, 0x204000
	s_addc_u32 s21, s23, 0
	s_add_u32 s80, s22, 0x400000
	s_addc_u32 s81, s23, 0
	s_mov_b32 s82, -2
	s_waitcnt vmcnt(25)
	s_waitcnt vmcnt(24)
	s_waitcnt vmcnt(23)
	s_waitcnt vmcnt(22)
	s_waitcnt vmcnt(21)
	s_waitcnt vmcnt(20)
	s_waitcnt vmcnt(15)
	s_waitcnt vmcnt(14)
	s_waitcnt vmcnt(13)
	s_waitcnt vmcnt(12)
	s_waitcnt vmcnt(7)
	s_waitcnt vmcnt(6)
	s_waitcnt vmcnt(5)
	s_waitcnt vmcnt(4)
	s_waitcnt vmcnt(3)
	s_waitcnt vmcnt(2)
	s_waitcnt vmcnt(1)
	s_waitcnt vmcnt(0)
	ds_read_b128 v[134:137], v161
	ds_read_b128 v[138:141], v161 offset:1024
	ds_read_b128 v[142:145], v161 offset:2048
	ds_read_b128 v[146:149], v161 offset:3072
	ds_read_b128 v[150:153], v162
	ds_read_b128 v[166:169], v162 offset:1024
	ds_read_b128 v[170:173], v162 offset:2048
	ds_read_b128 v[174:177], v162 offset:3072
	s_cmpk_eq_i32 s82, 0x52
	s_cselect_b32 s23, s11, s79
	s_cselect_b32 s22, s77, s78
	s_cselect_b32 s25, s13, s81
	s_cselect_b32 s24, s76, s80
	ds_read_b128 v[178:181], v163
	ds_read_b128 v[182:185], v163 offset:1024
	ds_read_b128 v[186:189], v163 offset:2048
	ds_read_b128 v[190:193], v163 offset:3072
	ds_read_b128 v[194:197], v163 offset:4096
	ds_read_b128 v[198:201], v163 offset:5120
	ds_read_b128 v[202:205], v163 offset:6144
	ds_read_b128 v[206:209], v163 offset:7168
	s_add_u32 s86, s20, 0xffffc000
	s_addc_u32 s87, s21, -1
	s_mov_b32 s83, m0
	s_mov_b32 m0, s65
	s_nop 0
	global_load_lds_dwordx4 v1, s[86:87]
	s_mov_b32 m0, s83
	s_nop 0
	s_mov_b32 s83, m0
	s_mov_b32 m0, s67
	s_nop 0
	global_load_lds_dwordx4 v157, s[86:87]
	s_mov_b32 m0, s83
	s_nop 0
	s_mov_b32 s83, m0
	s_mov_b32 m0, s66
	s_nop 0
	global_load_lds_dwordx4 v1, s[20:21]
	s_mov_b32 m0, s83
	s_nop 0
	s_mov_b32 s83, m0
	s_mov_b32 m0, s73
	s_nop 0
	global_load_lds_dwordx4 v157, s[20:21]
	s_mov_b32 m0, s83
	s_waitcnt vmcnt(8)
	s_waitcnt lgkmcnt(0)
	s_barrier
	s_setprio 1
	.p2align 3
	v_mfma_f32_16x16x32_bf16 v[126:129], v[134:137], v[178:181], 0
	v_mfma_f32_16x16x32_bf16 v[126:129], v[138:141], v[182:185], v[126:129]
	v_mfma_f32_16x16x32_bf16 v[122:125], v[142:145], v[178:181], 0
	v_mfma_f32_16x16x32_bf16 v[122:125], v[146:149], v[182:185], v[122:125]
	v_mfma_f32_16x16x32_bf16 v[114:117], v[142:145], v[186:189], 0
	v_mfma_f32_16x16x32_bf16 v[114:117], v[146:149], v[190:193], v[114:117]
	v_mfma_f32_16x16x32_bf16 v[118:121], v[134:137], v[186:189], 0
	v_mfma_f32_16x16x32_bf16 v[118:121], v[138:141], v[190:193], v[118:121]
	v_mfma_f32_16x16x32_bf16 v[102:105], v[134:137], v[194:197], 0
	v_mfma_f32_16x16x32_bf16 v[102:105], v[138:141], v[198:201], v[102:105]
	v_mfma_f32_16x16x32_bf16 v[94:97], v[142:145], v[194:197], 0
	v_mfma_f32_16x16x32_bf16 v[94:97], v[146:149], v[198:201], v[94:97]
	v_mfma_f32_16x16x32_bf16 v[78:81], v[142:145], v[202:205], 0
	v_mfma_f32_16x16x32_bf16 v[78:81], v[146:149], v[206:209], v[78:81]
	v_mfma_f32_16x16x32_bf16 v[86:89], v[134:137], v[202:205], 0
	v_mfma_f32_16x16x32_bf16 v[86:89], v[138:141], v[206:209], v[86:89]
	v_mfma_f32_16x16x32_bf16 v[110:113], v[150:153], v[178:181], 0
	v_mfma_f32_16x16x32_bf16 v[110:113], v[166:169], v[182:185], v[110:113]
	v_mfma_f32_16x16x32_bf16 v[106:109], v[170:173], v[178:181], 0
	v_mfma_f32_16x16x32_bf16 v[106:109], v[174:177], v[182:185], v[106:109]
	v_mfma_f32_16x16x32_bf16 v[90:93], v[170:173], v[186:189], 0
	v_mfma_f32_16x16x32_bf16 v[90:93], v[174:177], v[190:193], v[90:93]
	v_mfma_f32_16x16x32_bf16 v[98:101], v[150:153], v[186:189], 0
	v_mfma_f32_16x16x32_bf16 v[98:101], v[166:169], v[190:193], v[98:101]
	v_mfma_f32_16x16x32_bf16 v[82:85], v[150:153], v[194:197], 0
	v_mfma_f32_16x16x32_bf16 v[82:85], v[166:169], v[198:201], v[82:85]
	v_mfma_f32_16x16x32_bf16 v[74:77], v[170:173], v[194:197], 0
	v_mfma_f32_16x16x32_bf16 v[74:77], v[174:177], v[198:201], v[74:77]
	v_mfma_f32_16x16x32_bf16 v[66:69], v[170:173], v[202:205], 0
	v_mfma_f32_16x16x32_bf16 v[66:69], v[174:177], v[206:209], v[66:69]
	s_setprio 2
	s_barrier
	v_mfma_f32_16x16x32_bf16 v[70:73], v[150:153], v[202:205], 0
	v_mfma_f32_16x16x32_bf16 v[70:73], v[166:169], v[206:209], v[70:73]
	s_setprio 0
	ds_read_b128 v[178:181], v163 offset:16384
	ds_read_b128 v[182:185], v163 offset:17408
	ds_read_b128 v[186:189], v163 offset:18432
	ds_read_b128 v[190:193], v163 offset:19456
	ds_read_b128 v[194:197], v163 offset:20480
	ds_read_b128 v[198:201], v163 offset:21504
	ds_read_b128 v[202:205], v163 offset:22528
	ds_read_b128 v[206:209], v163 offset:23552
	s_mov_b32 s83, m0
	s_mov_b32 m0, s19
	s_nop 0
	global_load_lds_dwordx4 v156, s[22:23]
	s_mov_b32 m0, s83
	s_add_u32 s86, s22, 0x4000
	s_mov_b32 s83, m0
	s_mov_b32 m0, s35
	s_nop 0
	global_load_lds_dwordx4 v158, s[22:23]
	s_mov_b32 m0, s83
	s_addc_u32 s87, s23, 0
	s_mov_b32 s83, m0
	s_mov_b32 m0, s36
	s_nop 0
	global_load_lds_dwordx4 v156, s[86:87]
	s_mov_b32 m0, s83
	s_nop 0
	s_mov_b32 s83, m0
	s_mov_b32 m0, s37
	s_nop 0
	global_load_lds_dwordx4 v158, s[86:87]
	s_mov_b32 m0, s83
	s_waitcnt vmcnt(4)
	s_waitcnt lgkmcnt(0)
	s_barrier
	s_setprio 1
	.p2align 3
	v_mfma_f32_16x16x32_bf16 v[62:65], v[134:137], v[178:181], 0
	v_mfma_f32_16x16x32_bf16 v[62:65], v[138:141], v[182:185], v[62:65]
	v_mfma_f32_16x16x32_bf16 v[58:61], v[142:145], v[178:181], 0
	v_mfma_f32_16x16x32_bf16 v[58:61], v[146:149], v[182:185], v[58:61]
	v_mfma_f32_16x16x32_bf16 v[46:49], v[142:145], v[186:189], 0
	v_mfma_f32_16x16x32_bf16 v[46:49], v[146:149], v[190:193], v[46:49]
	v_mfma_f32_16x16x32_bf16 v[54:57], v[134:137], v[186:189], 0
	v_mfma_f32_16x16x32_bf16 v[54:57], v[138:141], v[190:193], v[54:57]
	v_mfma_f32_16x16x32_bf16 v[38:41], v[134:137], v[194:197], 0
	v_mfma_f32_16x16x32_bf16 v[38:41], v[138:141], v[198:201], v[38:41]
	v_mfma_f32_16x16x32_bf16 v[30:33], v[142:145], v[194:197], 0
	v_mfma_f32_16x16x32_bf16 v[30:33], v[146:149], v[198:201], v[30:33]
	v_mfma_f32_16x16x32_bf16 v[14:17], v[142:145], v[202:205], 0
	v_mfma_f32_16x16x32_bf16 v[14:17], v[146:149], v[206:209], v[14:17]
	v_mfma_f32_16x16x32_bf16 v[22:25], v[134:137], v[202:205], 0
	v_mfma_f32_16x16x32_bf16 v[22:25], v[138:141], v[206:209], v[22:25]
	v_mfma_f32_16x16x32_bf16 v[50:53], v[150:153], v[178:181], 0
	v_mfma_f32_16x16x32_bf16 v[50:53], v[166:169], v[182:185], v[50:53]
	v_mfma_f32_16x16x32_bf16 v[42:45], v[170:173], v[178:181], 0
	v_mfma_f32_16x16x32_bf16 v[42:45], v[174:177], v[182:185], v[42:45]
	v_mfma_f32_16x16x32_bf16 v[26:29], v[170:173], v[186:189], 0
	v_mfma_f32_16x16x32_bf16 v[26:29], v[174:177], v[190:193], v[26:29]
	v_mfma_f32_16x16x32_bf16 v[34:37], v[150:153], v[186:189], 0
	v_mfma_f32_16x16x32_bf16 v[34:37], v[166:169], v[190:193], v[34:37]
	v_mfma_f32_16x16x32_bf16 v[18:21], v[150:153], v[194:197], 0
	v_mfma_f32_16x16x32_bf16 v[18:21], v[166:169], v[198:201], v[18:21]
	v_mfma_f32_16x16x32_bf16 v[10:13], v[170:173], v[194:197], 0
	v_mfma_f32_16x16x32_bf16 v[10:13], v[174:177], v[198:201], v[10:13]
	v_mfma_f32_16x16x32_bf16 v[2:5], v[170:173], v[202:205], 0
	v_mfma_f32_16x16x32_bf16 v[2:5], v[174:177], v[206:209], v[2:5]
	s_setprio 2
	s_barrier
	v_mfma_f32_16x16x32_bf16 v[6:9], v[150:153], v[202:205], 0
	v_mfma_f32_16x16x32_bf16 v[6:9], v[166:169], v[206:209], v[6:9]
	s_setprio 0
	ds_read_b128 v[134:137], v164
	ds_read_b128 v[138:141], v164 offset:1024
	ds_read_b128 v[142:145], v164 offset:2048
	ds_read_b128 v[146:149], v164 offset:3072
	ds_read_b128 v[150:153], v165
	ds_read_b128 v[166:169], v165 offset:1024
	ds_read_b128 v[170:173], v165 offset:2048
	ds_read_b128 v[174:177], v165 offset:3072
	ds_read_b128 v[178:181], v163 offset:32768
	ds_read_b128 v[182:185], v163 offset:33792
	ds_read_b128 v[186:189], v163 offset:34816
	ds_read_b128 v[190:193], v163 offset:35840
	ds_read_b128 v[194:197], v163 offset:36864
	ds_read_b128 v[198:201], v163 offset:37888
	ds_read_b128 v[202:205], v163 offset:38912
	ds_read_b128 v[206:209], v163 offset:39936
	s_mov_b32 s83, m0
	s_mov_b32 m0, s34
	s_nop 0
	global_load_lds_dwordx4 v1, s[24:25]
	s_mov_b32 m0, s83
	s_nop 0
	s_mov_b32 s83, m0
	s_mov_b32 m0, s42
	s_nop 0
	global_load_lds_dwordx4 v157, s[24:25]
	s_mov_b32 m0, s83
	s_add_u32 s24, s24, 0x4000
	s_addc_u32 s25, s25, 0
	s_mov_b32 s83, m0
	s_mov_b32 m0, s43
	s_nop 0
	global_load_lds_dwordx4 v1, s[24:25]
	s_mov_b32 m0, s83
	s_nop 0
	s_mov_b32 s83, m0
	s_mov_b32 m0, s46
	s_nop 0
	global_load_lds_dwordx4 v157, s[24:25]
	s_mov_b32 m0, s83
	s_waitcnt vmcnt(8)
	s_waitcnt lgkmcnt(0)
	s_barrier
	s_setprio 1
	.p2align 3
	v_mfma_f32_16x16x32_bf16 v[126:129], v[134:137], v[178:181], v[126:129]
	v_mfma_f32_16x16x32_bf16 v[126:129], v[138:141], v[182:185], v[126:129]
	v_mfma_f32_16x16x32_bf16 v[122:125], v[142:145], v[178:181], v[122:125]
	v_mfma_f32_16x16x32_bf16 v[122:125], v[146:149], v[182:185], v[122:125]
	v_mfma_f32_16x16x32_bf16 v[114:117], v[142:145], v[186:189], v[114:117]
	v_mfma_f32_16x16x32_bf16 v[114:117], v[146:149], v[190:193], v[114:117]
	v_mfma_f32_16x16x32_bf16 v[118:121], v[134:137], v[186:189], v[118:121]
	v_mfma_f32_16x16x32_bf16 v[118:121], v[138:141], v[190:193], v[118:121]
	v_mfma_f32_16x16x32_bf16 v[102:105], v[134:137], v[194:197], v[102:105]
	v_mfma_f32_16x16x32_bf16 v[102:105], v[138:141], v[198:201], v[102:105]
	v_mfma_f32_16x16x32_bf16 v[94:97], v[142:145], v[194:197], v[94:97]
	v_mfma_f32_16x16x32_bf16 v[94:97], v[146:149], v[198:201], v[94:97]
	v_mfma_f32_16x16x32_bf16 v[78:81], v[142:145], v[202:205], v[78:81]
	v_mfma_f32_16x16x32_bf16 v[78:81], v[146:149], v[206:209], v[78:81]
	v_mfma_f32_16x16x32_bf16 v[86:89], v[134:137], v[202:205], v[86:89]
	v_mfma_f32_16x16x32_bf16 v[86:89], v[138:141], v[206:209], v[86:89]
	v_mfma_f32_16x16x32_bf16 v[110:113], v[150:153], v[178:181], v[110:113]
	v_mfma_f32_16x16x32_bf16 v[110:113], v[166:169], v[182:185], v[110:113]
	v_mfma_f32_16x16x32_bf16 v[106:109], v[170:173], v[178:181], v[106:109]
	v_mfma_f32_16x16x32_bf16 v[106:109], v[174:177], v[182:185], v[106:109]
	v_mfma_f32_16x16x32_bf16 v[90:93], v[170:173], v[186:189], v[90:93]
	v_mfma_f32_16x16x32_bf16 v[90:93], v[174:177], v[190:193], v[90:93]
	v_mfma_f32_16x16x32_bf16 v[98:101], v[150:153], v[186:189], v[98:101]
	v_mfma_f32_16x16x32_bf16 v[98:101], v[166:169], v[190:193], v[98:101]
	v_mfma_f32_16x16x32_bf16 v[82:85], v[150:153], v[194:197], v[82:85]
	v_mfma_f32_16x16x32_bf16 v[82:85], v[166:169], v[198:201], v[82:85]
	v_mfma_f32_16x16x32_bf16 v[74:77], v[170:173], v[194:197], v[74:77]
	v_mfma_f32_16x16x32_bf16 v[74:77], v[174:177], v[198:201], v[74:77]
	v_mfma_f32_16x16x32_bf16 v[66:69], v[170:173], v[202:205], v[66:69]
	v_mfma_f32_16x16x32_bf16 v[66:69], v[174:177], v[206:209], v[66:69]
	s_setprio 2
	s_barrier
	v_mfma_f32_16x16x32_bf16 v[70:73], v[150:153], v[202:205], v[70:73]
	v_mfma_f32_16x16x32_bf16 v[70:73], v[166:169], v[206:209], v[70:73]
	s_setprio 0
	ds_read_b128 v[178:181], v163 offset:49152
	ds_read_b128 v[182:185], v163 offset:50176
	ds_read_b128 v[186:189], v163 offset:51200
	ds_read_b128 v[190:193], v163 offset:52224
	ds_read_b128 v[194:197], v163 offset:53248
	ds_read_b128 v[198:201], v163 offset:54272
	ds_read_b128 v[202:205], v163 offset:55296
	ds_read_b128 v[206:209], v163 offset:56320
	s_add_u32 s24, s22, 0x40000
	s_addc_u32 s25, s23, 0
	s_mov_b32 s83, m0
	s_mov_b32 m0, s47
	s_nop 0
	global_load_lds_dwordx4 v156, s[24:25]
	s_mov_b32 m0, s83
	s_add_u32 s22, s22, 0x44000
	s_mov_b32 s83, m0
	s_mov_b32 m0, s48
	s_nop 0
	global_load_lds_dwordx4 v158, s[24:25]
	s_mov_b32 m0, s83
	s_addc_u32 s23, s23, 0
	s_mov_b32 s24, m0
	s_mov_b32 m0, s49
	s_nop 0
	global_load_lds_dwordx4 v156, s[22:23]
	s_mov_b32 m0, s24
	s_nop 0
	s_mov_b32 s24, m0
	s_mov_b32 m0, s56
	s_nop 0
	global_load_lds_dwordx4 v158, s[22:23]
	s_mov_b32 m0, s24
	s_waitcnt vmcnt(4)
	s_waitcnt lgkmcnt(0)
	s_barrier
	s_setprio 1
	.p2align 3
	v_mfma_f32_16x16x32_bf16 v[62:65], v[134:137], v[178:181], v[62:65]
	v_mfma_f32_16x16x32_bf16 v[62:65], v[138:141], v[182:185], v[62:65]
	v_mfma_f32_16x16x32_bf16 v[58:61], v[142:145], v[178:181], v[58:61]
	v_mfma_f32_16x16x32_bf16 v[58:61], v[146:149], v[182:185], v[58:61]
	v_mfma_f32_16x16x32_bf16 v[46:49], v[142:145], v[186:189], v[46:49]
	v_mfma_f32_16x16x32_bf16 v[46:49], v[146:149], v[190:193], v[46:49]
	v_mfma_f32_16x16x32_bf16 v[54:57], v[134:137], v[186:189], v[54:57]
	v_mfma_f32_16x16x32_bf16 v[54:57], v[138:141], v[190:193], v[54:57]
	v_mfma_f32_16x16x32_bf16 v[38:41], v[134:137], v[194:197], v[38:41]
	v_mfma_f32_16x16x32_bf16 v[38:41], v[138:141], v[198:201], v[38:41]
	v_mfma_f32_16x16x32_bf16 v[30:33], v[142:145], v[194:197], v[30:33]
	v_mfma_f32_16x16x32_bf16 v[30:33], v[146:149], v[198:201], v[30:33]
	v_mfma_f32_16x16x32_bf16 v[14:17], v[142:145], v[202:205], v[14:17]
	v_mfma_f32_16x16x32_bf16 v[14:17], v[146:149], v[206:209], v[14:17]
	v_mfma_f32_16x16x32_bf16 v[22:25], v[134:137], v[202:205], v[22:25]
	v_mfma_f32_16x16x32_bf16 v[22:25], v[138:141], v[206:209], v[22:25]
	v_mfma_f32_16x16x32_bf16 v[50:53], v[150:153], v[178:181], v[50:53]
	v_mfma_f32_16x16x32_bf16 v[50:53], v[166:169], v[182:185], v[50:53]
	v_mfma_f32_16x16x32_bf16 v[42:45], v[170:173], v[178:181], v[42:45]
	v_mfma_f32_16x16x32_bf16 v[42:45], v[174:177], v[182:185], v[42:45]
	v_mfma_f32_16x16x32_bf16 v[26:29], v[170:173], v[186:189], v[26:29]
	v_mfma_f32_16x16x32_bf16 v[26:29], v[174:177], v[190:193], v[26:29]
	v_mfma_f32_16x16x32_bf16 v[34:37], v[150:153], v[186:189], v[34:37]
	v_mfma_f32_16x16x32_bf16 v[34:37], v[166:169], v[190:193], v[34:37]
	v_mfma_f32_16x16x32_bf16 v[18:21], v[150:153], v[194:197], v[18:21]
	v_mfma_f32_16x16x32_bf16 v[18:21], v[166:169], v[198:201], v[18:21]
	v_mfma_f32_16x16x32_bf16 v[10:13], v[170:173], v[194:197], v[10:13]
	v_mfma_f32_16x16x32_bf16 v[10:13], v[174:177], v[198:201], v[10:13]
	v_mfma_f32_16x16x32_bf16 v[2:5], v[170:173], v[202:205], v[2:5]
	v_mfma_f32_16x16x32_bf16 v[2:5], v[174:177], v[206:209], v[2:5]
	s_setprio 2
	s_barrier
	v_mfma_f32_16x16x32_bf16 v[6:9], v[150:153], v[202:205], v[6:9]
	v_mfma_f32_16x16x32_bf16 v[6:9], v[166:169], v[206:209], v[6:9]
	s_setprio 0
	s_add_i32 s82, s82, 2
	s_add_u32 s78, s78, 0x80000
	s_addc_u32 s79, s79, 0
	s_add_u32 s20, s20, 0x400000
	s_addc_u32 s21, s21, 0
	s_add_u32 s80, s80, 0x400000
	s_addc_u32 s81, s81, 0
	s_cmpk_gt_u32 s82, 0x53
	.p2align 6
.LBB0_473:
	ds_read_b128 v[134:137], v161
	ds_read_b128 v[138:141], v161 offset:1024
	ds_read_b128 v[142:145], v161 offset:2048
	ds_read_b128 v[146:149], v161 offset:3072
	ds_read_b128 v[150:153], v162
	ds_read_b128 v[166:169], v162 offset:1024
	ds_read_b128 v[170:173], v162 offset:2048
	ds_read_b128 v[174:177], v162 offset:3072
	s_cmpk_eq_i32 s82, 0x52
	s_cselect_b32 s23, s11, s79
	s_cselect_b32 s22, s77, s78
	s_cselect_b32 s25, s13, s81
	s_cselect_b32 s24, s76, s80
	ds_read_b128 v[178:181], v163
	ds_read_b128 v[182:185], v163 offset:1024
	ds_read_b128 v[186:189], v163 offset:2048
	ds_read_b128 v[190:193], v163 offset:3072
	ds_read_b128 v[194:197], v163 offset:4096
	ds_read_b128 v[198:201], v163 offset:5120
	ds_read_b128 v[202:205], v163 offset:6144
	ds_read_b128 v[206:209], v163 offset:7168
	s_add_u32 s86, s20, 0xffffc000
	s_addc_u32 s87, s21, -1
	s_mov_b32 s83, m0
	s_mov_b32 m0, s65
	s_nop 0
	global_load_lds_dwordx4 v1, s[86:87]
	s_mov_b32 m0, s83
	s_nop 0
	s_mov_b32 s83, m0
	s_mov_b32 m0, s67
	s_nop 0
	global_load_lds_dwordx4 v157, s[86:87]
	s_mov_b32 m0, s83
	s_nop 0
	s_mov_b32 s83, m0
	s_mov_b32 m0, s66
	s_nop 0
	global_load_lds_dwordx4 v1, s[20:21]
	s_mov_b32 m0, s83
	s_nop 0
	s_mov_b32 s83, m0
	s_mov_b32 m0, s73
	s_nop 0
	global_load_lds_dwordx4 v157, s[20:21]
	s_mov_b32 m0, s83
	s_waitcnt vmcnt(8)
	s_waitcnt lgkmcnt(0)
	s_barrier
	s_setprio 1
	.p2align 3
	v_mfma_f32_16x16x32_bf16 v[126:129], v[134:137], v[178:181], v[126:129]
	v_mfma_f32_16x16x32_bf16 v[126:129], v[138:141], v[182:185], v[126:129]
	v_mfma_f32_16x16x32_bf16 v[122:125], v[142:145], v[178:181], v[122:125]
	v_mfma_f32_16x16x32_bf16 v[122:125], v[146:149], v[182:185], v[122:125]
	v_mfma_f32_16x16x32_bf16 v[114:117], v[142:145], v[186:189], v[114:117]
	v_mfma_f32_16x16x32_bf16 v[114:117], v[146:149], v[190:193], v[114:117]
	v_mfma_f32_16x16x32_bf16 v[118:121], v[134:137], v[186:189], v[118:121]
	v_mfma_f32_16x16x32_bf16 v[118:121], v[138:141], v[190:193], v[118:121]
	v_mfma_f32_16x16x32_bf16 v[102:105], v[134:137], v[194:197], v[102:105]
	v_mfma_f32_16x16x32_bf16 v[102:105], v[138:141], v[198:201], v[102:105]
	v_mfma_f32_16x16x32_bf16 v[94:97], v[142:145], v[194:197], v[94:97]
	v_mfma_f32_16x16x32_bf16 v[94:97], v[146:149], v[198:201], v[94:97]
	v_mfma_f32_16x16x32_bf16 v[78:81], v[142:145], v[202:205], v[78:81]
	v_mfma_f32_16x16x32_bf16 v[78:81], v[146:149], v[206:209], v[78:81]
	v_mfma_f32_16x16x32_bf16 v[86:89], v[134:137], v[202:205], v[86:89]
	v_mfma_f32_16x16x32_bf16 v[86:89], v[138:141], v[206:209], v[86:89]
	v_mfma_f32_16x16x32_bf16 v[110:113], v[150:153], v[178:181], v[110:113]
	v_mfma_f32_16x16x32_bf16 v[110:113], v[166:169], v[182:185], v[110:113]
	v_mfma_f32_16x16x32_bf16 v[106:109], v[170:173], v[178:181], v[106:109]
	v_mfma_f32_16x16x32_bf16 v[106:109], v[174:177], v[182:185], v[106:109]
	v_mfma_f32_16x16x32_bf16 v[90:93], v[170:173], v[186:189], v[90:93]
	v_mfma_f32_16x16x32_bf16 v[90:93], v[174:177], v[190:193], v[90:93]
	v_mfma_f32_16x16x32_bf16 v[98:101], v[150:153], v[186:189], v[98:101]
	v_mfma_f32_16x16x32_bf16 v[98:101], v[166:169], v[190:193], v[98:101]
	v_mfma_f32_16x16x32_bf16 v[82:85], v[150:153], v[194:197], v[82:85]
	v_mfma_f32_16x16x32_bf16 v[82:85], v[166:169], v[198:201], v[82:85]
	v_mfma_f32_16x16x32_bf16 v[74:77], v[170:173], v[194:197], v[74:77]
	v_mfma_f32_16x16x32_bf16 v[74:77], v[174:177], v[198:201], v[74:77]
	v_mfma_f32_16x16x32_bf16 v[66:69], v[170:173], v[202:205], v[66:69]
	v_mfma_f32_16x16x32_bf16 v[66:69], v[174:177], v[206:209], v[66:69]
	s_setprio 2
	s_barrier
	v_mfma_f32_16x16x32_bf16 v[70:73], v[150:153], v[202:205], v[70:73]
	v_mfma_f32_16x16x32_bf16 v[70:73], v[166:169], v[206:209], v[70:73]
	s_setprio 0
	ds_read_b128 v[178:181], v163 offset:16384
	ds_read_b128 v[182:185], v163 offset:17408
	ds_read_b128 v[186:189], v163 offset:18432
	ds_read_b128 v[190:193], v163 offset:19456
	ds_read_b128 v[194:197], v163 offset:20480
	ds_read_b128 v[198:201], v163 offset:21504
	ds_read_b128 v[202:205], v163 offset:22528
	ds_read_b128 v[206:209], v163 offset:23552
	s_mov_b32 s83, m0
	s_mov_b32 m0, s19
	s_nop 0
	global_load_lds_dwordx4 v156, s[22:23]
	s_mov_b32 m0, s83
	s_add_u32 s86, s22, 0x4000
	s_mov_b32 s83, m0
	s_mov_b32 m0, s35
	s_nop 0
	global_load_lds_dwordx4 v158, s[22:23]
	s_mov_b32 m0, s83
	s_addc_u32 s87, s23, 0
	s_mov_b32 s83, m0
	s_mov_b32 m0, s36
	s_nop 0
	global_load_lds_dwordx4 v156, s[86:87]
	s_mov_b32 m0, s83
	s_nop 0
	s_mov_b32 s83, m0
	s_mov_b32 m0, s37
	s_nop 0
	global_load_lds_dwordx4 v158, s[86:87]
	s_mov_b32 m0, s83
	s_waitcnt vmcnt(4)
	s_waitcnt lgkmcnt(0)
	s_barrier
	s_setprio 1
	.p2align 3
	v_mfma_f32_16x16x32_bf16 v[62:65], v[134:137], v[178:181], v[62:65]
	v_mfma_f32_16x16x32_bf16 v[62:65], v[138:141], v[182:185], v[62:65]
	v_mfma_f32_16x16x32_bf16 v[58:61], v[142:145], v[178:181], v[58:61]
	v_mfma_f32_16x16x32_bf16 v[58:61], v[146:149], v[182:185], v[58:61]
	v_mfma_f32_16x16x32_bf16 v[46:49], v[142:145], v[186:189], v[46:49]
	v_mfma_f32_16x16x32_bf16 v[46:49], v[146:149], v[190:193], v[46:49]
	v_mfma_f32_16x16x32_bf16 v[54:57], v[134:137], v[186:189], v[54:57]
	v_mfma_f32_16x16x32_bf16 v[54:57], v[138:141], v[190:193], v[54:57]
	v_mfma_f32_16x16x32_bf16 v[38:41], v[134:137], v[194:197], v[38:41]
	v_mfma_f32_16x16x32_bf16 v[38:41], v[138:141], v[198:201], v[38:41]
	v_mfma_f32_16x16x32_bf16 v[30:33], v[142:145], v[194:197], v[30:33]
	v_mfma_f32_16x16x32_bf16 v[30:33], v[146:149], v[198:201], v[30:33]
	v_mfma_f32_16x16x32_bf16 v[14:17], v[142:145], v[202:205], v[14:17]
	v_mfma_f32_16x16x32_bf16 v[14:17], v[146:149], v[206:209], v[14:17]
	v_mfma_f32_16x16x32_bf16 v[22:25], v[134:137], v[202:205], v[22:25]
	v_mfma_f32_16x16x32_bf16 v[22:25], v[138:141], v[206:209], v[22:25]
	v_mfma_f32_16x16x32_bf16 v[50:53], v[150:153], v[178:181], v[50:53]
	v_mfma_f32_16x16x32_bf16 v[50:53], v[166:169], v[182:185], v[50:53]
	v_mfma_f32_16x16x32_bf16 v[42:45], v[170:173], v[178:181], v[42:45]
	v_mfma_f32_16x16x32_bf16 v[42:45], v[174:177], v[182:185], v[42:45]
	v_mfma_f32_16x16x32_bf16 v[26:29], v[170:173], v[186:189], v[26:29]
	v_mfma_f32_16x16x32_bf16 v[26:29], v[174:177], v[190:193], v[26:29]
	v_mfma_f32_16x16x32_bf16 v[34:37], v[150:153], v[186:189], v[34:37]
	v_mfma_f32_16x16x32_bf16 v[34:37], v[166:169], v[190:193], v[34:37]
	v_mfma_f32_16x16x32_bf16 v[18:21], v[150:153], v[194:197], v[18:21]
	v_mfma_f32_16x16x32_bf16 v[18:21], v[166:169], v[198:201], v[18:21]
	v_mfma_f32_16x16x32_bf16 v[10:13], v[170:173], v[194:197], v[10:13]
	v_mfma_f32_16x16x32_bf16 v[10:13], v[174:177], v[198:201], v[10:13]
	v_mfma_f32_16x16x32_bf16 v[2:5], v[170:173], v[202:205], v[2:5]
	v_mfma_f32_16x16x32_bf16 v[2:5], v[174:177], v[206:209], v[2:5]
	s_setprio 2
	s_barrier
	v_mfma_f32_16x16x32_bf16 v[6:9], v[150:153], v[202:205], v[6:9]
	v_mfma_f32_16x16x32_bf16 v[6:9], v[166:169], v[206:209], v[6:9]
	s_setprio 0
	ds_read_b128 v[134:137], v164
	ds_read_b128 v[138:141], v164 offset:1024
	ds_read_b128 v[142:145], v164 offset:2048
	ds_read_b128 v[146:149], v164 offset:3072
	ds_read_b128 v[150:153], v165
	ds_read_b128 v[166:169], v165 offset:1024
	ds_read_b128 v[170:173], v165 offset:2048
	ds_read_b128 v[174:177], v165 offset:3072
	ds_read_b128 v[178:181], v163 offset:32768
	ds_read_b128 v[182:185], v163 offset:33792
	ds_read_b128 v[186:189], v163 offset:34816
	ds_read_b128 v[190:193], v163 offset:35840
	ds_read_b128 v[194:197], v163 offset:36864
	ds_read_b128 v[198:201], v163 offset:37888
	ds_read_b128 v[202:205], v163 offset:38912
	ds_read_b128 v[206:209], v163 offset:39936
	s_mov_b32 s83, m0
	s_mov_b32 m0, s34
	s_nop 0
	global_load_lds_dwordx4 v1, s[24:25]
	s_mov_b32 m0, s83
	s_nop 0
	s_mov_b32 s83, m0
	s_mov_b32 m0, s42
	s_nop 0
	global_load_lds_dwordx4 v157, s[24:25]
	s_mov_b32 m0, s83
	s_add_u32 s24, s24, 0x4000
	s_addc_u32 s25, s25, 0
	s_mov_b32 s83, m0
	s_mov_b32 m0, s43
	s_nop 0
	global_load_lds_dwordx4 v1, s[24:25]
	s_mov_b32 m0, s83
	s_nop 0
	s_mov_b32 s83, m0
	s_mov_b32 m0, s46
	s_nop 0
	global_load_lds_dwordx4 v157, s[24:25]
	s_mov_b32 m0, s83
	s_waitcnt vmcnt(8)
	s_waitcnt lgkmcnt(0)
	s_barrier
	s_setprio 1
	.p2align 3
	v_mfma_f32_16x16x32_bf16 v[126:129], v[134:137], v[178:181], v[126:129]
	v_mfma_f32_16x16x32_bf16 v[126:129], v[138:141], v[182:185], v[126:129]
	v_mfma_f32_16x16x32_bf16 v[122:125], v[142:145], v[178:181], v[122:125]
	v_mfma_f32_16x16x32_bf16 v[122:125], v[146:149], v[182:185], v[122:125]
	v_mfma_f32_16x16x32_bf16 v[114:117], v[142:145], v[186:189], v[114:117]
	v_mfma_f32_16x16x32_bf16 v[114:117], v[146:149], v[190:193], v[114:117]
	v_mfma_f32_16x16x32_bf16 v[118:121], v[134:137], v[186:189], v[118:121]
	v_mfma_f32_16x16x32_bf16 v[118:121], v[138:141], v[190:193], v[118:121]
	v_mfma_f32_16x16x32_bf16 v[102:105], v[134:137], v[194:197], v[102:105]
	v_mfma_f32_16x16x32_bf16 v[102:105], v[138:141], v[198:201], v[102:105]
	v_mfma_f32_16x16x32_bf16 v[94:97], v[142:145], v[194:197], v[94:97]
	v_mfma_f32_16x16x32_bf16 v[94:97], v[146:149], v[198:201], v[94:97]
	v_mfma_f32_16x16x32_bf16 v[78:81], v[142:145], v[202:205], v[78:81]
	v_mfma_f32_16x16x32_bf16 v[78:81], v[146:149], v[206:209], v[78:81]
	v_mfma_f32_16x16x32_bf16 v[86:89], v[134:137], v[202:205], v[86:89]
	v_mfma_f32_16x16x32_bf16 v[86:89], v[138:141], v[206:209], v[86:89]
	v_mfma_f32_16x16x32_bf16 v[110:113], v[150:153], v[178:181], v[110:113]
	v_mfma_f32_16x16x32_bf16 v[110:113], v[166:169], v[182:185], v[110:113]
	v_mfma_f32_16x16x32_bf16 v[106:109], v[170:173], v[178:181], v[106:109]
	v_mfma_f32_16x16x32_bf16 v[106:109], v[174:177], v[182:185], v[106:109]
	v_mfma_f32_16x16x32_bf16 v[90:93], v[170:173], v[186:189], v[90:93]
	v_mfma_f32_16x16x32_bf16 v[90:93], v[174:177], v[190:193], v[90:93]
	v_mfma_f32_16x16x32_bf16 v[98:101], v[150:153], v[186:189], v[98:101]
	v_mfma_f32_16x16x32_bf16 v[98:101], v[166:169], v[190:193], v[98:101]
	v_mfma_f32_16x16x32_bf16 v[82:85], v[150:153], v[194:197], v[82:85]
	v_mfma_f32_16x16x32_bf16 v[82:85], v[166:169], v[198:201], v[82:85]
	v_mfma_f32_16x16x32_bf16 v[74:77], v[170:173], v[194:197], v[74:77]
	v_mfma_f32_16x16x32_bf16 v[74:77], v[174:177], v[198:201], v[74:77]
	v_mfma_f32_16x16x32_bf16 v[66:69], v[170:173], v[202:205], v[66:69]
	v_mfma_f32_16x16x32_bf16 v[66:69], v[174:177], v[206:209], v[66:69]
	s_setprio 2
	s_barrier
	v_mfma_f32_16x16x32_bf16 v[70:73], v[150:153], v[202:205], v[70:73]
	v_mfma_f32_16x16x32_bf16 v[70:73], v[166:169], v[206:209], v[70:73]
	s_setprio 0
	ds_read_b128 v[178:181], v163 offset:49152
	ds_read_b128 v[182:185], v163 offset:50176
	ds_read_b128 v[186:189], v163 offset:51200
	ds_read_b128 v[190:193], v163 offset:52224
	ds_read_b128 v[194:197], v163 offset:53248
	ds_read_b128 v[198:201], v163 offset:54272
	ds_read_b128 v[202:205], v163 offset:55296
	ds_read_b128 v[206:209], v163 offset:56320
	s_add_u32 s24, s22, 0x40000
	s_addc_u32 s25, s23, 0
	s_mov_b32 s83, m0
	s_mov_b32 m0, s47
	s_nop 0
	global_load_lds_dwordx4 v156, s[24:25]
	s_mov_b32 m0, s83
	s_add_u32 s22, s22, 0x44000
	s_mov_b32 s83, m0
	s_mov_b32 m0, s48
	s_nop 0
	global_load_lds_dwordx4 v158, s[24:25]
	s_mov_b32 m0, s83
	s_addc_u32 s23, s23, 0
	s_mov_b32 s24, m0
	s_mov_b32 m0, s49
	s_nop 0
	global_load_lds_dwordx4 v156, s[22:23]
	s_mov_b32 m0, s24
	s_nop 0
	s_mov_b32 s24, m0
	s_mov_b32 m0, s56
	s_nop 0
	global_load_lds_dwordx4 v158, s[22:23]
	s_mov_b32 m0, s24
	s_waitcnt vmcnt(4)
	s_waitcnt lgkmcnt(0)
	s_barrier
	s_setprio 1
	.p2align 3
	v_mfma_f32_16x16x32_bf16 v[62:65], v[134:137], v[178:181], v[62:65]
	v_mfma_f32_16x16x32_bf16 v[62:65], v[138:141], v[182:185], v[62:65]
	v_mfma_f32_16x16x32_bf16 v[58:61], v[142:145], v[178:181], v[58:61]
	v_mfma_f32_16x16x32_bf16 v[58:61], v[146:149], v[182:185], v[58:61]
	v_mfma_f32_16x16x32_bf16 v[46:49], v[142:145], v[186:189], v[46:49]
	v_mfma_f32_16x16x32_bf16 v[46:49], v[146:149], v[190:193], v[46:49]
	v_mfma_f32_16x16x32_bf16 v[54:57], v[134:137], v[186:189], v[54:57]
	v_mfma_f32_16x16x32_bf16 v[54:57], v[138:141], v[190:193], v[54:57]
	v_mfma_f32_16x16x32_bf16 v[38:41], v[134:137], v[194:197], v[38:41]
	v_mfma_f32_16x16x32_bf16 v[38:41], v[138:141], v[198:201], v[38:41]
	v_mfma_f32_16x16x32_bf16 v[30:33], v[142:145], v[194:197], v[30:33]
	v_mfma_f32_16x16x32_bf16 v[30:33], v[146:149], v[198:201], v[30:33]
	v_mfma_f32_16x16x32_bf16 v[14:17], v[142:145], v[202:205], v[14:17]
	v_mfma_f32_16x16x32_bf16 v[14:17], v[146:149], v[206:209], v[14:17]
	v_mfma_f32_16x16x32_bf16 v[22:25], v[134:137], v[202:205], v[22:25]
	v_mfma_f32_16x16x32_bf16 v[22:25], v[138:141], v[206:209], v[22:25]
	v_mfma_f32_16x16x32_bf16 v[50:53], v[150:153], v[178:181], v[50:53]
	v_mfma_f32_16x16x32_bf16 v[50:53], v[166:169], v[182:185], v[50:53]
	v_mfma_f32_16x16x32_bf16 v[42:45], v[170:173], v[178:181], v[42:45]
	v_mfma_f32_16x16x32_bf16 v[42:45], v[174:177], v[182:185], v[42:45]
	v_mfma_f32_16x16x32_bf16 v[26:29], v[170:173], v[186:189], v[26:29]
	v_mfma_f32_16x16x32_bf16 v[26:29], v[174:177], v[190:193], v[26:29]
	v_mfma_f32_16x16x32_bf16 v[34:37], v[150:153], v[186:189], v[34:37]
	v_mfma_f32_16x16x32_bf16 v[34:37], v[166:169], v[190:193], v[34:37]
	v_mfma_f32_16x16x32_bf16 v[18:21], v[150:153], v[194:197], v[18:21]
	v_mfma_f32_16x16x32_bf16 v[18:21], v[166:169], v[198:201], v[18:21]
	v_mfma_f32_16x16x32_bf16 v[10:13], v[170:173], v[194:197], v[10:13]
	v_mfma_f32_16x16x32_bf16 v[10:13], v[174:177], v[198:201], v[10:13]
	v_mfma_f32_16x16x32_bf16 v[2:5], v[170:173], v[202:205], v[2:5]
	v_mfma_f32_16x16x32_bf16 v[2:5], v[174:177], v[206:209], v[2:5]
	s_setprio 2
	s_barrier
	v_mfma_f32_16x16x32_bf16 v[6:9], v[150:153], v[202:205], v[6:9]
	v_mfma_f32_16x16x32_bf16 v[6:9], v[166:169], v[206:209], v[6:9]
	s_setprio 0
	s_add_i32 s82, s82, 2
	s_add_u32 s78, s78, 0x80000
	s_addc_u32 s79, s79, 0
	s_add_u32 s20, s20, 0x400000
	s_addc_u32 s21, s21, 0
	s_add_u32 s80, s80, 0x400000
	s_addc_u32 s81, s81, 0
	s_cmpk_gt_u32 s82, 0x53
	s_cbranch_scc0 .LBB0_473
	s_and_b64 vcc, exec, s[8:9]
	s_cbranch_vccz .LBB0_476
	s_barrier

.LBB0_653:
	s_ashr_i32 s23, s22, 31
	s_lshl_b64 s[24:25], s[22:23], 20
	s_add_u32 s24, s35, s24
	s_addc_u32 s25, s36, s25
	s_and_b64 s[26:27], s[2:3], exec
	s_cselect_b32 s7, s25, s11
	s_cselect_b32 s9, s24, s10
	s_ashr_i32 s21, s20, 31
	s_lshl_b64 s[26:27], s[20:21], 20
	s_add_u32 s26, s37, s26
	s_addc_u32 s27, s40, s27
	s_and_b64 s[28:29], s[2:3], exec
	s_cselect_b32 s21, s27, s5
	s_cselect_b32 s23, s26, s4
	s_add_u32 s30, s4, 0x100
	s_addc_u32 s31, s5, 0
	s_add_u32 s4, s10, 0x80080
	s_addc_u32 s5, s11, 0
	s_add_u32 s33, s10, 0x100
	s_addc_u32 s73, s11, 0
	s_mov_b32 s74, -2
	s_waitcnt vmcnt(25)
	s_waitcnt vmcnt(24)
	s_waitcnt vmcnt(15)
	s_waitcnt vmcnt(14)
	s_waitcnt vmcnt(13)
	s_waitcnt vmcnt(12)
	s_waitcnt vmcnt(11)
	s_waitcnt vmcnt(10)
	s_waitcnt vmcnt(9)
	s_waitcnt vmcnt(8)
	s_waitcnt vmcnt(7)
	s_waitcnt vmcnt(6)
	s_waitcnt vmcnt(5)
	s_waitcnt vmcnt(4)
	s_waitcnt vmcnt(3)
	s_waitcnt vmcnt(2)
	s_waitcnt vmcnt(1)
	s_waitcnt vmcnt(0)
	ds_read_b128 v[130:133], v161
	ds_read_b128 v[138:141], v161 offset:1024
	ds_read_b128 v[142:145], v161 offset:2048
	ds_read_b128 v[146:149], v161 offset:3072
	ds_read_b128 v[150:153], v162
	ds_read_b128 v[168:171], v162 offset:1024
	ds_read_b128 v[172:175], v162 offset:2048
	ds_read_b128 v[176:179], v162 offset:3072
	s_cmp_eq_u32 s74, 28
	s_cselect_b32 s11, s21, s31
	s_cselect_b32 s10, s23, s30
	s_cselect_b32 s29, s7, s73
	s_cselect_b32 s28, s9, s33
	ds_read_b128 v[180:183], v163
	ds_read_b128 v[184:187], v163 offset:1024
	ds_read_b128 v[188:191], v163 offset:2048
	ds_read_b128 v[192:195], v163 offset:3072
	ds_read_b128 v[196:199], v163 offset:4096
	ds_read_b128 v[200:203], v163 offset:5120
	ds_read_b128 v[204:207], v163 offset:6144
	ds_read_b128 v[208:211], v163 offset:7168
	s_add_u32 s76, s4, 0xfff80000
	s_addc_u32 s77, s5, -1
	s_mov_b32 s75, m0
	s_mov_b32 m0, s80
	s_nop 0
	global_load_lds_dwordx4 v1, s[76:77]
	s_mov_b32 m0, s75
	s_nop 0
	s_mov_b32 s75, m0
	s_mov_b32 m0, s82
	s_nop 0
	global_load_lds_dwordx4 v157, s[76:77]
	s_mov_b32 m0, s75
	s_nop 0
	s_mov_b32 s75, m0
	s_mov_b32 m0, s81
	s_nop 0
	global_load_lds_dwordx4 v1, s[4:5]
	s_mov_b32 m0, s75
	s_nop 0
	s_mov_b32 s75, m0
	s_mov_b32 m0, s83
	s_nop 0
	global_load_lds_dwordx4 v157, s[4:5]
	s_mov_b32 m0, s75
	s_waitcnt vmcnt(8)
	s_waitcnt lgkmcnt(0)
	s_barrier
	s_setprio 1
	.p2align 3
	v_mfma_f32_16x16x32_bf16 v[126:129], v[130:133], v[180:183], 0
	v_mfma_f32_16x16x32_bf16 v[126:129], v[138:141], v[184:187], v[126:129]
	v_mfma_f32_16x16x32_bf16 v[122:125], v[142:145], v[180:183], 0
	v_mfma_f32_16x16x32_bf16 v[122:125], v[146:149], v[184:187], v[122:125]
	v_mfma_f32_16x16x32_bf16 v[106:109], v[142:145], v[188:191], 0
	v_mfma_f32_16x16x32_bf16 v[106:109], v[146:149], v[192:195], v[106:109]
	v_mfma_f32_16x16x32_bf16 v[110:113], v[130:133], v[188:191], 0
	v_mfma_f32_16x16x32_bf16 v[110:113], v[138:141], v[192:195], v[110:113]
	v_mfma_f32_16x16x32_bf16 v[94:97], v[130:133], v[196:199], 0
	v_mfma_f32_16x16x32_bf16 v[94:97], v[138:141], v[200:203], v[94:97]
	v_mfma_f32_16x16x32_bf16 v[90:93], v[142:145], v[196:199], 0
	v_mfma_f32_16x16x32_bf16 v[90:93], v[146:149], v[200:203], v[90:93]
	v_mfma_f32_16x16x32_bf16 v[74:77], v[142:145], v[204:207], 0
	v_mfma_f32_16x16x32_bf16 v[74:77], v[146:149], v[208:211], v[74:77]
	v_mfma_f32_16x16x32_bf16 v[78:81], v[130:133], v[204:207], 0
	v_mfma_f32_16x16x32_bf16 v[78:81], v[138:141], v[208:211], v[78:81]
	v_mfma_f32_16x16x32_bf16 v[118:121], v[150:153], v[180:183], 0
	v_mfma_f32_16x16x32_bf16 v[118:121], v[168:171], v[184:187], v[118:121]
	v_mfma_f32_16x16x32_bf16 v[114:117], v[172:175], v[180:183], 0
	v_mfma_f32_16x16x32_bf16 v[114:117], v[176:179], v[184:187], v[114:117]
	v_mfma_f32_16x16x32_bf16 v[98:101], v[172:175], v[188:191], 0
	v_mfma_f32_16x16x32_bf16 v[98:101], v[176:179], v[192:195], v[98:101]
	v_mfma_f32_16x16x32_bf16 v[102:105], v[150:153], v[188:191], 0
	v_mfma_f32_16x16x32_bf16 v[102:105], v[168:171], v[192:195], v[102:105]
	v_mfma_f32_16x16x32_bf16 v[86:89], v[150:153], v[196:199], 0
	v_mfma_f32_16x16x32_bf16 v[86:89], v[168:171], v[200:203], v[86:89]
	v_mfma_f32_16x16x32_bf16 v[82:85], v[172:175], v[196:199], 0
	v_mfma_f32_16x16x32_bf16 v[82:85], v[176:179], v[200:203], v[82:85]
	v_mfma_f32_16x16x32_bf16 v[66:69], v[172:175], v[204:207], 0
	v_mfma_f32_16x16x32_bf16 v[66:69], v[176:179], v[208:211], v[66:69]
	s_setprio 2
	s_barrier
	v_mfma_f32_16x16x32_bf16 v[70:73], v[150:153], v[204:207], 0
	v_mfma_f32_16x16x32_bf16 v[70:73], v[168:171], v[208:211], v[70:73]
	s_setprio 0
	ds_read_b128 v[180:183], v163 offset:16384
	ds_read_b128 v[184:187], v163 offset:17408
	ds_read_b128 v[188:191], v163 offset:18432
	ds_read_b128 v[192:195], v163 offset:19456
	ds_read_b128 v[196:199], v163 offset:20480
	ds_read_b128 v[200:203], v163 offset:21504
	ds_read_b128 v[204:207], v163 offset:22528
	ds_read_b128 v[208:211], v163 offset:23552
	s_mov_b32 s75, m0
	s_mov_b32 m0, s43
	s_nop 0
	global_load_lds_dwordx4 v156, s[10:11]
	s_mov_b32 m0, s75
	s_add_u32 s76, s10, 0x80000
	s_mov_b32 s75, m0
	s_mov_b32 m0, s46
	s_nop 0
	global_load_lds_dwordx4 v158, s[10:11]
	s_mov_b32 m0, s75
	s_addc_u32 s77, s11, 0
	s_mov_b32 s75, m0
	s_mov_b32 m0, s47
	s_nop 0
	global_load_lds_dwordx4 v156, s[76:77]
	s_mov_b32 m0, s75
	s_nop 0
	s_mov_b32 s75, m0
	s_mov_b32 m0, s48
	s_nop 0
	global_load_lds_dwordx4 v158, s[76:77]
	s_mov_b32 m0, s75
	s_waitcnt vmcnt(4)
	s_waitcnt lgkmcnt(0)
	s_barrier
	s_setprio 1
	.p2align 3
	v_mfma_f32_16x16x32_bf16 v[62:65], v[130:133], v[180:183], 0
	v_mfma_f32_16x16x32_bf16 v[62:65], v[138:141], v[184:187], v[62:65]
	v_mfma_f32_16x16x32_bf16 v[58:61], v[142:145], v[180:183], 0
	v_mfma_f32_16x16x32_bf16 v[58:61], v[146:149], v[184:187], v[58:61]
	v_mfma_f32_16x16x32_bf16 v[42:45], v[142:145], v[188:191], 0
	v_mfma_f32_16x16x32_bf16 v[42:45], v[146:149], v[192:195], v[42:45]
	v_mfma_f32_16x16x32_bf16 v[46:49], v[130:133], v[188:191], 0
	v_mfma_f32_16x16x32_bf16 v[46:49], v[138:141], v[192:195], v[46:49]
	v_mfma_f32_16x16x32_bf16 v[30:33], v[130:133], v[196:199], 0
	v_mfma_f32_16x16x32_bf16 v[30:33], v[138:141], v[200:203], v[30:33]
	v_mfma_f32_16x16x32_bf16 v[26:29], v[142:145], v[196:199], 0
	v_mfma_f32_16x16x32_bf16 v[26:29], v[146:149], v[200:203], v[26:29]
	v_mfma_f32_16x16x32_bf16 v[10:13], v[142:145], v[204:207], 0
	v_mfma_f32_16x16x32_bf16 v[10:13], v[146:149], v[208:211], v[10:13]
	v_mfma_f32_16x16x32_bf16 v[14:17], v[130:133], v[204:207], 0
	v_mfma_f32_16x16x32_bf16 v[14:17], v[138:141], v[208:211], v[14:17]
	v_mfma_f32_16x16x32_bf16 v[54:57], v[150:153], v[180:183], 0
	v_mfma_f32_16x16x32_bf16 v[54:57], v[168:171], v[184:187], v[54:57]
	v_mfma_f32_16x16x32_bf16 v[50:53], v[172:175], v[180:183], 0
	v_mfma_f32_16x16x32_bf16 v[50:53], v[176:179], v[184:187], v[50:53]
	v_mfma_f32_16x16x32_bf16 v[34:37], v[172:175], v[188:191], 0
	v_mfma_f32_16x16x32_bf16 v[34:37], v[176:179], v[192:195], v[34:37]
	v_mfma_f32_16x16x32_bf16 v[38:41], v[150:153], v[188:191], 0
	v_mfma_f32_16x16x32_bf16 v[38:41], v[168:171], v[192:195], v[38:41]
	v_mfma_f32_16x16x32_bf16 v[22:25], v[150:153], v[196:199], 0
	v_mfma_f32_16x16x32_bf16 v[22:25], v[168:171], v[200:203], v[22:25]
	v_mfma_f32_16x16x32_bf16 v[18:21], v[172:175], v[196:199], 0
	v_mfma_f32_16x16x32_bf16 v[18:21], v[176:179], v[200:203], v[18:21]
	v_mfma_f32_16x16x32_bf16 v[2:5], v[172:175], v[204:207], 0
	v_mfma_f32_16x16x32_bf16 v[2:5], v[176:179], v[208:211], v[2:5]
	s_setprio 2
	s_barrier
	v_mfma_f32_16x16x32_bf16 v[6:9], v[150:153], v[204:207], 0
	v_mfma_f32_16x16x32_bf16 v[6:9], v[168:171], v[208:211], v[6:9]
	s_setprio 0
	ds_read_b128 v[130:133], v164
	ds_read_b128 v[138:141], v164 offset:1024
	ds_read_b128 v[142:145], v164 offset:2048
	ds_read_b128 v[146:149], v164 offset:3072
	ds_read_b128 v[150:153], v165
	ds_read_b128 v[168:171], v165 offset:1024
	ds_read_b128 v[172:175], v165 offset:2048
	ds_read_b128 v[176:179], v165 offset:3072
	ds_read_b128 v[180:183], v163 offset:32768
	ds_read_b128 v[184:187], v163 offset:33792
	ds_read_b128 v[188:191], v163 offset:34816
	ds_read_b128 v[192:195], v163 offset:35840
	ds_read_b128 v[196:199], v163 offset:36864
	ds_read_b128 v[200:203], v163 offset:37888
	ds_read_b128 v[204:207], v163 offset:38912
	ds_read_b128 v[208:211], v163 offset:39936
	s_mov_b32 s75, m0
	s_mov_b32 m0, s42
	s_nop 0
	global_load_lds_dwordx4 v1, s[28:29]
	s_mov_b32 m0, s75
	s_nop 0
	s_mov_b32 s75, m0
	s_mov_b32 m0, s49
	s_nop 0
	global_load_lds_dwordx4 v157, s[28:29]
	s_mov_b32 m0, s75
	s_add_u32 s28, s28, 0x80000
	s_addc_u32 s29, s29, 0
	s_mov_b32 s75, m0
	s_mov_b32 m0, s56
	s_nop 0
	global_load_lds_dwordx4 v1, s[28:29]
	s_mov_b32 m0, s75
	s_nop 0
	s_mov_b32 s75, m0
	s_mov_b32 m0, s57
	s_nop 0
	global_load_lds_dwordx4 v157, s[28:29]
	s_mov_b32 m0, s75
	s_waitcnt vmcnt(8)
	s_waitcnt lgkmcnt(0)
	s_barrier
	s_setprio 1
	.p2align 3
	v_mfma_f32_16x16x32_bf16 v[126:129], v[130:133], v[180:183], v[126:129]
	v_mfma_f32_16x16x32_bf16 v[126:129], v[138:141], v[184:187], v[126:129]
	v_mfma_f32_16x16x32_bf16 v[122:125], v[142:145], v[180:183], v[122:125]
	v_mfma_f32_16x16x32_bf16 v[122:125], v[146:149], v[184:187], v[122:125]
	v_mfma_f32_16x16x32_bf16 v[106:109], v[142:145], v[188:191], v[106:109]
	v_mfma_f32_16x16x32_bf16 v[106:109], v[146:149], v[192:195], v[106:109]
	v_mfma_f32_16x16x32_bf16 v[110:113], v[130:133], v[188:191], v[110:113]
	v_mfma_f32_16x16x32_bf16 v[110:113], v[138:141], v[192:195], v[110:113]
	v_mfma_f32_16x16x32_bf16 v[94:97], v[130:133], v[196:199], v[94:97]
	v_mfma_f32_16x16x32_bf16 v[94:97], v[138:141], v[200:203], v[94:97]
	v_mfma_f32_16x16x32_bf16 v[90:93], v[142:145], v[196:199], v[90:93]
	v_mfma_f32_16x16x32_bf16 v[90:93], v[146:149], v[200:203], v[90:93]
	v_mfma_f32_16x16x32_bf16 v[74:77], v[142:145], v[204:207], v[74:77]
	v_mfma_f32_16x16x32_bf16 v[74:77], v[146:149], v[208:211], v[74:77]
	v_mfma_f32_16x16x32_bf16 v[78:81], v[130:133], v[204:207], v[78:81]
	v_mfma_f32_16x16x32_bf16 v[78:81], v[138:141], v[208:211], v[78:81]
	v_mfma_f32_16x16x32_bf16 v[118:121], v[150:153], v[180:183], v[118:121]
	v_mfma_f32_16x16x32_bf16 v[118:121], v[168:171], v[184:187], v[118:121]
	v_mfma_f32_16x16x32_bf16 v[114:117], v[172:175], v[180:183], v[114:117]
	v_mfma_f32_16x16x32_bf16 v[114:117], v[176:179], v[184:187], v[114:117]
	v_mfma_f32_16x16x32_bf16 v[98:101], v[172:175], v[188:191], v[98:101]
	v_mfma_f32_16x16x32_bf16 v[98:101], v[176:179], v[192:195], v[98:101]
	v_mfma_f32_16x16x32_bf16 v[102:105], v[150:153], v[188:191], v[102:105]
	v_mfma_f32_16x16x32_bf16 v[102:105], v[168:171], v[192:195], v[102:105]
	v_mfma_f32_16x16x32_bf16 v[86:89], v[150:153], v[196:199], v[86:89]
	v_mfma_f32_16x16x32_bf16 v[86:89], v[168:171], v[200:203], v[86:89]
	v_mfma_f32_16x16x32_bf16 v[82:85], v[172:175], v[196:199], v[82:85]
	v_mfma_f32_16x16x32_bf16 v[82:85], v[176:179], v[200:203], v[82:85]
	v_mfma_f32_16x16x32_bf16 v[66:69], v[172:175], v[204:207], v[66:69]
	v_mfma_f32_16x16x32_bf16 v[66:69], v[176:179], v[208:211], v[66:69]
	s_setprio 2
	s_barrier
	v_mfma_f32_16x16x32_bf16 v[70:73], v[150:153], v[204:207], v[70:73]
	v_mfma_f32_16x16x32_bf16 v[70:73], v[168:171], v[208:211], v[70:73]
	s_setprio 0
	ds_read_b128 v[180:183], v163 offset:49152
	ds_read_b128 v[184:187], v163 offset:50176
	ds_read_b128 v[188:191], v163 offset:51200
	ds_read_b128 v[192:195], v163 offset:52224
	ds_read_b128 v[196:199], v163 offset:53248
	ds_read_b128 v[200:203], v163 offset:54272
	ds_read_b128 v[204:207], v163 offset:55296
	ds_read_b128 v[208:211], v163 offset:56320
	s_add_u32 s28, s10, 0x80
	s_addc_u32 s29, s11, 0
	s_mov_b32 s75, m0
	s_mov_b32 m0, s64
	s_nop 0
	global_load_lds_dwordx4 v156, s[28:29]
	s_mov_b32 m0, s75
	s_add_u32 s10, s10, 0x80080
	s_mov_b32 s75, m0
	s_mov_b32 m0, s65
	s_nop 0
	global_load_lds_dwordx4 v158, s[28:29]
	s_mov_b32 m0, s75
	s_addc_u32 s11, s11, 0
	s_mov_b32 s28, m0
	s_mov_b32 m0, s66
	s_nop 0
	global_load_lds_dwordx4 v156, s[10:11]
	s_mov_b32 m0, s28
	s_nop 0
	s_mov_b32 s28, m0
	s_mov_b32 m0, s67
	s_nop 0
	global_load_lds_dwordx4 v158, s[10:11]
	s_mov_b32 m0, s28
	s_waitcnt vmcnt(4)
	s_waitcnt lgkmcnt(0)
	s_barrier
	s_setprio 1
	.p2align 3
	v_mfma_f32_16x16x32_bf16 v[62:65], v[130:133], v[180:183], v[62:65]
	v_mfma_f32_16x16x32_bf16 v[62:65], v[138:141], v[184:187], v[62:65]
	v_mfma_f32_16x16x32_bf16 v[58:61], v[142:145], v[180:183], v[58:61]
	v_mfma_f32_16x16x32_bf16 v[58:61], v[146:149], v[184:187], v[58:61]
	v_mfma_f32_16x16x32_bf16 v[42:45], v[142:145], v[188:191], v[42:45]
	v_mfma_f32_16x16x32_bf16 v[42:45], v[146:149], v[192:195], v[42:45]
	v_mfma_f32_16x16x32_bf16 v[46:49], v[130:133], v[188:191], v[46:49]
	v_mfma_f32_16x16x32_bf16 v[46:49], v[138:141], v[192:195], v[46:49]
	v_mfma_f32_16x16x32_bf16 v[30:33], v[130:133], v[196:199], v[30:33]
	v_mfma_f32_16x16x32_bf16 v[30:33], v[138:141], v[200:203], v[30:33]
	v_mfma_f32_16x16x32_bf16 v[26:29], v[142:145], v[196:199], v[26:29]
	v_mfma_f32_16x16x32_bf16 v[26:29], v[146:149], v[200:203], v[26:29]
	v_mfma_f32_16x16x32_bf16 v[10:13], v[142:145], v[204:207], v[10:13]
	v_mfma_f32_16x16x32_bf16 v[10:13], v[146:149], v[208:211], v[10:13]
	v_mfma_f32_16x16x32_bf16 v[14:17], v[130:133], v[204:207], v[14:17]
	v_mfma_f32_16x16x32_bf16 v[14:17], v[138:141], v[208:211], v[14:17]
	v_mfma_f32_16x16x32_bf16 v[54:57], v[150:153], v[180:183], v[54:57]
	v_mfma_f32_16x16x32_bf16 v[54:57], v[168:171], v[184:187], v[54:57]
	v_mfma_f32_16x16x32_bf16 v[50:53], v[172:175], v[180:183], v[50:53]
	v_mfma_f32_16x16x32_bf16 v[50:53], v[176:179], v[184:187], v[50:53]
	v_mfma_f32_16x16x32_bf16 v[34:37], v[172:175], v[188:191], v[34:37]
	v_mfma_f32_16x16x32_bf16 v[34:37], v[176:179], v[192:195], v[34:37]
	v_mfma_f32_16x16x32_bf16 v[38:41], v[150:153], v[188:191], v[38:41]
	v_mfma_f32_16x16x32_bf16 v[38:41], v[168:171], v[192:195], v[38:41]
	v_mfma_f32_16x16x32_bf16 v[22:25], v[150:153], v[196:199], v[22:25]
	v_mfma_f32_16x16x32_bf16 v[22:25], v[168:171], v[200:203], v[22:25]
	v_mfma_f32_16x16x32_bf16 v[18:21], v[172:175], v[196:199], v[18:21]
	v_mfma_f32_16x16x32_bf16 v[18:21], v[176:179], v[200:203], v[18:21]
	v_mfma_f32_16x16x32_bf16 v[2:5], v[172:175], v[204:207], v[2:5]
	v_mfma_f32_16x16x32_bf16 v[2:5], v[176:179], v[208:211], v[2:5]
	s_setprio 2
	s_barrier
	v_mfma_f32_16x16x32_bf16 v[6:9], v[150:153], v[204:207], v[6:9]
	v_mfma_f32_16x16x32_bf16 v[6:9], v[168:171], v[208:211], v[6:9]
	s_setprio 0
	s_add_i32 s74, s74, 2
	s_add_u32 s30, s30, 0x100
	s_addc_u32 s31, s31, 0
	s_add_u32 s4, s4, 0x100
	s_addc_u32 s5, s5, 0
	s_add_u32 s33, s33, 0x100
	s_addc_u32 s73, s73, 0
	s_cmp_gt_u32 s74, 29
	.p2align 6
.LBB0_654:
	ds_read_b128 v[130:133], v161
	ds_read_b128 v[138:141], v161 offset:1024
	ds_read_b128 v[142:145], v161 offset:2048
	ds_read_b128 v[146:149], v161 offset:3072
	ds_read_b128 v[150:153], v162
	ds_read_b128 v[168:171], v162 offset:1024
	ds_read_b128 v[172:175], v162 offset:2048
	ds_read_b128 v[176:179], v162 offset:3072
	s_cmp_eq_u32 s74, 28
	s_cselect_b32 s11, s21, s31
	s_cselect_b32 s10, s23, s30
	s_cselect_b32 s29, s7, s73
	s_cselect_b32 s28, s9, s33
	ds_read_b128 v[180:183], v163
	ds_read_b128 v[184:187], v163 offset:1024
	ds_read_b128 v[188:191], v163 offset:2048
	ds_read_b128 v[192:195], v163 offset:3072
	ds_read_b128 v[196:199], v163 offset:4096
	ds_read_b128 v[200:203], v163 offset:5120
	ds_read_b128 v[204:207], v163 offset:6144
	ds_read_b128 v[208:211], v163 offset:7168
	s_add_u32 s76, s4, 0xfff80000
	s_addc_u32 s77, s5, -1
	s_mov_b32 s75, m0
	s_mov_b32 m0, s80
	s_nop 0
	global_load_lds_dwordx4 v1, s[76:77]
	s_mov_b32 m0, s75
	s_nop 0
	s_mov_b32 s75, m0
	s_mov_b32 m0, s82
	s_nop 0
	global_load_lds_dwordx4 v157, s[76:77]
	s_mov_b32 m0, s75
	s_nop 0
	s_mov_b32 s75, m0
	s_mov_b32 m0, s81
	s_nop 0
	global_load_lds_dwordx4 v1, s[4:5]
	s_mov_b32 m0, s75
	s_nop 0
	s_mov_b32 s75, m0
	s_mov_b32 m0, s83
	s_nop 0
	global_load_lds_dwordx4 v157, s[4:5]
	s_mov_b32 m0, s75
	s_waitcnt vmcnt(8)
	s_waitcnt lgkmcnt(0)
	s_barrier
	s_setprio 1
	.p2align 3
	v_mfma_f32_16x16x32_bf16 v[126:129], v[130:133], v[180:183], v[126:129]
	v_mfma_f32_16x16x32_bf16 v[126:129], v[138:141], v[184:187], v[126:129]
	v_mfma_f32_16x16x32_bf16 v[122:125], v[142:145], v[180:183], v[122:125]
	v_mfma_f32_16x16x32_bf16 v[122:125], v[146:149], v[184:187], v[122:125]
	v_mfma_f32_16x16x32_bf16 v[106:109], v[142:145], v[188:191], v[106:109]
	v_mfma_f32_16x16x32_bf16 v[106:109], v[146:149], v[192:195], v[106:109]
	v_mfma_f32_16x16x32_bf16 v[110:113], v[130:133], v[188:191], v[110:113]
	v_mfma_f32_16x16x32_bf16 v[110:113], v[138:141], v[192:195], v[110:113]
	v_mfma_f32_16x16x32_bf16 v[94:97], v[130:133], v[196:199], v[94:97]
	v_mfma_f32_16x16x32_bf16 v[94:97], v[138:141], v[200:203], v[94:97]
	v_mfma_f32_16x16x32_bf16 v[90:93], v[142:145], v[196:199], v[90:93]
	v_mfma_f32_16x16x32_bf16 v[90:93], v[146:149], v[200:203], v[90:93]
	v_mfma_f32_16x16x32_bf16 v[74:77], v[142:145], v[204:207], v[74:77]
	v_mfma_f32_16x16x32_bf16 v[74:77], v[146:149], v[208:211], v[74:77]
	v_mfma_f32_16x16x32_bf16 v[78:81], v[130:133], v[204:207], v[78:81]
	v_mfma_f32_16x16x32_bf16 v[78:81], v[138:141], v[208:211], v[78:81]
	v_mfma_f32_16x16x32_bf16 v[118:121], v[150:153], v[180:183], v[118:121]
	v_mfma_f32_16x16x32_bf16 v[118:121], v[168:171], v[184:187], v[118:121]
	v_mfma_f32_16x16x32_bf16 v[114:117], v[172:175], v[180:183], v[114:117]
	v_mfma_f32_16x16x32_bf16 v[114:117], v[176:179], v[184:187], v[114:117]
	v_mfma_f32_16x16x32_bf16 v[98:101], v[172:175], v[188:191], v[98:101]
	v_mfma_f32_16x16x32_bf16 v[98:101], v[176:179], v[192:195], v[98:101]
	v_mfma_f32_16x16x32_bf16 v[102:105], v[150:153], v[188:191], v[102:105]
	v_mfma_f32_16x16x32_bf16 v[102:105], v[168:171], v[192:195], v[102:105]
	v_mfma_f32_16x16x32_bf16 v[86:89], v[150:153], v[196:199], v[86:89]
	v_mfma_f32_16x16x32_bf16 v[86:89], v[168:171], v[200:203], v[86:89]
	v_mfma_f32_16x16x32_bf16 v[82:85], v[172:175], v[196:199], v[82:85]
	v_mfma_f32_16x16x32_bf16 v[82:85], v[176:179], v[200:203], v[82:85]
	v_mfma_f32_16x16x32_bf16 v[66:69], v[172:175], v[204:207], v[66:69]
	v_mfma_f32_16x16x32_bf16 v[66:69], v[176:179], v[208:211], v[66:69]
	s_setprio 2
	s_barrier
	v_mfma_f32_16x16x32_bf16 v[70:73], v[150:153], v[204:207], v[70:73]
	v_mfma_f32_16x16x32_bf16 v[70:73], v[168:171], v[208:211], v[70:73]
	s_setprio 0
	ds_read_b128 v[180:183], v163 offset:16384
	ds_read_b128 v[184:187], v163 offset:17408
	ds_read_b128 v[188:191], v163 offset:18432
	ds_read_b128 v[192:195], v163 offset:19456
	ds_read_b128 v[196:199], v163 offset:20480
	ds_read_b128 v[200:203], v163 offset:21504
	ds_read_b128 v[204:207], v163 offset:22528
	ds_read_b128 v[208:211], v163 offset:23552
	s_mov_b32 s75, m0
	s_mov_b32 m0, s43
	s_nop 0
	global_load_lds_dwordx4 v156, s[10:11]
	s_mov_b32 m0, s75
	s_add_u32 s76, s10, 0x80000
	s_mov_b32 s75, m0
	s_mov_b32 m0, s46
	s_nop 0
	global_load_lds_dwordx4 v158, s[10:11]
	s_mov_b32 m0, s75
	s_addc_u32 s77, s11, 0
	s_mov_b32 s75, m0
	s_mov_b32 m0, s47
	s_nop 0
	global_load_lds_dwordx4 v156, s[76:77]
	s_mov_b32 m0, s75
	s_nop 0
	s_mov_b32 s75, m0
	s_mov_b32 m0, s48
	s_nop 0
	global_load_lds_dwordx4 v158, s[76:77]
	s_mov_b32 m0, s75
	s_waitcnt vmcnt(4)
	s_waitcnt lgkmcnt(0)
	s_barrier
	s_setprio 1
	.p2align 3
	v_mfma_f32_16x16x32_bf16 v[62:65], v[130:133], v[180:183], v[62:65]
	v_mfma_f32_16x16x32_bf16 v[62:65], v[138:141], v[184:187], v[62:65]
	v_mfma_f32_16x16x32_bf16 v[58:61], v[142:145], v[180:183], v[58:61]
	v_mfma_f32_16x16x32_bf16 v[58:61], v[146:149], v[184:187], v[58:61]
	v_mfma_f32_16x16x32_bf16 v[42:45], v[142:145], v[188:191], v[42:45]
	v_mfma_f32_16x16x32_bf16 v[42:45], v[146:149], v[192:195], v[42:45]
	v_mfma_f32_16x16x32_bf16 v[46:49], v[130:133], v[188:191], v[46:49]
	v_mfma_f32_16x16x32_bf16 v[46:49], v[138:141], v[192:195], v[46:49]
	v_mfma_f32_16x16x32_bf16 v[30:33], v[130:133], v[196:199], v[30:33]
	v_mfma_f32_16x16x32_bf16 v[30:33], v[138:141], v[200:203], v[30:33]
	v_mfma_f32_16x16x32_bf16 v[26:29], v[142:145], v[196:199], v[26:29]
	v_mfma_f32_16x16x32_bf16 v[26:29], v[146:149], v[200:203], v[26:29]
	v_mfma_f32_16x16x32_bf16 v[10:13], v[142:145], v[204:207], v[10:13]
	v_mfma_f32_16x16x32_bf16 v[10:13], v[146:149], v[208:211], v[10:13]
	v_mfma_f32_16x16x32_bf16 v[14:17], v[130:133], v[204:207], v[14:17]
	v_mfma_f32_16x16x32_bf16 v[14:17], v[138:141], v[208:211], v[14:17]
	v_mfma_f32_16x16x32_bf16 v[54:57], v[150:153], v[180:183], v[54:57]
	v_mfma_f32_16x16x32_bf16 v[54:57], v[168:171], v[184:187], v[54:57]
	v_mfma_f32_16x16x32_bf16 v[50:53], v[172:175], v[180:183], v[50:53]
	v_mfma_f32_16x16x32_bf16 v[50:53], v[176:179], v[184:187], v[50:53]
	v_mfma_f32_16x16x32_bf16 v[34:37], v[172:175], v[188:191], v[34:37]
	v_mfma_f32_16x16x32_bf16 v[34:37], v[176:179], v[192:195], v[34:37]
	v_mfma_f32_16x16x32_bf16 v[38:41], v[150:153], v[188:191], v[38:41]
	v_mfma_f32_16x16x32_bf16 v[38:41], v[168:171], v[192:195], v[38:41]
	v_mfma_f32_16x16x32_bf16 v[22:25], v[150:153], v[196:199], v[22:25]
	v_mfma_f32_16x16x32_bf16 v[22:25], v[168:171], v[200:203], v[22:25]
	v_mfma_f32_16x16x32_bf16 v[18:21], v[172:175], v[196:199], v[18:21]
	v_mfma_f32_16x16x32_bf16 v[18:21], v[176:179], v[200:203], v[18:21]
	v_mfma_f32_16x16x32_bf16 v[2:5], v[172:175], v[204:207], v[2:5]
	v_mfma_f32_16x16x32_bf16 v[2:5], v[176:179], v[208:211], v[2:5]
	s_setprio 2
	s_barrier
	v_mfma_f32_16x16x32_bf16 v[6:9], v[150:153], v[204:207], v[6:9]
	v_mfma_f32_16x16x32_bf16 v[6:9], v[168:171], v[208:211], v[6:9]
	s_setprio 0
	ds_read_b128 v[130:133], v164
	ds_read_b128 v[138:141], v164 offset:1024
	ds_read_b128 v[142:145], v164 offset:2048
	ds_read_b128 v[146:149], v164 offset:3072
	ds_read_b128 v[150:153], v165
	ds_read_b128 v[168:171], v165 offset:1024
	ds_read_b128 v[172:175], v165 offset:2048
	ds_read_b128 v[176:179], v165 offset:3072
	ds_read_b128 v[180:183], v163 offset:32768
	ds_read_b128 v[184:187], v163 offset:33792
	ds_read_b128 v[188:191], v163 offset:34816
	ds_read_b128 v[192:195], v163 offset:35840
	ds_read_b128 v[196:199], v163 offset:36864
	ds_read_b128 v[200:203], v163 offset:37888
	ds_read_b128 v[204:207], v163 offset:38912
	ds_read_b128 v[208:211], v163 offset:39936
	s_mov_b32 s75, m0
	s_mov_b32 m0, s42
	s_nop 0
	global_load_lds_dwordx4 v1, s[28:29]
	s_mov_b32 m0, s75
	s_nop 0
	s_mov_b32 s75, m0
	s_mov_b32 m0, s49
	s_nop 0
	global_load_lds_dwordx4 v157, s[28:29]
	s_mov_b32 m0, s75
	s_add_u32 s28, s28, 0x80000
	s_addc_u32 s29, s29, 0
	s_mov_b32 s75, m0
	s_mov_b32 m0, s56
	s_nop 0
	global_load_lds_dwordx4 v1, s[28:29]
	s_mov_b32 m0, s75
	s_nop 0
	s_mov_b32 s75, m0
	s_mov_b32 m0, s57
	s_nop 0
	global_load_lds_dwordx4 v157, s[28:29]
	s_mov_b32 m0, s75
	s_waitcnt vmcnt(8)
	s_waitcnt lgkmcnt(0)
	s_barrier
	s_setprio 1
	.p2align 3
	v_mfma_f32_16x16x32_bf16 v[126:129], v[130:133], v[180:183], v[126:129]
	v_mfma_f32_16x16x32_bf16 v[126:129], v[138:141], v[184:187], v[126:129]
	v_mfma_f32_16x16x32_bf16 v[122:125], v[142:145], v[180:183], v[122:125]
	v_mfma_f32_16x16x32_bf16 v[122:125], v[146:149], v[184:187], v[122:125]
	v_mfma_f32_16x16x32_bf16 v[106:109], v[142:145], v[188:191], v[106:109]
	v_mfma_f32_16x16x32_bf16 v[106:109], v[146:149], v[192:195], v[106:109]
	v_mfma_f32_16x16x32_bf16 v[110:113], v[130:133], v[188:191], v[110:113]
	v_mfma_f32_16x16x32_bf16 v[110:113], v[138:141], v[192:195], v[110:113]
	v_mfma_f32_16x16x32_bf16 v[94:97], v[130:133], v[196:199], v[94:97]
	v_mfma_f32_16x16x32_bf16 v[94:97], v[138:141], v[200:203], v[94:97]
	v_mfma_f32_16x16x32_bf16 v[90:93], v[142:145], v[196:199], v[90:93]
	v_mfma_f32_16x16x32_bf16 v[90:93], v[146:149], v[200:203], v[90:93]
	v_mfma_f32_16x16x32_bf16 v[74:77], v[142:145], v[204:207], v[74:77]
	v_mfma_f32_16x16x32_bf16 v[74:77], v[146:149], v[208:211], v[74:77]
	v_mfma_f32_16x16x32_bf16 v[78:81], v[130:133], v[204:207], v[78:81]
	v_mfma_f32_16x16x32_bf16 v[78:81], v[138:141], v[208:211], v[78:81]
	v_mfma_f32_16x16x32_bf16 v[118:121], v[150:153], v[180:183], v[118:121]
	v_mfma_f32_16x16x32_bf16 v[118:121], v[168:171], v[184:187], v[118:121]
	v_mfma_f32_16x16x32_bf16 v[114:117], v[172:175], v[180:183], v[114:117]
	v_mfma_f32_16x16x32_bf16 v[114:117], v[176:179], v[184:187], v[114:117]
	v_mfma_f32_16x16x32_bf16 v[98:101], v[172:175], v[188:191], v[98:101]
	v_mfma_f32_16x16x32_bf16 v[98:101], v[176:179], v[192:195], v[98:101]
	v_mfma_f32_16x16x32_bf16 v[102:105], v[150:153], v[188:191], v[102:105]
	v_mfma_f32_16x16x32_bf16 v[102:105], v[168:171], v[192:195], v[102:105]
	v_mfma_f32_16x16x32_bf16 v[86:89], v[150:153], v[196:199], v[86:89]
	v_mfma_f32_16x16x32_bf16 v[86:89], v[168:171], v[200:203], v[86:89]
	v_mfma_f32_16x16x32_bf16 v[82:85], v[172:175], v[196:199], v[82:85]
	v_mfma_f32_16x16x32_bf16 v[82:85], v[176:179], v[200:203], v[82:85]
	v_mfma_f32_16x16x32_bf16 v[66:69], v[172:175], v[204:207], v[66:69]
	v_mfma_f32_16x16x32_bf16 v[66:69], v[176:179], v[208:211], v[66:69]
	s_setprio 2
	s_barrier
	v_mfma_f32_16x16x32_bf16 v[70:73], v[150:153], v[204:207], v[70:73]
	v_mfma_f32_16x16x32_bf16 v[70:73], v[168:171], v[208:211], v[70:73]
	s_setprio 0
	ds_read_b128 v[180:183], v163 offset:49152
	ds_read_b128 v[184:187], v163 offset:50176
	ds_read_b128 v[188:191], v163 offset:51200
	ds_read_b128 v[192:195], v163 offset:52224
	ds_read_b128 v[196:199], v163 offset:53248
	ds_read_b128 v[200:203], v163 offset:54272
	ds_read_b128 v[204:207], v163 offset:55296
	ds_read_b128 v[208:211], v163 offset:56320
	s_add_u32 s28, s10, 0x80
	s_addc_u32 s29, s11, 0
	s_mov_b32 s75, m0
	s_mov_b32 m0, s64
	s_nop 0
	global_load_lds_dwordx4 v156, s[28:29]
	s_mov_b32 m0, s75
	s_add_u32 s10, s10, 0x80080
	s_mov_b32 s75, m0
	s_mov_b32 m0, s65
	s_nop 0
	global_load_lds_dwordx4 v158, s[28:29]
	s_mov_b32 m0, s75
	s_addc_u32 s11, s11, 0
	s_mov_b32 s28, m0
	s_mov_b32 m0, s66
	s_nop 0
	global_load_lds_dwordx4 v156, s[10:11]
	s_mov_b32 m0, s28
	s_nop 0
	s_mov_b32 s28, m0
	s_mov_b32 m0, s67
	s_nop 0
	global_load_lds_dwordx4 v158, s[10:11]
	s_mov_b32 m0, s28
	s_waitcnt vmcnt(4)
	s_waitcnt lgkmcnt(0)
	s_barrier
	s_setprio 1
	.p2align 3
	v_mfma_f32_16x16x32_bf16 v[62:65], v[130:133], v[180:183], v[62:65]
	v_mfma_f32_16x16x32_bf16 v[62:65], v[138:141], v[184:187], v[62:65]
	v_mfma_f32_16x16x32_bf16 v[58:61], v[142:145], v[180:183], v[58:61]
	v_mfma_f32_16x16x32_bf16 v[58:61], v[146:149], v[184:187], v[58:61]
	v_mfma_f32_16x16x32_bf16 v[42:45], v[142:145], v[188:191], v[42:45]
	v_mfma_f32_16x16x32_bf16 v[42:45], v[146:149], v[192:195], v[42:45]
	v_mfma_f32_16x16x32_bf16 v[46:49], v[130:133], v[188:191], v[46:49]
	v_mfma_f32_16x16x32_bf16 v[46:49], v[138:141], v[192:195], v[46:49]
	v_mfma_f32_16x16x32_bf16 v[30:33], v[130:133], v[196:199], v[30:33]
	v_mfma_f32_16x16x32_bf16 v[30:33], v[138:141], v[200:203], v[30:33]
	v_mfma_f32_16x16x32_bf16 v[26:29], v[142:145], v[196:199], v[26:29]
	v_mfma_f32_16x16x32_bf16 v[26:29], v[146:149], v[200:203], v[26:29]
	v_mfma_f32_16x16x32_bf16 v[10:13], v[142:145], v[204:207], v[10:13]
	v_mfma_f32_16x16x32_bf16 v[10:13], v[146:149], v[208:211], v[10:13]
	v_mfma_f32_16x16x32_bf16 v[14:17], v[130:133], v[204:207], v[14:17]
	v_mfma_f32_16x16x32_bf16 v[14:17], v[138:141], v[208:211], v[14:17]
	v_mfma_f32_16x16x32_bf16 v[54:57], v[150:153], v[180:183], v[54:57]
	v_mfma_f32_16x16x32_bf16 v[54:57], v[168:171], v[184:187], v[54:57]
	v_mfma_f32_16x16x32_bf16 v[50:53], v[172:175], v[180:183], v[50:53]
	v_mfma_f32_16x16x32_bf16 v[50:53], v[176:179], v[184:187], v[50:53]
	v_mfma_f32_16x16x32_bf16 v[34:37], v[172:175], v[188:191], v[34:37]
	v_mfma_f32_16x16x32_bf16 v[34:37], v[176:179], v[192:195], v[34:37]
	v_mfma_f32_16x16x32_bf16 v[38:41], v[150:153], v[188:191], v[38:41]
	v_mfma_f32_16x16x32_bf16 v[38:41], v[168:171], v[192:195], v[38:41]
	v_mfma_f32_16x16x32_bf16 v[22:25], v[150:153], v[196:199], v[22:25]
	v_mfma_f32_16x16x32_bf16 v[22:25], v[168:171], v[200:203], v[22:25]
	v_mfma_f32_16x16x32_bf16 v[18:21], v[172:175], v[196:199], v[18:21]
	v_mfma_f32_16x16x32_bf16 v[18:21], v[176:179], v[200:203], v[18:21]
	v_mfma_f32_16x16x32_bf16 v[2:5], v[172:175], v[204:207], v[2:5]
	v_mfma_f32_16x16x32_bf16 v[2:5], v[176:179], v[208:211], v[2:5]
	s_setprio 2
	s_barrier
	v_mfma_f32_16x16x32_bf16 v[6:9], v[150:153], v[204:207], v[6:9]
	v_mfma_f32_16x16x32_bf16 v[6:9], v[168:171], v[208:211], v[6:9]
	s_setprio 0
	s_add_i32 s74, s74, 2
	s_add_u32 s30, s30, 0x100
	s_addc_u32 s31, s31, 0
	s_add_u32 s4, s4, 0x100
	s_addc_u32 s5, s5, 0
	s_add_u32 s33, s33, 0x100
	s_addc_u32 s73, s73, 0
	s_cmp_gt_u32 s74, 29
	s_cbranch_scc0 .LBB0_654
	s_and_b64 vcc, exec, s[18:19]
	s_cbranch_vccz .LBB0_657
	s_barrier

.LBB0_1052:
	s_ashr_i32 s13, s12, 31
	s_lshl_b64 s[14:15], s[12:13], 20
	s_add_u32 s14, s28, s14
	s_addc_u32 s15, s29, s15
	s_and_b64 s[16:17], s[2:3], exec
	s_cselect_b32 s13, s15, s23
	s_cselect_b32 s67, s14, s22
	s_ashr_i32 s11, s10, 31
	s_lshl_b64 s[16:17], s[10:11], 20
	s_add_u32 s16, s30, s16
	s_addc_u32 s17, s31, s17
	s_and_b64 s[24:25], s[2:3], exec
	s_cselect_b32 s11, s17, s21
	s_cselect_b32 s73, s16, s20
	s_add_u32 s74, s20, 0x100
	s_addc_u32 s75, s21, 0
	s_add_u32 s20, s22, 0x80080
	s_addc_u32 s21, s23, 0
	s_add_u32 s76, s22, 0x100
	s_addc_u32 s77, s23, 0
	s_mov_b32 s78, -2
	s_waitcnt vmcnt(25)
	s_waitcnt vmcnt(24)
	s_waitcnt vmcnt(15)
	s_waitcnt vmcnt(14)
	s_waitcnt vmcnt(13)
	s_waitcnt vmcnt(12)
	s_waitcnt vmcnt(11)
	s_waitcnt vmcnt(10)
	s_waitcnt vmcnt(9)
	s_waitcnt vmcnt(8)
	s_waitcnt vmcnt(7)
	s_waitcnt vmcnt(6)
	s_waitcnt vmcnt(5)
	s_waitcnt vmcnt(4)
	s_waitcnt vmcnt(3)
	s_waitcnt vmcnt(2)
	s_waitcnt vmcnt(1)
	s_waitcnt vmcnt(0)
	ds_read_b128 v[130:133], v181
	ds_read_b128 v[134:137], v181 offset:1024
	ds_read_b128 v[138:141], v181 offset:2048
	ds_read_b128 v[142:145], v181 offset:3072
	ds_read_b128 v[146:149], v182
	ds_read_b128 v[150:153], v182 offset:1024
	ds_read_b128 v[154:157], v182 offset:2048
	ds_read_b128 v[158:161], v182 offset:3072
	s_cmp_eq_u32 s78, 28
	s_cselect_b32 s23, s11, s75
	s_cselect_b32 s22, s73, s74
	s_cselect_b32 s25, s13, s77
	s_cselect_b32 s24, s67, s76
	ds_read_b128 v[166:169], v183
	ds_read_b128 v[170:173], v183 offset:1024
	ds_read_b128 v[186:189], v183 offset:2048
	ds_read_b128 v[190:193], v183 offset:3072
	ds_read_b128 v[194:197], v183 offset:4096
	ds_read_b128 v[198:201], v183 offset:5120
	ds_read_b128 v[202:205], v183 offset:6144
	ds_read_b128 v[206:209], v183 offset:7168
	s_add_u32 s80, s20, 0xfff80000
	s_addc_u32 s81, s21, -1
	s_mov_b32 s79, m0
	s_mov_b32 m0, s58
	s_nop 0
	global_load_lds_dwordx4 v1, s[80:81]
	s_mov_b32 m0, s79
	s_nop 0
	s_mov_b32 s79, m0
	s_mov_b32 m0, s64
	s_nop 0
	global_load_lds_dwordx4 v177, s[80:81]
	s_mov_b32 m0, s79
	s_nop 0
	s_mov_b32 s79, m0
	s_mov_b32 m0, s59
	s_nop 0
	global_load_lds_dwordx4 v1, s[20:21]
	s_mov_b32 m0, s79
	s_nop 0
	s_mov_b32 s79, m0
	s_mov_b32 m0, s65
	s_nop 0
	global_load_lds_dwordx4 v177, s[20:21]
	s_mov_b32 m0, s79
	s_waitcnt vmcnt(8)
	s_waitcnt lgkmcnt(0)
	s_barrier
	s_setprio 1
	.p2align 3
	v_mfma_f32_16x16x32_bf16 v[126:129], v[130:133], v[166:169], 0
	v_mfma_f32_16x16x32_bf16 v[126:129], v[134:137], v[170:173], v[126:129]
	v_mfma_f32_16x16x32_bf16 v[122:125], v[138:141], v[166:169], 0
	v_mfma_f32_16x16x32_bf16 v[122:125], v[142:145], v[170:173], v[122:125]
	v_mfma_f32_16x16x32_bf16 v[114:117], v[138:141], v[186:189], 0
	v_mfma_f32_16x16x32_bf16 v[114:117], v[142:145], v[190:193], v[114:117]
	v_mfma_f32_16x16x32_bf16 v[118:121], v[130:133], v[186:189], 0
	v_mfma_f32_16x16x32_bf16 v[118:121], v[134:137], v[190:193], v[118:121]
	v_mfma_f32_16x16x32_bf16 v[94:97], v[130:133], v[194:197], 0
	v_mfma_f32_16x16x32_bf16 v[94:97], v[134:137], v[198:201], v[94:97]
	v_mfma_f32_16x16x32_bf16 v[90:93], v[138:141], v[194:197], 0
	v_mfma_f32_16x16x32_bf16 v[90:93], v[142:145], v[198:201], v[90:93]
	v_mfma_f32_16x16x32_bf16 v[78:81], v[138:141], v[202:205], 0
	v_mfma_f32_16x16x32_bf16 v[78:81], v[142:145], v[206:209], v[78:81]
	v_mfma_f32_16x16x32_bf16 v[86:89], v[130:133], v[202:205], 0
	v_mfma_f32_16x16x32_bf16 v[86:89], v[134:137], v[206:209], v[86:89]
	v_mfma_f32_16x16x32_bf16 v[110:113], v[146:149], v[166:169], 0
	v_mfma_f32_16x16x32_bf16 v[110:113], v[150:153], v[170:173], v[110:113]
	v_mfma_f32_16x16x32_bf16 v[106:109], v[154:157], v[166:169], 0
	v_mfma_f32_16x16x32_bf16 v[106:109], v[158:161], v[170:173], v[106:109]
	v_mfma_f32_16x16x32_bf16 v[98:101], v[154:157], v[186:189], 0
	v_mfma_f32_16x16x32_bf16 v[98:101], v[158:161], v[190:193], v[98:101]
	v_mfma_f32_16x16x32_bf16 v[102:105], v[146:149], v[186:189], 0
	v_mfma_f32_16x16x32_bf16 v[102:105], v[150:153], v[190:193], v[102:105]
	v_mfma_f32_16x16x32_bf16 v[82:85], v[146:149], v[194:197], 0
	v_mfma_f32_16x16x32_bf16 v[82:85], v[150:153], v[198:201], v[82:85]
	v_mfma_f32_16x16x32_bf16 v[74:77], v[154:157], v[194:197], 0
	v_mfma_f32_16x16x32_bf16 v[74:77], v[158:161], v[198:201], v[74:77]
	v_mfma_f32_16x16x32_bf16 v[66:69], v[154:157], v[202:205], 0
	v_mfma_f32_16x16x32_bf16 v[66:69], v[158:161], v[206:209], v[66:69]
	s_setprio 2
	s_barrier
	v_mfma_f32_16x16x32_bf16 v[70:73], v[146:149], v[202:205], 0
	v_mfma_f32_16x16x32_bf16 v[70:73], v[150:153], v[206:209], v[70:73]
	s_setprio 0
	ds_read_b128 v[166:169], v183 offset:16384
	ds_read_b128 v[170:173], v183 offset:17408
	ds_read_b128 v[186:189], v183 offset:18432
	ds_read_b128 v[190:193], v183 offset:19456
	ds_read_b128 v[194:197], v183 offset:20480
	ds_read_b128 v[198:201], v183 offset:21504
	ds_read_b128 v[202:205], v183 offset:22528
	ds_read_b128 v[206:209], v183 offset:23552
	s_mov_b32 s79, m0
	s_mov_b32 m0, s35
	s_nop 0
	global_load_lds_dwordx4 v176, s[22:23]
	s_mov_b32 m0, s79
	s_add_u32 s80, s22, 0x80000
	s_mov_b32 s79, m0
	s_mov_b32 m0, s36
	s_nop 0
	global_load_lds_dwordx4 v178, s[22:23]
	s_mov_b32 m0, s79
	s_addc_u32 s81, s23, 0
	s_mov_b32 s79, m0
	s_mov_b32 m0, s37
	s_nop 0
	global_load_lds_dwordx4 v176, s[80:81]
	s_mov_b32 m0, s79
	s_nop 0
	s_mov_b32 s79, m0
	s_mov_b32 m0, s40
	s_nop 0
	global_load_lds_dwordx4 v178, s[80:81]
	s_mov_b32 m0, s79
	s_waitcnt vmcnt(4)
	s_waitcnt lgkmcnt(0)
	s_barrier
	s_setprio 1
	.p2align 3
	v_mfma_f32_16x16x32_bf16 v[62:65], v[130:133], v[166:169], 0
	v_mfma_f32_16x16x32_bf16 v[62:65], v[134:137], v[170:173], v[62:65]
	v_mfma_f32_16x16x32_bf16 v[58:61], v[138:141], v[166:169], 0
	v_mfma_f32_16x16x32_bf16 v[58:61], v[142:145], v[170:173], v[58:61]
	v_mfma_f32_16x16x32_bf16 v[42:45], v[138:141], v[186:189], 0
	v_mfma_f32_16x16x32_bf16 v[42:45], v[142:145], v[190:193], v[42:45]
	v_mfma_f32_16x16x32_bf16 v[46:49], v[130:133], v[186:189], 0
	v_mfma_f32_16x16x32_bf16 v[46:49], v[134:137], v[190:193], v[46:49]
	v_mfma_f32_16x16x32_bf16 v[30:33], v[130:133], v[194:197], 0
	v_mfma_f32_16x16x32_bf16 v[30:33], v[134:137], v[198:201], v[30:33]
	v_mfma_f32_16x16x32_bf16 v[26:29], v[138:141], v[194:197], 0
	v_mfma_f32_16x16x32_bf16 v[26:29], v[142:145], v[198:201], v[26:29]
	v_mfma_f32_16x16x32_bf16 v[10:13], v[138:141], v[202:205], 0
	v_mfma_f32_16x16x32_bf16 v[10:13], v[142:145], v[206:209], v[10:13]
	v_mfma_f32_16x16x32_bf16 v[14:17], v[130:133], v[202:205], 0
	v_mfma_f32_16x16x32_bf16 v[14:17], v[134:137], v[206:209], v[14:17]
	v_mfma_f32_16x16x32_bf16 v[54:57], v[146:149], v[166:169], 0
	v_mfma_f32_16x16x32_bf16 v[54:57], v[150:153], v[170:173], v[54:57]
	v_mfma_f32_16x16x32_bf16 v[50:53], v[154:157], v[166:169], 0
	v_mfma_f32_16x16x32_bf16 v[50:53], v[158:161], v[170:173], v[50:53]
	v_mfma_f32_16x16x32_bf16 v[34:37], v[154:157], v[186:189], 0
	v_mfma_f32_16x16x32_bf16 v[34:37], v[158:161], v[190:193], v[34:37]
	v_mfma_f32_16x16x32_bf16 v[38:41], v[146:149], v[186:189], 0
	v_mfma_f32_16x16x32_bf16 v[38:41], v[150:153], v[190:193], v[38:41]
	v_mfma_f32_16x16x32_bf16 v[22:25], v[146:149], v[194:197], 0
	v_mfma_f32_16x16x32_bf16 v[22:25], v[150:153], v[198:201], v[22:25]
	v_mfma_f32_16x16x32_bf16 v[18:21], v[154:157], v[194:197], 0
	v_mfma_f32_16x16x32_bf16 v[18:21], v[158:161], v[198:201], v[18:21]
	v_mfma_f32_16x16x32_bf16 v[2:5], v[154:157], v[202:205], 0
	v_mfma_f32_16x16x32_bf16 v[2:5], v[158:161], v[206:209], v[2:5]
	s_setprio 2
	s_barrier
	v_mfma_f32_16x16x32_bf16 v[6:9], v[146:149], v[202:205], 0
	v_mfma_f32_16x16x32_bf16 v[6:9], v[150:153], v[206:209], v[6:9]
	s_setprio 0
	ds_read_b128 v[130:133], v184
	ds_read_b128 v[134:137], v184 offset:1024
	ds_read_b128 v[138:141], v184 offset:2048
	ds_read_b128 v[142:145], v184 offset:3072
	ds_read_b128 v[146:149], v185
	ds_read_b128 v[150:153], v185 offset:1024
	ds_read_b128 v[154:157], v185 offset:2048
	ds_read_b128 v[158:161], v185 offset:3072
	ds_read_b128 v[166:169], v183 offset:32768
	ds_read_b128 v[170:173], v183 offset:33792
	ds_read_b128 v[186:189], v183 offset:34816
	ds_read_b128 v[190:193], v183 offset:35840
	ds_read_b128 v[194:197], v183 offset:36864
	ds_read_b128 v[198:201], v183 offset:37888
	ds_read_b128 v[202:205], v183 offset:38912
	ds_read_b128 v[206:209], v183 offset:39936
	s_mov_b32 s79, m0
	s_mov_b32 m0, s34
	s_nop 0
	global_load_lds_dwordx4 v1, s[24:25]
	s_mov_b32 m0, s79
	s_nop 0
	s_mov_b32 s79, m0
	s_mov_b32 m0, s41
	s_nop 0
	global_load_lds_dwordx4 v177, s[24:25]
	s_mov_b32 m0, s79
	s_add_u32 s24, s24, 0x80000
	s_addc_u32 s25, s25, 0
	s_mov_b32 s79, m0
	s_mov_b32 m0, s42
	s_nop 0
	global_load_lds_dwordx4 v1, s[24:25]
	s_mov_b32 m0, s79
	s_nop 0
	s_mov_b32 s79, m0
	s_mov_b32 m0, s43
	s_nop 0
	global_load_lds_dwordx4 v177, s[24:25]
	s_mov_b32 m0, s79
	s_waitcnt vmcnt(8)
	s_waitcnt lgkmcnt(0)
	s_barrier
	s_setprio 1
	.p2align 3
	v_mfma_f32_16x16x32_bf16 v[126:129], v[130:133], v[166:169], v[126:129]
	v_mfma_f32_16x16x32_bf16 v[126:129], v[134:137], v[170:173], v[126:129]
	v_mfma_f32_16x16x32_bf16 v[122:125], v[138:141], v[166:169], v[122:125]
	v_mfma_f32_16x16x32_bf16 v[122:125], v[142:145], v[170:173], v[122:125]
	v_mfma_f32_16x16x32_bf16 v[114:117], v[138:141], v[186:189], v[114:117]
	v_mfma_f32_16x16x32_bf16 v[114:117], v[142:145], v[190:193], v[114:117]
	v_mfma_f32_16x16x32_bf16 v[118:121], v[130:133], v[186:189], v[118:121]
	v_mfma_f32_16x16x32_bf16 v[118:121], v[134:137], v[190:193], v[118:121]
	v_mfma_f32_16x16x32_bf16 v[94:97], v[130:133], v[194:197], v[94:97]
	v_mfma_f32_16x16x32_bf16 v[94:97], v[134:137], v[198:201], v[94:97]
	v_mfma_f32_16x16x32_bf16 v[90:93], v[138:141], v[194:197], v[90:93]
	v_mfma_f32_16x16x32_bf16 v[90:93], v[142:145], v[198:201], v[90:93]
	v_mfma_f32_16x16x32_bf16 v[78:81], v[138:141], v[202:205], v[78:81]
	v_mfma_f32_16x16x32_bf16 v[78:81], v[142:145], v[206:209], v[78:81]
	v_mfma_f32_16x16x32_bf16 v[86:89], v[130:133], v[202:205], v[86:89]
	v_mfma_f32_16x16x32_bf16 v[86:89], v[134:137], v[206:209], v[86:89]
	v_mfma_f32_16x16x32_bf16 v[110:113], v[146:149], v[166:169], v[110:113]
	v_mfma_f32_16x16x32_bf16 v[110:113], v[150:153], v[170:173], v[110:113]
	v_mfma_f32_16x16x32_bf16 v[106:109], v[154:157], v[166:169], v[106:109]
	v_mfma_f32_16x16x32_bf16 v[106:109], v[158:161], v[170:173], v[106:109]
	v_mfma_f32_16x16x32_bf16 v[98:101], v[154:157], v[186:189], v[98:101]
	v_mfma_f32_16x16x32_bf16 v[98:101], v[158:161], v[190:193], v[98:101]
	v_mfma_f32_16x16x32_bf16 v[102:105], v[146:149], v[186:189], v[102:105]
	v_mfma_f32_16x16x32_bf16 v[102:105], v[150:153], v[190:193], v[102:105]
	v_mfma_f32_16x16x32_bf16 v[82:85], v[146:149], v[194:197], v[82:85]
	v_mfma_f32_16x16x32_bf16 v[82:85], v[150:153], v[198:201], v[82:85]
	v_mfma_f32_16x16x32_bf16 v[74:77], v[154:157], v[194:197], v[74:77]
	v_mfma_f32_16x16x32_bf16 v[74:77], v[158:161], v[198:201], v[74:77]
	v_mfma_f32_16x16x32_bf16 v[66:69], v[154:157], v[202:205], v[66:69]
	v_mfma_f32_16x16x32_bf16 v[66:69], v[158:161], v[206:209], v[66:69]
	s_setprio 2
	s_barrier
	v_mfma_f32_16x16x32_bf16 v[70:73], v[146:149], v[202:205], v[70:73]
	v_mfma_f32_16x16x32_bf16 v[70:73], v[150:153], v[206:209], v[70:73]
	s_setprio 0
	ds_read_b128 v[166:169], v183 offset:49152
	ds_read_b128 v[170:173], v183 offset:50176
	ds_read_b128 v[186:189], v183 offset:51200
	ds_read_b128 v[190:193], v183 offset:52224
	ds_read_b128 v[194:197], v183 offset:53248
	ds_read_b128 v[198:201], v183 offset:54272
	ds_read_b128 v[202:205], v183 offset:55296
	ds_read_b128 v[206:209], v183 offset:56320
	s_add_u32 s24, s22, 0x80
	s_addc_u32 s25, s23, 0
	s_mov_b32 s79, m0
	s_mov_b32 m0, s46
	s_nop 0
	global_load_lds_dwordx4 v176, s[24:25]
	s_mov_b32 m0, s79
	s_add_u32 s22, s22, 0x80080
	s_mov_b32 s79, m0
	s_mov_b32 m0, s47
	s_nop 0
	global_load_lds_dwordx4 v178, s[24:25]
	s_mov_b32 m0, s79
	s_addc_u32 s23, s23, 0
	s_mov_b32 s24, m0
	s_mov_b32 m0, s48
	s_nop 0
	global_load_lds_dwordx4 v176, s[22:23]
	s_mov_b32 m0, s24
	s_nop 0
	s_mov_b32 s24, m0
	s_mov_b32 m0, s49
	s_nop 0
	global_load_lds_dwordx4 v178, s[22:23]
	s_mov_b32 m0, s24
	s_waitcnt vmcnt(4)
	s_waitcnt lgkmcnt(0)
	s_barrier
	s_setprio 1
	.p2align 3
	v_mfma_f32_16x16x32_bf16 v[62:65], v[130:133], v[166:169], v[62:65]
	v_mfma_f32_16x16x32_bf16 v[62:65], v[134:137], v[170:173], v[62:65]
	v_mfma_f32_16x16x32_bf16 v[58:61], v[138:141], v[166:169], v[58:61]
	v_mfma_f32_16x16x32_bf16 v[58:61], v[142:145], v[170:173], v[58:61]
	v_mfma_f32_16x16x32_bf16 v[42:45], v[138:141], v[186:189], v[42:45]
	v_mfma_f32_16x16x32_bf16 v[42:45], v[142:145], v[190:193], v[42:45]
	v_mfma_f32_16x16x32_bf16 v[46:49], v[130:133], v[186:189], v[46:49]
	v_mfma_f32_16x16x32_bf16 v[46:49], v[134:137], v[190:193], v[46:49]
	v_mfma_f32_16x16x32_bf16 v[30:33], v[130:133], v[194:197], v[30:33]
	v_mfma_f32_16x16x32_bf16 v[30:33], v[134:137], v[198:201], v[30:33]
	v_mfma_f32_16x16x32_bf16 v[26:29], v[138:141], v[194:197], v[26:29]
	v_mfma_f32_16x16x32_bf16 v[26:29], v[142:145], v[198:201], v[26:29]
	v_mfma_f32_16x16x32_bf16 v[10:13], v[138:141], v[202:205], v[10:13]
	v_mfma_f32_16x16x32_bf16 v[10:13], v[142:145], v[206:209], v[10:13]
	v_mfma_f32_16x16x32_bf16 v[14:17], v[130:133], v[202:205], v[14:17]
	v_mfma_f32_16x16x32_bf16 v[14:17], v[134:137], v[206:209], v[14:17]
	v_mfma_f32_16x16x32_bf16 v[54:57], v[146:149], v[166:169], v[54:57]
	v_mfma_f32_16x16x32_bf16 v[54:57], v[150:153], v[170:173], v[54:57]
	v_mfma_f32_16x16x32_bf16 v[50:53], v[154:157], v[166:169], v[50:53]
	v_mfma_f32_16x16x32_bf16 v[50:53], v[158:161], v[170:173], v[50:53]
	v_mfma_f32_16x16x32_bf16 v[34:37], v[154:157], v[186:189], v[34:37]
	v_mfma_f32_16x16x32_bf16 v[34:37], v[158:161], v[190:193], v[34:37]
	v_mfma_f32_16x16x32_bf16 v[38:41], v[146:149], v[186:189], v[38:41]
	v_mfma_f32_16x16x32_bf16 v[38:41], v[150:153], v[190:193], v[38:41]
	v_mfma_f32_16x16x32_bf16 v[22:25], v[146:149], v[194:197], v[22:25]
	v_mfma_f32_16x16x32_bf16 v[22:25], v[150:153], v[198:201], v[22:25]
	v_mfma_f32_16x16x32_bf16 v[18:21], v[154:157], v[194:197], v[18:21]
	v_mfma_f32_16x16x32_bf16 v[18:21], v[158:161], v[198:201], v[18:21]
	v_mfma_f32_16x16x32_bf16 v[2:5], v[154:157], v[202:205], v[2:5]
	v_mfma_f32_16x16x32_bf16 v[2:5], v[158:161], v[206:209], v[2:5]
	s_setprio 2
	s_barrier
	v_mfma_f32_16x16x32_bf16 v[6:9], v[146:149], v[202:205], v[6:9]
	v_mfma_f32_16x16x32_bf16 v[6:9], v[150:153], v[206:209], v[6:9]
	s_setprio 0
	s_add_i32 s78, s78, 2
	s_add_u32 s74, s74, 0x100
	s_addc_u32 s75, s75, 0
	s_add_u32 s20, s20, 0x100
	s_addc_u32 s21, s21, 0
	s_add_u32 s76, s76, 0x100
	s_addc_u32 s77, s77, 0
	s_cmp_gt_u32 s78, 29
	.p2align 6
.LBB0_1053:
	ds_read_b128 v[130:133], v181
	ds_read_b128 v[134:137], v181 offset:1024
	ds_read_b128 v[138:141], v181 offset:2048
	ds_read_b128 v[142:145], v181 offset:3072
	ds_read_b128 v[146:149], v182
	ds_read_b128 v[150:153], v182 offset:1024
	ds_read_b128 v[154:157], v182 offset:2048
	ds_read_b128 v[158:161], v182 offset:3072
	s_cmp_eq_u32 s78, 28
	s_cselect_b32 s23, s11, s75
	s_cselect_b32 s22, s73, s74
	s_cselect_b32 s25, s13, s77
	s_cselect_b32 s24, s67, s76
	ds_read_b128 v[166:169], v183
	ds_read_b128 v[170:173], v183 offset:1024
	ds_read_b128 v[186:189], v183 offset:2048
	ds_read_b128 v[190:193], v183 offset:3072
	ds_read_b128 v[194:197], v183 offset:4096
	ds_read_b128 v[198:201], v183 offset:5120
	ds_read_b128 v[202:205], v183 offset:6144
	ds_read_b128 v[206:209], v183 offset:7168
	s_add_u32 s80, s20, 0xfff80000
	s_addc_u32 s81, s21, -1
	s_mov_b32 s79, m0
	s_mov_b32 m0, s58
	s_nop 0
	global_load_lds_dwordx4 v1, s[80:81]
	s_mov_b32 m0, s79
	s_nop 0
	s_mov_b32 s79, m0
	s_mov_b32 m0, s64
	s_nop 0
	global_load_lds_dwordx4 v177, s[80:81]
	s_mov_b32 m0, s79
	s_nop 0
	s_mov_b32 s79, m0
	s_mov_b32 m0, s59
	s_nop 0
	global_load_lds_dwordx4 v1, s[20:21]
	s_mov_b32 m0, s79
	s_nop 0
	s_mov_b32 s79, m0
	s_mov_b32 m0, s65
	s_nop 0
	global_load_lds_dwordx4 v177, s[20:21]
	s_mov_b32 m0, s79
	s_waitcnt vmcnt(8)
	s_waitcnt lgkmcnt(0)
	s_barrier
	s_setprio 1
	.p2align 3
	v_mfma_f32_16x16x32_bf16 v[126:129], v[130:133], v[166:169], v[126:129]
	v_mfma_f32_16x16x32_bf16 v[126:129], v[134:137], v[170:173], v[126:129]
	v_mfma_f32_16x16x32_bf16 v[122:125], v[138:141], v[166:169], v[122:125]
	v_mfma_f32_16x16x32_bf16 v[122:125], v[142:145], v[170:173], v[122:125]
	v_mfma_f32_16x16x32_bf16 v[114:117], v[138:141], v[186:189], v[114:117]
	v_mfma_f32_16x16x32_bf16 v[114:117], v[142:145], v[190:193], v[114:117]
	v_mfma_f32_16x16x32_bf16 v[118:121], v[130:133], v[186:189], v[118:121]
	v_mfma_f32_16x16x32_bf16 v[118:121], v[134:137], v[190:193], v[118:121]
	v_mfma_f32_16x16x32_bf16 v[94:97], v[130:133], v[194:197], v[94:97]
	v_mfma_f32_16x16x32_bf16 v[94:97], v[134:137], v[198:201], v[94:97]
	v_mfma_f32_16x16x32_bf16 v[90:93], v[138:141], v[194:197], v[90:93]
	v_mfma_f32_16x16x32_bf16 v[90:93], v[142:145], v[198:201], v[90:93]
	v_mfma_f32_16x16x32_bf16 v[78:81], v[138:141], v[202:205], v[78:81]
	v_mfma_f32_16x16x32_bf16 v[78:81], v[142:145], v[206:209], v[78:81]
	v_mfma_f32_16x16x32_bf16 v[86:89], v[130:133], v[202:205], v[86:89]
	v_mfma_f32_16x16x32_bf16 v[86:89], v[134:137], v[206:209], v[86:89]
	v_mfma_f32_16x16x32_bf16 v[110:113], v[146:149], v[166:169], v[110:113]
	v_mfma_f32_16x16x32_bf16 v[110:113], v[150:153], v[170:173], v[110:113]
	v_mfma_f32_16x16x32_bf16 v[106:109], v[154:157], v[166:169], v[106:109]
	v_mfma_f32_16x16x32_bf16 v[106:109], v[158:161], v[170:173], v[106:109]
	v_mfma_f32_16x16x32_bf16 v[98:101], v[154:157], v[186:189], v[98:101]
	v_mfma_f32_16x16x32_bf16 v[98:101], v[158:161], v[190:193], v[98:101]
	v_mfma_f32_16x16x32_bf16 v[102:105], v[146:149], v[186:189], v[102:105]
	v_mfma_f32_16x16x32_bf16 v[102:105], v[150:153], v[190:193], v[102:105]
	v_mfma_f32_16x16x32_bf16 v[82:85], v[146:149], v[194:197], v[82:85]
	v_mfma_f32_16x16x32_bf16 v[82:85], v[150:153], v[198:201], v[82:85]
	v_mfma_f32_16x16x32_bf16 v[74:77], v[154:157], v[194:197], v[74:77]
	v_mfma_f32_16x16x32_bf16 v[74:77], v[158:161], v[198:201], v[74:77]
	v_mfma_f32_16x16x32_bf16 v[66:69], v[154:157], v[202:205], v[66:69]
	v_mfma_f32_16x16x32_bf16 v[66:69], v[158:161], v[206:209], v[66:69]
	s_setprio 2
	s_barrier
	v_mfma_f32_16x16x32_bf16 v[70:73], v[146:149], v[202:205], v[70:73]
	v_mfma_f32_16x16x32_bf16 v[70:73], v[150:153], v[206:209], v[70:73]
	s_setprio 0
	ds_read_b128 v[166:169], v183 offset:16384
	ds_read_b128 v[170:173], v183 offset:17408
	ds_read_b128 v[186:189], v183 offset:18432
	ds_read_b128 v[190:193], v183 offset:19456
	ds_read_b128 v[194:197], v183 offset:20480
	ds_read_b128 v[198:201], v183 offset:21504
	ds_read_b128 v[202:205], v183 offset:22528
	ds_read_b128 v[206:209], v183 offset:23552
	s_mov_b32 s79, m0
	s_mov_b32 m0, s35
	s_nop 0
	global_load_lds_dwordx4 v176, s[22:23]
	s_mov_b32 m0, s79
	s_add_u32 s80, s22, 0x80000
	s_mov_b32 s79, m0
	s_mov_b32 m0, s36
	s_nop 0
	global_load_lds_dwordx4 v178, s[22:23]
	s_mov_b32 m0, s79
	s_addc_u32 s81, s23, 0
	s_mov_b32 s79, m0
	s_mov_b32 m0, s37
	s_nop 0
	global_load_lds_dwordx4 v176, s[80:81]
	s_mov_b32 m0, s79
	s_nop 0
	s_mov_b32 s79, m0
	s_mov_b32 m0, s40
	s_nop 0
	global_load_lds_dwordx4 v178, s[80:81]
	s_mov_b32 m0, s79
	s_waitcnt vmcnt(4)
	s_waitcnt lgkmcnt(0)
	s_barrier
	s_setprio 1
	.p2align 3
	v_mfma_f32_16x16x32_bf16 v[62:65], v[130:133], v[166:169], v[62:65]
	v_mfma_f32_16x16x32_bf16 v[62:65], v[134:137], v[170:173], v[62:65]
	v_mfma_f32_16x16x32_bf16 v[58:61], v[138:141], v[166:169], v[58:61]
	v_mfma_f32_16x16x32_bf16 v[58:61], v[142:145], v[170:173], v[58:61]
	v_mfma_f32_16x16x32_bf16 v[42:45], v[138:141], v[186:189], v[42:45]
	v_mfma_f32_16x16x32_bf16 v[42:45], v[142:145], v[190:193], v[42:45]
	v_mfma_f32_16x16x32_bf16 v[46:49], v[130:133], v[186:189], v[46:49]
	v_mfma_f32_16x16x32_bf16 v[46:49], v[134:137], v[190:193], v[46:49]
	v_mfma_f32_16x16x32_bf16 v[30:33], v[130:133], v[194:197], v[30:33]
	v_mfma_f32_16x16x32_bf16 v[30:33], v[134:137], v[198:201], v[30:33]
	v_mfma_f32_16x16x32_bf16 v[26:29], v[138:141], v[194:197], v[26:29]
	v_mfma_f32_16x16x32_bf16 v[26:29], v[142:145], v[198:201], v[26:29]
	v_mfma_f32_16x16x32_bf16 v[10:13], v[138:141], v[202:205], v[10:13]
	v_mfma_f32_16x16x32_bf16 v[10:13], v[142:145], v[206:209], v[10:13]
	v_mfma_f32_16x16x32_bf16 v[14:17], v[130:133], v[202:205], v[14:17]
	v_mfma_f32_16x16x32_bf16 v[14:17], v[134:137], v[206:209], v[14:17]
	v_mfma_f32_16x16x32_bf16 v[54:57], v[146:149], v[166:169], v[54:57]
	v_mfma_f32_16x16x32_bf16 v[54:57], v[150:153], v[170:173], v[54:57]
	v_mfma_f32_16x16x32_bf16 v[50:53], v[154:157], v[166:169], v[50:53]
	v_mfma_f32_16x16x32_bf16 v[50:53], v[158:161], v[170:173], v[50:53]
	v_mfma_f32_16x16x32_bf16 v[34:37], v[154:157], v[186:189], v[34:37]
	v_mfma_f32_16x16x32_bf16 v[34:37], v[158:161], v[190:193], v[34:37]
	v_mfma_f32_16x16x32_bf16 v[38:41], v[146:149], v[186:189], v[38:41]
	v_mfma_f32_16x16x32_bf16 v[38:41], v[150:153], v[190:193], v[38:41]
	v_mfma_f32_16x16x32_bf16 v[22:25], v[146:149], v[194:197], v[22:25]
	v_mfma_f32_16x16x32_bf16 v[22:25], v[150:153], v[198:201], v[22:25]
	v_mfma_f32_16x16x32_bf16 v[18:21], v[154:157], v[194:197], v[18:21]
	v_mfma_f32_16x16x32_bf16 v[18:21], v[158:161], v[198:201], v[18:21]
	v_mfma_f32_16x16x32_bf16 v[2:5], v[154:157], v[202:205], v[2:5]
	v_mfma_f32_16x16x32_bf16 v[2:5], v[158:161], v[206:209], v[2:5]
	s_setprio 2
	s_barrier
	v_mfma_f32_16x16x32_bf16 v[6:9], v[146:149], v[202:205], v[6:9]
	v_mfma_f32_16x16x32_bf16 v[6:9], v[150:153], v[206:209], v[6:9]
	s_setprio 0
	ds_read_b128 v[130:133], v184
	ds_read_b128 v[134:137], v184 offset:1024
	ds_read_b128 v[138:141], v184 offset:2048
	ds_read_b128 v[142:145], v184 offset:3072
	ds_read_b128 v[146:149], v185
	ds_read_b128 v[150:153], v185 offset:1024
	ds_read_b128 v[154:157], v185 offset:2048
	ds_read_b128 v[158:161], v185 offset:3072
	ds_read_b128 v[166:169], v183 offset:32768
	ds_read_b128 v[170:173], v183 offset:33792
	ds_read_b128 v[186:189], v183 offset:34816
	ds_read_b128 v[190:193], v183 offset:35840
	ds_read_b128 v[194:197], v183 offset:36864
	ds_read_b128 v[198:201], v183 offset:37888
	ds_read_b128 v[202:205], v183 offset:38912
	ds_read_b128 v[206:209], v183 offset:39936
	s_mov_b32 s79, m0
	s_mov_b32 m0, s34
	s_nop 0
	global_load_lds_dwordx4 v1, s[24:25]
	s_mov_b32 m0, s79
	s_nop 0
	s_mov_b32 s79, m0
	s_mov_b32 m0, s41
	s_nop 0
	global_load_lds_dwordx4 v177, s[24:25]
	s_mov_b32 m0, s79
	s_add_u32 s24, s24, 0x80000
	s_addc_u32 s25, s25, 0
	s_mov_b32 s79, m0
	s_mov_b32 m0, s42
	s_nop 0
	global_load_lds_dwordx4 v1, s[24:25]
	s_mov_b32 m0, s79
	s_nop 0
	s_mov_b32 s79, m0
	s_mov_b32 m0, s43
	s_nop 0
	global_load_lds_dwordx4 v177, s[24:25]
	s_mov_b32 m0, s79
	s_waitcnt vmcnt(8)
	s_waitcnt lgkmcnt(0)
	s_barrier
	s_setprio 1
	.p2align 3
	v_mfma_f32_16x16x32_bf16 v[126:129], v[130:133], v[166:169], v[126:129]
	v_mfma_f32_16x16x32_bf16 v[126:129], v[134:137], v[170:173], v[126:129]
	v_mfma_f32_16x16x32_bf16 v[122:125], v[138:141], v[166:169], v[122:125]
	v_mfma_f32_16x16x32_bf16 v[122:125], v[142:145], v[170:173], v[122:125]
	v_mfma_f32_16x16x32_bf16 v[114:117], v[138:141], v[186:189], v[114:117]
	v_mfma_f32_16x16x32_bf16 v[114:117], v[142:145], v[190:193], v[114:117]
	v_mfma_f32_16x16x32_bf16 v[118:121], v[130:133], v[186:189], v[118:121]
	v_mfma_f32_16x16x32_bf16 v[118:121], v[134:137], v[190:193], v[118:121]
	v_mfma_f32_16x16x32_bf16 v[94:97], v[130:133], v[194:197], v[94:97]
	v_mfma_f32_16x16x32_bf16 v[94:97], v[134:137], v[198:201], v[94:97]
	v_mfma_f32_16x16x32_bf16 v[90:93], v[138:141], v[194:197], v[90:93]
	v_mfma_f32_16x16x32_bf16 v[90:93], v[142:145], v[198:201], v[90:93]
	v_mfma_f32_16x16x32_bf16 v[78:81], v[138:141], v[202:205], v[78:81]
	v_mfma_f32_16x16x32_bf16 v[78:81], v[142:145], v[206:209], v[78:81]
	v_mfma_f32_16x16x32_bf16 v[86:89], v[130:133], v[202:205], v[86:89]
	v_mfma_f32_16x16x32_bf16 v[86:89], v[134:137], v[206:209], v[86:89]
	v_mfma_f32_16x16x32_bf16 v[110:113], v[146:149], v[166:169], v[110:113]
	v_mfma_f32_16x16x32_bf16 v[110:113], v[150:153], v[170:173], v[110:113]
	v_mfma_f32_16x16x32_bf16 v[106:109], v[154:157], v[166:169], v[106:109]
	v_mfma_f32_16x16x32_bf16 v[106:109], v[158:161], v[170:173], v[106:109]
	v_mfma_f32_16x16x32_bf16 v[98:101], v[154:157], v[186:189], v[98:101]
	v_mfma_f32_16x16x32_bf16 v[98:101], v[158:161], v[190:193], v[98:101]
	v_mfma_f32_16x16x32_bf16 v[102:105], v[146:149], v[186:189], v[102:105]
	v_mfma_f32_16x16x32_bf16 v[102:105], v[150:153], v[190:193], v[102:105]
	v_mfma_f32_16x16x32_bf16 v[82:85], v[146:149], v[194:197], v[82:85]
	v_mfma_f32_16x16x32_bf16 v[82:85], v[150:153], v[198:201], v[82:85]
	v_mfma_f32_16x16x32_bf16 v[74:77], v[154:157], v[194:197], v[74:77]
	v_mfma_f32_16x16x32_bf16 v[74:77], v[158:161], v[198:201], v[74:77]
	v_mfma_f32_16x16x32_bf16 v[66:69], v[154:157], v[202:205], v[66:69]
	v_mfma_f32_16x16x32_bf16 v[66:69], v[158:161], v[206:209], v[66:69]
	s_setprio 2
	s_barrier
	v_mfma_f32_16x16x32_bf16 v[70:73], v[146:149], v[202:205], v[70:73]
	v_mfma_f32_16x16x32_bf16 v[70:73], v[150:153], v[206:209], v[70:73]
	s_setprio 0
	ds_read_b128 v[166:169], v183 offset:49152
	ds_read_b128 v[170:173], v183 offset:50176
	ds_read_b128 v[186:189], v183 offset:51200
	ds_read_b128 v[190:193], v183 offset:52224
	ds_read_b128 v[194:197], v183 offset:53248
	ds_read_b128 v[198:201], v183 offset:54272
	ds_read_b128 v[202:205], v183 offset:55296
	ds_read_b128 v[206:209], v183 offset:56320
	s_add_u32 s24, s22, 0x80
	s_addc_u32 s25, s23, 0
	s_mov_b32 s79, m0
	s_mov_b32 m0, s46
	s_nop 0
	global_load_lds_dwordx4 v176, s[24:25]
	s_mov_b32 m0, s79
	s_add_u32 s22, s22, 0x80080
	s_mov_b32 s79, m0
	s_mov_b32 m0, s47
	s_nop 0
	global_load_lds_dwordx4 v178, s[24:25]
	s_mov_b32 m0, s79
	s_addc_u32 s23, s23, 0
	s_mov_b32 s24, m0
	s_mov_b32 m0, s48
	s_nop 0
	global_load_lds_dwordx4 v176, s[22:23]
	s_mov_b32 m0, s24
	s_nop 0
	s_mov_b32 s24, m0
	s_mov_b32 m0, s49
	s_nop 0
	global_load_lds_dwordx4 v178, s[22:23]
	s_mov_b32 m0, s24
	s_waitcnt vmcnt(4)
	s_waitcnt lgkmcnt(0)
	s_barrier
	s_setprio 1
	.p2align 3
	v_mfma_f32_16x16x32_bf16 v[62:65], v[130:133], v[166:169], v[62:65]
	v_mfma_f32_16x16x32_bf16 v[62:65], v[134:137], v[170:173], v[62:65]
	v_mfma_f32_16x16x32_bf16 v[58:61], v[138:141], v[166:169], v[58:61]
	v_mfma_f32_16x16x32_bf16 v[58:61], v[142:145], v[170:173], v[58:61]
	v_mfma_f32_16x16x32_bf16 v[42:45], v[138:141], v[186:189], v[42:45]
	v_mfma_f32_16x16x32_bf16 v[42:45], v[142:145], v[190:193], v[42:45]
	v_mfma_f32_16x16x32_bf16 v[46:49], v[130:133], v[186:189], v[46:49]
	v_mfma_f32_16x16x32_bf16 v[46:49], v[134:137], v[190:193], v[46:49]
	v_mfma_f32_16x16x32_bf16 v[30:33], v[130:133], v[194:197], v[30:33]
	v_mfma_f32_16x16x32_bf16 v[30:33], v[134:137], v[198:201], v[30:33]
	v_mfma_f32_16x16x32_bf16 v[26:29], v[138:141], v[194:197], v[26:29]
	v_mfma_f32_16x16x32_bf16 v[26:29], v[142:145], v[198:201], v[26:29]
	v_mfma_f32_16x16x32_bf16 v[10:13], v[138:141], v[202:205], v[10:13]
	v_mfma_f32_16x16x32_bf16 v[10:13], v[142:145], v[206:209], v[10:13]
	v_mfma_f32_16x16x32_bf16 v[14:17], v[130:133], v[202:205], v[14:17]
	v_mfma_f32_16x16x32_bf16 v[14:17], v[134:137], v[206:209], v[14:17]
	v_mfma_f32_16x16x32_bf16 v[54:57], v[146:149], v[166:169], v[54:57]
	v_mfma_f32_16x16x32_bf16 v[54:57], v[150:153], v[170:173], v[54:57]
	v_mfma_f32_16x16x32_bf16 v[50:53], v[154:157], v[166:169], v[50:53]
	v_mfma_f32_16x16x32_bf16 v[50:53], v[158:161], v[170:173], v[50:53]
	v_mfma_f32_16x16x32_bf16 v[34:37], v[154:157], v[186:189], v[34:37]
	v_mfma_f32_16x16x32_bf16 v[34:37], v[158:161], v[190:193], v[34:37]
	v_mfma_f32_16x16x32_bf16 v[38:41], v[146:149], v[186:189], v[38:41]
	v_mfma_f32_16x16x32_bf16 v[38:41], v[150:153], v[190:193], v[38:41]
	v_mfma_f32_16x16x32_bf16 v[22:25], v[146:149], v[194:197], v[22:25]
	v_mfma_f32_16x16x32_bf16 v[22:25], v[150:153], v[198:201], v[22:25]
	v_mfma_f32_16x16x32_bf16 v[18:21], v[154:157], v[194:197], v[18:21]
	v_mfma_f32_16x16x32_bf16 v[18:21], v[158:161], v[198:201], v[18:21]
	v_mfma_f32_16x16x32_bf16 v[2:5], v[154:157], v[202:205], v[2:5]
	v_mfma_f32_16x16x32_bf16 v[2:5], v[158:161], v[206:209], v[2:5]
	s_setprio 2
	s_barrier
	v_mfma_f32_16x16x32_bf16 v[6:9], v[146:149], v[202:205], v[6:9]
	v_mfma_f32_16x16x32_bf16 v[6:9], v[150:153], v[206:209], v[6:9]
	s_setprio 0
	s_add_i32 s78, s78, 2
	s_add_u32 s74, s74, 0x100
	s_addc_u32 s75, s75, 0
	s_add_u32 s20, s20, 0x100
	s_addc_u32 s21, s21, 0
	s_add_u32 s76, s76, 0x100
	s_addc_u32 s77, s77, 0
	s_cmp_gt_u32 s78, 29
	s_cbranch_scc0 .LBB0_1053
	s_and_b64 vcc, exec, s[8:9]
	s_cbranch_vccz .LBB0_1056
	s_barrier

.LBB0_1223:
	s_ashr_i32 s11, s10, 31
	s_lshl_b64 s[12:13], s[10:11], 20
	s_add_u32 s12, s26, s12
	s_addc_u32 s13, s27, s13
	s_and_b64 s[14:15], s[2:3], exec
	s_cselect_b32 s11, s13, s21
	s_cselect_b32 s66, s12, s20
	s_ashr_i32 s9, s8, 31
	s_lshl_b64 s[14:15], s[8:9], 20
	s_add_u32 s14, s28, s14
	s_addc_u32 s15, s29, s15
	s_and_b64 s[22:23], s[2:3], exec
	s_cselect_b32 s9, s15, s19
	s_cselect_b32 s67, s14, s18
	s_add_u32 s73, s18, 0x100
	s_addc_u32 s74, s19, 0
	s_add_u32 s18, s20, 0x80080
	s_addc_u32 s19, s21, 0
	s_add_u32 s75, s20, 0x100
	s_addc_u32 s76, s21, 0
	s_mov_b32 s77, -2
	ds_read_b128 v[148:151], v143
	ds_read_b128 v[152:155], v143 offset:1024
	ds_read_b128 v[156:159], v143 offset:2048
	ds_read_b128 v[160:163], v143 offset:3072
	ds_read_b128 v[164:167], v144
	ds_read_b128 v[168:171], v144 offset:1024
	ds_read_b128 v[172:175], v144 offset:2048
	ds_read_b128 v[176:179], v144 offset:3072
	s_cmp_eq_u32 s77, 28
	s_cselect_b32 s21, s9, s74
	s_cselect_b32 s20, s67, s73
	s_cselect_b32 s23, s11, s76
	s_cselect_b32 s22, s66, s75
	ds_read_b128 v[180:183], v145
	ds_read_b128 v[184:187], v145 offset:1024
	ds_read_b128 v[188:191], v145 offset:2048
	ds_read_b128 v[192:195], v145 offset:3072
	ds_read_b128 v[196:199], v145 offset:4096
	ds_read_b128 v[200:203], v145 offset:5120
	ds_read_b128 v[204:207], v145 offset:6144
	ds_read_b128 v[208:211], v145 offset:7168
	s_add_u32 s78, s18, 0xfff80000
	s_addc_u32 s79, s19, -1
	s_mov_b32 s80, m0
	s_mov_b32 m0, s56
	s_nop 0
	global_load_lds_dwordx4 v138, s[78:79]
	s_mov_b32 m0, s80
	s_nop 0
	s_mov_b32 s80, m0
	s_mov_b32 m0, s59
	s_nop 0
	global_load_lds_dwordx4 v140, s[78:79]
	s_mov_b32 m0, s80
	s_mov_b32 s78, m0
	s_mov_b32 m0, s57
	s_nop 0
	global_load_lds_dwordx4 v138, s[18:19]
	s_mov_b32 m0, s78
	s_nop 0
	s_mov_b32 s78, m0
	s_mov_b32 m0, s64
	s_nop 0
	global_load_lds_dwordx4 v140, s[18:19]
	s_mov_b32 m0, s78
	s_waitcnt vmcnt(8)
	s_waitcnt lgkmcnt(0)
	s_barrier
	s_setprio 1
	.p2align 3
	v_mfma_f32_16x16x32_bf16 v[126:129], v[148:151], v[180:183], 0
	v_mfma_f32_16x16x32_bf16 v[126:129], v[152:155], v[184:187], v[126:129]
	v_mfma_f32_16x16x32_bf16 v[122:125], v[156:159], v[180:183], 0
	v_mfma_f32_16x16x32_bf16 v[122:125], v[160:163], v[184:187], v[122:125]
	v_mfma_f32_16x16x32_bf16 v[106:109], v[156:159], v[188:191], 0
	v_mfma_f32_16x16x32_bf16 v[106:109], v[160:163], v[192:195], v[106:109]
	v_mfma_f32_16x16x32_bf16 v[110:113], v[148:151], v[188:191], 0
	v_mfma_f32_16x16x32_bf16 v[110:113], v[152:155], v[192:195], v[110:113]
	v_mfma_f32_16x16x32_bf16 v[94:97], v[148:151], v[196:199], 0
	v_mfma_f32_16x16x32_bf16 v[94:97], v[152:155], v[200:203], v[94:97]
	v_mfma_f32_16x16x32_bf16 v[90:93], v[156:159], v[196:199], 0
	v_mfma_f32_16x16x32_bf16 v[90:93], v[160:163], v[200:203], v[90:93]
	v_mfma_f32_16x16x32_bf16 v[74:77], v[156:159], v[204:207], 0
	v_mfma_f32_16x16x32_bf16 v[74:77], v[160:163], v[208:211], v[74:77]
	v_mfma_f32_16x16x32_bf16 v[78:81], v[148:151], v[204:207], 0
	v_mfma_f32_16x16x32_bf16 v[78:81], v[152:155], v[208:211], v[78:81]
	v_mfma_f32_16x16x32_bf16 v[118:121], v[164:167], v[180:183], 0
	v_mfma_f32_16x16x32_bf16 v[118:121], v[168:171], v[184:187], v[118:121]
	v_mfma_f32_16x16x32_bf16 v[114:117], v[172:175], v[180:183], 0
	v_mfma_f32_16x16x32_bf16 v[114:117], v[176:179], v[184:187], v[114:117]
	v_mfma_f32_16x16x32_bf16 v[98:101], v[172:175], v[188:191], 0
	v_mfma_f32_16x16x32_bf16 v[98:101], v[176:179], v[192:195], v[98:101]
	v_mfma_f32_16x16x32_bf16 v[102:105], v[164:167], v[188:191], 0
	v_mfma_f32_16x16x32_bf16 v[102:105], v[168:171], v[192:195], v[102:105]
	v_mfma_f32_16x16x32_bf16 v[86:89], v[164:167], v[196:199], 0
	v_mfma_f32_16x16x32_bf16 v[86:89], v[168:171], v[200:203], v[86:89]
	v_mfma_f32_16x16x32_bf16 v[82:85], v[172:175], v[196:199], 0
	v_mfma_f32_16x16x32_bf16 v[82:85], v[176:179], v[200:203], v[82:85]
	v_mfma_f32_16x16x32_bf16 v[66:69], v[172:175], v[204:207], 0
	v_mfma_f32_16x16x32_bf16 v[66:69], v[176:179], v[208:211], v[66:69]
	s_setprio 2
	s_barrier
	v_mfma_f32_16x16x32_bf16 v[70:73], v[164:167], v[204:207], 0
	v_mfma_f32_16x16x32_bf16 v[70:73], v[168:171], v[208:211], v[70:73]
	s_setprio 0
	ds_read_b128 v[180:183], v145 offset:16384
	ds_read_b128 v[184:187], v145 offset:17408
	ds_read_b128 v[188:191], v145 offset:18432
	ds_read_b128 v[192:195], v145 offset:19456
	ds_read_b128 v[196:199], v145 offset:20480
	ds_read_b128 v[200:203], v145 offset:21504
	ds_read_b128 v[204:207], v145 offset:22528
	ds_read_b128 v[208:211], v145 offset:23552
	s_mov_b32 s78, m0
	s_mov_b32 m0, s35
	s_nop 0
	global_load_lds_dwordx4 v139, s[20:21]
	s_mov_b32 m0, s78
	s_nop 0
	s_mov_b32 s78, m0
	s_mov_b32 m0, s36
	s_nop 0
	global_load_lds_dwordx4 v141, s[20:21]
	s_mov_b32 m0, s78
	s_add_u32 s78, s20, 0x80000
	s_addc_u32 s79, s21, 0
	s_mov_b32 s80, m0
	s_mov_b32 m0, s37
	s_nop 0
	global_load_lds_dwordx4 v139, s[78:79]
	s_mov_b32 m0, s80
	s_nop 0
	s_mov_b32 s80, m0
	s_mov_b32 m0, s40
	s_nop 0
	global_load_lds_dwordx4 v141, s[78:79]
	s_mov_b32 m0, s80
	s_waitcnt vmcnt(4)
	s_waitcnt lgkmcnt(0)
	s_barrier
	s_setprio 1
	.p2align 3
	v_mfma_f32_16x16x32_bf16 v[62:65], v[148:151], v[180:183], 0
	v_mfma_f32_16x16x32_bf16 v[62:65], v[152:155], v[184:187], v[62:65]
	v_mfma_f32_16x16x32_bf16 v[58:61], v[156:159], v[180:183], 0
	v_mfma_f32_16x16x32_bf16 v[58:61], v[160:163], v[184:187], v[58:61]
	v_mfma_f32_16x16x32_bf16 v[42:45], v[156:159], v[188:191], 0
	v_mfma_f32_16x16x32_bf16 v[42:45], v[160:163], v[192:195], v[42:45]
	v_mfma_f32_16x16x32_bf16 v[46:49], v[148:151], v[188:191], 0
	v_mfma_f32_16x16x32_bf16 v[46:49], v[152:155], v[192:195], v[46:49]
	v_mfma_f32_16x16x32_bf16 v[30:33], v[148:151], v[196:199], 0
	v_mfma_f32_16x16x32_bf16 v[30:33], v[152:155], v[200:203], v[30:33]
	v_mfma_f32_16x16x32_bf16 v[26:29], v[156:159], v[196:199], 0
	v_mfma_f32_16x16x32_bf16 v[26:29], v[160:163], v[200:203], v[26:29]
	v_mfma_f32_16x16x32_bf16 v[10:13], v[156:159], v[204:207], 0
	v_mfma_f32_16x16x32_bf16 v[10:13], v[160:163], v[208:211], v[10:13]
	v_mfma_f32_16x16x32_bf16 v[14:17], v[148:151], v[204:207], 0
	v_mfma_f32_16x16x32_bf16 v[14:17], v[152:155], v[208:211], v[14:17]
	v_mfma_f32_16x16x32_bf16 v[54:57], v[164:167], v[180:183], 0
	v_mfma_f32_16x16x32_bf16 v[54:57], v[168:171], v[184:187], v[54:57]
	v_mfma_f32_16x16x32_bf16 v[50:53], v[172:175], v[180:183], 0
	v_mfma_f32_16x16x32_bf16 v[50:53], v[176:179], v[184:187], v[50:53]
	v_mfma_f32_16x16x32_bf16 v[34:37], v[172:175], v[188:191], 0
	v_mfma_f32_16x16x32_bf16 v[34:37], v[176:179], v[192:195], v[34:37]
	v_mfma_f32_16x16x32_bf16 v[38:41], v[164:167], v[188:191], 0
	v_mfma_f32_16x16x32_bf16 v[38:41], v[168:171], v[192:195], v[38:41]
	v_mfma_f32_16x16x32_bf16 v[22:25], v[164:167], v[196:199], 0
	v_mfma_f32_16x16x32_bf16 v[22:25], v[168:171], v[200:203], v[22:25]
	v_mfma_f32_16x16x32_bf16 v[18:21], v[172:175], v[196:199], 0
	v_mfma_f32_16x16x32_bf16 v[18:21], v[176:179], v[200:203], v[18:21]
	v_mfma_f32_16x16x32_bf16 v[2:5], v[172:175], v[204:207], 0
	v_mfma_f32_16x16x32_bf16 v[2:5], v[176:179], v[208:211], v[2:5]
	s_setprio 2
	s_barrier
	v_mfma_f32_16x16x32_bf16 v[6:9], v[164:167], v[204:207], 0
	v_mfma_f32_16x16x32_bf16 v[6:9], v[168:171], v[208:211], v[6:9]
	s_setprio 0
	ds_read_b128 v[148:151], v146
	ds_read_b128 v[152:155], v146 offset:1024
	ds_read_b128 v[156:159], v146 offset:2048
	ds_read_b128 v[160:163], v146 offset:3072
	ds_read_b128 v[164:167], v147
	ds_read_b128 v[168:171], v147 offset:1024
	ds_read_b128 v[172:175], v147 offset:2048
	ds_read_b128 v[176:179], v147 offset:3072
	ds_read_b128 v[180:183], v145 offset:32768
	ds_read_b128 v[184:187], v145 offset:33792
	ds_read_b128 v[188:191], v145 offset:34816
	ds_read_b128 v[192:195], v145 offset:35840
	ds_read_b128 v[196:199], v145 offset:36864
	ds_read_b128 v[200:203], v145 offset:37888
	ds_read_b128 v[204:207], v145 offset:38912
	ds_read_b128 v[208:211], v145 offset:39936
	s_mov_b32 s78, m0
	s_mov_b32 m0, s31
	s_nop 0
	global_load_lds_dwordx4 v138, s[22:23]
	s_mov_b32 m0, s78
	s_nop 0
	s_mov_b32 s78, m0
	s_mov_b32 m0, s41
	s_nop 0
	global_load_lds_dwordx4 v140, s[22:23]
	s_mov_b32 m0, s78
	s_add_u32 s22, s22, 0x80000
	s_addc_u32 s23, s23, 0
	s_mov_b32 s78, m0
	s_mov_b32 m0, s42
	s_nop 0
	global_load_lds_dwordx4 v138, s[22:23]
	s_mov_b32 m0, s78
	s_nop 0
	s_mov_b32 s78, m0
	s_mov_b32 m0, s43
	s_nop 0
	global_load_lds_dwordx4 v140, s[22:23]
	s_mov_b32 m0, s78
	s_waitcnt vmcnt(8)
	s_waitcnt lgkmcnt(0)
	s_barrier
	s_setprio 1
	.p2align 3
	v_mfma_f32_16x16x32_bf16 v[126:129], v[148:151], v[180:183], v[126:129]
	v_mfma_f32_16x16x32_bf16 v[126:129], v[152:155], v[184:187], v[126:129]
	v_mfma_f32_16x16x32_bf16 v[122:125], v[156:159], v[180:183], v[122:125]
	v_mfma_f32_16x16x32_bf16 v[122:125], v[160:163], v[184:187], v[122:125]
	v_mfma_f32_16x16x32_bf16 v[106:109], v[156:159], v[188:191], v[106:109]
	v_mfma_f32_16x16x32_bf16 v[106:109], v[160:163], v[192:195], v[106:109]
	v_mfma_f32_16x16x32_bf16 v[110:113], v[148:151], v[188:191], v[110:113]
	v_mfma_f32_16x16x32_bf16 v[110:113], v[152:155], v[192:195], v[110:113]
	v_mfma_f32_16x16x32_bf16 v[94:97], v[148:151], v[196:199], v[94:97]
	v_mfma_f32_16x16x32_bf16 v[94:97], v[152:155], v[200:203], v[94:97]
	v_mfma_f32_16x16x32_bf16 v[90:93], v[156:159], v[196:199], v[90:93]
	v_mfma_f32_16x16x32_bf16 v[90:93], v[160:163], v[200:203], v[90:93]
	v_mfma_f32_16x16x32_bf16 v[74:77], v[156:159], v[204:207], v[74:77]
	v_mfma_f32_16x16x32_bf16 v[74:77], v[160:163], v[208:211], v[74:77]
	v_mfma_f32_16x16x32_bf16 v[78:81], v[148:151], v[204:207], v[78:81]
	v_mfma_f32_16x16x32_bf16 v[78:81], v[152:155], v[208:211], v[78:81]
	v_mfma_f32_16x16x32_bf16 v[118:121], v[164:167], v[180:183], v[118:121]
	v_mfma_f32_16x16x32_bf16 v[118:121], v[168:171], v[184:187], v[118:121]
	v_mfma_f32_16x16x32_bf16 v[114:117], v[172:175], v[180:183], v[114:117]
	v_mfma_f32_16x16x32_bf16 v[114:117], v[176:179], v[184:187], v[114:117]
	v_mfma_f32_16x16x32_bf16 v[98:101], v[172:175], v[188:191], v[98:101]
	v_mfma_f32_16x16x32_bf16 v[98:101], v[176:179], v[192:195], v[98:101]
	v_mfma_f32_16x16x32_bf16 v[102:105], v[164:167], v[188:191], v[102:105]
	v_mfma_f32_16x16x32_bf16 v[102:105], v[168:171], v[192:195], v[102:105]
	v_mfma_f32_16x16x32_bf16 v[86:89], v[164:167], v[196:199], v[86:89]
	v_mfma_f32_16x16x32_bf16 v[86:89], v[168:171], v[200:203], v[86:89]
	v_mfma_f32_16x16x32_bf16 v[82:85], v[172:175], v[196:199], v[82:85]
	v_mfma_f32_16x16x32_bf16 v[82:85], v[176:179], v[200:203], v[82:85]
	v_mfma_f32_16x16x32_bf16 v[66:69], v[172:175], v[204:207], v[66:69]
	v_mfma_f32_16x16x32_bf16 v[66:69], v[176:179], v[208:211], v[66:69]
	s_setprio 2
	s_barrier
	v_mfma_f32_16x16x32_bf16 v[70:73], v[164:167], v[204:207], v[70:73]
	v_mfma_f32_16x16x32_bf16 v[70:73], v[168:171], v[208:211], v[70:73]
	s_setprio 0
	ds_read_b128 v[180:183], v145 offset:49152
	ds_read_b128 v[184:187], v145 offset:50176
	ds_read_b128 v[188:191], v145 offset:51200
	ds_read_b128 v[192:195], v145 offset:52224
	ds_read_b128 v[196:199], v145 offset:53248
	ds_read_b128 v[200:203], v145 offset:54272
	ds_read_b128 v[204:207], v145 offset:55296
	ds_read_b128 v[208:211], v145 offset:56320
	s_add_u32 s22, s20, 0x80
	s_addc_u32 s23, s21, 0
	s_mov_b32 s78, m0
	s_mov_b32 m0, s46
	s_nop 0
	global_load_lds_dwordx4 v139, s[22:23]
	s_mov_b32 m0, s78
	s_add_u32 s20, s20, 0x80080
	s_mov_b32 s78, m0
	s_mov_b32 m0, s47
	s_nop 0
	global_load_lds_dwordx4 v141, s[22:23]
	s_mov_b32 m0, s78
	s_addc_u32 s21, s21, 0
	s_mov_b32 s22, m0
	s_mov_b32 m0, s48
	s_nop 0
	global_load_lds_dwordx4 v139, s[20:21]
	s_mov_b32 m0, s22
	s_nop 0
	s_mov_b32 s22, m0
	s_mov_b32 m0, s49
	s_nop 0
	global_load_lds_dwordx4 v141, s[20:21]
	s_mov_b32 m0, s22
	s_waitcnt vmcnt(4)
	s_waitcnt lgkmcnt(0)
	s_barrier
	s_setprio 1
	.p2align 3
	v_mfma_f32_16x16x32_bf16 v[62:65], v[148:151], v[180:183], v[62:65]
	v_mfma_f32_16x16x32_bf16 v[62:65], v[152:155], v[184:187], v[62:65]
	v_mfma_f32_16x16x32_bf16 v[58:61], v[156:159], v[180:183], v[58:61]
	v_mfma_f32_16x16x32_bf16 v[58:61], v[160:163], v[184:187], v[58:61]
	v_mfma_f32_16x16x32_bf16 v[42:45], v[156:159], v[188:191], v[42:45]
	v_mfma_f32_16x16x32_bf16 v[42:45], v[160:163], v[192:195], v[42:45]
	v_mfma_f32_16x16x32_bf16 v[46:49], v[148:151], v[188:191], v[46:49]
	v_mfma_f32_16x16x32_bf16 v[46:49], v[152:155], v[192:195], v[46:49]
	v_mfma_f32_16x16x32_bf16 v[30:33], v[148:151], v[196:199], v[30:33]
	v_mfma_f32_16x16x32_bf16 v[30:33], v[152:155], v[200:203], v[30:33]
	v_mfma_f32_16x16x32_bf16 v[26:29], v[156:159], v[196:199], v[26:29]
	v_mfma_f32_16x16x32_bf16 v[26:29], v[160:163], v[200:203], v[26:29]
	v_mfma_f32_16x16x32_bf16 v[10:13], v[156:159], v[204:207], v[10:13]
	v_mfma_f32_16x16x32_bf16 v[10:13], v[160:163], v[208:211], v[10:13]
	v_mfma_f32_16x16x32_bf16 v[14:17], v[148:151], v[204:207], v[14:17]
	v_mfma_f32_16x16x32_bf16 v[14:17], v[152:155], v[208:211], v[14:17]
	v_mfma_f32_16x16x32_bf16 v[54:57], v[164:167], v[180:183], v[54:57]
	v_mfma_f32_16x16x32_bf16 v[54:57], v[168:171], v[184:187], v[54:57]
	v_mfma_f32_16x16x32_bf16 v[50:53], v[172:175], v[180:183], v[50:53]
	v_mfma_f32_16x16x32_bf16 v[50:53], v[176:179], v[184:187], v[50:53]
	v_mfma_f32_16x16x32_bf16 v[34:37], v[172:175], v[188:191], v[34:37]
	v_mfma_f32_16x16x32_bf16 v[34:37], v[176:179], v[192:195], v[34:37]
	v_mfma_f32_16x16x32_bf16 v[38:41], v[164:167], v[188:191], v[38:41]
	v_mfma_f32_16x16x32_bf16 v[38:41], v[168:171], v[192:195], v[38:41]
	v_mfma_f32_16x16x32_bf16 v[22:25], v[164:167], v[196:199], v[22:25]
	v_mfma_f32_16x16x32_bf16 v[22:25], v[168:171], v[200:203], v[22:25]
	v_mfma_f32_16x16x32_bf16 v[18:21], v[172:175], v[196:199], v[18:21]
	v_mfma_f32_16x16x32_bf16 v[18:21], v[176:179], v[200:203], v[18:21]
	v_mfma_f32_16x16x32_bf16 v[2:5], v[172:175], v[204:207], v[2:5]
	v_mfma_f32_16x16x32_bf16 v[2:5], v[176:179], v[208:211], v[2:5]
	s_setprio 2
	s_barrier
	v_mfma_f32_16x16x32_bf16 v[6:9], v[164:167], v[204:207], v[6:9]
	v_mfma_f32_16x16x32_bf16 v[6:9], v[168:171], v[208:211], v[6:9]
	s_setprio 0
	s_add_i32 s77, s77, 2
	s_add_u32 s73, s73, 0x100
	s_addc_u32 s74, s74, 0
	s_add_u32 s18, s18, 0x100
	s_addc_u32 s19, s19, 0
	s_add_u32 s75, s75, 0x100
	s_addc_u32 s76, s76, 0
	s_cmp_gt_u32 s77, 29
	.p2align 6
.LBB0_1224:
	ds_read_b128 v[148:151], v143
	ds_read_b128 v[152:155], v143 offset:1024
	ds_read_b128 v[156:159], v143 offset:2048
	ds_read_b128 v[160:163], v143 offset:3072
	ds_read_b128 v[164:167], v144
	ds_read_b128 v[168:171], v144 offset:1024
	ds_read_b128 v[172:175], v144 offset:2048
	ds_read_b128 v[176:179], v144 offset:3072
	s_cmp_eq_u32 s77, 28
	s_cselect_b32 s21, s9, s74
	s_cselect_b32 s20, s67, s73
	s_cselect_b32 s23, s11, s76
	s_cselect_b32 s22, s66, s75
	ds_read_b128 v[180:183], v145
	ds_read_b128 v[184:187], v145 offset:1024
	ds_read_b128 v[188:191], v145 offset:2048
	ds_read_b128 v[192:195], v145 offset:3072
	ds_read_b128 v[196:199], v145 offset:4096
	ds_read_b128 v[200:203], v145 offset:5120
	ds_read_b128 v[204:207], v145 offset:6144
	ds_read_b128 v[208:211], v145 offset:7168
	s_add_u32 s78, s18, 0xfff80000
	s_addc_u32 s79, s19, -1
	s_mov_b32 s80, m0
	s_mov_b32 m0, s56
	s_nop 0
	global_load_lds_dwordx4 v138, s[78:79]
	s_mov_b32 m0, s80
	s_nop 0
	s_mov_b32 s80, m0
	s_mov_b32 m0, s59
	s_nop 0
	global_load_lds_dwordx4 v140, s[78:79]
	s_mov_b32 m0, s80
	s_mov_b32 s78, m0
	s_mov_b32 m0, s57
	s_nop 0
	global_load_lds_dwordx4 v138, s[18:19]
	s_mov_b32 m0, s78
	s_nop 0
	s_mov_b32 s78, m0
	s_mov_b32 m0, s64
	s_nop 0
	global_load_lds_dwordx4 v140, s[18:19]
	s_mov_b32 m0, s78
	s_waitcnt vmcnt(8)
	s_waitcnt lgkmcnt(0)
	s_barrier
	s_setprio 1
	.p2align 3
	v_mfma_f32_16x16x32_bf16 v[126:129], v[148:151], v[180:183], v[126:129]
	v_mfma_f32_16x16x32_bf16 v[126:129], v[152:155], v[184:187], v[126:129]
	v_mfma_f32_16x16x32_bf16 v[122:125], v[156:159], v[180:183], v[122:125]
	v_mfma_f32_16x16x32_bf16 v[122:125], v[160:163], v[184:187], v[122:125]
	v_mfma_f32_16x16x32_bf16 v[106:109], v[156:159], v[188:191], v[106:109]
	v_mfma_f32_16x16x32_bf16 v[106:109], v[160:163], v[192:195], v[106:109]
	v_mfma_f32_16x16x32_bf16 v[110:113], v[148:151], v[188:191], v[110:113]
	v_mfma_f32_16x16x32_bf16 v[110:113], v[152:155], v[192:195], v[110:113]
	v_mfma_f32_16x16x32_bf16 v[94:97], v[148:151], v[196:199], v[94:97]
	v_mfma_f32_16x16x32_bf16 v[94:97], v[152:155], v[200:203], v[94:97]
	v_mfma_f32_16x16x32_bf16 v[90:93], v[156:159], v[196:199], v[90:93]
	v_mfma_f32_16x16x32_bf16 v[90:93], v[160:163], v[200:203], v[90:93]
	v_mfma_f32_16x16x32_bf16 v[74:77], v[156:159], v[204:207], v[74:77]
	v_mfma_f32_16x16x32_bf16 v[74:77], v[160:163], v[208:211], v[74:77]
	v_mfma_f32_16x16x32_bf16 v[78:81], v[148:151], v[204:207], v[78:81]
	v_mfma_f32_16x16x32_bf16 v[78:81], v[152:155], v[208:211], v[78:81]
	v_mfma_f32_16x16x32_bf16 v[118:121], v[164:167], v[180:183], v[118:121]
	v_mfma_f32_16x16x32_bf16 v[118:121], v[168:171], v[184:187], v[118:121]
	v_mfma_f32_16x16x32_bf16 v[114:117], v[172:175], v[180:183], v[114:117]
	v_mfma_f32_16x16x32_bf16 v[114:117], v[176:179], v[184:187], v[114:117]
	v_mfma_f32_16x16x32_bf16 v[98:101], v[172:175], v[188:191], v[98:101]
	v_mfma_f32_16x16x32_bf16 v[98:101], v[176:179], v[192:195], v[98:101]
	v_mfma_f32_16x16x32_bf16 v[102:105], v[164:167], v[188:191], v[102:105]
	v_mfma_f32_16x16x32_bf16 v[102:105], v[168:171], v[192:195], v[102:105]
	v_mfma_f32_16x16x32_bf16 v[86:89], v[164:167], v[196:199], v[86:89]
	v_mfma_f32_16x16x32_bf16 v[86:89], v[168:171], v[200:203], v[86:89]
	v_mfma_f32_16x16x32_bf16 v[82:85], v[172:175], v[196:199], v[82:85]
	v_mfma_f32_16x16x32_bf16 v[82:85], v[176:179], v[200:203], v[82:85]
	v_mfma_f32_16x16x32_bf16 v[66:69], v[172:175], v[204:207], v[66:69]
	v_mfma_f32_16x16x32_bf16 v[66:69], v[176:179], v[208:211], v[66:69]
	s_setprio 2
	s_barrier
	v_mfma_f32_16x16x32_bf16 v[70:73], v[164:167], v[204:207], v[70:73]
	v_mfma_f32_16x16x32_bf16 v[70:73], v[168:171], v[208:211], v[70:73]
	s_setprio 0
	ds_read_b128 v[180:183], v145 offset:16384
	ds_read_b128 v[184:187], v145 offset:17408
	ds_read_b128 v[188:191], v145 offset:18432
	ds_read_b128 v[192:195], v145 offset:19456
	ds_read_b128 v[196:199], v145 offset:20480
	ds_read_b128 v[200:203], v145 offset:21504
	ds_read_b128 v[204:207], v145 offset:22528
	ds_read_b128 v[208:211], v145 offset:23552
	s_mov_b32 s78, m0
	s_mov_b32 m0, s35
	s_nop 0
	global_load_lds_dwordx4 v139, s[20:21]
	s_mov_b32 m0, s78
	s_nop 0
	s_mov_b32 s78, m0
	s_mov_b32 m0, s36
	s_nop 0
	global_load_lds_dwordx4 v141, s[20:21]
	s_mov_b32 m0, s78
	s_add_u32 s78, s20, 0x80000
	s_addc_u32 s79, s21, 0
	s_mov_b32 s80, m0
	s_mov_b32 m0, s37
	s_nop 0
	global_load_lds_dwordx4 v139, s[78:79]
	s_mov_b32 m0, s80
	s_nop 0
	s_mov_b32 s80, m0
	s_mov_b32 m0, s40
	s_nop 0
	global_load_lds_dwordx4 v141, s[78:79]
	s_mov_b32 m0, s80
	s_waitcnt vmcnt(4)
	s_waitcnt lgkmcnt(0)
	s_barrier
	s_setprio 1
	.p2align 3
	v_mfma_f32_16x16x32_bf16 v[62:65], v[148:151], v[180:183], v[62:65]
	v_mfma_f32_16x16x32_bf16 v[62:65], v[152:155], v[184:187], v[62:65]
	v_mfma_f32_16x16x32_bf16 v[58:61], v[156:159], v[180:183], v[58:61]
	v_mfma_f32_16x16x32_bf16 v[58:61], v[160:163], v[184:187], v[58:61]
	v_mfma_f32_16x16x32_bf16 v[42:45], v[156:159], v[188:191], v[42:45]
	v_mfma_f32_16x16x32_bf16 v[42:45], v[160:163], v[192:195], v[42:45]
	v_mfma_f32_16x16x32_bf16 v[46:49], v[148:151], v[188:191], v[46:49]
	v_mfma_f32_16x16x32_bf16 v[46:49], v[152:155], v[192:195], v[46:49]
	v_mfma_f32_16x16x32_bf16 v[30:33], v[148:151], v[196:199], v[30:33]
	v_mfma_f32_16x16x32_bf16 v[30:33], v[152:155], v[200:203], v[30:33]
	v_mfma_f32_16x16x32_bf16 v[26:29], v[156:159], v[196:199], v[26:29]
	v_mfma_f32_16x16x32_bf16 v[26:29], v[160:163], v[200:203], v[26:29]
	v_mfma_f32_16x16x32_bf16 v[10:13], v[156:159], v[204:207], v[10:13]
	v_mfma_f32_16x16x32_bf16 v[10:13], v[160:163], v[208:211], v[10:13]
	v_mfma_f32_16x16x32_bf16 v[14:17], v[148:151], v[204:207], v[14:17]
	v_mfma_f32_16x16x32_bf16 v[14:17], v[152:155], v[208:211], v[14:17]
	v_mfma_f32_16x16x32_bf16 v[54:57], v[164:167], v[180:183], v[54:57]
	v_mfma_f32_16x16x32_bf16 v[54:57], v[168:171], v[184:187], v[54:57]
	v_mfma_f32_16x16x32_bf16 v[50:53], v[172:175], v[180:183], v[50:53]
	v_mfma_f32_16x16x32_bf16 v[50:53], v[176:179], v[184:187], v[50:53]
	v_mfma_f32_16x16x32_bf16 v[34:37], v[172:175], v[188:191], v[34:37]
	v_mfma_f32_16x16x32_bf16 v[34:37], v[176:179], v[192:195], v[34:37]
	v_mfma_f32_16x16x32_bf16 v[38:41], v[164:167], v[188:191], v[38:41]
	v_mfma_f32_16x16x32_bf16 v[38:41], v[168:171], v[192:195], v[38:41]
	v_mfma_f32_16x16x32_bf16 v[22:25], v[164:167], v[196:199], v[22:25]
	v_mfma_f32_16x16x32_bf16 v[22:25], v[168:171], v[200:203], v[22:25]
	v_mfma_f32_16x16x32_bf16 v[18:21], v[172:175], v[196:199], v[18:21]
	v_mfma_f32_16x16x32_bf16 v[18:21], v[176:179], v[200:203], v[18:21]
	v_mfma_f32_16x16x32_bf16 v[2:5], v[172:175], v[204:207], v[2:5]
	v_mfma_f32_16x16x32_bf16 v[2:5], v[176:179], v[208:211], v[2:5]
	s_setprio 2
	s_barrier
	v_mfma_f32_16x16x32_bf16 v[6:9], v[164:167], v[204:207], v[6:9]
	v_mfma_f32_16x16x32_bf16 v[6:9], v[168:171], v[208:211], v[6:9]
	s_setprio 0
	ds_read_b128 v[148:151], v146
	ds_read_b128 v[152:155], v146 offset:1024
	ds_read_b128 v[156:159], v146 offset:2048
	ds_read_b128 v[160:163], v146 offset:3072
	ds_read_b128 v[164:167], v147
	ds_read_b128 v[168:171], v147 offset:1024
	ds_read_b128 v[172:175], v147 offset:2048
	ds_read_b128 v[176:179], v147 offset:3072
	ds_read_b128 v[180:183], v145 offset:32768
	ds_read_b128 v[184:187], v145 offset:33792
	ds_read_b128 v[188:191], v145 offset:34816
	ds_read_b128 v[192:195], v145 offset:35840
	ds_read_b128 v[196:199], v145 offset:36864
	ds_read_b128 v[200:203], v145 offset:37888
	ds_read_b128 v[204:207], v145 offset:38912
	ds_read_b128 v[208:211], v145 offset:39936
	s_mov_b32 s78, m0
	s_mov_b32 m0, s31
	s_nop 0
	global_load_lds_dwordx4 v138, s[22:23]
	s_mov_b32 m0, s78
	s_nop 0
	s_mov_b32 s78, m0
	s_mov_b32 m0, s41
	s_nop 0
	global_load_lds_dwordx4 v140, s[22:23]
	s_mov_b32 m0, s78
	s_add_u32 s22, s22, 0x80000
	s_addc_u32 s23, s23, 0
	s_mov_b32 s78, m0
	s_mov_b32 m0, s42
	s_nop 0
	global_load_lds_dwordx4 v138, s[22:23]
	s_mov_b32 m0, s78
	s_nop 0
	s_mov_b32 s78, m0
	s_mov_b32 m0, s43
	s_nop 0
	global_load_lds_dwordx4 v140, s[22:23]
	s_mov_b32 m0, s78
	s_waitcnt vmcnt(8)
	s_waitcnt lgkmcnt(0)
	s_barrier
	s_setprio 1
	.p2align 3
	v_mfma_f32_16x16x32_bf16 v[126:129], v[148:151], v[180:183], v[126:129]
	v_mfma_f32_16x16x32_bf16 v[126:129], v[152:155], v[184:187], v[126:129]
	v_mfma_f32_16x16x32_bf16 v[122:125], v[156:159], v[180:183], v[122:125]
	v_mfma_f32_16x16x32_bf16 v[122:125], v[160:163], v[184:187], v[122:125]
	v_mfma_f32_16x16x32_bf16 v[106:109], v[156:159], v[188:191], v[106:109]
	v_mfma_f32_16x16x32_bf16 v[106:109], v[160:163], v[192:195], v[106:109]
	v_mfma_f32_16x16x32_bf16 v[110:113], v[148:151], v[188:191], v[110:113]
	v_mfma_f32_16x16x32_bf16 v[110:113], v[152:155], v[192:195], v[110:113]
	v_mfma_f32_16x16x32_bf16 v[94:97], v[148:151], v[196:199], v[94:97]
	v_mfma_f32_16x16x32_bf16 v[94:97], v[152:155], v[200:203], v[94:97]
	v_mfma_f32_16x16x32_bf16 v[90:93], v[156:159], v[196:199], v[90:93]
	v_mfma_f32_16x16x32_bf16 v[90:93], v[160:163], v[200:203], v[90:93]
	v_mfma_f32_16x16x32_bf16 v[74:77], v[156:159], v[204:207], v[74:77]
	v_mfma_f32_16x16x32_bf16 v[74:77], v[160:163], v[208:211], v[74:77]
	v_mfma_f32_16x16x32_bf16 v[78:81], v[148:151], v[204:207], v[78:81]
	v_mfma_f32_16x16x32_bf16 v[78:81], v[152:155], v[208:211], v[78:81]
	v_mfma_f32_16x16x32_bf16 v[118:121], v[164:167], v[180:183], v[118:121]
	v_mfma_f32_16x16x32_bf16 v[118:121], v[168:171], v[184:187], v[118:121]
	v_mfma_f32_16x16x32_bf16 v[114:117], v[172:175], v[180:183], v[114:117]
	v_mfma_f32_16x16x32_bf16 v[114:117], v[176:179], v[184:187], v[114:117]
	v_mfma_f32_16x16x32_bf16 v[98:101], v[172:175], v[188:191], v[98:101]
	v_mfma_f32_16x16x32_bf16 v[98:101], v[176:179], v[192:195], v[98:101]
	v_mfma_f32_16x16x32_bf16 v[102:105], v[164:167], v[188:191], v[102:105]
	v_mfma_f32_16x16x32_bf16 v[102:105], v[168:171], v[192:195], v[102:105]
	v_mfma_f32_16x16x32_bf16 v[86:89], v[164:167], v[196:199], v[86:89]
	v_mfma_f32_16x16x32_bf16 v[86:89], v[168:171], v[200:203], v[86:89]
	v_mfma_f32_16x16x32_bf16 v[82:85], v[172:175], v[196:199], v[82:85]
	v_mfma_f32_16x16x32_bf16 v[82:85], v[176:179], v[200:203], v[82:85]
	v_mfma_f32_16x16x32_bf16 v[66:69], v[172:175], v[204:207], v[66:69]
	v_mfma_f32_16x16x32_bf16 v[66:69], v[176:179], v[208:211], v[66:69]
	s_setprio 2
	s_barrier
	v_mfma_f32_16x16x32_bf16 v[70:73], v[164:167], v[204:207], v[70:73]
	v_mfma_f32_16x16x32_bf16 v[70:73], v[168:171], v[208:211], v[70:73]
	s_setprio 0
	ds_read_b128 v[180:183], v145 offset:49152
	ds_read_b128 v[184:187], v145 offset:50176
	ds_read_b128 v[188:191], v145 offset:51200
	ds_read_b128 v[192:195], v145 offset:52224
	ds_read_b128 v[196:199], v145 offset:53248
	ds_read_b128 v[200:203], v145 offset:54272
	ds_read_b128 v[204:207], v145 offset:55296
	ds_read_b128 v[208:211], v145 offset:56320
	s_add_u32 s22, s20, 0x80
	s_addc_u32 s23, s21, 0
	s_mov_b32 s78, m0
	s_mov_b32 m0, s46
	s_nop 0
	global_load_lds_dwordx4 v139, s[22:23]
	s_mov_b32 m0, s78
	s_add_u32 s20, s20, 0x80080
	s_mov_b32 s78, m0
	s_mov_b32 m0, s47
	s_nop 0
	global_load_lds_dwordx4 v141, s[22:23]
	s_mov_b32 m0, s78
	s_addc_u32 s21, s21, 0
	s_mov_b32 s22, m0
	s_mov_b32 m0, s48
	s_nop 0
	global_load_lds_dwordx4 v139, s[20:21]
	s_mov_b32 m0, s22
	s_nop 0
	s_mov_b32 s22, m0
	s_mov_b32 m0, s49
	s_nop 0
	global_load_lds_dwordx4 v141, s[20:21]
	s_mov_b32 m0, s22
	s_waitcnt vmcnt(4)
	s_waitcnt lgkmcnt(0)
	s_barrier
	s_setprio 1
	.p2align 3
	v_mfma_f32_16x16x32_bf16 v[62:65], v[148:151], v[180:183], v[62:65]
	v_mfma_f32_16x16x32_bf16 v[62:65], v[152:155], v[184:187], v[62:65]
	v_mfma_f32_16x16x32_bf16 v[58:61], v[156:159], v[180:183], v[58:61]
	v_mfma_f32_16x16x32_bf16 v[58:61], v[160:163], v[184:187], v[58:61]
	v_mfma_f32_16x16x32_bf16 v[42:45], v[156:159], v[188:191], v[42:45]
	v_mfma_f32_16x16x32_bf16 v[42:45], v[160:163], v[192:195], v[42:45]
	v_mfma_f32_16x16x32_bf16 v[46:49], v[148:151], v[188:191], v[46:49]
	v_mfma_f32_16x16x32_bf16 v[46:49], v[152:155], v[192:195], v[46:49]
	v_mfma_f32_16x16x32_bf16 v[30:33], v[148:151], v[196:199], v[30:33]
	v_mfma_f32_16x16x32_bf16 v[30:33], v[152:155], v[200:203], v[30:33]
	v_mfma_f32_16x16x32_bf16 v[26:29], v[156:159], v[196:199], v[26:29]
	v_mfma_f32_16x16x32_bf16 v[26:29], v[160:163], v[200:203], v[26:29]
	v_mfma_f32_16x16x32_bf16 v[10:13], v[156:159], v[204:207], v[10:13]
	v_mfma_f32_16x16x32_bf16 v[10:13], v[160:163], v[208:211], v[10:13]
	v_mfma_f32_16x16x32_bf16 v[14:17], v[148:151], v[204:207], v[14:17]
	v_mfma_f32_16x16x32_bf16 v[14:17], v[152:155], v[208:211], v[14:17]
	v_mfma_f32_16x16x32_bf16 v[54:57], v[164:167], v[180:183], v[54:57]
	v_mfma_f32_16x16x32_bf16 v[54:57], v[168:171], v[184:187], v[54:57]
	v_mfma_f32_16x16x32_bf16 v[50:53], v[172:175], v[180:183], v[50:53]
	v_mfma_f32_16x16x32_bf16 v[50:53], v[176:179], v[184:187], v[50:53]
	v_mfma_f32_16x16x32_bf16 v[34:37], v[172:175], v[188:191], v[34:37]
	v_mfma_f32_16x16x32_bf16 v[34:37], v[176:179], v[192:195], v[34:37]
	v_mfma_f32_16x16x32_bf16 v[38:41], v[164:167], v[188:191], v[38:41]
	v_mfma_f32_16x16x32_bf16 v[38:41], v[168:171], v[192:195], v[38:41]
	v_mfma_f32_16x16x32_bf16 v[22:25], v[164:167], v[196:199], v[22:25]
	v_mfma_f32_16x16x32_bf16 v[22:25], v[168:171], v[200:203], v[22:25]
	v_mfma_f32_16x16x32_bf16 v[18:21], v[172:175], v[196:199], v[18:21]
	v_mfma_f32_16x16x32_bf16 v[18:21], v[176:179], v[200:203], v[18:21]
	v_mfma_f32_16x16x32_bf16 v[2:5], v[172:175], v[204:207], v[2:5]
	v_mfma_f32_16x16x32_bf16 v[2:5], v[176:179], v[208:211], v[2:5]
	s_setprio 2
	s_barrier
	v_mfma_f32_16x16x32_bf16 v[6:9], v[164:167], v[204:207], v[6:9]
	v_mfma_f32_16x16x32_bf16 v[6:9], v[168:171], v[208:211], v[6:9]
	s_setprio 0
	s_add_i32 s77, s77, 2
	s_add_u32 s73, s73, 0x100
	s_addc_u32 s74, s74, 0
	s_add_u32 s18, s18, 0x100
	s_addc_u32 s19, s19, 0
	s_add_u32 s75, s75, 0x100
	s_addc_u32 s76, s76, 0
	s_cmp_gt_u32 s77, 29
	s_cbranch_scc0 .LBB0_1224
	s_and_b64 vcc, exec, s[6:7]
	s_cbranch_vccz .LBB0_1227
	s_barrier

.LBB0_1356:
	s_ashr_i32 s13, s12, 31
	s_lshl_b64 s[14:15], s[12:13], 15
	s_add_u32 s14, s28, s14
	s_addc_u32 s15, s29, s15
	s_and_b64 s[16:17], s[2:3], exec
	s_cselect_b32 s13, s15, s23
	s_cselect_b32 s67, s14, s22
	s_ashr_i32 s11, s10, 31
	s_lshl_b64 s[16:17], s[10:11], 15
	s_add_u32 s16, s30, s16
	s_addc_u32 s17, s31, s17
	s_and_b64 s[24:25], s[2:3], exec
	s_cselect_b32 s11, s17, s21
	s_cselect_b32 s73, s16, s20
	s_add_u32 s74, s20, 0x80000
	s_addc_u32 s75, s21, 0
	s_add_u32 s20, s22, 0x204000
	s_addc_u32 s21, s23, 0
	s_add_u32 s76, s22, 0x400000
	s_addc_u32 s77, s23, 0
	s_mov_b32 s78, -2
	s_waitcnt vmcnt(25)
	s_waitcnt vmcnt(24)
	s_waitcnt vmcnt(15)
	s_waitcnt vmcnt(14)
	s_waitcnt vmcnt(13)
	s_waitcnt vmcnt(12)
	s_waitcnt vmcnt(11)
	s_waitcnt vmcnt(10)
	s_waitcnt vmcnt(9)
	s_waitcnt vmcnt(8)
	s_waitcnt vmcnt(7)
	s_waitcnt vmcnt(6)
	s_waitcnt vmcnt(5)
	s_waitcnt vmcnt(4)
	s_waitcnt vmcnt(3)
	s_waitcnt vmcnt(2)
	s_waitcnt vmcnt(1)
	s_waitcnt vmcnt(0)
	ds_read_b128 v[130:133], v181
	ds_read_b128 v[134:137], v181 offset:1024
	ds_read_b128 v[138:141], v181 offset:2048
	ds_read_b128 v[142:145], v181 offset:3072
	ds_read_b128 v[150:153], v182
	ds_read_b128 v[154:157], v182 offset:1024
	ds_read_b128 v[158:161], v182 offset:2048
	ds_read_b128 v[162:165], v182 offset:3072
	s_cmpk_eq_i32 s78, 0x52
	s_cselect_b32 s23, s11, s75
	s_cselect_b32 s22, s73, s74
	s_cselect_b32 s25, s13, s77
	s_cselect_b32 s24, s67, s76
	ds_read_b128 v[166:169], v183
	ds_read_b128 v[170:173], v183 offset:1024
	ds_read_b128 v[186:189], v183 offset:2048
	ds_read_b128 v[190:193], v183 offset:3072
	ds_read_b128 v[194:197], v183 offset:4096
	ds_read_b128 v[198:201], v183 offset:5120
	ds_read_b128 v[202:205], v183 offset:6144
	ds_read_b128 v[206:209], v183 offset:7168
	s_add_u32 s80, s20, 0xffffc000
	s_addc_u32 s81, s21, -1
	s_mov_b32 s79, m0
	s_mov_b32 m0, s58
	s_nop 0
	global_load_lds_dwordx4 v1, s[80:81]
	s_mov_b32 m0, s79
	s_nop 0
	s_mov_b32 s79, m0
	s_mov_b32 m0, s64
	s_nop 0
	global_load_lds_dwordx4 v177, s[80:81]
	s_mov_b32 m0, s79
	s_nop 0
	s_mov_b32 s79, m0
	s_mov_b32 m0, s59
	s_nop 0
	global_load_lds_dwordx4 v1, s[20:21]
	s_mov_b32 m0, s79
	s_nop 0
	s_mov_b32 s79, m0
	s_mov_b32 m0, s65
	s_nop 0
	global_load_lds_dwordx4 v177, s[20:21]
	s_mov_b32 m0, s79
	s_waitcnt vmcnt(8)
	s_waitcnt lgkmcnt(0)
	s_barrier
	s_setprio 1
	.p2align 3
	v_mfma_f32_16x16x32_bf16 v[126:129], v[130:133], v[166:169], 0
	v_mfma_f32_16x16x32_bf16 v[126:129], v[134:137], v[170:173], v[126:129]
	v_mfma_f32_16x16x32_bf16 v[122:125], v[138:141], v[166:169], 0
	v_mfma_f32_16x16x32_bf16 v[122:125], v[142:145], v[170:173], v[122:125]
	v_mfma_f32_16x16x32_bf16 v[110:113], v[138:141], v[186:189], 0
	v_mfma_f32_16x16x32_bf16 v[110:113], v[142:145], v[190:193], v[110:113]
	v_mfma_f32_16x16x32_bf16 v[118:121], v[130:133], v[186:189], 0
	v_mfma_f32_16x16x32_bf16 v[118:121], v[134:137], v[190:193], v[118:121]
	v_mfma_f32_16x16x32_bf16 v[94:97], v[130:133], v[194:197], 0
	v_mfma_f32_16x16x32_bf16 v[94:97], v[134:137], v[198:201], v[94:97]
	v_mfma_f32_16x16x32_bf16 v[90:93], v[138:141], v[194:197], 0
	v_mfma_f32_16x16x32_bf16 v[90:93], v[142:145], v[198:201], v[90:93]
	v_mfma_f32_16x16x32_bf16 v[78:81], v[138:141], v[202:205], 0
	v_mfma_f32_16x16x32_bf16 v[78:81], v[142:145], v[206:209], v[78:81]
	v_mfma_f32_16x16x32_bf16 v[86:89], v[130:133], v[202:205], 0
	v_mfma_f32_16x16x32_bf16 v[86:89], v[134:137], v[206:209], v[86:89]
	v_mfma_f32_16x16x32_bf16 v[114:117], v[150:153], v[166:169], 0
	v_mfma_f32_16x16x32_bf16 v[114:117], v[154:157], v[170:173], v[114:117]
	v_mfma_f32_16x16x32_bf16 v[106:109], v[158:161], v[166:169], 0
	v_mfma_f32_16x16x32_bf16 v[106:109], v[162:165], v[170:173], v[106:109]
	v_mfma_f32_16x16x32_bf16 v[98:101], v[158:161], v[186:189], 0
	v_mfma_f32_16x16x32_bf16 v[98:101], v[162:165], v[190:193], v[98:101]
	v_mfma_f32_16x16x32_bf16 v[102:105], v[150:153], v[186:189], 0
	v_mfma_f32_16x16x32_bf16 v[102:105], v[154:157], v[190:193], v[102:105]
	v_mfma_f32_16x16x32_bf16 v[82:85], v[150:153], v[194:197], 0
	v_mfma_f32_16x16x32_bf16 v[82:85], v[154:157], v[198:201], v[82:85]
	v_mfma_f32_16x16x32_bf16 v[74:77], v[158:161], v[194:197], 0
	v_mfma_f32_16x16x32_bf16 v[74:77], v[162:165], v[198:201], v[74:77]
	v_mfma_f32_16x16x32_bf16 v[66:69], v[158:161], v[202:205], 0
	v_mfma_f32_16x16x32_bf16 v[66:69], v[162:165], v[206:209], v[66:69]
	s_setprio 2
	s_barrier
	v_mfma_f32_16x16x32_bf16 v[70:73], v[150:153], v[202:205], 0
	v_mfma_f32_16x16x32_bf16 v[70:73], v[154:157], v[206:209], v[70:73]
	s_setprio 0
	ds_read_b128 v[166:169], v183 offset:16384
	ds_read_b128 v[170:173], v183 offset:17408
	ds_read_b128 v[186:189], v183 offset:18432
	ds_read_b128 v[190:193], v183 offset:19456
	ds_read_b128 v[194:197], v183 offset:20480
	ds_read_b128 v[198:201], v183 offset:21504
	ds_read_b128 v[202:205], v183 offset:22528
	ds_read_b128 v[206:209], v183 offset:23552
	s_mov_b32 s79, m0
	s_mov_b32 m0, s35
	s_nop 0
	global_load_lds_dwordx4 v176, s[22:23]
	s_mov_b32 m0, s79
	s_add_u32 s80, s22, 0x4000
	s_mov_b32 s79, m0
	s_mov_b32 m0, s36
	s_nop 0
	global_load_lds_dwordx4 v178, s[22:23]
	s_mov_b32 m0, s79
	s_addc_u32 s81, s23, 0
	s_mov_b32 s79, m0
	s_mov_b32 m0, s37
	s_nop 0
	global_load_lds_dwordx4 v176, s[80:81]
	s_mov_b32 m0, s79
	s_nop 0
	s_mov_b32 s79, m0
	s_mov_b32 m0, s40
	s_nop 0
	global_load_lds_dwordx4 v178, s[80:81]
	s_mov_b32 m0, s79
	s_waitcnt vmcnt(4)
	s_waitcnt lgkmcnt(0)
	s_barrier
	s_setprio 1
	.p2align 3
	v_mfma_f32_16x16x32_bf16 v[62:65], v[130:133], v[166:169], 0
	v_mfma_f32_16x16x32_bf16 v[62:65], v[134:137], v[170:173], v[62:65]
	v_mfma_f32_16x16x32_bf16 v[58:61], v[138:141], v[166:169], 0
	v_mfma_f32_16x16x32_bf16 v[58:61], v[142:145], v[170:173], v[58:61]
	v_mfma_f32_16x16x32_bf16 v[42:45], v[138:141], v[186:189], 0
	v_mfma_f32_16x16x32_bf16 v[42:45], v[142:145], v[190:193], v[42:45]
	v_mfma_f32_16x16x32_bf16 v[46:49], v[130:133], v[186:189], 0
	v_mfma_f32_16x16x32_bf16 v[46:49], v[134:137], v[190:193], v[46:49]
	v_mfma_f32_16x16x32_bf16 v[30:33], v[130:133], v[194:197], 0
	v_mfma_f32_16x16x32_bf16 v[30:33], v[134:137], v[198:201], v[30:33]
	v_mfma_f32_16x16x32_bf16 v[26:29], v[138:141], v[194:197], 0
	v_mfma_f32_16x16x32_bf16 v[26:29], v[142:145], v[198:201], v[26:29]
	v_mfma_f32_16x16x32_bf16 v[10:13], v[138:141], v[202:205], 0
	v_mfma_f32_16x16x32_bf16 v[10:13], v[142:145], v[206:209], v[10:13]
	v_mfma_f32_16x16x32_bf16 v[14:17], v[130:133], v[202:205], 0
	v_mfma_f32_16x16x32_bf16 v[14:17], v[134:137], v[206:209], v[14:17]
	v_mfma_f32_16x16x32_bf16 v[54:57], v[150:153], v[166:169], 0
	v_mfma_f32_16x16x32_bf16 v[54:57], v[154:157], v[170:173], v[54:57]
	v_mfma_f32_16x16x32_bf16 v[50:53], v[158:161], v[166:169], 0
	v_mfma_f32_16x16x32_bf16 v[50:53], v[162:165], v[170:173], v[50:53]
	v_mfma_f32_16x16x32_bf16 v[34:37], v[158:161], v[186:189], 0
	v_mfma_f32_16x16x32_bf16 v[34:37], v[162:165], v[190:193], v[34:37]
	v_mfma_f32_16x16x32_bf16 v[38:41], v[150:153], v[186:189], 0
	v_mfma_f32_16x16x32_bf16 v[38:41], v[154:157], v[190:193], v[38:41]
	v_mfma_f32_16x16x32_bf16 v[22:25], v[150:153], v[194:197], 0
	v_mfma_f32_16x16x32_bf16 v[22:25], v[154:157], v[198:201], v[22:25]
	v_mfma_f32_16x16x32_bf16 v[18:21], v[158:161], v[194:197], 0
	v_mfma_f32_16x16x32_bf16 v[18:21], v[162:165], v[198:201], v[18:21]
	v_mfma_f32_16x16x32_bf16 v[2:5], v[158:161], v[202:205], 0
	v_mfma_f32_16x16x32_bf16 v[2:5], v[162:165], v[206:209], v[2:5]
	s_setprio 2
	s_barrier
	v_mfma_f32_16x16x32_bf16 v[6:9], v[150:153], v[202:205], 0
	v_mfma_f32_16x16x32_bf16 v[6:9], v[154:157], v[206:209], v[6:9]
	s_setprio 0
	ds_read_b128 v[130:133], v184
	ds_read_b128 v[134:137], v184 offset:1024
	ds_read_b128 v[138:141], v184 offset:2048
	ds_read_b128 v[142:145], v184 offset:3072
	ds_read_b128 v[150:153], v185
	ds_read_b128 v[154:157], v185 offset:1024
	ds_read_b128 v[158:161], v185 offset:2048
	ds_read_b128 v[162:165], v185 offset:3072
	ds_read_b128 v[166:169], v183 offset:32768
	ds_read_b128 v[170:173], v183 offset:33792
	ds_read_b128 v[186:189], v183 offset:34816
	ds_read_b128 v[190:193], v183 offset:35840
	ds_read_b128 v[194:197], v183 offset:36864
	ds_read_b128 v[198:201], v183 offset:37888
	ds_read_b128 v[202:205], v183 offset:38912
	ds_read_b128 v[206:209], v183 offset:39936
	s_mov_b32 s79, m0
	s_mov_b32 m0, s34
	s_nop 0
	global_load_lds_dwordx4 v1, s[24:25]
	s_mov_b32 m0, s79
	s_nop 0
	s_mov_b32 s79, m0
	s_mov_b32 m0, s41
	s_nop 0
	global_load_lds_dwordx4 v177, s[24:25]
	s_mov_b32 m0, s79
	s_add_u32 s24, s24, 0x4000
	s_addc_u32 s25, s25, 0
	s_mov_b32 s79, m0
	s_mov_b32 m0, s42
	s_nop 0
	global_load_lds_dwordx4 v1, s[24:25]
	s_mov_b32 m0, s79
	s_nop 0
	s_mov_b32 s79, m0
	s_mov_b32 m0, s43
	s_nop 0
	global_load_lds_dwordx4 v177, s[24:25]
	s_mov_b32 m0, s79
	s_waitcnt vmcnt(8)
	s_waitcnt lgkmcnt(0)
	s_barrier
	s_setprio 1
	.p2align 3
	v_mfma_f32_16x16x32_bf16 v[126:129], v[130:133], v[166:169], v[126:129]
	v_mfma_f32_16x16x32_bf16 v[126:129], v[134:137], v[170:173], v[126:129]
	v_mfma_f32_16x16x32_bf16 v[122:125], v[138:141], v[166:169], v[122:125]
	v_mfma_f32_16x16x32_bf16 v[122:125], v[142:145], v[170:173], v[122:125]
	v_mfma_f32_16x16x32_bf16 v[110:113], v[138:141], v[186:189], v[110:113]
	v_mfma_f32_16x16x32_bf16 v[110:113], v[142:145], v[190:193], v[110:113]
	v_mfma_f32_16x16x32_bf16 v[118:121], v[130:133], v[186:189], v[118:121]
	v_mfma_f32_16x16x32_bf16 v[118:121], v[134:137], v[190:193], v[118:121]
	v_mfma_f32_16x16x32_bf16 v[94:97], v[130:133], v[194:197], v[94:97]
	v_mfma_f32_16x16x32_bf16 v[94:97], v[134:137], v[198:201], v[94:97]
	v_mfma_f32_16x16x32_bf16 v[90:93], v[138:141], v[194:197], v[90:93]
	v_mfma_f32_16x16x32_bf16 v[90:93], v[142:145], v[198:201], v[90:93]
	v_mfma_f32_16x16x32_bf16 v[78:81], v[138:141], v[202:205], v[78:81]
	v_mfma_f32_16x16x32_bf16 v[78:81], v[142:145], v[206:209], v[78:81]
	v_mfma_f32_16x16x32_bf16 v[86:89], v[130:133], v[202:205], v[86:89]
	v_mfma_f32_16x16x32_bf16 v[86:89], v[134:137], v[206:209], v[86:89]
	v_mfma_f32_16x16x32_bf16 v[114:117], v[150:153], v[166:169], v[114:117]
	v_mfma_f32_16x16x32_bf16 v[114:117], v[154:157], v[170:173], v[114:117]
	v_mfma_f32_16x16x32_bf16 v[106:109], v[158:161], v[166:169], v[106:109]
	v_mfma_f32_16x16x32_bf16 v[106:109], v[162:165], v[170:173], v[106:109]
	v_mfma_f32_16x16x32_bf16 v[98:101], v[158:161], v[186:189], v[98:101]
	v_mfma_f32_16x16x32_bf16 v[98:101], v[162:165], v[190:193], v[98:101]
	v_mfma_f32_16x16x32_bf16 v[102:105], v[150:153], v[186:189], v[102:105]
	v_mfma_f32_16x16x32_bf16 v[102:105], v[154:157], v[190:193], v[102:105]
	v_mfma_f32_16x16x32_bf16 v[82:85], v[150:153], v[194:197], v[82:85]
	v_mfma_f32_16x16x32_bf16 v[82:85], v[154:157], v[198:201], v[82:85]
	v_mfma_f32_16x16x32_bf16 v[74:77], v[158:161], v[194:197], v[74:77]
	v_mfma_f32_16x16x32_bf16 v[74:77], v[162:165], v[198:201], v[74:77]
	v_mfma_f32_16x16x32_bf16 v[66:69], v[158:161], v[202:205], v[66:69]
	v_mfma_f32_16x16x32_bf16 v[66:69], v[162:165], v[206:209], v[66:69]
	s_setprio 2
	s_barrier
	v_mfma_f32_16x16x32_bf16 v[70:73], v[150:153], v[202:205], v[70:73]
	v_mfma_f32_16x16x32_bf16 v[70:73], v[154:157], v[206:209], v[70:73]
	s_setprio 0
	ds_read_b128 v[166:169], v183 offset:49152
	ds_read_b128 v[170:173], v183 offset:50176
	ds_read_b128 v[186:189], v183 offset:51200
	ds_read_b128 v[190:193], v183 offset:52224
	ds_read_b128 v[194:197], v183 offset:53248
	ds_read_b128 v[198:201], v183 offset:54272
	ds_read_b128 v[202:205], v183 offset:55296
	ds_read_b128 v[206:209], v183 offset:56320
	s_add_u32 s24, s22, 0x40000
	s_addc_u32 s25, s23, 0
	s_mov_b32 s79, m0
	s_mov_b32 m0, s46
	s_nop 0
	global_load_lds_dwordx4 v176, s[24:25]
	s_mov_b32 m0, s79
	s_add_u32 s22, s22, 0x44000
	s_mov_b32 s79, m0
	s_mov_b32 m0, s47
	s_nop 0
	global_load_lds_dwordx4 v178, s[24:25]
	s_mov_b32 m0, s79
	s_addc_u32 s23, s23, 0
	s_mov_b32 s24, m0
	s_mov_b32 m0, s48
	s_nop 0
	global_load_lds_dwordx4 v176, s[22:23]
	s_mov_b32 m0, s24
	s_nop 0
	s_mov_b32 s24, m0
	s_mov_b32 m0, s49
	s_nop 0
	global_load_lds_dwordx4 v178, s[22:23]
	s_mov_b32 m0, s24
	s_waitcnt vmcnt(4)
	s_waitcnt lgkmcnt(0)
	s_barrier
	s_setprio 1
	.p2align 3
	v_mfma_f32_16x16x32_bf16 v[62:65], v[130:133], v[166:169], v[62:65]
	v_mfma_f32_16x16x32_bf16 v[62:65], v[134:137], v[170:173], v[62:65]
	v_mfma_f32_16x16x32_bf16 v[58:61], v[138:141], v[166:169], v[58:61]
	v_mfma_f32_16x16x32_bf16 v[58:61], v[142:145], v[170:173], v[58:61]
	v_mfma_f32_16x16x32_bf16 v[42:45], v[138:141], v[186:189], v[42:45]
	v_mfma_f32_16x16x32_bf16 v[42:45], v[142:145], v[190:193], v[42:45]
	v_mfma_f32_16x16x32_bf16 v[46:49], v[130:133], v[186:189], v[46:49]
	v_mfma_f32_16x16x32_bf16 v[46:49], v[134:137], v[190:193], v[46:49]
	v_mfma_f32_16x16x32_bf16 v[30:33], v[130:133], v[194:197], v[30:33]
	v_mfma_f32_16x16x32_bf16 v[30:33], v[134:137], v[198:201], v[30:33]
	v_mfma_f32_16x16x32_bf16 v[26:29], v[138:141], v[194:197], v[26:29]
	v_mfma_f32_16x16x32_bf16 v[26:29], v[142:145], v[198:201], v[26:29]
	v_mfma_f32_16x16x32_bf16 v[10:13], v[138:141], v[202:205], v[10:13]
	v_mfma_f32_16x16x32_bf16 v[10:13], v[142:145], v[206:209], v[10:13]
	v_mfma_f32_16x16x32_bf16 v[14:17], v[130:133], v[202:205], v[14:17]
	v_mfma_f32_16x16x32_bf16 v[14:17], v[134:137], v[206:209], v[14:17]
	v_mfma_f32_16x16x32_bf16 v[54:57], v[150:153], v[166:169], v[54:57]
	v_mfma_f32_16x16x32_bf16 v[54:57], v[154:157], v[170:173], v[54:57]
	v_mfma_f32_16x16x32_bf16 v[50:53], v[158:161], v[166:169], v[50:53]
	v_mfma_f32_16x16x32_bf16 v[50:53], v[162:165], v[170:173], v[50:53]
	v_mfma_f32_16x16x32_bf16 v[34:37], v[158:161], v[186:189], v[34:37]
	v_mfma_f32_16x16x32_bf16 v[34:37], v[162:165], v[190:193], v[34:37]
	v_mfma_f32_16x16x32_bf16 v[38:41], v[150:153], v[186:189], v[38:41]
	v_mfma_f32_16x16x32_bf16 v[38:41], v[154:157], v[190:193], v[38:41]
	v_mfma_f32_16x16x32_bf16 v[22:25], v[150:153], v[194:197], v[22:25]
	v_mfma_f32_16x16x32_bf16 v[22:25], v[154:157], v[198:201], v[22:25]
	v_mfma_f32_16x16x32_bf16 v[18:21], v[158:161], v[194:197], v[18:21]
	v_mfma_f32_16x16x32_bf16 v[18:21], v[162:165], v[198:201], v[18:21]
	v_mfma_f32_16x16x32_bf16 v[2:5], v[158:161], v[202:205], v[2:5]
	v_mfma_f32_16x16x32_bf16 v[2:5], v[162:165], v[206:209], v[2:5]
	s_setprio 2
	s_barrier
	v_mfma_f32_16x16x32_bf16 v[6:9], v[150:153], v[202:205], v[6:9]
	v_mfma_f32_16x16x32_bf16 v[6:9], v[154:157], v[206:209], v[6:9]
	s_setprio 0
	s_add_i32 s78, s78, 2
	s_add_u32 s74, s74, 0x80000
	s_addc_u32 s75, s75, 0
	s_add_u32 s20, s20, 0x400000
	s_addc_u32 s21, s21, 0
	s_add_u32 s76, s76, 0x400000
	s_addc_u32 s77, s77, 0
	s_cmpk_gt_u32 s78, 0x53
	.p2align 6
.LBB0_1357:
	ds_read_b128 v[130:133], v181
	ds_read_b128 v[134:137], v181 offset:1024
	ds_read_b128 v[138:141], v181 offset:2048
	ds_read_b128 v[142:145], v181 offset:3072
	ds_read_b128 v[150:153], v182
	ds_read_b128 v[154:157], v182 offset:1024
	ds_read_b128 v[158:161], v182 offset:2048
	ds_read_b128 v[162:165], v182 offset:3072
	s_cmpk_eq_i32 s78, 0x52
	s_cselect_b32 s23, s11, s75
	s_cselect_b32 s22, s73, s74
	s_cselect_b32 s25, s13, s77
	s_cselect_b32 s24, s67, s76
	ds_read_b128 v[166:169], v183
	ds_read_b128 v[170:173], v183 offset:1024
	ds_read_b128 v[186:189], v183 offset:2048
	ds_read_b128 v[190:193], v183 offset:3072
	ds_read_b128 v[194:197], v183 offset:4096
	ds_read_b128 v[198:201], v183 offset:5120
	ds_read_b128 v[202:205], v183 offset:6144
	ds_read_b128 v[206:209], v183 offset:7168
	s_add_u32 s80, s20, 0xffffc000
	s_addc_u32 s81, s21, -1
	s_mov_b32 s79, m0
	s_mov_b32 m0, s58
	s_nop 0
	global_load_lds_dwordx4 v1, s[80:81]
	s_mov_b32 m0, s79
	s_nop 0
	s_mov_b32 s79, m0
	s_mov_b32 m0, s64
	s_nop 0
	global_load_lds_dwordx4 v177, s[80:81]
	s_mov_b32 m0, s79
	s_nop 0
	s_mov_b32 s79, m0
	s_mov_b32 m0, s59
	s_nop 0
	global_load_lds_dwordx4 v1, s[20:21]
	s_mov_b32 m0, s79
	s_nop 0
	s_mov_b32 s79, m0
	s_mov_b32 m0, s65
	s_nop 0
	global_load_lds_dwordx4 v177, s[20:21]
	s_mov_b32 m0, s79
	s_waitcnt vmcnt(8)
	s_waitcnt lgkmcnt(0)
	s_barrier
	s_setprio 1
	.p2align 3
	v_mfma_f32_16x16x32_bf16 v[126:129], v[130:133], v[166:169], v[126:129]
	v_mfma_f32_16x16x32_bf16 v[126:129], v[134:137], v[170:173], v[126:129]
	v_mfma_f32_16x16x32_bf16 v[122:125], v[138:141], v[166:169], v[122:125]
	v_mfma_f32_16x16x32_bf16 v[122:125], v[142:145], v[170:173], v[122:125]
	v_mfma_f32_16x16x32_bf16 v[110:113], v[138:141], v[186:189], v[110:113]
	v_mfma_f32_16x16x32_bf16 v[110:113], v[142:145], v[190:193], v[110:113]
	v_mfma_f32_16x16x32_bf16 v[118:121], v[130:133], v[186:189], v[118:121]
	v_mfma_f32_16x16x32_bf16 v[118:121], v[134:137], v[190:193], v[118:121]
	v_mfma_f32_16x16x32_bf16 v[94:97], v[130:133], v[194:197], v[94:97]
	v_mfma_f32_16x16x32_bf16 v[94:97], v[134:137], v[198:201], v[94:97]
	v_mfma_f32_16x16x32_bf16 v[90:93], v[138:141], v[194:197], v[90:93]
	v_mfma_f32_16x16x32_bf16 v[90:93], v[142:145], v[198:201], v[90:93]
	v_mfma_f32_16x16x32_bf16 v[78:81], v[138:141], v[202:205], v[78:81]
	v_mfma_f32_16x16x32_bf16 v[78:81], v[142:145], v[206:209], v[78:81]
	v_mfma_f32_16x16x32_bf16 v[86:89], v[130:133], v[202:205], v[86:89]
	v_mfma_f32_16x16x32_bf16 v[86:89], v[134:137], v[206:209], v[86:89]
	v_mfma_f32_16x16x32_bf16 v[114:117], v[150:153], v[166:169], v[114:117]
	v_mfma_f32_16x16x32_bf16 v[114:117], v[154:157], v[170:173], v[114:117]
	v_mfma_f32_16x16x32_bf16 v[106:109], v[158:161], v[166:169], v[106:109]
	v_mfma_f32_16x16x32_bf16 v[106:109], v[162:165], v[170:173], v[106:109]
	v_mfma_f32_16x16x32_bf16 v[98:101], v[158:161], v[186:189], v[98:101]
	v_mfma_f32_16x16x32_bf16 v[98:101], v[162:165], v[190:193], v[98:101]
	v_mfma_f32_16x16x32_bf16 v[102:105], v[150:153], v[186:189], v[102:105]
	v_mfma_f32_16x16x32_bf16 v[102:105], v[154:157], v[190:193], v[102:105]
	v_mfma_f32_16x16x32_bf16 v[82:85], v[150:153], v[194:197], v[82:85]
	v_mfma_f32_16x16x32_bf16 v[82:85], v[154:157], v[198:201], v[82:85]
	v_mfma_f32_16x16x32_bf16 v[74:77], v[158:161], v[194:197], v[74:77]
	v_mfma_f32_16x16x32_bf16 v[74:77], v[162:165], v[198:201], v[74:77]
	v_mfma_f32_16x16x32_bf16 v[66:69], v[158:161], v[202:205], v[66:69]
	v_mfma_f32_16x16x32_bf16 v[66:69], v[162:165], v[206:209], v[66:69]
	s_setprio 2
	s_barrier
	v_mfma_f32_16x16x32_bf16 v[70:73], v[150:153], v[202:205], v[70:73]
	v_mfma_f32_16x16x32_bf16 v[70:73], v[154:157], v[206:209], v[70:73]
	s_setprio 0
	ds_read_b128 v[166:169], v183 offset:16384
	ds_read_b128 v[170:173], v183 offset:17408
	ds_read_b128 v[186:189], v183 offset:18432
	ds_read_b128 v[190:193], v183 offset:19456
	ds_read_b128 v[194:197], v183 offset:20480
	ds_read_b128 v[198:201], v183 offset:21504
	ds_read_b128 v[202:205], v183 offset:22528
	ds_read_b128 v[206:209], v183 offset:23552
	s_mov_b32 s79, m0
	s_mov_b32 m0, s35
	s_nop 0
	global_load_lds_dwordx4 v176, s[22:23]
	s_mov_b32 m0, s79
	s_add_u32 s80, s22, 0x4000
	s_mov_b32 s79, m0
	s_mov_b32 m0, s36
	s_nop 0
	global_load_lds_dwordx4 v178, s[22:23]
	s_mov_b32 m0, s79
	s_addc_u32 s81, s23, 0
	s_mov_b32 s79, m0
	s_mov_b32 m0, s37
	s_nop 0
	global_load_lds_dwordx4 v176, s[80:81]
	s_mov_b32 m0, s79
	s_nop 0
	s_mov_b32 s79, m0
	s_mov_b32 m0, s40
	s_nop 0
	global_load_lds_dwordx4 v178, s[80:81]
	s_mov_b32 m0, s79
	s_waitcnt vmcnt(4)
	s_waitcnt lgkmcnt(0)
	s_barrier
	s_setprio 1
	.p2align 3
	v_mfma_f32_16x16x32_bf16 v[62:65], v[130:133], v[166:169], v[62:65]
	v_mfma_f32_16x16x32_bf16 v[62:65], v[134:137], v[170:173], v[62:65]
	v_mfma_f32_16x16x32_bf16 v[58:61], v[138:141], v[166:169], v[58:61]
	v_mfma_f32_16x16x32_bf16 v[58:61], v[142:145], v[170:173], v[58:61]
	v_mfma_f32_16x16x32_bf16 v[42:45], v[138:141], v[186:189], v[42:45]
	v_mfma_f32_16x16x32_bf16 v[42:45], v[142:145], v[190:193], v[42:45]
	v_mfma_f32_16x16x32_bf16 v[46:49], v[130:133], v[186:189], v[46:49]
	v_mfma_f32_16x16x32_bf16 v[46:49], v[134:137], v[190:193], v[46:49]
	v_mfma_f32_16x16x32_bf16 v[30:33], v[130:133], v[194:197], v[30:33]
	v_mfma_f32_16x16x32_bf16 v[30:33], v[134:137], v[198:201], v[30:33]
	v_mfma_f32_16x16x32_bf16 v[26:29], v[138:141], v[194:197], v[26:29]
	v_mfma_f32_16x16x32_bf16 v[26:29], v[142:145], v[198:201], v[26:29]
	v_mfma_f32_16x16x32_bf16 v[10:13], v[138:141], v[202:205], v[10:13]
	v_mfma_f32_16x16x32_bf16 v[10:13], v[142:145], v[206:209], v[10:13]
	v_mfma_f32_16x16x32_bf16 v[14:17], v[130:133], v[202:205], v[14:17]
	v_mfma_f32_16x16x32_bf16 v[14:17], v[134:137], v[206:209], v[14:17]
	v_mfma_f32_16x16x32_bf16 v[54:57], v[150:153], v[166:169], v[54:57]
	v_mfma_f32_16x16x32_bf16 v[54:57], v[154:157], v[170:173], v[54:57]
	v_mfma_f32_16x16x32_bf16 v[50:53], v[158:161], v[166:169], v[50:53]
	v_mfma_f32_16x16x32_bf16 v[50:53], v[162:165], v[170:173], v[50:53]
	v_mfma_f32_16x16x32_bf16 v[34:37], v[158:161], v[186:189], v[34:37]
	v_mfma_f32_16x16x32_bf16 v[34:37], v[162:165], v[190:193], v[34:37]
	v_mfma_f32_16x16x32_bf16 v[38:41], v[150:153], v[186:189], v[38:41]
	v_mfma_f32_16x16x32_bf16 v[38:41], v[154:157], v[190:193], v[38:41]
	v_mfma_f32_16x16x32_bf16 v[22:25], v[150:153], v[194:197], v[22:25]
	v_mfma_f32_16x16x32_bf16 v[22:25], v[154:157], v[198:201], v[22:25]
	v_mfma_f32_16x16x32_bf16 v[18:21], v[158:161], v[194:197], v[18:21]
	v_mfma_f32_16x16x32_bf16 v[18:21], v[162:165], v[198:201], v[18:21]
	v_mfma_f32_16x16x32_bf16 v[2:5], v[158:161], v[202:205], v[2:5]
	v_mfma_f32_16x16x32_bf16 v[2:5], v[162:165], v[206:209], v[2:5]
	s_setprio 2
	s_barrier
	v_mfma_f32_16x16x32_bf16 v[6:9], v[150:153], v[202:205], v[6:9]
	v_mfma_f32_16x16x32_bf16 v[6:9], v[154:157], v[206:209], v[6:9]
	s_setprio 0
	ds_read_b128 v[130:133], v184
	ds_read_b128 v[134:137], v184 offset:1024
	ds_read_b128 v[138:141], v184 offset:2048
	ds_read_b128 v[142:145], v184 offset:3072
	ds_read_b128 v[150:153], v185
	ds_read_b128 v[154:157], v185 offset:1024
	ds_read_b128 v[158:161], v185 offset:2048
	ds_read_b128 v[162:165], v185 offset:3072
	ds_read_b128 v[166:169], v183 offset:32768
	ds_read_b128 v[170:173], v183 offset:33792
	ds_read_b128 v[186:189], v183 offset:34816
	ds_read_b128 v[190:193], v183 offset:35840
	ds_read_b128 v[194:197], v183 offset:36864
	ds_read_b128 v[198:201], v183 offset:37888
	ds_read_b128 v[202:205], v183 offset:38912
	ds_read_b128 v[206:209], v183 offset:39936
	s_mov_b32 s79, m0
	s_mov_b32 m0, s34
	s_nop 0
	global_load_lds_dwordx4 v1, s[24:25]
	s_mov_b32 m0, s79
	s_nop 0
	s_mov_b32 s79, m0
	s_mov_b32 m0, s41
	s_nop 0
	global_load_lds_dwordx4 v177, s[24:25]
	s_mov_b32 m0, s79
	s_add_u32 s24, s24, 0x4000
	s_addc_u32 s25, s25, 0
	s_mov_b32 s79, m0
	s_mov_b32 m0, s42
	s_nop 0
	global_load_lds_dwordx4 v1, s[24:25]
	s_mov_b32 m0, s79
	s_nop 0
	s_mov_b32 s79, m0
	s_mov_b32 m0, s43
	s_nop 0
	global_load_lds_dwordx4 v177, s[24:25]
	s_mov_b32 m0, s79
	s_waitcnt vmcnt(8)
	s_waitcnt lgkmcnt(0)
	s_barrier
	s_setprio 1
	.p2align 3
	v_mfma_f32_16x16x32_bf16 v[126:129], v[130:133], v[166:169], v[126:129]
	v_mfma_f32_16x16x32_bf16 v[126:129], v[134:137], v[170:173], v[126:129]
	v_mfma_f32_16x16x32_bf16 v[122:125], v[138:141], v[166:169], v[122:125]
	v_mfma_f32_16x16x32_bf16 v[122:125], v[142:145], v[170:173], v[122:125]
	v_mfma_f32_16x16x32_bf16 v[110:113], v[138:141], v[186:189], v[110:113]
	v_mfma_f32_16x16x32_bf16 v[110:113], v[142:145], v[190:193], v[110:113]
	v_mfma_f32_16x16x32_bf16 v[118:121], v[130:133], v[186:189], v[118:121]
	v_mfma_f32_16x16x32_bf16 v[118:121], v[134:137], v[190:193], v[118:121]
	v_mfma_f32_16x16x32_bf16 v[94:97], v[130:133], v[194:197], v[94:97]
	v_mfma_f32_16x16x32_bf16 v[94:97], v[134:137], v[198:201], v[94:97]
	v_mfma_f32_16x16x32_bf16 v[90:93], v[138:141], v[194:197], v[90:93]
	v_mfma_f32_16x16x32_bf16 v[90:93], v[142:145], v[198:201], v[90:93]
	v_mfma_f32_16x16x32_bf16 v[78:81], v[138:141], v[202:205], v[78:81]
	v_mfma_f32_16x16x32_bf16 v[78:81], v[142:145], v[206:209], v[78:81]
	v_mfma_f32_16x16x32_bf16 v[86:89], v[130:133], v[202:205], v[86:89]
	v_mfma_f32_16x16x32_bf16 v[86:89], v[134:137], v[206:209], v[86:89]
	v_mfma_f32_16x16x32_bf16 v[114:117], v[150:153], v[166:169], v[114:117]
	v_mfma_f32_16x16x32_bf16 v[114:117], v[154:157], v[170:173], v[114:117]
	v_mfma_f32_16x16x32_bf16 v[106:109], v[158:161], v[166:169], v[106:109]
	v_mfma_f32_16x16x32_bf16 v[106:109], v[162:165], v[170:173], v[106:109]
	v_mfma_f32_16x16x32_bf16 v[98:101], v[158:161], v[186:189], v[98:101]
	v_mfma_f32_16x16x32_bf16 v[98:101], v[162:165], v[190:193], v[98:101]
	v_mfma_f32_16x16x32_bf16 v[102:105], v[150:153], v[186:189], v[102:105]
	v_mfma_f32_16x16x32_bf16 v[102:105], v[154:157], v[190:193], v[102:105]
	v_mfma_f32_16x16x32_bf16 v[82:85], v[150:153], v[194:197], v[82:85]
	v_mfma_f32_16x16x32_bf16 v[82:85], v[154:157], v[198:201], v[82:85]
	v_mfma_f32_16x16x32_bf16 v[74:77], v[158:161], v[194:197], v[74:77]
	v_mfma_f32_16x16x32_bf16 v[74:77], v[162:165], v[198:201], v[74:77]
	v_mfma_f32_16x16x32_bf16 v[66:69], v[158:161], v[202:205], v[66:69]
	v_mfma_f32_16x16x32_bf16 v[66:69], v[162:165], v[206:209], v[66:69]
	s_setprio 2
	s_barrier
	v_mfma_f32_16x16x32_bf16 v[70:73], v[150:153], v[202:205], v[70:73]
	v_mfma_f32_16x16x32_bf16 v[70:73], v[154:157], v[206:209], v[70:73]
	s_setprio 0
	ds_read_b128 v[166:169], v183 offset:49152
	ds_read_b128 v[170:173], v183 offset:50176
	ds_read_b128 v[186:189], v183 offset:51200
	ds_read_b128 v[190:193], v183 offset:52224
	ds_read_b128 v[194:197], v183 offset:53248
	ds_read_b128 v[198:201], v183 offset:54272
	ds_read_b128 v[202:205], v183 offset:55296
	ds_read_b128 v[206:209], v183 offset:56320
	s_add_u32 s24, s22, 0x40000
	s_addc_u32 s25, s23, 0
	s_mov_b32 s79, m0
	s_mov_b32 m0, s46
	s_nop 0
	global_load_lds_dwordx4 v176, s[24:25]
	s_mov_b32 m0, s79
	s_add_u32 s22, s22, 0x44000
	s_mov_b32 s79, m0
	s_mov_b32 m0, s47
	s_nop 0
	global_load_lds_dwordx4 v178, s[24:25]
	s_mov_b32 m0, s79
	s_addc_u32 s23, s23, 0
	s_mov_b32 s24, m0
	s_mov_b32 m0, s48
	s_nop 0
	global_load_lds_dwordx4 v176, s[22:23]
	s_mov_b32 m0, s24
	s_nop 0
	s_mov_b32 s24, m0
	s_mov_b32 m0, s49
	s_nop 0
	global_load_lds_dwordx4 v178, s[22:23]
	s_mov_b32 m0, s24
	s_waitcnt vmcnt(4)
	s_waitcnt lgkmcnt(0)
	s_barrier
	s_setprio 1
	.p2align 3
	v_mfma_f32_16x16x32_bf16 v[62:65], v[130:133], v[166:169], v[62:65]
	v_mfma_f32_16x16x32_bf16 v[62:65], v[134:137], v[170:173], v[62:65]
	v_mfma_f32_16x16x32_bf16 v[58:61], v[138:141], v[166:169], v[58:61]
	v_mfma_f32_16x16x32_bf16 v[58:61], v[142:145], v[170:173], v[58:61]
	v_mfma_f32_16x16x32_bf16 v[42:45], v[138:141], v[186:189], v[42:45]
	v_mfma_f32_16x16x32_bf16 v[42:45], v[142:145], v[190:193], v[42:45]
	v_mfma_f32_16x16x32_bf16 v[46:49], v[130:133], v[186:189], v[46:49]
	v_mfma_f32_16x16x32_bf16 v[46:49], v[134:137], v[190:193], v[46:49]
	v_mfma_f32_16x16x32_bf16 v[30:33], v[130:133], v[194:197], v[30:33]
	v_mfma_f32_16x16x32_bf16 v[30:33], v[134:137], v[198:201], v[30:33]
	v_mfma_f32_16x16x32_bf16 v[26:29], v[138:141], v[194:197], v[26:29]
	v_mfma_f32_16x16x32_bf16 v[26:29], v[142:145], v[198:201], v[26:29]
	v_mfma_f32_16x16x32_bf16 v[10:13], v[138:141], v[202:205], v[10:13]
	v_mfma_f32_16x16x32_bf16 v[10:13], v[142:145], v[206:209], v[10:13]
	v_mfma_f32_16x16x32_bf16 v[14:17], v[130:133], v[202:205], v[14:17]
	v_mfma_f32_16x16x32_bf16 v[14:17], v[134:137], v[206:209], v[14:17]
	v_mfma_f32_16x16x32_bf16 v[54:57], v[150:153], v[166:169], v[54:57]
	v_mfma_f32_16x16x32_bf16 v[54:57], v[154:157], v[170:173], v[54:57]
	v_mfma_f32_16x16x32_bf16 v[50:53], v[158:161], v[166:169], v[50:53]
	v_mfma_f32_16x16x32_bf16 v[50:53], v[162:165], v[170:173], v[50:53]
	v_mfma_f32_16x16x32_bf16 v[34:37], v[158:161], v[186:189], v[34:37]
	v_mfma_f32_16x16x32_bf16 v[34:37], v[162:165], v[190:193], v[34:37]
	v_mfma_f32_16x16x32_bf16 v[38:41], v[150:153], v[186:189], v[38:41]
	v_mfma_f32_16x16x32_bf16 v[38:41], v[154:157], v[190:193], v[38:41]
	v_mfma_f32_16x16x32_bf16 v[22:25], v[150:153], v[194:197], v[22:25]
	v_mfma_f32_16x16x32_bf16 v[22:25], v[154:157], v[198:201], v[22:25]
	v_mfma_f32_16x16x32_bf16 v[18:21], v[158:161], v[194:197], v[18:21]
	v_mfma_f32_16x16x32_bf16 v[18:21], v[162:165], v[198:201], v[18:21]
	v_mfma_f32_16x16x32_bf16 v[2:5], v[158:161], v[202:205], v[2:5]
	v_mfma_f32_16x16x32_bf16 v[2:5], v[162:165], v[206:209], v[2:5]
	s_setprio 2
	s_barrier
	v_mfma_f32_16x16x32_bf16 v[6:9], v[150:153], v[202:205], v[6:9]
	v_mfma_f32_16x16x32_bf16 v[6:9], v[154:157], v[206:209], v[6:9]
	s_setprio 0
	s_add_i32 s78, s78, 2
	s_add_u32 s74, s74, 0x80000
	s_addc_u32 s75, s75, 0
	s_add_u32 s20, s20, 0x400000
	s_addc_u32 s21, s21, 0
	s_add_u32 s76, s76, 0x400000
	s_addc_u32 s77, s77, 0
	s_cmpk_gt_u32 s78, 0x53
	s_cbranch_scc0 .LBB0_1357
	s_and_b64 vcc, exec, s[8:9]
	s_cbranch_vccz .LBB0_1360
	s_barrier

.LBB0_1537:
	s_ashr_i32 s23, s22, 31
	s_lshl_b64 s[24:25], s[22:23], 20
	s_add_u32 s24, s41, s24
	s_addc_u32 s25, s42, s25
	s_and_b64 s[26:27], s[4:5], exec
	s_cselect_b32 s7, s25, s35
	s_cselect_b32 s23, s24, s34
	s_ashr_i32 s21, s20, 31
	s_lshl_b64 s[26:27], s[20:21], 20
	s_add_u32 s26, s43, s26
	s_addc_u32 s27, s46, s27
	s_and_b64 s[36:37], s[4:5], exec
	s_cselect_b32 s21, s27, s31
	s_cselect_b32 s29, s26, s30
	s_add_u32 s79, s30, 0x100
	s_addc_u32 s80, s31, 0
	s_add_u32 s30, s34, 0x80080
	s_addc_u32 s31, s35, 0
	s_add_u32 s81, s34, 0x100
	s_addc_u32 s82, s35, 0
	s_mov_b32 s83, -2
	s_waitcnt vmcnt(25)
	s_waitcnt vmcnt(24)
	s_waitcnt vmcnt(4)
	s_waitcnt vmcnt(14)
	s_waitcnt vmcnt(13)
	s_waitcnt vmcnt(12)
	s_waitcnt vmcnt(2)
	s_waitcnt vmcnt(10)
	s_waitcnt vmcnt(9)
	s_waitcnt vmcnt(8)
	s_waitcnt vmcnt(7)
	s_waitcnt vmcnt(6)
	s_waitcnt vmcnt(5)
	s_waitcnt vmcnt(4)
	s_waitcnt vmcnt(3)
	s_waitcnt vmcnt(2)
	s_waitcnt vmcnt(1)
	s_waitcnt vmcnt(0)
	ds_read_b128 v[46:49], v182
	ds_read_b128 v[54:57], v182 offset:1024
	ds_read_b128 v[58:61], v182 offset:2048
	ds_read_b128 v[62:65], v182 offset:3072
	ds_read_b128 v[146:149], v183
	ds_read_b128 v[150:153], v183 offset:1024
	ds_read_b128 v[154:157], v183 offset:2048
	ds_read_b128 v[158:161], v183 offset:3072
	s_cmp_eq_u32 s83, 28
	s_cselect_b32 s35, s21, s80
	s_cselect_b32 s34, s29, s79
	s_cselect_b32 s37, s7, s82
	s_cselect_b32 s36, s23, s81
	ds_read_b128 v[170:173], v184
	ds_read_b128 v[188:191], v184 offset:1024
	ds_read_b128 v[192:195], v184 offset:2048
	ds_read_b128 v[196:199], v184 offset:3072
	ds_read_b128 v[200:203], v184 offset:4096
	ds_read_b128 v[204:207], v184 offset:5120
	ds_read_b128 v[208:211], v184 offset:6144
	ds_read_b128 v[212:215], v184 offset:7168
	s_add_u32 s86, s30, 0xfff80000
	s_addc_u32 s87, s31, -1
	s_mov_b32 s92, m0
	s_mov_b32 m0, s73
	s_nop 0
	global_load_lds_dwordx4 v176, s[86:87]
	s_mov_b32 m0, s92
	s_nop 0
	s_mov_b32 s92, m0
	s_mov_b32 m0, s75
	s_nop 0
	global_load_lds_dwordx4 v178, s[86:87]
	s_mov_b32 m0, s92
	s_mov_b32 s86, m0
	s_mov_b32 m0, s74
	s_nop 0
	global_load_lds_dwordx4 v176, s[30:31]
	s_mov_b32 m0, s86
	s_nop 0
	s_mov_b32 s86, m0
	s_mov_b32 m0, s76
	s_nop 0
	global_load_lds_dwordx4 v178, s[30:31]
	s_mov_b32 m0, s86
	s_waitcnt vmcnt(8)
	s_waitcnt lgkmcnt(0)
	s_barrier
	s_setprio 1
	.p2align 3
	v_mfma_f32_16x16x32_bf16 v[142:145], v[46:49], v[170:173], 0
	v_mfma_f32_16x16x32_bf16 v[142:145], v[54:57], v[188:191], v[142:145]
	v_mfma_f32_16x16x32_bf16 v[138:141], v[58:61], v[170:173], 0
	v_mfma_f32_16x16x32_bf16 v[138:141], v[62:65], v[188:191], v[138:141]
	v_mfma_f32_16x16x32_bf16 v[126:129], v[46:49], v[192:195], 0
	v_mfma_f32_16x16x32_bf16 v[126:129], v[54:57], v[196:199], v[126:129]
	v_mfma_f32_16x16x32_bf16 v[122:125], v[58:61], v[192:195], 0
	v_mfma_f32_16x16x32_bf16 v[122:125], v[62:65], v[196:199], v[122:125]
	v_mfma_f32_16x16x32_bf16 v[110:113], v[46:49], v[200:203], 0
	v_mfma_f32_16x16x32_bf16 v[110:113], v[54:57], v[204:207], v[110:113]
	v_mfma_f32_16x16x32_bf16 v[106:109], v[58:61], v[200:203], 0
	v_mfma_f32_16x16x32_bf16 v[106:109], v[62:65], v[204:207], v[106:109]
	v_mfma_f32_16x16x32_bf16 v[94:97], v[46:49], v[208:211], 0
	v_mfma_f32_16x16x32_bf16 v[94:97], v[54:57], v[212:215], v[94:97]
	v_mfma_f32_16x16x32_bf16 v[90:93], v[58:61], v[208:211], 0
	v_mfma_f32_16x16x32_bf16 v[90:93], v[62:65], v[212:215], v[90:93]
	v_mfma_f32_16x16x32_bf16 v[134:137], v[146:149], v[170:173], 0
	v_mfma_f32_16x16x32_bf16 v[134:137], v[150:153], v[188:191], v[134:137]
	v_mfma_f32_16x16x32_bf16 v[130:133], v[154:157], v[170:173], 0
	v_mfma_f32_16x16x32_bf16 v[130:133], v[158:161], v[188:191], v[130:133]
	v_mfma_f32_16x16x32_bf16 v[118:121], v[146:149], v[192:195], 0
	v_mfma_f32_16x16x32_bf16 v[118:121], v[150:153], v[196:199], v[118:121]
	v_mfma_f32_16x16x32_bf16 v[114:117], v[154:157], v[192:195], 0
	v_mfma_f32_16x16x32_bf16 v[114:117], v[158:161], v[196:199], v[114:117]
	v_mfma_f32_16x16x32_bf16 v[102:105], v[146:149], v[200:203], 0
	v_mfma_f32_16x16x32_bf16 v[102:105], v[150:153], v[204:207], v[102:105]
	v_mfma_f32_16x16x32_bf16 v[98:101], v[154:157], v[200:203], 0
	v_mfma_f32_16x16x32_bf16 v[98:101], v[158:161], v[204:207], v[98:101]
	v_mfma_f32_16x16x32_bf16 v[86:89], v[146:149], v[208:211], 0
	v_mfma_f32_16x16x32_bf16 v[86:89], v[150:153], v[212:215], v[86:89]
	s_setprio 2
	s_barrier
	v_mfma_f32_16x16x32_bf16 v[82:85], v[154:157], v[208:211], 0
	v_mfma_f32_16x16x32_bf16 v[82:85], v[158:161], v[212:215], v[82:85]
	s_setprio 0
	ds_read_b128 v[170:173], v184 offset:16384
	ds_read_b128 v[188:191], v184 offset:17408
	ds_read_b128 v[192:195], v184 offset:18432
	ds_read_b128 v[196:199], v184 offset:19456
	ds_read_b128 v[200:203], v184 offset:20480
	ds_read_b128 v[204:207], v184 offset:21504
	ds_read_b128 v[208:211], v184 offset:22528
	ds_read_b128 v[212:215], v184 offset:23552
	s_mov_b32 s86, m0
	s_mov_b32 m0, s49
	s_nop 0
	global_load_lds_dwordx4 v177, s[34:35]
	s_mov_b32 m0, s86
	s_nop 0
	s_mov_b32 s86, m0
	s_mov_b32 m0, s56
	s_nop 0
	global_load_lds_dwordx4 v179, s[34:35]
	s_mov_b32 m0, s86
	s_add_u32 s86, s34, 0x80000
	s_addc_u32 s87, s35, 0
	s_mov_b32 s92, m0
	s_mov_b32 m0, s57
	s_nop 0
	global_load_lds_dwordx4 v177, s[86:87]
	s_mov_b32 m0, s92
	s_nop 0
	s_mov_b32 s92, m0
	s_mov_b32 m0, s58
	s_nop 0
	global_load_lds_dwordx4 v179, s[86:87]
	s_mov_b32 m0, s92
	s_waitcnt vmcnt(4)
	s_waitcnt lgkmcnt(0)
	s_barrier
	s_setprio 1
	.p2align 3
	v_mfma_f32_16x16x32_bf16 v[78:81], v[46:49], v[170:173], 0
	v_mfma_f32_16x16x32_bf16 v[78:81], v[54:57], v[188:191], v[78:81]
	v_mfma_f32_16x16x32_bf16 v[74:77], v[58:61], v[170:173], 0
	v_mfma_f32_16x16x32_bf16 v[74:77], v[62:65], v[188:191], v[74:77]
	v_mfma_f32_16x16x32_bf16 v[50:53], v[46:49], v[192:195], 0
	v_mfma_f32_16x16x32_bf16 v[50:53], v[54:57], v[196:199], v[50:53]
	v_mfma_f32_16x16x32_bf16 v[42:45], v[58:61], v[192:195], 0
	v_mfma_f32_16x16x32_bf16 v[42:45], v[62:65], v[196:199], v[42:45]
	v_mfma_f32_16x16x32_bf16 v[30:33], v[46:49], v[200:203], 0
	v_mfma_f32_16x16x32_bf16 v[30:33], v[54:57], v[204:207], v[30:33]
	v_mfma_f32_16x16x32_bf16 v[26:29], v[58:61], v[200:203], 0
	v_mfma_f32_16x16x32_bf16 v[26:29], v[62:65], v[204:207], v[26:29]
	v_mfma_f32_16x16x32_bf16 v[14:17], v[46:49], v[208:211], 0
	v_mfma_f32_16x16x32_bf16 v[14:17], v[54:57], v[212:215], v[14:17]
	v_mfma_f32_16x16x32_bf16 v[10:13], v[58:61], v[208:211], 0
	v_mfma_f32_16x16x32_bf16 v[10:13], v[62:65], v[212:215], v[10:13]
	v_mfma_f32_16x16x32_bf16 v[38:41], v[146:149], v[192:195], 0
	v_mfma_f32_16x16x32_bf16 v[38:41], v[150:153], v[196:199], v[38:41]
	v_mfma_f32_16x16x32_bf16 v[34:37], v[154:157], v[192:195], 0
	v_mfma_f32_16x16x32_bf16 v[34:37], v[158:161], v[196:199], v[34:37]
	v_mfma_f32_16x16x32_bf16 v[22:25], v[146:149], v[200:203], 0
	v_mfma_f32_16x16x32_bf16 v[22:25], v[150:153], v[204:207], v[22:25]
	v_mfma_f32_16x16x32_bf16 v[18:21], v[154:157], v[200:203], 0
	v_mfma_f32_16x16x32_bf16 v[18:21], v[158:161], v[204:207], v[18:21]
	v_mfma_f32_16x16x32_bf16 v[6:9], v[146:149], v[208:211], 0
	v_mfma_f32_16x16x32_bf16 v[6:9], v[150:153], v[212:215], v[6:9]
	v_mfma_f32_16x16x32_bf16 v[2:5], v[154:157], v[208:211], 0
	v_mfma_f32_16x16x32_bf16 v[2:5], v[158:161], v[212:215], v[2:5]
	v_mfma_f32_16x16x32_bf16 v[46:49], v[146:149], v[170:173], 0
	v_mfma_f32_16x16x32_bf16 v[46:49], v[150:153], v[188:191], v[46:49]
	s_setprio 2
	s_barrier
	v_mfma_f32_16x16x32_bf16 v[54:57], v[154:157], v[170:173], 0
	v_mfma_f32_16x16x32_bf16 v[54:57], v[158:161], v[188:191], v[54:57]
	s_setprio 0
	ds_read_b128 v[58:61], v185
	ds_read_b128 v[62:65], v185 offset:1024
	ds_read_b128 v[66:69], v185 offset:2048
	ds_read_b128 v[70:73], v185 offset:3072
	ds_read_b128 v[146:149], v186
	ds_read_b128 v[150:153], v186 offset:1024
	ds_read_b128 v[154:157], v186 offset:2048
	ds_read_b128 v[158:161], v186 offset:3072
	ds_read_b128 v[170:173], v184 offset:32768
	ds_read_b128 v[188:191], v184 offset:33792
	ds_read_b128 v[192:195], v184 offset:34816
	ds_read_b128 v[196:199], v184 offset:35840
	ds_read_b128 v[200:203], v184 offset:36864
	ds_read_b128 v[204:207], v184 offset:37888
	ds_read_b128 v[208:211], v184 offset:38912
	ds_read_b128 v[212:215], v184 offset:39936
	s_mov_b32 s86, m0
	s_mov_b32 m0, s48
	s_nop 0
	global_load_lds_dwordx4 v176, s[36:37]
	s_mov_b32 m0, s86
	s_nop 0
	s_mov_b32 s86, m0
	s_mov_b32 m0, s59
	s_nop 0
	global_load_lds_dwordx4 v178, s[36:37]
	s_mov_b32 m0, s86
	s_add_u32 s36, s36, 0x80000
	s_addc_u32 s37, s37, 0
	s_mov_b32 s86, m0
	s_mov_b32 m0, s62
	s_nop 0
	global_load_lds_dwordx4 v176, s[36:37]
	s_mov_b32 m0, s86
	s_nop 0
	s_mov_b32 s86, m0
	s_mov_b32 m0, s63
	s_nop 0
	global_load_lds_dwordx4 v178, s[36:37]
	s_mov_b32 m0, s86
	s_waitcnt vmcnt(8)
	s_waitcnt lgkmcnt(0)
	s_barrier
	s_setprio 1
	.p2align 3
	v_mfma_f32_16x16x32_bf16 v[142:145], v[58:61], v[170:173], v[142:145]
	v_mfma_f32_16x16x32_bf16 v[142:145], v[62:65], v[188:191], v[142:145]
	v_mfma_f32_16x16x32_bf16 v[138:141], v[66:69], v[170:173], v[138:141]
	v_mfma_f32_16x16x32_bf16 v[138:141], v[70:73], v[188:191], v[138:141]
	v_mfma_f32_16x16x32_bf16 v[126:129], v[58:61], v[192:195], v[126:129]
	v_mfma_f32_16x16x32_bf16 v[126:129], v[62:65], v[196:199], v[126:129]
	v_mfma_f32_16x16x32_bf16 v[122:125], v[66:69], v[192:195], v[122:125]
	v_mfma_f32_16x16x32_bf16 v[122:125], v[70:73], v[196:199], v[122:125]
	v_mfma_f32_16x16x32_bf16 v[110:113], v[58:61], v[200:203], v[110:113]
	v_mfma_f32_16x16x32_bf16 v[110:113], v[62:65], v[204:207], v[110:113]
	v_mfma_f32_16x16x32_bf16 v[106:109], v[66:69], v[200:203], v[106:109]
	v_mfma_f32_16x16x32_bf16 v[106:109], v[70:73], v[204:207], v[106:109]
	v_mfma_f32_16x16x32_bf16 v[94:97], v[58:61], v[208:211], v[94:97]
	v_mfma_f32_16x16x32_bf16 v[94:97], v[62:65], v[212:215], v[94:97]
	v_mfma_f32_16x16x32_bf16 v[90:93], v[66:69], v[208:211], v[90:93]
	v_mfma_f32_16x16x32_bf16 v[90:93], v[70:73], v[212:215], v[90:93]
	v_mfma_f32_16x16x32_bf16 v[134:137], v[146:149], v[170:173], v[134:137]
	v_mfma_f32_16x16x32_bf16 v[134:137], v[150:153], v[188:191], v[134:137]
	v_mfma_f32_16x16x32_bf16 v[130:133], v[154:157], v[170:173], v[130:133]
	v_mfma_f32_16x16x32_bf16 v[130:133], v[158:161], v[188:191], v[130:133]
	v_mfma_f32_16x16x32_bf16 v[118:121], v[146:149], v[192:195], v[118:121]
	v_mfma_f32_16x16x32_bf16 v[118:121], v[150:153], v[196:199], v[118:121]
	v_mfma_f32_16x16x32_bf16 v[114:117], v[154:157], v[192:195], v[114:117]
	v_mfma_f32_16x16x32_bf16 v[114:117], v[158:161], v[196:199], v[114:117]
	v_mfma_f32_16x16x32_bf16 v[102:105], v[146:149], v[200:203], v[102:105]
	v_mfma_f32_16x16x32_bf16 v[102:105], v[150:153], v[204:207], v[102:105]
	v_mfma_f32_16x16x32_bf16 v[98:101], v[154:157], v[200:203], v[98:101]
	v_mfma_f32_16x16x32_bf16 v[98:101], v[158:161], v[204:207], v[98:101]
	v_mfma_f32_16x16x32_bf16 v[86:89], v[146:149], v[208:211], v[86:89]
	v_mfma_f32_16x16x32_bf16 v[86:89], v[150:153], v[212:215], v[86:89]
	s_setprio 2
	s_barrier
	v_mfma_f32_16x16x32_bf16 v[82:85], v[154:157], v[208:211], v[82:85]
	v_mfma_f32_16x16x32_bf16 v[82:85], v[158:161], v[212:215], v[82:85]
	s_setprio 0
	ds_read_b128 v[170:173], v184 offset:49152
	ds_read_b128 v[188:191], v184 offset:50176
	ds_read_b128 v[192:195], v184 offset:51200
	ds_read_b128 v[196:199], v184 offset:52224
	ds_read_b128 v[200:203], v184 offset:53248
	ds_read_b128 v[204:207], v184 offset:54272
	ds_read_b128 v[208:211], v184 offset:55296
	ds_read_b128 v[212:215], v184 offset:56320
	s_add_u32 s36, s34, 0x80
	s_addc_u32 s37, s35, 0
	s_mov_b32 s86, m0
	s_mov_b32 m0, s64
	s_nop 0
	global_load_lds_dwordx4 v177, s[36:37]
	s_mov_b32 m0, s86
	s_add_u32 s34, s34, 0x80080
	s_mov_b32 s86, m0
	s_mov_b32 m0, s65
	s_nop 0
	global_load_lds_dwordx4 v179, s[36:37]
	s_mov_b32 m0, s86
	s_addc_u32 s35, s35, 0
	s_mov_b32 s36, m0
	s_mov_b32 m0, s66
	s_nop 0
	global_load_lds_dwordx4 v177, s[34:35]
	s_mov_b32 m0, s36
	s_nop 0
	s_mov_b32 s36, m0
	s_mov_b32 m0, s67
	s_nop 0
	global_load_lds_dwordx4 v179, s[34:35]
	s_mov_b32 m0, s36
	s_waitcnt vmcnt(4)
	s_waitcnt lgkmcnt(0)
	s_barrier
	s_setprio 1
	.p2align 3
	v_mfma_f32_16x16x32_bf16 v[78:81], v[58:61], v[170:173], v[78:81]
	v_mfma_f32_16x16x32_bf16 v[78:81], v[62:65], v[188:191], v[78:81]
	v_mfma_f32_16x16x32_bf16 v[74:77], v[66:69], v[170:173], v[74:77]
	v_mfma_f32_16x16x32_bf16 v[74:77], v[70:73], v[188:191], v[74:77]
	v_mfma_f32_16x16x32_bf16 v[50:53], v[58:61], v[192:195], v[50:53]
	v_mfma_f32_16x16x32_bf16 v[50:53], v[62:65], v[196:199], v[50:53]
	v_mfma_f32_16x16x32_bf16 v[42:45], v[66:69], v[192:195], v[42:45]
	v_mfma_f32_16x16x32_bf16 v[42:45], v[70:73], v[196:199], v[42:45]
	v_mfma_f32_16x16x32_bf16 v[30:33], v[58:61], v[200:203], v[30:33]
	v_mfma_f32_16x16x32_bf16 v[30:33], v[62:65], v[204:207], v[30:33]
	v_mfma_f32_16x16x32_bf16 v[26:29], v[66:69], v[200:203], v[26:29]
	v_mfma_f32_16x16x32_bf16 v[26:29], v[70:73], v[204:207], v[26:29]
	v_mfma_f32_16x16x32_bf16 v[14:17], v[58:61], v[208:211], v[14:17]
	v_mfma_f32_16x16x32_bf16 v[14:17], v[62:65], v[212:215], v[14:17]
	v_mfma_f32_16x16x32_bf16 v[10:13], v[66:69], v[208:211], v[10:13]
	v_mfma_f32_16x16x32_bf16 v[10:13], v[70:73], v[212:215], v[10:13]
	v_mfma_f32_16x16x32_bf16 v[46:49], v[146:149], v[170:173], v[46:49]
	v_mfma_f32_16x16x32_bf16 v[70:73], v[150:153], v[188:191], v[46:49]
	v_mfma_f32_16x16x32_bf16 v[46:49], v[154:157], v[170:173], v[54:57]
	v_mfma_f32_16x16x32_bf16 v[66:69], v[158:161], v[188:191], v[46:49]
	v_mfma_f32_16x16x32_bf16 v[38:41], v[146:149], v[192:195], v[38:41]
	v_mfma_f32_16x16x32_bf16 v[38:41], v[150:153], v[196:199], v[38:41]
	v_mfma_f32_16x16x32_bf16 v[34:37], v[154:157], v[192:195], v[34:37]
	v_mfma_f32_16x16x32_bf16 v[34:37], v[158:161], v[196:199], v[34:37]
	v_mfma_f32_16x16x32_bf16 v[22:25], v[146:149], v[200:203], v[22:25]
	v_mfma_f32_16x16x32_bf16 v[22:25], v[150:153], v[204:207], v[22:25]
	v_mfma_f32_16x16x32_bf16 v[18:21], v[154:157], v[200:203], v[18:21]
	v_mfma_f32_16x16x32_bf16 v[18:21], v[158:161], v[204:207], v[18:21]
	v_mfma_f32_16x16x32_bf16 v[6:9], v[146:149], v[208:211], v[6:9]
	v_mfma_f32_16x16x32_bf16 v[6:9], v[150:153], v[212:215], v[6:9]
	s_setprio 2
	s_barrier
	v_mfma_f32_16x16x32_bf16 v[2:5], v[154:157], v[208:211], v[2:5]
	v_mfma_f32_16x16x32_bf16 v[2:5], v[158:161], v[212:215], v[2:5]
	s_setprio 0
	s_add_i32 s83, s83, 2
	s_add_u32 s79, s79, 0x100
	s_addc_u32 s80, s80, 0
	s_add_u32 s30, s30, 0x100
	s_addc_u32 s31, s31, 0
	s_add_u32 s81, s81, 0x100
	s_addc_u32 s82, s82, 0
	s_cmp_gt_u32 s83, 29
	.p2align 6
.LBB0_1538:
	ds_read_b128 v[46:49], v182
	ds_read_b128 v[54:57], v182 offset:1024
	ds_read_b128 v[58:61], v182 offset:2048
	ds_read_b128 v[62:65], v182 offset:3072
	ds_read_b128 v[146:149], v183
	ds_read_b128 v[150:153], v183 offset:1024
	ds_read_b128 v[154:157], v183 offset:2048
	ds_read_b128 v[158:161], v183 offset:3072
	s_cmp_eq_u32 s83, 28
	s_cselect_b32 s35, s21, s80
	s_cselect_b32 s34, s29, s79
	s_cselect_b32 s37, s7, s82
	s_cselect_b32 s36, s23, s81
	ds_read_b128 v[170:173], v184
	ds_read_b128 v[188:191], v184 offset:1024
	ds_read_b128 v[192:195], v184 offset:2048
	ds_read_b128 v[196:199], v184 offset:3072
	ds_read_b128 v[200:203], v184 offset:4096
	ds_read_b128 v[204:207], v184 offset:5120
	ds_read_b128 v[208:211], v184 offset:6144
	ds_read_b128 v[212:215], v184 offset:7168
	s_add_u32 s86, s30, 0xfff80000
	s_addc_u32 s87, s31, -1
	s_mov_b32 s92, m0
	s_mov_b32 m0, s73
	s_nop 0
	global_load_lds_dwordx4 v176, s[86:87]
	s_mov_b32 m0, s92
	s_nop 0
	s_mov_b32 s92, m0
	s_mov_b32 m0, s75
	s_nop 0
	global_load_lds_dwordx4 v178, s[86:87]
	s_mov_b32 m0, s92
	s_mov_b32 s86, m0
	s_mov_b32 m0, s74
	s_nop 0
	global_load_lds_dwordx4 v176, s[30:31]
	s_mov_b32 m0, s86
	s_nop 0
	s_mov_b32 s86, m0
	s_mov_b32 m0, s76
	s_nop 0
	global_load_lds_dwordx4 v178, s[30:31]
	s_mov_b32 m0, s86
	s_waitcnt vmcnt(8)
	s_waitcnt lgkmcnt(0)
	s_barrier
	s_setprio 1
	.p2align 3
	v_mfma_f32_16x16x32_bf16 v[142:145], v[46:49], v[170:173], v[142:145]
	v_mfma_f32_16x16x32_bf16 v[142:145], v[54:57], v[188:191], v[142:145]
	v_mfma_f32_16x16x32_bf16 v[138:141], v[58:61], v[170:173], v[138:141]
	v_mfma_f32_16x16x32_bf16 v[138:141], v[62:65], v[188:191], v[138:141]
	v_mfma_f32_16x16x32_bf16 v[126:129], v[46:49], v[192:195], v[126:129]
	v_mfma_f32_16x16x32_bf16 v[126:129], v[54:57], v[196:199], v[126:129]
	v_mfma_f32_16x16x32_bf16 v[122:125], v[58:61], v[192:195], v[122:125]
	v_mfma_f32_16x16x32_bf16 v[122:125], v[62:65], v[196:199], v[122:125]
	v_mfma_f32_16x16x32_bf16 v[110:113], v[46:49], v[200:203], v[110:113]
	v_mfma_f32_16x16x32_bf16 v[110:113], v[54:57], v[204:207], v[110:113]
	v_mfma_f32_16x16x32_bf16 v[106:109], v[58:61], v[200:203], v[106:109]
	v_mfma_f32_16x16x32_bf16 v[106:109], v[62:65], v[204:207], v[106:109]
	v_mfma_f32_16x16x32_bf16 v[94:97], v[46:49], v[208:211], v[94:97]
	v_mfma_f32_16x16x32_bf16 v[94:97], v[54:57], v[212:215], v[94:97]
	v_mfma_f32_16x16x32_bf16 v[90:93], v[58:61], v[208:211], v[90:93]
	v_mfma_f32_16x16x32_bf16 v[90:93], v[62:65], v[212:215], v[90:93]
	v_mfma_f32_16x16x32_bf16 v[134:137], v[146:149], v[170:173], v[134:137]
	v_mfma_f32_16x16x32_bf16 v[134:137], v[150:153], v[188:191], v[134:137]
	v_mfma_f32_16x16x32_bf16 v[130:133], v[154:157], v[170:173], v[130:133]
	v_mfma_f32_16x16x32_bf16 v[130:133], v[158:161], v[188:191], v[130:133]
	v_mfma_f32_16x16x32_bf16 v[118:121], v[146:149], v[192:195], v[118:121]
	v_mfma_f32_16x16x32_bf16 v[118:121], v[150:153], v[196:199], v[118:121]
	v_mfma_f32_16x16x32_bf16 v[114:117], v[154:157], v[192:195], v[114:117]
	v_mfma_f32_16x16x32_bf16 v[114:117], v[158:161], v[196:199], v[114:117]
	v_mfma_f32_16x16x32_bf16 v[102:105], v[146:149], v[200:203], v[102:105]
	v_mfma_f32_16x16x32_bf16 v[102:105], v[150:153], v[204:207], v[102:105]
	v_mfma_f32_16x16x32_bf16 v[98:101], v[154:157], v[200:203], v[98:101]
	v_mfma_f32_16x16x32_bf16 v[98:101], v[158:161], v[204:207], v[98:101]
	v_mfma_f32_16x16x32_bf16 v[86:89], v[146:149], v[208:211], v[86:89]
	v_mfma_f32_16x16x32_bf16 v[86:89], v[150:153], v[212:215], v[86:89]
	s_setprio 2
	s_barrier
	v_mfma_f32_16x16x32_bf16 v[82:85], v[154:157], v[208:211], v[82:85]
	v_mfma_f32_16x16x32_bf16 v[82:85], v[158:161], v[212:215], v[82:85]
	s_setprio 0
	ds_read_b128 v[170:173], v184 offset:16384
	ds_read_b128 v[188:191], v184 offset:17408
	ds_read_b128 v[192:195], v184 offset:18432
	ds_read_b128 v[196:199], v184 offset:19456
	ds_read_b128 v[200:203], v184 offset:20480
	ds_read_b128 v[204:207], v184 offset:21504
	ds_read_b128 v[208:211], v184 offset:22528
	ds_read_b128 v[212:215], v184 offset:23552
	s_mov_b32 s86, m0
	s_mov_b32 m0, s49
	s_nop 0
	global_load_lds_dwordx4 v177, s[34:35]
	s_mov_b32 m0, s86
	s_nop 0
	s_mov_b32 s86, m0
	s_mov_b32 m0, s56
	s_nop 0
	global_load_lds_dwordx4 v179, s[34:35]
	s_mov_b32 m0, s86
	s_add_u32 s86, s34, 0x80000
	s_addc_u32 s87, s35, 0
	s_mov_b32 s92, m0
	s_mov_b32 m0, s57
	s_nop 0
	global_load_lds_dwordx4 v177, s[86:87]
	s_mov_b32 m0, s92
	s_nop 0
	s_mov_b32 s92, m0
	s_mov_b32 m0, s58
	s_nop 0
	global_load_lds_dwordx4 v179, s[86:87]
	s_mov_b32 m0, s92
	s_waitcnt vmcnt(4)
	s_waitcnt lgkmcnt(0)
	s_barrier
	s_setprio 1
	.p2align 3
	v_mfma_f32_16x16x32_bf16 v[78:81], v[46:49], v[170:173], v[78:81]
	v_mfma_f32_16x16x32_bf16 v[78:81], v[54:57], v[188:191], v[78:81]
	v_mfma_f32_16x16x32_bf16 v[74:77], v[58:61], v[170:173], v[74:77]
	v_mfma_f32_16x16x32_bf16 v[74:77], v[62:65], v[188:191], v[74:77]
	v_mfma_f32_16x16x32_bf16 v[50:53], v[46:49], v[192:195], v[50:53]
	v_mfma_f32_16x16x32_bf16 v[50:53], v[54:57], v[196:199], v[50:53]
	v_mfma_f32_16x16x32_bf16 v[42:45], v[58:61], v[192:195], v[42:45]
	v_mfma_f32_16x16x32_bf16 v[42:45], v[62:65], v[196:199], v[42:45]
	v_mfma_f32_16x16x32_bf16 v[30:33], v[46:49], v[200:203], v[30:33]
	v_mfma_f32_16x16x32_bf16 v[30:33], v[54:57], v[204:207], v[30:33]
	v_mfma_f32_16x16x32_bf16 v[26:29], v[58:61], v[200:203], v[26:29]
	v_mfma_f32_16x16x32_bf16 v[26:29], v[62:65], v[204:207], v[26:29]
	v_mfma_f32_16x16x32_bf16 v[14:17], v[46:49], v[208:211], v[14:17]
	v_mfma_f32_16x16x32_bf16 v[14:17], v[54:57], v[212:215], v[14:17]
	v_mfma_f32_16x16x32_bf16 v[10:13], v[58:61], v[208:211], v[10:13]
	v_mfma_f32_16x16x32_bf16 v[10:13], v[62:65], v[212:215], v[10:13]
	v_mfma_f32_16x16x32_bf16 v[38:41], v[146:149], v[192:195], v[38:41]
	v_mfma_f32_16x16x32_bf16 v[38:41], v[150:153], v[196:199], v[38:41]
	v_mfma_f32_16x16x32_bf16 v[34:37], v[154:157], v[192:195], v[34:37]
	v_mfma_f32_16x16x32_bf16 v[34:37], v[158:161], v[196:199], v[34:37]
	v_mfma_f32_16x16x32_bf16 v[22:25], v[146:149], v[200:203], v[22:25]
	v_mfma_f32_16x16x32_bf16 v[22:25], v[150:153], v[204:207], v[22:25]
	v_mfma_f32_16x16x32_bf16 v[18:21], v[154:157], v[200:203], v[18:21]
	v_mfma_f32_16x16x32_bf16 v[18:21], v[158:161], v[204:207], v[18:21]
	v_mfma_f32_16x16x32_bf16 v[6:9], v[146:149], v[208:211], v[6:9]
	v_mfma_f32_16x16x32_bf16 v[6:9], v[150:153], v[212:215], v[6:9]
	v_mfma_f32_16x16x32_bf16 v[2:5], v[154:157], v[208:211], v[2:5]
	v_mfma_f32_16x16x32_bf16 v[2:5], v[158:161], v[212:215], v[2:5]
	v_mfma_f32_16x16x32_bf16 v[46:49], v[146:149], v[170:173], v[70:73]
	v_mfma_f32_16x16x32_bf16 v[46:49], v[150:153], v[188:191], v[46:49]
	s_setprio 2
	s_barrier
	v_mfma_f32_16x16x32_bf16 v[54:57], v[154:157], v[170:173], v[66:69]
	v_mfma_f32_16x16x32_bf16 v[54:57], v[158:161], v[188:191], v[54:57]
	s_setprio 0
	ds_read_b128 v[58:61], v185
	ds_read_b128 v[62:65], v185 offset:1024
	ds_read_b128 v[66:69], v185 offset:2048
	ds_read_b128 v[70:73], v185 offset:3072
	ds_read_b128 v[146:149], v186
	ds_read_b128 v[150:153], v186 offset:1024
	ds_read_b128 v[154:157], v186 offset:2048
	ds_read_b128 v[158:161], v186 offset:3072
	ds_read_b128 v[170:173], v184 offset:32768
	ds_read_b128 v[188:191], v184 offset:33792
	ds_read_b128 v[192:195], v184 offset:34816
	ds_read_b128 v[196:199], v184 offset:35840
	ds_read_b128 v[200:203], v184 offset:36864
	ds_read_b128 v[204:207], v184 offset:37888
	ds_read_b128 v[208:211], v184 offset:38912
	ds_read_b128 v[212:215], v184 offset:39936
	s_mov_b32 s86, m0
	s_mov_b32 m0, s48
	s_nop 0
	global_load_lds_dwordx4 v176, s[36:37]
	s_mov_b32 m0, s86
	s_nop 0
	s_mov_b32 s86, m0
	s_mov_b32 m0, s59
	s_nop 0
	global_load_lds_dwordx4 v178, s[36:37]
	s_mov_b32 m0, s86
	s_add_u32 s36, s36, 0x80000
	s_addc_u32 s37, s37, 0
	s_mov_b32 s86, m0
	s_mov_b32 m0, s62
	s_nop 0
	global_load_lds_dwordx4 v176, s[36:37]
	s_mov_b32 m0, s86
	s_nop 0
	s_mov_b32 s86, m0
	s_mov_b32 m0, s63
	s_nop 0
	global_load_lds_dwordx4 v178, s[36:37]
	s_mov_b32 m0, s86
	s_waitcnt vmcnt(8)
	s_waitcnt lgkmcnt(0)
	s_barrier
	s_setprio 1
	.p2align 3
	v_mfma_f32_16x16x32_bf16 v[142:145], v[58:61], v[170:173], v[142:145]
	v_mfma_f32_16x16x32_bf16 v[142:145], v[62:65], v[188:191], v[142:145]
	v_mfma_f32_16x16x32_bf16 v[138:141], v[66:69], v[170:173], v[138:141]
	v_mfma_f32_16x16x32_bf16 v[138:141], v[70:73], v[188:191], v[138:141]
	v_mfma_f32_16x16x32_bf16 v[126:129], v[58:61], v[192:195], v[126:129]
	v_mfma_f32_16x16x32_bf16 v[126:129], v[62:65], v[196:199], v[126:129]
	v_mfma_f32_16x16x32_bf16 v[122:125], v[66:69], v[192:195], v[122:125]
	v_mfma_f32_16x16x32_bf16 v[122:125], v[70:73], v[196:199], v[122:125]
	v_mfma_f32_16x16x32_bf16 v[110:113], v[58:61], v[200:203], v[110:113]
	v_mfma_f32_16x16x32_bf16 v[110:113], v[62:65], v[204:207], v[110:113]
	v_mfma_f32_16x16x32_bf16 v[106:109], v[66:69], v[200:203], v[106:109]
	v_mfma_f32_16x16x32_bf16 v[106:109], v[70:73], v[204:207], v[106:109]
	v_mfma_f32_16x16x32_bf16 v[94:97], v[58:61], v[208:211], v[94:97]
	v_mfma_f32_16x16x32_bf16 v[94:97], v[62:65], v[212:215], v[94:97]
	v_mfma_f32_16x16x32_bf16 v[90:93], v[66:69], v[208:211], v[90:93]
	v_mfma_f32_16x16x32_bf16 v[90:93], v[70:73], v[212:215], v[90:93]
	v_mfma_f32_16x16x32_bf16 v[134:137], v[146:149], v[170:173], v[134:137]
	v_mfma_f32_16x16x32_bf16 v[134:137], v[150:153], v[188:191], v[134:137]
	v_mfma_f32_16x16x32_bf16 v[130:133], v[154:157], v[170:173], v[130:133]
	v_mfma_f32_16x16x32_bf16 v[130:133], v[158:161], v[188:191], v[130:133]
	v_mfma_f32_16x16x32_bf16 v[118:121], v[146:149], v[192:195], v[118:121]
	v_mfma_f32_16x16x32_bf16 v[118:121], v[150:153], v[196:199], v[118:121]
	v_mfma_f32_16x16x32_bf16 v[114:117], v[154:157], v[192:195], v[114:117]
	v_mfma_f32_16x16x32_bf16 v[114:117], v[158:161], v[196:199], v[114:117]
	v_mfma_f32_16x16x32_bf16 v[102:105], v[146:149], v[200:203], v[102:105]
	v_mfma_f32_16x16x32_bf16 v[102:105], v[150:153], v[204:207], v[102:105]
	v_mfma_f32_16x16x32_bf16 v[98:101], v[154:157], v[200:203], v[98:101]
	v_mfma_f32_16x16x32_bf16 v[98:101], v[158:161], v[204:207], v[98:101]
	v_mfma_f32_16x16x32_bf16 v[86:89], v[146:149], v[208:211], v[86:89]
	v_mfma_f32_16x16x32_bf16 v[86:89], v[150:153], v[212:215], v[86:89]
	s_setprio 2
	s_barrier
	v_mfma_f32_16x16x32_bf16 v[82:85], v[154:157], v[208:211], v[82:85]
	v_mfma_f32_16x16x32_bf16 v[82:85], v[158:161], v[212:215], v[82:85]
	s_setprio 0
	ds_read_b128 v[170:173], v184 offset:49152
	ds_read_b128 v[188:191], v184 offset:50176
	ds_read_b128 v[192:195], v184 offset:51200
	ds_read_b128 v[196:199], v184 offset:52224
	ds_read_b128 v[200:203], v184 offset:53248
	ds_read_b128 v[204:207], v184 offset:54272
	ds_read_b128 v[208:211], v184 offset:55296
	ds_read_b128 v[212:215], v184 offset:56320
	s_add_u32 s36, s34, 0x80
	s_addc_u32 s37, s35, 0
	s_mov_b32 s86, m0
	s_mov_b32 m0, s64
	s_nop 0
	global_load_lds_dwordx4 v177, s[36:37]
	s_mov_b32 m0, s86
	s_add_u32 s34, s34, 0x80080
	s_mov_b32 s86, m0
	s_mov_b32 m0, s65
	s_nop 0
	global_load_lds_dwordx4 v179, s[36:37]
	s_mov_b32 m0, s86
	s_addc_u32 s35, s35, 0
	s_mov_b32 s36, m0
	s_mov_b32 m0, s66
	s_nop 0
	global_load_lds_dwordx4 v177, s[34:35]
	s_mov_b32 m0, s36
	s_nop 0
	s_mov_b32 s36, m0
	s_mov_b32 m0, s67
	s_nop 0
	global_load_lds_dwordx4 v179, s[34:35]
	s_mov_b32 m0, s36
	s_waitcnt vmcnt(4)
	s_waitcnt lgkmcnt(0)
	s_barrier
	s_setprio 1
	.p2align 3
	v_mfma_f32_16x16x32_bf16 v[78:81], v[58:61], v[170:173], v[78:81]
	v_mfma_f32_16x16x32_bf16 v[78:81], v[62:65], v[188:191], v[78:81]
	v_mfma_f32_16x16x32_bf16 v[74:77], v[66:69], v[170:173], v[74:77]
	v_mfma_f32_16x16x32_bf16 v[74:77], v[70:73], v[188:191], v[74:77]
	v_mfma_f32_16x16x32_bf16 v[50:53], v[58:61], v[192:195], v[50:53]
	v_mfma_f32_16x16x32_bf16 v[50:53], v[62:65], v[196:199], v[50:53]
	v_mfma_f32_16x16x32_bf16 v[42:45], v[66:69], v[192:195], v[42:45]
	v_mfma_f32_16x16x32_bf16 v[42:45], v[70:73], v[196:199], v[42:45]
	v_mfma_f32_16x16x32_bf16 v[30:33], v[58:61], v[200:203], v[30:33]
	v_mfma_f32_16x16x32_bf16 v[30:33], v[62:65], v[204:207], v[30:33]
	v_mfma_f32_16x16x32_bf16 v[26:29], v[66:69], v[200:203], v[26:29]
	v_mfma_f32_16x16x32_bf16 v[26:29], v[70:73], v[204:207], v[26:29]
	v_mfma_f32_16x16x32_bf16 v[14:17], v[58:61], v[208:211], v[14:17]
	v_mfma_f32_16x16x32_bf16 v[14:17], v[62:65], v[212:215], v[14:17]
	v_mfma_f32_16x16x32_bf16 v[10:13], v[66:69], v[208:211], v[10:13]
	v_mfma_f32_16x16x32_bf16 v[10:13], v[70:73], v[212:215], v[10:13]
	v_mfma_f32_16x16x32_bf16 v[46:49], v[146:149], v[170:173], v[46:49]
	v_mfma_f32_16x16x32_bf16 v[70:73], v[150:153], v[188:191], v[46:49]
	v_mfma_f32_16x16x32_bf16 v[46:49], v[154:157], v[170:173], v[54:57]
	v_mfma_f32_16x16x32_bf16 v[66:69], v[158:161], v[188:191], v[46:49]
	v_mfma_f32_16x16x32_bf16 v[38:41], v[146:149], v[192:195], v[38:41]
	v_mfma_f32_16x16x32_bf16 v[38:41], v[150:153], v[196:199], v[38:41]
	v_mfma_f32_16x16x32_bf16 v[34:37], v[154:157], v[192:195], v[34:37]
	v_mfma_f32_16x16x32_bf16 v[34:37], v[158:161], v[196:199], v[34:37]
	v_mfma_f32_16x16x32_bf16 v[22:25], v[146:149], v[200:203], v[22:25]
	v_mfma_f32_16x16x32_bf16 v[22:25], v[150:153], v[204:207], v[22:25]
	v_mfma_f32_16x16x32_bf16 v[18:21], v[154:157], v[200:203], v[18:21]
	v_mfma_f32_16x16x32_bf16 v[18:21], v[158:161], v[204:207], v[18:21]
	v_mfma_f32_16x16x32_bf16 v[6:9], v[146:149], v[208:211], v[6:9]
	v_mfma_f32_16x16x32_bf16 v[6:9], v[150:153], v[212:215], v[6:9]
	s_setprio 2
	s_barrier
	v_mfma_f32_16x16x32_bf16 v[2:5], v[154:157], v[208:211], v[2:5]
	v_mfma_f32_16x16x32_bf16 v[2:5], v[158:161], v[212:215], v[2:5]
	s_setprio 0
	s_add_i32 s83, s83, 2
	s_add_u32 s79, s79, 0x100
	s_addc_u32 s80, s80, 0
	s_add_u32 s30, s30, 0x100
	s_addc_u32 s31, s31, 0
	s_add_u32 s81, s81, 0x100
	s_addc_u32 s82, s82, 0
	s_cmp_gt_u32 s83, 29
	s_cbranch_scc0 .LBB0_1538
	s_and_b64 vcc, exec, s[16:17]
	s_cbranch_vccz .LBB0_1541
	s_barrier

.LBB0_1784:
	s_ashr_i32 s11, s10, 31
	s_lshl_b64 s[12:13], s[10:11], 20
	s_add_u32 s12, s26, s12
	s_addc_u32 s13, s27, s13
	s_and_b64 s[14:15], s[2:3], exec
	s_cselect_b32 s11, s13, s21
	s_cselect_b32 s64, s12, s20
	s_ashr_i32 s9, s8, 31
	s_lshl_b64 s[14:15], s[8:9], 20
	s_add_u32 s14, s28, s14
	s_addc_u32 s15, s29, s15
	s_and_b64 s[22:23], s[2:3], exec
	s_cselect_b32 s9, s15, s19
	s_cselect_b32 s65, s14, s18
	s_add_u32 s66, s18, 0x100
	s_addc_u32 s67, s19, 0
	s_add_u32 s18, s20, 0x80080
	s_addc_u32 s19, s21, 0
	s_add_u32 s70, s20, 0x100
	s_addc_u32 s71, s21, 0
	s_mov_b32 s73, -2
	ds_read_b128 v[148:151], v143
	ds_read_b128 v[152:155], v143 offset:1024
	ds_read_b128 v[156:159], v143 offset:2048
	ds_read_b128 v[160:163], v143 offset:3072
	ds_read_b128 v[164:167], v144
	ds_read_b128 v[168:171], v144 offset:1024
	ds_read_b128 v[172:175], v144 offset:2048
	ds_read_b128 v[176:179], v144 offset:3072
	s_cmp_eq_u32 s73, 28
	s_cselect_b32 s21, s9, s67
	s_cselect_b32 s20, s65, s66
	s_cselect_b32 s23, s11, s71
	s_cselect_b32 s22, s64, s70
	ds_read_b128 v[180:183], v145
	ds_read_b128 v[184:187], v145 offset:1024
	ds_read_b128 v[188:191], v145 offset:2048
	ds_read_b128 v[192:195], v145 offset:3072
	ds_read_b128 v[196:199], v145 offset:4096
	ds_read_b128 v[200:203], v145 offset:5120
	ds_read_b128 v[204:207], v145 offset:6144
	ds_read_b128 v[208:211], v145 offset:7168
	s_add_u32 s74, s18, 0xfff80000
	s_addc_u32 s75, s19, -1
	s_mov_b32 s76, m0
	s_mov_b32 m0, s56
	s_nop 0
	global_load_lds_dwordx4 v138, s[74:75]
	s_mov_b32 m0, s76
	s_nop 0
	s_mov_b32 s76, m0
	s_mov_b32 m0, s59
	s_nop 0
	global_load_lds_dwordx4 v140, s[74:75]
	s_mov_b32 m0, s76
	s_mov_b32 s74, m0
	s_mov_b32 m0, s57
	s_nop 0
	global_load_lds_dwordx4 v138, s[18:19]
	s_mov_b32 m0, s74
	s_nop 0
	s_mov_b32 s74, m0
	s_mov_b32 m0, s62
	s_nop 0
	global_load_lds_dwordx4 v140, s[18:19]
	s_mov_b32 m0, s74
	s_waitcnt vmcnt(8)
	s_waitcnt lgkmcnt(0)
	s_barrier
	s_setprio 1
	.p2align 3
	v_mfma_f32_16x16x32_bf16 v[126:129], v[148:151], v[180:183], 0
	v_mfma_f32_16x16x32_bf16 v[126:129], v[152:155], v[184:187], v[126:129]
	v_mfma_f32_16x16x32_bf16 v[122:125], v[156:159], v[180:183], 0
	v_mfma_f32_16x16x32_bf16 v[122:125], v[160:163], v[184:187], v[122:125]
	v_mfma_f32_16x16x32_bf16 v[106:109], v[156:159], v[188:191], 0
	v_mfma_f32_16x16x32_bf16 v[106:109], v[160:163], v[192:195], v[106:109]
	v_mfma_f32_16x16x32_bf16 v[110:113], v[148:151], v[188:191], 0
	v_mfma_f32_16x16x32_bf16 v[110:113], v[152:155], v[192:195], v[110:113]
	v_mfma_f32_16x16x32_bf16 v[94:97], v[148:151], v[196:199], 0
	v_mfma_f32_16x16x32_bf16 v[94:97], v[152:155], v[200:203], v[94:97]
	v_mfma_f32_16x16x32_bf16 v[90:93], v[156:159], v[196:199], 0
	v_mfma_f32_16x16x32_bf16 v[90:93], v[160:163], v[200:203], v[90:93]
	v_mfma_f32_16x16x32_bf16 v[74:77], v[156:159], v[204:207], 0
	v_mfma_f32_16x16x32_bf16 v[74:77], v[160:163], v[208:211], v[74:77]
	v_mfma_f32_16x16x32_bf16 v[78:81], v[148:151], v[204:207], 0
	v_mfma_f32_16x16x32_bf16 v[78:81], v[152:155], v[208:211], v[78:81]
	v_mfma_f32_16x16x32_bf16 v[118:121], v[164:167], v[180:183], 0
	v_mfma_f32_16x16x32_bf16 v[118:121], v[168:171], v[184:187], v[118:121]
	v_mfma_f32_16x16x32_bf16 v[114:117], v[172:175], v[180:183], 0
	v_mfma_f32_16x16x32_bf16 v[114:117], v[176:179], v[184:187], v[114:117]
	v_mfma_f32_16x16x32_bf16 v[98:101], v[172:175], v[188:191], 0
	v_mfma_f32_16x16x32_bf16 v[98:101], v[176:179], v[192:195], v[98:101]
	v_mfma_f32_16x16x32_bf16 v[102:105], v[164:167], v[188:191], 0
	v_mfma_f32_16x16x32_bf16 v[102:105], v[168:171], v[192:195], v[102:105]
	v_mfma_f32_16x16x32_bf16 v[86:89], v[164:167], v[196:199], 0
	v_mfma_f32_16x16x32_bf16 v[86:89], v[168:171], v[200:203], v[86:89]
	v_mfma_f32_16x16x32_bf16 v[82:85], v[172:175], v[196:199], 0
	v_mfma_f32_16x16x32_bf16 v[82:85], v[176:179], v[200:203], v[82:85]
	v_mfma_f32_16x16x32_bf16 v[66:69], v[172:175], v[204:207], 0
	v_mfma_f32_16x16x32_bf16 v[66:69], v[176:179], v[208:211], v[66:69]
	s_setprio 2
	s_barrier
	v_mfma_f32_16x16x32_bf16 v[70:73], v[164:167], v[204:207], 0
	v_mfma_f32_16x16x32_bf16 v[70:73], v[168:171], v[208:211], v[70:73]
	s_setprio 0
	ds_read_b128 v[180:183], v145 offset:16384
	ds_read_b128 v[184:187], v145 offset:17408
	ds_read_b128 v[188:191], v145 offset:18432
	ds_read_b128 v[192:195], v145 offset:19456
	ds_read_b128 v[196:199], v145 offset:20480
	ds_read_b128 v[200:203], v145 offset:21504
	ds_read_b128 v[204:207], v145 offset:22528
	ds_read_b128 v[208:211], v145 offset:23552
	s_mov_b32 s74, m0
	s_mov_b32 m0, s35
	s_nop 0
	global_load_lds_dwordx4 v139, s[20:21]
	s_mov_b32 m0, s74
	s_nop 0
	s_mov_b32 s74, m0
	s_mov_b32 m0, s36
	s_nop 0
	global_load_lds_dwordx4 v141, s[20:21]
	s_mov_b32 m0, s74
	s_add_u32 s74, s20, 0x80000
	s_addc_u32 s75, s21, 0
	s_mov_b32 s76, m0
	s_mov_b32 m0, s37
	s_nop 0
	global_load_lds_dwordx4 v139, s[74:75]
	s_mov_b32 m0, s76
	s_nop 0
	s_mov_b32 s76, m0
	s_mov_b32 m0, s40
	s_nop 0
	global_load_lds_dwordx4 v141, s[74:75]
	s_mov_b32 m0, s76
	s_waitcnt vmcnt(4)
	s_waitcnt lgkmcnt(0)
	s_barrier
	s_setprio 1
	.p2align 3
	v_mfma_f32_16x16x32_bf16 v[62:65], v[148:151], v[180:183], 0
	v_mfma_f32_16x16x32_bf16 v[62:65], v[152:155], v[184:187], v[62:65]
	v_mfma_f32_16x16x32_bf16 v[58:61], v[156:159], v[180:183], 0
	v_mfma_f32_16x16x32_bf16 v[58:61], v[160:163], v[184:187], v[58:61]
	v_mfma_f32_16x16x32_bf16 v[42:45], v[156:159], v[188:191], 0
	v_mfma_f32_16x16x32_bf16 v[42:45], v[160:163], v[192:195], v[42:45]
	v_mfma_f32_16x16x32_bf16 v[46:49], v[148:151], v[188:191], 0
	v_mfma_f32_16x16x32_bf16 v[46:49], v[152:155], v[192:195], v[46:49]
	v_mfma_f32_16x16x32_bf16 v[30:33], v[148:151], v[196:199], 0
	v_mfma_f32_16x16x32_bf16 v[30:33], v[152:155], v[200:203], v[30:33]
	v_mfma_f32_16x16x32_bf16 v[26:29], v[156:159], v[196:199], 0
	v_mfma_f32_16x16x32_bf16 v[26:29], v[160:163], v[200:203], v[26:29]
	v_mfma_f32_16x16x32_bf16 v[10:13], v[156:159], v[204:207], 0
	v_mfma_f32_16x16x32_bf16 v[10:13], v[160:163], v[208:211], v[10:13]
	v_mfma_f32_16x16x32_bf16 v[14:17], v[148:151], v[204:207], 0
	v_mfma_f32_16x16x32_bf16 v[14:17], v[152:155], v[208:211], v[14:17]
	v_mfma_f32_16x16x32_bf16 v[54:57], v[164:167], v[180:183], 0
	v_mfma_f32_16x16x32_bf16 v[54:57], v[168:171], v[184:187], v[54:57]
	v_mfma_f32_16x16x32_bf16 v[50:53], v[172:175], v[180:183], 0
	v_mfma_f32_16x16x32_bf16 v[50:53], v[176:179], v[184:187], v[50:53]
	v_mfma_f32_16x16x32_bf16 v[34:37], v[172:175], v[188:191], 0
	v_mfma_f32_16x16x32_bf16 v[34:37], v[176:179], v[192:195], v[34:37]
	v_mfma_f32_16x16x32_bf16 v[38:41], v[164:167], v[188:191], 0
	v_mfma_f32_16x16x32_bf16 v[38:41], v[168:171], v[192:195], v[38:41]
	v_mfma_f32_16x16x32_bf16 v[22:25], v[164:167], v[196:199], 0
	v_mfma_f32_16x16x32_bf16 v[22:25], v[168:171], v[200:203], v[22:25]
	v_mfma_f32_16x16x32_bf16 v[18:21], v[172:175], v[196:199], 0
	v_mfma_f32_16x16x32_bf16 v[18:21], v[176:179], v[200:203], v[18:21]
	v_mfma_f32_16x16x32_bf16 v[2:5], v[172:175], v[204:207], 0
	v_mfma_f32_16x16x32_bf16 v[2:5], v[176:179], v[208:211], v[2:5]
	s_setprio 2
	s_barrier
	v_mfma_f32_16x16x32_bf16 v[6:9], v[164:167], v[204:207], 0
	v_mfma_f32_16x16x32_bf16 v[6:9], v[168:171], v[208:211], v[6:9]
	s_setprio 0
	ds_read_b128 v[148:151], v146
	ds_read_b128 v[152:155], v146 offset:1024
	ds_read_b128 v[156:159], v146 offset:2048
	ds_read_b128 v[160:163], v146 offset:3072
	ds_read_b128 v[164:167], v147
	ds_read_b128 v[168:171], v147 offset:1024
	ds_read_b128 v[172:175], v147 offset:2048
	ds_read_b128 v[176:179], v147 offset:3072
	ds_read_b128 v[180:183], v145 offset:32768
	ds_read_b128 v[184:187], v145 offset:33792
	ds_read_b128 v[188:191], v145 offset:34816
	ds_read_b128 v[192:195], v145 offset:35840
	ds_read_b128 v[196:199], v145 offset:36864
	ds_read_b128 v[200:203], v145 offset:37888
	ds_read_b128 v[204:207], v145 offset:38912
	ds_read_b128 v[208:211], v145 offset:39936
	s_mov_b32 s74, m0
	s_mov_b32 m0, s31
	s_nop 0
	global_load_lds_dwordx4 v138, s[22:23]
	s_mov_b32 m0, s74
	s_nop 0
	s_mov_b32 s74, m0
	s_mov_b32 m0, s41
	s_nop 0
	global_load_lds_dwordx4 v140, s[22:23]
	s_mov_b32 m0, s74
	s_add_u32 s22, s22, 0x80000
	s_addc_u32 s23, s23, 0
	s_mov_b32 s74, m0
	s_mov_b32 m0, s42
	s_nop 0
	global_load_lds_dwordx4 v138, s[22:23]
	s_mov_b32 m0, s74
	s_nop 0
	s_mov_b32 s74, m0
	s_mov_b32 m0, s43
	s_nop 0
	global_load_lds_dwordx4 v140, s[22:23]
	s_mov_b32 m0, s74
	s_waitcnt vmcnt(8)
	s_waitcnt lgkmcnt(0)
	s_barrier
	s_setprio 1
	.p2align 3
	v_mfma_f32_16x16x32_bf16 v[126:129], v[148:151], v[180:183], v[126:129]
	v_mfma_f32_16x16x32_bf16 v[126:129], v[152:155], v[184:187], v[126:129]
	v_mfma_f32_16x16x32_bf16 v[122:125], v[156:159], v[180:183], v[122:125]
	v_mfma_f32_16x16x32_bf16 v[122:125], v[160:163], v[184:187], v[122:125]
	v_mfma_f32_16x16x32_bf16 v[106:109], v[156:159], v[188:191], v[106:109]
	v_mfma_f32_16x16x32_bf16 v[106:109], v[160:163], v[192:195], v[106:109]
	v_mfma_f32_16x16x32_bf16 v[110:113], v[148:151], v[188:191], v[110:113]
	v_mfma_f32_16x16x32_bf16 v[110:113], v[152:155], v[192:195], v[110:113]
	v_mfma_f32_16x16x32_bf16 v[94:97], v[148:151], v[196:199], v[94:97]
	v_mfma_f32_16x16x32_bf16 v[94:97], v[152:155], v[200:203], v[94:97]
	v_mfma_f32_16x16x32_bf16 v[90:93], v[156:159], v[196:199], v[90:93]
	v_mfma_f32_16x16x32_bf16 v[90:93], v[160:163], v[200:203], v[90:93]
	v_mfma_f32_16x16x32_bf16 v[74:77], v[156:159], v[204:207], v[74:77]
	v_mfma_f32_16x16x32_bf16 v[74:77], v[160:163], v[208:211], v[74:77]
	v_mfma_f32_16x16x32_bf16 v[78:81], v[148:151], v[204:207], v[78:81]
	v_mfma_f32_16x16x32_bf16 v[78:81], v[152:155], v[208:211], v[78:81]
	v_mfma_f32_16x16x32_bf16 v[118:121], v[164:167], v[180:183], v[118:121]
	v_mfma_f32_16x16x32_bf16 v[118:121], v[168:171], v[184:187], v[118:121]
	v_mfma_f32_16x16x32_bf16 v[114:117], v[172:175], v[180:183], v[114:117]
	v_mfma_f32_16x16x32_bf16 v[114:117], v[176:179], v[184:187], v[114:117]
	v_mfma_f32_16x16x32_bf16 v[98:101], v[172:175], v[188:191], v[98:101]
	v_mfma_f32_16x16x32_bf16 v[98:101], v[176:179], v[192:195], v[98:101]
	v_mfma_f32_16x16x32_bf16 v[102:105], v[164:167], v[188:191], v[102:105]
	v_mfma_f32_16x16x32_bf16 v[102:105], v[168:171], v[192:195], v[102:105]
	v_mfma_f32_16x16x32_bf16 v[86:89], v[164:167], v[196:199], v[86:89]
	v_mfma_f32_16x16x32_bf16 v[86:89], v[168:171], v[200:203], v[86:89]
	v_mfma_f32_16x16x32_bf16 v[82:85], v[172:175], v[196:199], v[82:85]
	v_mfma_f32_16x16x32_bf16 v[82:85], v[176:179], v[200:203], v[82:85]
	v_mfma_f32_16x16x32_bf16 v[66:69], v[172:175], v[204:207], v[66:69]
	v_mfma_f32_16x16x32_bf16 v[66:69], v[176:179], v[208:211], v[66:69]
	s_setprio 2
	s_barrier
	v_mfma_f32_16x16x32_bf16 v[70:73], v[164:167], v[204:207], v[70:73]
	v_mfma_f32_16x16x32_bf16 v[70:73], v[168:171], v[208:211], v[70:73]
	s_setprio 0
	ds_read_b128 v[180:183], v145 offset:49152
	ds_read_b128 v[184:187], v145 offset:50176
	ds_read_b128 v[188:191], v145 offset:51200
	ds_read_b128 v[192:195], v145 offset:52224
	ds_read_b128 v[196:199], v145 offset:53248
	ds_read_b128 v[200:203], v145 offset:54272
	ds_read_b128 v[204:207], v145 offset:55296
	ds_read_b128 v[208:211], v145 offset:56320
	s_add_u32 s22, s20, 0x80
	s_addc_u32 s23, s21, 0
	s_mov_b32 s74, m0
	s_mov_b32 m0, s46
	s_nop 0
	global_load_lds_dwordx4 v139, s[22:23]
	s_mov_b32 m0, s74
	s_add_u32 s20, s20, 0x80080
	s_mov_b32 s74, m0
	s_mov_b32 m0, s47
	s_nop 0
	global_load_lds_dwordx4 v141, s[22:23]
	s_mov_b32 m0, s74
	s_addc_u32 s21, s21, 0
	s_mov_b32 s22, m0
	s_mov_b32 m0, s48
	s_nop 0
	global_load_lds_dwordx4 v139, s[20:21]
	s_mov_b32 m0, s22
	s_nop 0
	s_mov_b32 s22, m0
	s_mov_b32 m0, s49
	s_nop 0
	global_load_lds_dwordx4 v141, s[20:21]
	s_mov_b32 m0, s22
	s_waitcnt vmcnt(4)
	s_waitcnt lgkmcnt(0)
	s_barrier
	s_setprio 1
	.p2align 3
	v_mfma_f32_16x16x32_bf16 v[62:65], v[148:151], v[180:183], v[62:65]
	v_mfma_f32_16x16x32_bf16 v[62:65], v[152:155], v[184:187], v[62:65]
	v_mfma_f32_16x16x32_bf16 v[58:61], v[156:159], v[180:183], v[58:61]
	v_mfma_f32_16x16x32_bf16 v[58:61], v[160:163], v[184:187], v[58:61]
	v_mfma_f32_16x16x32_bf16 v[42:45], v[156:159], v[188:191], v[42:45]
	v_mfma_f32_16x16x32_bf16 v[42:45], v[160:163], v[192:195], v[42:45]
	v_mfma_f32_16x16x32_bf16 v[46:49], v[148:151], v[188:191], v[46:49]
	v_mfma_f32_16x16x32_bf16 v[46:49], v[152:155], v[192:195], v[46:49]
	v_mfma_f32_16x16x32_bf16 v[30:33], v[148:151], v[196:199], v[30:33]
	v_mfma_f32_16x16x32_bf16 v[30:33], v[152:155], v[200:203], v[30:33]
	v_mfma_f32_16x16x32_bf16 v[26:29], v[156:159], v[196:199], v[26:29]
	v_mfma_f32_16x16x32_bf16 v[26:29], v[160:163], v[200:203], v[26:29]
	v_mfma_f32_16x16x32_bf16 v[10:13], v[156:159], v[204:207], v[10:13]
	v_mfma_f32_16x16x32_bf16 v[10:13], v[160:163], v[208:211], v[10:13]
	v_mfma_f32_16x16x32_bf16 v[14:17], v[148:151], v[204:207], v[14:17]
	v_mfma_f32_16x16x32_bf16 v[14:17], v[152:155], v[208:211], v[14:17]
	v_mfma_f32_16x16x32_bf16 v[54:57], v[164:167], v[180:183], v[54:57]
	v_mfma_f32_16x16x32_bf16 v[54:57], v[168:171], v[184:187], v[54:57]
	v_mfma_f32_16x16x32_bf16 v[50:53], v[172:175], v[180:183], v[50:53]
	v_mfma_f32_16x16x32_bf16 v[50:53], v[176:179], v[184:187], v[50:53]
	v_mfma_f32_16x16x32_bf16 v[34:37], v[172:175], v[188:191], v[34:37]
	v_mfma_f32_16x16x32_bf16 v[34:37], v[176:179], v[192:195], v[34:37]
	v_mfma_f32_16x16x32_bf16 v[38:41], v[164:167], v[188:191], v[38:41]
	v_mfma_f32_16x16x32_bf16 v[38:41], v[168:171], v[192:195], v[38:41]
	v_mfma_f32_16x16x32_bf16 v[22:25], v[164:167], v[196:199], v[22:25]
	v_mfma_f32_16x16x32_bf16 v[22:25], v[168:171], v[200:203], v[22:25]
	v_mfma_f32_16x16x32_bf16 v[18:21], v[172:175], v[196:199], v[18:21]
	v_mfma_f32_16x16x32_bf16 v[18:21], v[176:179], v[200:203], v[18:21]
	v_mfma_f32_16x16x32_bf16 v[2:5], v[172:175], v[204:207], v[2:5]
	v_mfma_f32_16x16x32_bf16 v[2:5], v[176:179], v[208:211], v[2:5]
	s_setprio 2
	s_barrier
	v_mfma_f32_16x16x32_bf16 v[6:9], v[164:167], v[204:207], v[6:9]
	v_mfma_f32_16x16x32_bf16 v[6:9], v[168:171], v[208:211], v[6:9]
	s_setprio 0
	s_add_i32 s73, s73, 2
	s_add_u32 s66, s66, 0x100
	s_addc_u32 s67, s67, 0
	s_add_u32 s18, s18, 0x100
	s_addc_u32 s19, s19, 0
	s_add_u32 s70, s70, 0x100
	s_addc_u32 s71, s71, 0
	s_cmp_gt_u32 s73, 29
	.p2align 6
.LBB0_1785:
	ds_read_b128 v[148:151], v143
	ds_read_b128 v[152:155], v143 offset:1024
	ds_read_b128 v[156:159], v143 offset:2048
	ds_read_b128 v[160:163], v143 offset:3072
	ds_read_b128 v[164:167], v144
	ds_read_b128 v[168:171], v144 offset:1024
	ds_read_b128 v[172:175], v144 offset:2048
	ds_read_b128 v[176:179], v144 offset:3072
	s_cmp_eq_u32 s73, 28
	s_cselect_b32 s21, s9, s67
	s_cselect_b32 s20, s65, s66
	s_cselect_b32 s23, s11, s71
	s_cselect_b32 s22, s64, s70
	ds_read_b128 v[180:183], v145
	ds_read_b128 v[184:187], v145 offset:1024
	ds_read_b128 v[188:191], v145 offset:2048
	ds_read_b128 v[192:195], v145 offset:3072
	ds_read_b128 v[196:199], v145 offset:4096
	ds_read_b128 v[200:203], v145 offset:5120
	ds_read_b128 v[204:207], v145 offset:6144
	ds_read_b128 v[208:211], v145 offset:7168
	s_add_u32 s74, s18, 0xfff80000
	s_addc_u32 s75, s19, -1
	s_mov_b32 s76, m0
	s_mov_b32 m0, s56
	s_nop 0
	global_load_lds_dwordx4 v138, s[74:75]
	s_mov_b32 m0, s76
	s_nop 0
	s_mov_b32 s76, m0
	s_mov_b32 m0, s59
	s_nop 0
	global_load_lds_dwordx4 v140, s[74:75]
	s_mov_b32 m0, s76
	s_mov_b32 s74, m0
	s_mov_b32 m0, s57
	s_nop 0
	global_load_lds_dwordx4 v138, s[18:19]
	s_mov_b32 m0, s74
	s_nop 0
	s_mov_b32 s74, m0
	s_mov_b32 m0, s62
	s_nop 0
	global_load_lds_dwordx4 v140, s[18:19]
	s_mov_b32 m0, s74
	s_waitcnt vmcnt(8)
	s_waitcnt lgkmcnt(0)
	s_barrier
	s_setprio 1
	.p2align 3
	v_mfma_f32_16x16x32_bf16 v[126:129], v[148:151], v[180:183], v[126:129]
	v_mfma_f32_16x16x32_bf16 v[126:129], v[152:155], v[184:187], v[126:129]
	v_mfma_f32_16x16x32_bf16 v[122:125], v[156:159], v[180:183], v[122:125]
	v_mfma_f32_16x16x32_bf16 v[122:125], v[160:163], v[184:187], v[122:125]
	v_mfma_f32_16x16x32_bf16 v[106:109], v[156:159], v[188:191], v[106:109]
	v_mfma_f32_16x16x32_bf16 v[106:109], v[160:163], v[192:195], v[106:109]
	v_mfma_f32_16x16x32_bf16 v[110:113], v[148:151], v[188:191], v[110:113]
	v_mfma_f32_16x16x32_bf16 v[110:113], v[152:155], v[192:195], v[110:113]
	v_mfma_f32_16x16x32_bf16 v[94:97], v[148:151], v[196:199], v[94:97]
	v_mfma_f32_16x16x32_bf16 v[94:97], v[152:155], v[200:203], v[94:97]
	v_mfma_f32_16x16x32_bf16 v[90:93], v[156:159], v[196:199], v[90:93]
	v_mfma_f32_16x16x32_bf16 v[90:93], v[160:163], v[200:203], v[90:93]
	v_mfma_f32_16x16x32_bf16 v[74:77], v[156:159], v[204:207], v[74:77]
	v_mfma_f32_16x16x32_bf16 v[74:77], v[160:163], v[208:211], v[74:77]
	v_mfma_f32_16x16x32_bf16 v[78:81], v[148:151], v[204:207], v[78:81]
	v_mfma_f32_16x16x32_bf16 v[78:81], v[152:155], v[208:211], v[78:81]
	v_mfma_f32_16x16x32_bf16 v[118:121], v[164:167], v[180:183], v[118:121]
	v_mfma_f32_16x16x32_bf16 v[118:121], v[168:171], v[184:187], v[118:121]
	v_mfma_f32_16x16x32_bf16 v[114:117], v[172:175], v[180:183], v[114:117]
	v_mfma_f32_16x16x32_bf16 v[114:117], v[176:179], v[184:187], v[114:117]
	v_mfma_f32_16x16x32_bf16 v[98:101], v[172:175], v[188:191], v[98:101]
	v_mfma_f32_16x16x32_bf16 v[98:101], v[176:179], v[192:195], v[98:101]
	v_mfma_f32_16x16x32_bf16 v[102:105], v[164:167], v[188:191], v[102:105]
	v_mfma_f32_16x16x32_bf16 v[102:105], v[168:171], v[192:195], v[102:105]
	v_mfma_f32_16x16x32_bf16 v[86:89], v[164:167], v[196:199], v[86:89]
	v_mfma_f32_16x16x32_bf16 v[86:89], v[168:171], v[200:203], v[86:89]
	v_mfma_f32_16x16x32_bf16 v[82:85], v[172:175], v[196:199], v[82:85]
	v_mfma_f32_16x16x32_bf16 v[82:85], v[176:179], v[200:203], v[82:85]
	v_mfma_f32_16x16x32_bf16 v[66:69], v[172:175], v[204:207], v[66:69]
	v_mfma_f32_16x16x32_bf16 v[66:69], v[176:179], v[208:211], v[66:69]
	s_setprio 2
	s_barrier
	v_mfma_f32_16x16x32_bf16 v[70:73], v[164:167], v[204:207], v[70:73]
	v_mfma_f32_16x16x32_bf16 v[70:73], v[168:171], v[208:211], v[70:73]
	s_setprio 0
	ds_read_b128 v[180:183], v145 offset:16384
	ds_read_b128 v[184:187], v145 offset:17408
	ds_read_b128 v[188:191], v145 offset:18432
	ds_read_b128 v[192:195], v145 offset:19456
	ds_read_b128 v[196:199], v145 offset:20480
	ds_read_b128 v[200:203], v145 offset:21504
	ds_read_b128 v[204:207], v145 offset:22528
	ds_read_b128 v[208:211], v145 offset:23552
	s_mov_b32 s74, m0
	s_mov_b32 m0, s35
	s_nop 0
	global_load_lds_dwordx4 v139, s[20:21]
	s_mov_b32 m0, s74
	s_nop 0
	s_mov_b32 s74, m0
	s_mov_b32 m0, s36
	s_nop 0
	global_load_lds_dwordx4 v141, s[20:21]
	s_mov_b32 m0, s74
	s_add_u32 s74, s20, 0x80000
	s_addc_u32 s75, s21, 0
	s_mov_b32 s76, m0
	s_mov_b32 m0, s37
	s_nop 0
	global_load_lds_dwordx4 v139, s[74:75]
	s_mov_b32 m0, s76
	s_nop 0
	s_mov_b32 s76, m0
	s_mov_b32 m0, s40
	s_nop 0
	global_load_lds_dwordx4 v141, s[74:75]
	s_mov_b32 m0, s76
	s_waitcnt vmcnt(4)
	s_waitcnt lgkmcnt(0)
	s_barrier
	s_setprio 1
	.p2align 3
	v_mfma_f32_16x16x32_bf16 v[62:65], v[148:151], v[180:183], v[62:65]
	v_mfma_f32_16x16x32_bf16 v[62:65], v[152:155], v[184:187], v[62:65]
	v_mfma_f32_16x16x32_bf16 v[58:61], v[156:159], v[180:183], v[58:61]
	v_mfma_f32_16x16x32_bf16 v[58:61], v[160:163], v[184:187], v[58:61]
	v_mfma_f32_16x16x32_bf16 v[42:45], v[156:159], v[188:191], v[42:45]
	v_mfma_f32_16x16x32_bf16 v[42:45], v[160:163], v[192:195], v[42:45]
	v_mfma_f32_16x16x32_bf16 v[46:49], v[148:151], v[188:191], v[46:49]
	v_mfma_f32_16x16x32_bf16 v[46:49], v[152:155], v[192:195], v[46:49]
	v_mfma_f32_16x16x32_bf16 v[30:33], v[148:151], v[196:199], v[30:33]
	v_mfma_f32_16x16x32_bf16 v[30:33], v[152:155], v[200:203], v[30:33]
	v_mfma_f32_16x16x32_bf16 v[26:29], v[156:159], v[196:199], v[26:29]
	v_mfma_f32_16x16x32_bf16 v[26:29], v[160:163], v[200:203], v[26:29]
	v_mfma_f32_16x16x32_bf16 v[10:13], v[156:159], v[204:207], v[10:13]
	v_mfma_f32_16x16x32_bf16 v[10:13], v[160:163], v[208:211], v[10:13]
	v_mfma_f32_16x16x32_bf16 v[14:17], v[148:151], v[204:207], v[14:17]
	v_mfma_f32_16x16x32_bf16 v[14:17], v[152:155], v[208:211], v[14:17]
	v_mfma_f32_16x16x32_bf16 v[54:57], v[164:167], v[180:183], v[54:57]
	v_mfma_f32_16x16x32_bf16 v[54:57], v[168:171], v[184:187], v[54:57]
	v_mfma_f32_16x16x32_bf16 v[50:53], v[172:175], v[180:183], v[50:53]
	v_mfma_f32_16x16x32_bf16 v[50:53], v[176:179], v[184:187], v[50:53]
	v_mfma_f32_16x16x32_bf16 v[34:37], v[172:175], v[188:191], v[34:37]
	v_mfma_f32_16x16x32_bf16 v[34:37], v[176:179], v[192:195], v[34:37]
	v_mfma_f32_16x16x32_bf16 v[38:41], v[164:167], v[188:191], v[38:41]
	v_mfma_f32_16x16x32_bf16 v[38:41], v[168:171], v[192:195], v[38:41]
	v_mfma_f32_16x16x32_bf16 v[22:25], v[164:167], v[196:199], v[22:25]
	v_mfma_f32_16x16x32_bf16 v[22:25], v[168:171], v[200:203], v[22:25]
	v_mfma_f32_16x16x32_bf16 v[18:21], v[172:175], v[196:199], v[18:21]
	v_mfma_f32_16x16x32_bf16 v[18:21], v[176:179], v[200:203], v[18:21]
	v_mfma_f32_16x16x32_bf16 v[2:5], v[172:175], v[204:207], v[2:5]
	v_mfma_f32_16x16x32_bf16 v[2:5], v[176:179], v[208:211], v[2:5]
	s_setprio 2
	s_barrier
	v_mfma_f32_16x16x32_bf16 v[6:9], v[164:167], v[204:207], v[6:9]
	v_mfma_f32_16x16x32_bf16 v[6:9], v[168:171], v[208:211], v[6:9]
	s_setprio 0
	ds_read_b128 v[148:151], v146
	ds_read_b128 v[152:155], v146 offset:1024
	ds_read_b128 v[156:159], v146 offset:2048
	ds_read_b128 v[160:163], v146 offset:3072
	ds_read_b128 v[164:167], v147
	ds_read_b128 v[168:171], v147 offset:1024
	ds_read_b128 v[172:175], v147 offset:2048
	ds_read_b128 v[176:179], v147 offset:3072
	ds_read_b128 v[180:183], v145 offset:32768
	ds_read_b128 v[184:187], v145 offset:33792
	ds_read_b128 v[188:191], v145 offset:34816
	ds_read_b128 v[192:195], v145 offset:35840
	ds_read_b128 v[196:199], v145 offset:36864
	ds_read_b128 v[200:203], v145 offset:37888
	ds_read_b128 v[204:207], v145 offset:38912
	ds_read_b128 v[208:211], v145 offset:39936
	s_mov_b32 s74, m0
	s_mov_b32 m0, s31
	s_nop 0
	global_load_lds_dwordx4 v138, s[22:23]
	s_mov_b32 m0, s74
	s_nop 0
	s_mov_b32 s74, m0
	s_mov_b32 m0, s41
	s_nop 0
	global_load_lds_dwordx4 v140, s[22:23]
	s_mov_b32 m0, s74
	s_add_u32 s22, s22, 0x80000
	s_addc_u32 s23, s23, 0
	s_mov_b32 s74, m0
	s_mov_b32 m0, s42
	s_nop 0
	global_load_lds_dwordx4 v138, s[22:23]
	s_mov_b32 m0, s74
	s_nop 0
	s_mov_b32 s74, m0
	s_mov_b32 m0, s43
	s_nop 0
	global_load_lds_dwordx4 v140, s[22:23]
	s_mov_b32 m0, s74
	s_waitcnt vmcnt(8)
	s_waitcnt lgkmcnt(0)
	s_barrier
	s_setprio 1
	.p2align 3
	v_mfma_f32_16x16x32_bf16 v[126:129], v[148:151], v[180:183], v[126:129]
	v_mfma_f32_16x16x32_bf16 v[126:129], v[152:155], v[184:187], v[126:129]
	v_mfma_f32_16x16x32_bf16 v[122:125], v[156:159], v[180:183], v[122:125]
	v_mfma_f32_16x16x32_bf16 v[122:125], v[160:163], v[184:187], v[122:125]
	v_mfma_f32_16x16x32_bf16 v[106:109], v[156:159], v[188:191], v[106:109]
	v_mfma_f32_16x16x32_bf16 v[106:109], v[160:163], v[192:195], v[106:109]
	v_mfma_f32_16x16x32_bf16 v[110:113], v[148:151], v[188:191], v[110:113]
	v_mfma_f32_16x16x32_bf16 v[110:113], v[152:155], v[192:195], v[110:113]
	v_mfma_f32_16x16x32_bf16 v[94:97], v[148:151], v[196:199], v[94:97]
	v_mfma_f32_16x16x32_bf16 v[94:97], v[152:155], v[200:203], v[94:97]
	v_mfma_f32_16x16x32_bf16 v[90:93], v[156:159], v[196:199], v[90:93]
	v_mfma_f32_16x16x32_bf16 v[90:93], v[160:163], v[200:203], v[90:93]
	v_mfma_f32_16x16x32_bf16 v[74:77], v[156:159], v[204:207], v[74:77]
	v_mfma_f32_16x16x32_bf16 v[74:77], v[160:163], v[208:211], v[74:77]
	v_mfma_f32_16x16x32_bf16 v[78:81], v[148:151], v[204:207], v[78:81]
	v_mfma_f32_16x16x32_bf16 v[78:81], v[152:155], v[208:211], v[78:81]
	v_mfma_f32_16x16x32_bf16 v[118:121], v[164:167], v[180:183], v[118:121]
	v_mfma_f32_16x16x32_bf16 v[118:121], v[168:171], v[184:187], v[118:121]
	v_mfma_f32_16x16x32_bf16 v[114:117], v[172:175], v[180:183], v[114:117]
	v_mfma_f32_16x16x32_bf16 v[114:117], v[176:179], v[184:187], v[114:117]
	v_mfma_f32_16x16x32_bf16 v[98:101], v[172:175], v[188:191], v[98:101]
	v_mfma_f32_16x16x32_bf16 v[98:101], v[176:179], v[192:195], v[98:101]
	v_mfma_f32_16x16x32_bf16 v[102:105], v[164:167], v[188:191], v[102:105]
	v_mfma_f32_16x16x32_bf16 v[102:105], v[168:171], v[192:195], v[102:105]
	v_mfma_f32_16x16x32_bf16 v[86:89], v[164:167], v[196:199], v[86:89]
	v_mfma_f32_16x16x32_bf16 v[86:89], v[168:171], v[200:203], v[86:89]
	v_mfma_f32_16x16x32_bf16 v[82:85], v[172:175], v[196:199], v[82:85]
	v_mfma_f32_16x16x32_bf16 v[82:85], v[176:179], v[200:203], v[82:85]
	v_mfma_f32_16x16x32_bf16 v[66:69], v[172:175], v[204:207], v[66:69]
	v_mfma_f32_16x16x32_bf16 v[66:69], v[176:179], v[208:211], v[66:69]
	s_setprio 2
	s_barrier
	v_mfma_f32_16x16x32_bf16 v[70:73], v[164:167], v[204:207], v[70:73]
	v_mfma_f32_16x16x32_bf16 v[70:73], v[168:171], v[208:211], v[70:73]
	s_setprio 0
	ds_read_b128 v[180:183], v145 offset:49152
	ds_read_b128 v[184:187], v145 offset:50176
	ds_read_b128 v[188:191], v145 offset:51200
	ds_read_b128 v[192:195], v145 offset:52224
	ds_read_b128 v[196:199], v145 offset:53248
	ds_read_b128 v[200:203], v145 offset:54272
	ds_read_b128 v[204:207], v145 offset:55296
	ds_read_b128 v[208:211], v145 offset:56320
	s_add_u32 s22, s20, 0x80
	s_addc_u32 s23, s21, 0
	s_mov_b32 s74, m0
	s_mov_b32 m0, s46
	s_nop 0
	global_load_lds_dwordx4 v139, s[22:23]
	s_mov_b32 m0, s74
	s_add_u32 s20, s20, 0x80080
	s_mov_b32 s74, m0
	s_mov_b32 m0, s47
	s_nop 0
	global_load_lds_dwordx4 v141, s[22:23]
	s_mov_b32 m0, s74
	s_addc_u32 s21, s21, 0
	s_mov_b32 s22, m0
	s_mov_b32 m0, s48
	s_nop 0
	global_load_lds_dwordx4 v139, s[20:21]
	s_mov_b32 m0, s22
	s_nop 0
	s_mov_b32 s22, m0
	s_mov_b32 m0, s49
	s_nop 0
	global_load_lds_dwordx4 v141, s[20:21]
	s_mov_b32 m0, s22
	s_waitcnt vmcnt(4)
	s_waitcnt lgkmcnt(0)
	s_barrier
	s_setprio 1
	.p2align 3
	v_mfma_f32_16x16x32_bf16 v[62:65], v[148:151], v[180:183], v[62:65]
	v_mfma_f32_16x16x32_bf16 v[62:65], v[152:155], v[184:187], v[62:65]
	v_mfma_f32_16x16x32_bf16 v[58:61], v[156:159], v[180:183], v[58:61]
	v_mfma_f32_16x16x32_bf16 v[58:61], v[160:163], v[184:187], v[58:61]
	v_mfma_f32_16x16x32_bf16 v[42:45], v[156:159], v[188:191], v[42:45]
	v_mfma_f32_16x16x32_bf16 v[42:45], v[160:163], v[192:195], v[42:45]
	v_mfma_f32_16x16x32_bf16 v[46:49], v[148:151], v[188:191], v[46:49]
	v_mfma_f32_16x16x32_bf16 v[46:49], v[152:155], v[192:195], v[46:49]
	v_mfma_f32_16x16x32_bf16 v[30:33], v[148:151], v[196:199], v[30:33]
	v_mfma_f32_16x16x32_bf16 v[30:33], v[152:155], v[200:203], v[30:33]
	v_mfma_f32_16x16x32_bf16 v[26:29], v[156:159], v[196:199], v[26:29]
	v_mfma_f32_16x16x32_bf16 v[26:29], v[160:163], v[200:203], v[26:29]
	v_mfma_f32_16x16x32_bf16 v[10:13], v[156:159], v[204:207], v[10:13]
	v_mfma_f32_16x16x32_bf16 v[10:13], v[160:163], v[208:211], v[10:13]
	v_mfma_f32_16x16x32_bf16 v[14:17], v[148:151], v[204:207], v[14:17]
	v_mfma_f32_16x16x32_bf16 v[14:17], v[152:155], v[208:211], v[14:17]
	v_mfma_f32_16x16x32_bf16 v[54:57], v[164:167], v[180:183], v[54:57]
	v_mfma_f32_16x16x32_bf16 v[54:57], v[168:171], v[184:187], v[54:57]
	v_mfma_f32_16x16x32_bf16 v[50:53], v[172:175], v[180:183], v[50:53]
	v_mfma_f32_16x16x32_bf16 v[50:53], v[176:179], v[184:187], v[50:53]
	v_mfma_f32_16x16x32_bf16 v[34:37], v[172:175], v[188:191], v[34:37]
	v_mfma_f32_16x16x32_bf16 v[34:37], v[176:179], v[192:195], v[34:37]
	v_mfma_f32_16x16x32_bf16 v[38:41], v[164:167], v[188:191], v[38:41]
	v_mfma_f32_16x16x32_bf16 v[38:41], v[168:171], v[192:195], v[38:41]
	v_mfma_f32_16x16x32_bf16 v[22:25], v[164:167], v[196:199], v[22:25]
	v_mfma_f32_16x16x32_bf16 v[22:25], v[168:171], v[200:203], v[22:25]
	v_mfma_f32_16x16x32_bf16 v[18:21], v[172:175], v[196:199], v[18:21]
	v_mfma_f32_16x16x32_bf16 v[18:21], v[176:179], v[200:203], v[18:21]
	v_mfma_f32_16x16x32_bf16 v[2:5], v[172:175], v[204:207], v[2:5]
	v_mfma_f32_16x16x32_bf16 v[2:5], v[176:179], v[208:211], v[2:5]
	s_setprio 2
	s_barrier
	v_mfma_f32_16x16x32_bf16 v[6:9], v[164:167], v[204:207], v[6:9]
	v_mfma_f32_16x16x32_bf16 v[6:9], v[168:171], v[208:211], v[6:9]
	s_setprio 0
	s_add_i32 s73, s73, 2
	s_add_u32 s66, s66, 0x100
	s_addc_u32 s67, s67, 0
	s_add_u32 s18, s18, 0x100
	s_addc_u32 s19, s19, 0
	s_add_u32 s70, s70, 0x100
	s_addc_u32 s71, s71, 0
	s_cmp_gt_u32 s73, 29
	s_cbranch_scc0 .LBB0_1785
	s_and_b64 vcc, exec, s[6:7]
	s_cbranch_vccz .LBB0_1788
	s_barrier

.LBB0_1951:
	s_ashr_i32 s13, s12, 31
	s_lshl_b64 s[14:15], s[12:13], 15
	s_add_u32 s14, s28, s14
	s_addc_u32 s15, s29, s15
	s_and_b64 s[16:17], s[2:3], exec
	s_cselect_b32 s13, s15, s23
	s_cselect_b32 s65, s14, s22
	s_ashr_i32 s11, s10, 31
	s_lshl_b64 s[16:17], s[10:11], 15
	s_add_u32 s16, s30, s16
	s_addc_u32 s17, s31, s17
	s_and_b64 s[24:25], s[2:3], exec
	s_cselect_b32 s11, s17, s21
	s_cselect_b32 s66, s16, s20
	s_add_u32 s67, s20, 0x80000
	s_addc_u32 s70, s21, 0
	s_add_u32 s20, s22, 0x204000
	s_addc_u32 s21, s23, 0
	s_add_u32 s71, s22, 0x400000
	s_addc_u32 s73, s23, 0
	s_mov_b32 s74, -2
	s_waitcnt vmcnt(25)
	s_waitcnt vmcnt(24)
	s_waitcnt vmcnt(4)
	s_waitcnt vmcnt(2)
	s_waitcnt vmcnt(1)
	s_waitcnt vmcnt(0)
	ds_read_b128 v[130:133], v181
	ds_read_b128 v[134:137], v181 offset:1024
	ds_read_b128 v[138:141], v181 offset:2048
	ds_read_b128 v[142:145], v181 offset:3072
	ds_read_b128 v[150:153], v182
	ds_read_b128 v[154:157], v182 offset:1024
	ds_read_b128 v[158:161], v182 offset:2048
	ds_read_b128 v[162:165], v182 offset:3072
	s_cmpk_eq_i32 s74, 0x52
	s_cselect_b32 s23, s11, s70
	s_cselect_b32 s22, s66, s67
	s_cselect_b32 s25, s13, s73
	s_cselect_b32 s24, s65, s71
	ds_read_b128 v[166:169], v183
	ds_read_b128 v[170:173], v183 offset:1024
	ds_read_b128 v[186:189], v183 offset:2048
	ds_read_b128 v[190:193], v183 offset:3072
	ds_read_b128 v[194:197], v183 offset:4096
	ds_read_b128 v[198:201], v183 offset:5120
	ds_read_b128 v[202:205], v183 offset:6144
	ds_read_b128 v[206:209], v183 offset:7168
	s_add_u32 s76, s20, 0xffffc000
	s_addc_u32 s77, s21, -1
	s_mov_b32 s75, m0
	s_mov_b32 m0, s58
	s_nop 0
	global_load_lds_dwordx4 v1, s[76:77]
	s_mov_b32 m0, s75
	s_nop 0
	s_mov_b32 s75, m0
	s_mov_b32 m0, s62
	s_nop 0
	global_load_lds_dwordx4 v177, s[76:77]
	s_mov_b32 m0, s75
	s_nop 0
	s_mov_b32 s75, m0
	s_mov_b32 m0, s59
	s_nop 0
	global_load_lds_dwordx4 v1, s[20:21]
	s_mov_b32 m0, s75
	s_nop 0
	s_mov_b32 s75, m0
	s_mov_b32 m0, s63
	s_nop 0
	global_load_lds_dwordx4 v177, s[20:21]
	s_mov_b32 m0, s75
	s_waitcnt vmcnt(8)
	s_waitcnt lgkmcnt(0)
	s_barrier
	s_setprio 1
	.p2align 3
	v_mfma_f32_16x16x32_bf16 v[126:129], v[130:133], v[166:169], 0
	v_mfma_f32_16x16x32_bf16 v[126:129], v[134:137], v[170:173], v[126:129]
	v_mfma_f32_16x16x32_bf16 v[122:125], v[138:141], v[166:169], 0
	v_mfma_f32_16x16x32_bf16 v[122:125], v[142:145], v[170:173], v[122:125]
	v_mfma_f32_16x16x32_bf16 v[110:113], v[138:141], v[186:189], 0
	v_mfma_f32_16x16x32_bf16 v[110:113], v[142:145], v[190:193], v[110:113]
	v_mfma_f32_16x16x32_bf16 v[118:121], v[130:133], v[186:189], 0
	v_mfma_f32_16x16x32_bf16 v[118:121], v[134:137], v[190:193], v[118:121]
	v_mfma_f32_16x16x32_bf16 v[94:97], v[130:133], v[194:197], 0
	v_mfma_f32_16x16x32_bf16 v[94:97], v[134:137], v[198:201], v[94:97]
	v_mfma_f32_16x16x32_bf16 v[90:93], v[138:141], v[194:197], 0
	v_mfma_f32_16x16x32_bf16 v[90:93], v[142:145], v[198:201], v[90:93]
	v_mfma_f32_16x16x32_bf16 v[78:81], v[138:141], v[202:205], 0
	v_mfma_f32_16x16x32_bf16 v[78:81], v[142:145], v[206:209], v[78:81]
	v_mfma_f32_16x16x32_bf16 v[86:89], v[130:133], v[202:205], 0
	v_mfma_f32_16x16x32_bf16 v[86:89], v[134:137], v[206:209], v[86:89]
	v_mfma_f32_16x16x32_bf16 v[114:117], v[150:153], v[166:169], 0
	v_mfma_f32_16x16x32_bf16 v[114:117], v[154:157], v[170:173], v[114:117]
	v_mfma_f32_16x16x32_bf16 v[106:109], v[158:161], v[166:169], 0
	v_mfma_f32_16x16x32_bf16 v[106:109], v[162:165], v[170:173], v[106:109]
	v_mfma_f32_16x16x32_bf16 v[98:101], v[158:161], v[186:189], 0
	v_mfma_f32_16x16x32_bf16 v[98:101], v[162:165], v[190:193], v[98:101]
	v_mfma_f32_16x16x32_bf16 v[102:105], v[150:153], v[186:189], 0
	v_mfma_f32_16x16x32_bf16 v[102:105], v[154:157], v[190:193], v[102:105]
	v_mfma_f32_16x16x32_bf16 v[82:85], v[150:153], v[194:197], 0
	v_mfma_f32_16x16x32_bf16 v[82:85], v[154:157], v[198:201], v[82:85]
	v_mfma_f32_16x16x32_bf16 v[74:77], v[158:161], v[194:197], 0
	v_mfma_f32_16x16x32_bf16 v[74:77], v[162:165], v[198:201], v[74:77]
	v_mfma_f32_16x16x32_bf16 v[66:69], v[158:161], v[202:205], 0
	v_mfma_f32_16x16x32_bf16 v[66:69], v[162:165], v[206:209], v[66:69]
	s_setprio 2
	s_barrier
	v_mfma_f32_16x16x32_bf16 v[70:73], v[150:153], v[202:205], 0
	v_mfma_f32_16x16x32_bf16 v[70:73], v[154:157], v[206:209], v[70:73]
	s_setprio 0
	ds_read_b128 v[166:169], v183 offset:16384
	ds_read_b128 v[170:173], v183 offset:17408
	ds_read_b128 v[186:189], v183 offset:18432
	ds_read_b128 v[190:193], v183 offset:19456
	ds_read_b128 v[194:197], v183 offset:20480
	ds_read_b128 v[198:201], v183 offset:21504
	ds_read_b128 v[202:205], v183 offset:22528
	ds_read_b128 v[206:209], v183 offset:23552
	s_mov_b32 s75, m0
	s_mov_b32 m0, s35
	s_nop 0
	global_load_lds_dwordx4 v176, s[22:23]
	s_mov_b32 m0, s75
	s_add_u32 s76, s22, 0x4000
	s_mov_b32 s75, m0
	s_mov_b32 m0, s36
	s_nop 0
	global_load_lds_dwordx4 v178, s[22:23]
	s_mov_b32 m0, s75
	s_addc_u32 s77, s23, 0
	s_mov_b32 s75, m0
	s_mov_b32 m0, s37
	s_nop 0
	global_load_lds_dwordx4 v176, s[76:77]
	s_mov_b32 m0, s75
	s_nop 0
	s_mov_b32 s75, m0
	s_mov_b32 m0, s40
	s_nop 0
	global_load_lds_dwordx4 v178, s[76:77]
	s_mov_b32 m0, s75
	s_waitcnt vmcnt(4)
	s_waitcnt lgkmcnt(0)
	s_barrier
	s_setprio 1
	.p2align 3
	v_mfma_f32_16x16x32_bf16 v[62:65], v[130:133], v[166:169], 0
	v_mfma_f32_16x16x32_bf16 v[62:65], v[134:137], v[170:173], v[62:65]
	v_mfma_f32_16x16x32_bf16 v[58:61], v[138:141], v[166:169], 0
	v_mfma_f32_16x16x32_bf16 v[58:61], v[142:145], v[170:173], v[58:61]
	v_mfma_f32_16x16x32_bf16 v[42:45], v[138:141], v[186:189], 0
	v_mfma_f32_16x16x32_bf16 v[42:45], v[142:145], v[190:193], v[42:45]
	v_mfma_f32_16x16x32_bf16 v[46:49], v[130:133], v[186:189], 0
	v_mfma_f32_16x16x32_bf16 v[46:49], v[134:137], v[190:193], v[46:49]
	v_mfma_f32_16x16x32_bf16 v[30:33], v[130:133], v[194:197], 0
	v_mfma_f32_16x16x32_bf16 v[30:33], v[134:137], v[198:201], v[30:33]
	v_mfma_f32_16x16x32_bf16 v[26:29], v[138:141], v[194:197], 0
	v_mfma_f32_16x16x32_bf16 v[26:29], v[142:145], v[198:201], v[26:29]
	v_mfma_f32_16x16x32_bf16 v[10:13], v[138:141], v[202:205], 0
	v_mfma_f32_16x16x32_bf16 v[10:13], v[142:145], v[206:209], v[10:13]
	v_mfma_f32_16x16x32_bf16 v[14:17], v[130:133], v[202:205], 0
	v_mfma_f32_16x16x32_bf16 v[14:17], v[134:137], v[206:209], v[14:17]
	v_mfma_f32_16x16x32_bf16 v[54:57], v[150:153], v[166:169], 0
	v_mfma_f32_16x16x32_bf16 v[54:57], v[154:157], v[170:173], v[54:57]
	v_mfma_f32_16x16x32_bf16 v[50:53], v[158:161], v[166:169], 0
	v_mfma_f32_16x16x32_bf16 v[50:53], v[162:165], v[170:173], v[50:53]
	v_mfma_f32_16x16x32_bf16 v[34:37], v[158:161], v[186:189], 0
	v_mfma_f32_16x16x32_bf16 v[34:37], v[162:165], v[190:193], v[34:37]
	v_mfma_f32_16x16x32_bf16 v[38:41], v[150:153], v[186:189], 0
	v_mfma_f32_16x16x32_bf16 v[38:41], v[154:157], v[190:193], v[38:41]
	v_mfma_f32_16x16x32_bf16 v[22:25], v[150:153], v[194:197], 0
	v_mfma_f32_16x16x32_bf16 v[22:25], v[154:157], v[198:201], v[22:25]
	v_mfma_f32_16x16x32_bf16 v[18:21], v[158:161], v[194:197], 0
	v_mfma_f32_16x16x32_bf16 v[18:21], v[162:165], v[198:201], v[18:21]
	v_mfma_f32_16x16x32_bf16 v[2:5], v[158:161], v[202:205], 0
	v_mfma_f32_16x16x32_bf16 v[2:5], v[162:165], v[206:209], v[2:5]
	s_setprio 2
	s_barrier
	v_mfma_f32_16x16x32_bf16 v[6:9], v[150:153], v[202:205], 0
	v_mfma_f32_16x16x32_bf16 v[6:9], v[154:157], v[206:209], v[6:9]
	s_setprio 0
	ds_read_b128 v[130:133], v184
	ds_read_b128 v[134:137], v184 offset:1024
	ds_read_b128 v[138:141], v184 offset:2048
	ds_read_b128 v[142:145], v184 offset:3072
	ds_read_b128 v[150:153], v185
	ds_read_b128 v[154:157], v185 offset:1024
	ds_read_b128 v[158:161], v185 offset:2048
	ds_read_b128 v[162:165], v185 offset:3072
	ds_read_b128 v[166:169], v183 offset:32768
	ds_read_b128 v[170:173], v183 offset:33792
	ds_read_b128 v[186:189], v183 offset:34816
	ds_read_b128 v[190:193], v183 offset:35840
	ds_read_b128 v[194:197], v183 offset:36864
	ds_read_b128 v[198:201], v183 offset:37888
	ds_read_b128 v[202:205], v183 offset:38912
	ds_read_b128 v[206:209], v183 offset:39936
	s_mov_b32 s75, m0
	s_mov_b32 m0, s34
	s_nop 0
	global_load_lds_dwordx4 v1, s[24:25]
	s_mov_b32 m0, s75
	s_nop 0
	s_mov_b32 s75, m0
	s_mov_b32 m0, s41
	s_nop 0
	global_load_lds_dwordx4 v177, s[24:25]
	s_mov_b32 m0, s75
	s_add_u32 s24, s24, 0x4000
	s_addc_u32 s25, s25, 0
	s_mov_b32 s75, m0
	s_mov_b32 m0, s42
	s_nop 0
	global_load_lds_dwordx4 v1, s[24:25]
	s_mov_b32 m0, s75
	s_nop 0
	s_mov_b32 s75, m0
	s_mov_b32 m0, s43
	s_nop 0
	global_load_lds_dwordx4 v177, s[24:25]
	s_mov_b32 m0, s75
	s_waitcnt vmcnt(8)
	s_waitcnt lgkmcnt(0)
	s_barrier
	s_setprio 1
	.p2align 3
	v_mfma_f32_16x16x32_bf16 v[126:129], v[130:133], v[166:169], v[126:129]
	v_mfma_f32_16x16x32_bf16 v[126:129], v[134:137], v[170:173], v[126:129]
	v_mfma_f32_16x16x32_bf16 v[122:125], v[138:141], v[166:169], v[122:125]
	v_mfma_f32_16x16x32_bf16 v[122:125], v[142:145], v[170:173], v[122:125]
	v_mfma_f32_16x16x32_bf16 v[110:113], v[138:141], v[186:189], v[110:113]
	v_mfma_f32_16x16x32_bf16 v[110:113], v[142:145], v[190:193], v[110:113]
	v_mfma_f32_16x16x32_bf16 v[118:121], v[130:133], v[186:189], v[118:121]
	v_mfma_f32_16x16x32_bf16 v[118:121], v[134:137], v[190:193], v[118:121]
	v_mfma_f32_16x16x32_bf16 v[94:97], v[130:133], v[194:197], v[94:97]
	v_mfma_f32_16x16x32_bf16 v[94:97], v[134:137], v[198:201], v[94:97]
	v_mfma_f32_16x16x32_bf16 v[90:93], v[138:141], v[194:197], v[90:93]
	v_mfma_f32_16x16x32_bf16 v[90:93], v[142:145], v[198:201], v[90:93]
	v_mfma_f32_16x16x32_bf16 v[78:81], v[138:141], v[202:205], v[78:81]
	v_mfma_f32_16x16x32_bf16 v[78:81], v[142:145], v[206:209], v[78:81]
	v_mfma_f32_16x16x32_bf16 v[86:89], v[130:133], v[202:205], v[86:89]
	v_mfma_f32_16x16x32_bf16 v[86:89], v[134:137], v[206:209], v[86:89]
	v_mfma_f32_16x16x32_bf16 v[114:117], v[150:153], v[166:169], v[114:117]
	v_mfma_f32_16x16x32_bf16 v[114:117], v[154:157], v[170:173], v[114:117]
	v_mfma_f32_16x16x32_bf16 v[106:109], v[158:161], v[166:169], v[106:109]
	v_mfma_f32_16x16x32_bf16 v[106:109], v[162:165], v[170:173], v[106:109]
	v_mfma_f32_16x16x32_bf16 v[98:101], v[158:161], v[186:189], v[98:101]
	v_mfma_f32_16x16x32_bf16 v[98:101], v[162:165], v[190:193], v[98:101]
	v_mfma_f32_16x16x32_bf16 v[102:105], v[150:153], v[186:189], v[102:105]
	v_mfma_f32_16x16x32_bf16 v[102:105], v[154:157], v[190:193], v[102:105]
	v_mfma_f32_16x16x32_bf16 v[82:85], v[150:153], v[194:197], v[82:85]
	v_mfma_f32_16x16x32_bf16 v[82:85], v[154:157], v[198:201], v[82:85]
	v_mfma_f32_16x16x32_bf16 v[74:77], v[158:161], v[194:197], v[74:77]
	v_mfma_f32_16x16x32_bf16 v[74:77], v[162:165], v[198:201], v[74:77]
	v_mfma_f32_16x16x32_bf16 v[66:69], v[158:161], v[202:205], v[66:69]
	v_mfma_f32_16x16x32_bf16 v[66:69], v[162:165], v[206:209], v[66:69]
	s_setprio 2
	s_barrier
	v_mfma_f32_16x16x32_bf16 v[70:73], v[150:153], v[202:205], v[70:73]
	v_mfma_f32_16x16x32_bf16 v[70:73], v[154:157], v[206:209], v[70:73]
	s_setprio 0
	ds_read_b128 v[166:169], v183 offset:49152
	ds_read_b128 v[170:173], v183 offset:50176
	ds_read_b128 v[186:189], v183 offset:51200
	ds_read_b128 v[190:193], v183 offset:52224
	ds_read_b128 v[194:197], v183 offset:53248
	ds_read_b128 v[198:201], v183 offset:54272
	ds_read_b128 v[202:205], v183 offset:55296
	ds_read_b128 v[206:209], v183 offset:56320
	s_add_u32 s24, s22, 0x40000
	s_addc_u32 s25, s23, 0
	s_mov_b32 s75, m0
	s_mov_b32 m0, s46
	s_nop 0
	global_load_lds_dwordx4 v176, s[24:25]
	s_mov_b32 m0, s75
	s_add_u32 s22, s22, 0x44000
	s_mov_b32 s75, m0
	s_mov_b32 m0, s47
	s_nop 0
	global_load_lds_dwordx4 v178, s[24:25]
	s_mov_b32 m0, s75
	s_addc_u32 s23, s23, 0
	s_mov_b32 s24, m0
	s_mov_b32 m0, s48
	s_nop 0
	global_load_lds_dwordx4 v176, s[22:23]
	s_mov_b32 m0, s24
	s_nop 0
	s_mov_b32 s24, m0
	s_mov_b32 m0, s49
	s_nop 0
	global_load_lds_dwordx4 v178, s[22:23]
	s_mov_b32 m0, s24
	s_waitcnt vmcnt(4)
	s_waitcnt lgkmcnt(0)
	s_barrier
	s_setprio 1
	.p2align 3
	v_mfma_f32_16x16x32_bf16 v[62:65], v[130:133], v[166:169], v[62:65]
	v_mfma_f32_16x16x32_bf16 v[62:65], v[134:137], v[170:173], v[62:65]
	v_mfma_f32_16x16x32_bf16 v[58:61], v[138:141], v[166:169], v[58:61]
	v_mfma_f32_16x16x32_bf16 v[58:61], v[142:145], v[170:173], v[58:61]
	v_mfma_f32_16x16x32_bf16 v[42:45], v[138:141], v[186:189], v[42:45]
	v_mfma_f32_16x16x32_bf16 v[42:45], v[142:145], v[190:193], v[42:45]
	v_mfma_f32_16x16x32_bf16 v[46:49], v[130:133], v[186:189], v[46:49]
	v_mfma_f32_16x16x32_bf16 v[46:49], v[134:137], v[190:193], v[46:49]
	v_mfma_f32_16x16x32_bf16 v[30:33], v[130:133], v[194:197], v[30:33]
	v_mfma_f32_16x16x32_bf16 v[30:33], v[134:137], v[198:201], v[30:33]
	v_mfma_f32_16x16x32_bf16 v[26:29], v[138:141], v[194:197], v[26:29]
	v_mfma_f32_16x16x32_bf16 v[26:29], v[142:145], v[198:201], v[26:29]
	v_mfma_f32_16x16x32_bf16 v[10:13], v[138:141], v[202:205], v[10:13]
	v_mfma_f32_16x16x32_bf16 v[10:13], v[142:145], v[206:209], v[10:13]
	v_mfma_f32_16x16x32_bf16 v[14:17], v[130:133], v[202:205], v[14:17]
	v_mfma_f32_16x16x32_bf16 v[14:17], v[134:137], v[206:209], v[14:17]
	v_mfma_f32_16x16x32_bf16 v[54:57], v[150:153], v[166:169], v[54:57]
	v_mfma_f32_16x16x32_bf16 v[54:57], v[154:157], v[170:173], v[54:57]
	v_mfma_f32_16x16x32_bf16 v[50:53], v[158:161], v[166:169], v[50:53]
	v_mfma_f32_16x16x32_bf16 v[50:53], v[162:165], v[170:173], v[50:53]
	v_mfma_f32_16x16x32_bf16 v[34:37], v[158:161], v[186:189], v[34:37]
	v_mfma_f32_16x16x32_bf16 v[34:37], v[162:165], v[190:193], v[34:37]
	v_mfma_f32_16x16x32_bf16 v[38:41], v[150:153], v[186:189], v[38:41]
	v_mfma_f32_16x16x32_bf16 v[38:41], v[154:157], v[190:193], v[38:41]
	v_mfma_f32_16x16x32_bf16 v[22:25], v[150:153], v[194:197], v[22:25]
	v_mfma_f32_16x16x32_bf16 v[22:25], v[154:157], v[198:201], v[22:25]
	v_mfma_f32_16x16x32_bf16 v[18:21], v[158:161], v[194:197], v[18:21]
	v_mfma_f32_16x16x32_bf16 v[18:21], v[162:165], v[198:201], v[18:21]
	v_mfma_f32_16x16x32_bf16 v[2:5], v[158:161], v[202:205], v[2:5]
	v_mfma_f32_16x16x32_bf16 v[2:5], v[162:165], v[206:209], v[2:5]
	s_setprio 2
	s_barrier
	v_mfma_f32_16x16x32_bf16 v[6:9], v[150:153], v[202:205], v[6:9]
	v_mfma_f32_16x16x32_bf16 v[6:9], v[154:157], v[206:209], v[6:9]
	s_setprio 0
	s_add_i32 s74, s74, 2
	s_add_u32 s67, s67, 0x80000
	s_addc_u32 s70, s70, 0
	s_add_u32 s20, s20, 0x400000
	s_addc_u32 s21, s21, 0
	s_add_u32 s71, s71, 0x400000
	s_addc_u32 s73, s73, 0
	s_cmpk_gt_u32 s74, 0x53
	.p2align 6
.LBB0_1952:
	ds_read_b128 v[130:133], v181
	ds_read_b128 v[134:137], v181 offset:1024
	ds_read_b128 v[138:141], v181 offset:2048
	ds_read_b128 v[142:145], v181 offset:3072
	ds_read_b128 v[150:153], v182
	ds_read_b128 v[154:157], v182 offset:1024
	ds_read_b128 v[158:161], v182 offset:2048
	ds_read_b128 v[162:165], v182 offset:3072
	s_cmpk_eq_i32 s74, 0x52
	s_cselect_b32 s23, s11, s70
	s_cselect_b32 s22, s66, s67
	s_cselect_b32 s25, s13, s73
	s_cselect_b32 s24, s65, s71
	ds_read_b128 v[166:169], v183
	ds_read_b128 v[170:173], v183 offset:1024
	ds_read_b128 v[186:189], v183 offset:2048
	ds_read_b128 v[190:193], v183 offset:3072
	ds_read_b128 v[194:197], v183 offset:4096
	ds_read_b128 v[198:201], v183 offset:5120
	ds_read_b128 v[202:205], v183 offset:6144
	ds_read_b128 v[206:209], v183 offset:7168
	s_add_u32 s76, s20, 0xffffc000
	s_addc_u32 s77, s21, -1
	s_mov_b32 s75, m0
	s_mov_b32 m0, s58
	s_nop 0
	global_load_lds_dwordx4 v1, s[76:77]
	s_mov_b32 m0, s75
	s_nop 0
	s_mov_b32 s75, m0
	s_mov_b32 m0, s62
	s_nop 0
	global_load_lds_dwordx4 v177, s[76:77]
	s_mov_b32 m0, s75
	s_nop 0
	s_mov_b32 s75, m0
	s_mov_b32 m0, s59
	s_nop 0
	global_load_lds_dwordx4 v1, s[20:21]
	s_mov_b32 m0, s75
	s_nop 0
	s_mov_b32 s75, m0
	s_mov_b32 m0, s63
	s_nop 0
	global_load_lds_dwordx4 v177, s[20:21]
	s_mov_b32 m0, s75
	s_waitcnt vmcnt(8)
	s_waitcnt lgkmcnt(0)
	s_barrier
	s_setprio 1
	.p2align 3
	v_mfma_f32_16x16x32_bf16 v[126:129], v[130:133], v[166:169], v[126:129]
	v_mfma_f32_16x16x32_bf16 v[126:129], v[134:137], v[170:173], v[126:129]
	v_mfma_f32_16x16x32_bf16 v[122:125], v[138:141], v[166:169], v[122:125]
	v_mfma_f32_16x16x32_bf16 v[122:125], v[142:145], v[170:173], v[122:125]
	v_mfma_f32_16x16x32_bf16 v[110:113], v[138:141], v[186:189], v[110:113]
	v_mfma_f32_16x16x32_bf16 v[110:113], v[142:145], v[190:193], v[110:113]
	v_mfma_f32_16x16x32_bf16 v[118:121], v[130:133], v[186:189], v[118:121]
	v_mfma_f32_16x16x32_bf16 v[118:121], v[134:137], v[190:193], v[118:121]
	v_mfma_f32_16x16x32_bf16 v[94:97], v[130:133], v[194:197], v[94:97]
	v_mfma_f32_16x16x32_bf16 v[94:97], v[134:137], v[198:201], v[94:97]
	v_mfma_f32_16x16x32_bf16 v[90:93], v[138:141], v[194:197], v[90:93]
	v_mfma_f32_16x16x32_bf16 v[90:93], v[142:145], v[198:201], v[90:93]
	v_mfma_f32_16x16x32_bf16 v[78:81], v[138:141], v[202:205], v[78:81]
	v_mfma_f32_16x16x32_bf16 v[78:81], v[142:145], v[206:209], v[78:81]
	v_mfma_f32_16x16x32_bf16 v[86:89], v[130:133], v[202:205], v[86:89]
	v_mfma_f32_16x16x32_bf16 v[86:89], v[134:137], v[206:209], v[86:89]
	v_mfma_f32_16x16x32_bf16 v[114:117], v[150:153], v[166:169], v[114:117]
	v_mfma_f32_16x16x32_bf16 v[114:117], v[154:157], v[170:173], v[114:117]
	v_mfma_f32_16x16x32_bf16 v[106:109], v[158:161], v[166:169], v[106:109]
	v_mfma_f32_16x16x32_bf16 v[106:109], v[162:165], v[170:173], v[106:109]
	v_mfma_f32_16x16x32_bf16 v[98:101], v[158:161], v[186:189], v[98:101]
	v_mfma_f32_16x16x32_bf16 v[98:101], v[162:165], v[190:193], v[98:101]
	v_mfma_f32_16x16x32_bf16 v[102:105], v[150:153], v[186:189], v[102:105]
	v_mfma_f32_16x16x32_bf16 v[102:105], v[154:157], v[190:193], v[102:105]
	v_mfma_f32_16x16x32_bf16 v[82:85], v[150:153], v[194:197], v[82:85]
	v_mfma_f32_16x16x32_bf16 v[82:85], v[154:157], v[198:201], v[82:85]
	v_mfma_f32_16x16x32_bf16 v[74:77], v[158:161], v[194:197], v[74:77]
	v_mfma_f32_16x16x32_bf16 v[74:77], v[162:165], v[198:201], v[74:77]
	v_mfma_f32_16x16x32_bf16 v[66:69], v[158:161], v[202:205], v[66:69]
	v_mfma_f32_16x16x32_bf16 v[66:69], v[162:165], v[206:209], v[66:69]
	s_setprio 2
	s_barrier
	v_mfma_f32_16x16x32_bf16 v[70:73], v[150:153], v[202:205], v[70:73]
	v_mfma_f32_16x16x32_bf16 v[70:73], v[154:157], v[206:209], v[70:73]
	s_setprio 0
	ds_read_b128 v[166:169], v183 offset:16384
	ds_read_b128 v[170:173], v183 offset:17408
	ds_read_b128 v[186:189], v183 offset:18432
	ds_read_b128 v[190:193], v183 offset:19456
	ds_read_b128 v[194:197], v183 offset:20480
	ds_read_b128 v[198:201], v183 offset:21504
	ds_read_b128 v[202:205], v183 offset:22528
	ds_read_b128 v[206:209], v183 offset:23552
	s_mov_b32 s75, m0
	s_mov_b32 m0, s35
	s_nop 0
	global_load_lds_dwordx4 v176, s[22:23]
	s_mov_b32 m0, s75
	s_add_u32 s76, s22, 0x4000
	s_mov_b32 s75, m0
	s_mov_b32 m0, s36
	s_nop 0
	global_load_lds_dwordx4 v178, s[22:23]
	s_mov_b32 m0, s75
	s_addc_u32 s77, s23, 0
	s_mov_b32 s75, m0
	s_mov_b32 m0, s37
	s_nop 0
	global_load_lds_dwordx4 v176, s[76:77]
	s_mov_b32 m0, s75
	s_nop 0
	s_mov_b32 s75, m0
	s_mov_b32 m0, s40
	s_nop 0
	global_load_lds_dwordx4 v178, s[76:77]
	s_mov_b32 m0, s75
	s_waitcnt vmcnt(4)
	s_waitcnt lgkmcnt(0)
	s_barrier
	s_setprio 1
	.p2align 3
	v_mfma_f32_16x16x32_bf16 v[62:65], v[130:133], v[166:169], v[62:65]
	v_mfma_f32_16x16x32_bf16 v[62:65], v[134:137], v[170:173], v[62:65]
	v_mfma_f32_16x16x32_bf16 v[58:61], v[138:141], v[166:169], v[58:61]
	v_mfma_f32_16x16x32_bf16 v[58:61], v[142:145], v[170:173], v[58:61]
	v_mfma_f32_16x16x32_bf16 v[42:45], v[138:141], v[186:189], v[42:45]
	v_mfma_f32_16x16x32_bf16 v[42:45], v[142:145], v[190:193], v[42:45]
	v_mfma_f32_16x16x32_bf16 v[46:49], v[130:133], v[186:189], v[46:49]
	v_mfma_f32_16x16x32_bf16 v[46:49], v[134:137], v[190:193], v[46:49]
	v_mfma_f32_16x16x32_bf16 v[30:33], v[130:133], v[194:197], v[30:33]
	v_mfma_f32_16x16x32_bf16 v[30:33], v[134:137], v[198:201], v[30:33]
	v_mfma_f32_16x16x32_bf16 v[26:29], v[138:141], v[194:197], v[26:29]
	v_mfma_f32_16x16x32_bf16 v[26:29], v[142:145], v[198:201], v[26:29]
	v_mfma_f32_16x16x32_bf16 v[10:13], v[138:141], v[202:205], v[10:13]
	v_mfma_f32_16x16x32_bf16 v[10:13], v[142:145], v[206:209], v[10:13]
	v_mfma_f32_16x16x32_bf16 v[14:17], v[130:133], v[202:205], v[14:17]
	v_mfma_f32_16x16x32_bf16 v[14:17], v[134:137], v[206:209], v[14:17]
	v_mfma_f32_16x16x32_bf16 v[54:57], v[150:153], v[166:169], v[54:57]
	v_mfma_f32_16x16x32_bf16 v[54:57], v[154:157], v[170:173], v[54:57]
	v_mfma_f32_16x16x32_bf16 v[50:53], v[158:161], v[166:169], v[50:53]
	v_mfma_f32_16x16x32_bf16 v[50:53], v[162:165], v[170:173], v[50:53]
	v_mfma_f32_16x16x32_bf16 v[34:37], v[158:161], v[186:189], v[34:37]
	v_mfma_f32_16x16x32_bf16 v[34:37], v[162:165], v[190:193], v[34:37]
	v_mfma_f32_16x16x32_bf16 v[38:41], v[150:153], v[186:189], v[38:41]
	v_mfma_f32_16x16x32_bf16 v[38:41], v[154:157], v[190:193], v[38:41]
	v_mfma_f32_16x16x32_bf16 v[22:25], v[150:153], v[194:197], v[22:25]
	v_mfma_f32_16x16x32_bf16 v[22:25], v[154:157], v[198:201], v[22:25]
	v_mfma_f32_16x16x32_bf16 v[18:21], v[158:161], v[194:197], v[18:21]
	v_mfma_f32_16x16x32_bf16 v[18:21], v[162:165], v[198:201], v[18:21]
	v_mfma_f32_16x16x32_bf16 v[2:5], v[158:161], v[202:205], v[2:5]
	v_mfma_f32_16x16x32_bf16 v[2:5], v[162:165], v[206:209], v[2:5]
	s_setprio 2
	s_barrier
	v_mfma_f32_16x16x32_bf16 v[6:9], v[150:153], v[202:205], v[6:9]
	v_mfma_f32_16x16x32_bf16 v[6:9], v[154:157], v[206:209], v[6:9]
	s_setprio 0
	ds_read_b128 v[130:133], v184
	ds_read_b128 v[134:137], v184 offset:1024
	ds_read_b128 v[138:141], v184 offset:2048
	ds_read_b128 v[142:145], v184 offset:3072
	ds_read_b128 v[150:153], v185
	ds_read_b128 v[154:157], v185 offset:1024
	ds_read_b128 v[158:161], v185 offset:2048
	ds_read_b128 v[162:165], v185 offset:3072
	ds_read_b128 v[166:169], v183 offset:32768
	ds_read_b128 v[170:173], v183 offset:33792
	ds_read_b128 v[186:189], v183 offset:34816
	ds_read_b128 v[190:193], v183 offset:35840
	ds_read_b128 v[194:197], v183 offset:36864
	ds_read_b128 v[198:201], v183 offset:37888
	ds_read_b128 v[202:205], v183 offset:38912
	ds_read_b128 v[206:209], v183 offset:39936
	s_mov_b32 s75, m0
	s_mov_b32 m0, s34
	s_nop 0
	global_load_lds_dwordx4 v1, s[24:25]
	s_mov_b32 m0, s75
	s_nop 0
	s_mov_b32 s75, m0
	s_mov_b32 m0, s41
	s_nop 0
	global_load_lds_dwordx4 v177, s[24:25]
	s_mov_b32 m0, s75
	s_add_u32 s24, s24, 0x4000
	s_addc_u32 s25, s25, 0
	s_mov_b32 s75, m0
	s_mov_b32 m0, s42
	s_nop 0
	global_load_lds_dwordx4 v1, s[24:25]
	s_mov_b32 m0, s75
	s_nop 0
	s_mov_b32 s75, m0
	s_mov_b32 m0, s43
	s_nop 0
	global_load_lds_dwordx4 v177, s[24:25]
	s_mov_b32 m0, s75
	s_waitcnt vmcnt(8)
	s_waitcnt lgkmcnt(0)
	s_barrier
	s_setprio 1
	.p2align 3
	v_mfma_f32_16x16x32_bf16 v[126:129], v[130:133], v[166:169], v[126:129]
	v_mfma_f32_16x16x32_bf16 v[126:129], v[134:137], v[170:173], v[126:129]
	v_mfma_f32_16x16x32_bf16 v[122:125], v[138:141], v[166:169], v[122:125]
	v_mfma_f32_16x16x32_bf16 v[122:125], v[142:145], v[170:173], v[122:125]
	v_mfma_f32_16x16x32_bf16 v[110:113], v[138:141], v[186:189], v[110:113]
	v_mfma_f32_16x16x32_bf16 v[110:113], v[142:145], v[190:193], v[110:113]
	v_mfma_f32_16x16x32_bf16 v[118:121], v[130:133], v[186:189], v[118:121]
	v_mfma_f32_16x16x32_bf16 v[118:121], v[134:137], v[190:193], v[118:121]
	v_mfma_f32_16x16x32_bf16 v[94:97], v[130:133], v[194:197], v[94:97]
	v_mfma_f32_16x16x32_bf16 v[94:97], v[134:137], v[198:201], v[94:97]
	v_mfma_f32_16x16x32_bf16 v[90:93], v[138:141], v[194:197], v[90:93]
	v_mfma_f32_16x16x32_bf16 v[90:93], v[142:145], v[198:201], v[90:93]
	v_mfma_f32_16x16x32_bf16 v[78:81], v[138:141], v[202:205], v[78:81]
	v_mfma_f32_16x16x32_bf16 v[78:81], v[142:145], v[206:209], v[78:81]
	v_mfma_f32_16x16x32_bf16 v[86:89], v[130:133], v[202:205], v[86:89]
	v_mfma_f32_16x16x32_bf16 v[86:89], v[134:137], v[206:209], v[86:89]
	v_mfma_f32_16x16x32_bf16 v[114:117], v[150:153], v[166:169], v[114:117]
	v_mfma_f32_16x16x32_bf16 v[114:117], v[154:157], v[170:173], v[114:117]
	v_mfma_f32_16x16x32_bf16 v[106:109], v[158:161], v[166:169], v[106:109]
	v_mfma_f32_16x16x32_bf16 v[106:109], v[162:165], v[170:173], v[106:109]
	v_mfma_f32_16x16x32_bf16 v[98:101], v[158:161], v[186:189], v[98:101]
	v_mfma_f32_16x16x32_bf16 v[98:101], v[162:165], v[190:193], v[98:101]
	v_mfma_f32_16x16x32_bf16 v[102:105], v[150:153], v[186:189], v[102:105]
	v_mfma_f32_16x16x32_bf16 v[102:105], v[154:157], v[190:193], v[102:105]
	v_mfma_f32_16x16x32_bf16 v[82:85], v[150:153], v[194:197], v[82:85]
	v_mfma_f32_16x16x32_bf16 v[82:85], v[154:157], v[198:201], v[82:85]
	v_mfma_f32_16x16x32_bf16 v[74:77], v[158:161], v[194:197], v[74:77]
	v_mfma_f32_16x16x32_bf16 v[74:77], v[162:165], v[198:201], v[74:77]
	v_mfma_f32_16x16x32_bf16 v[66:69], v[158:161], v[202:205], v[66:69]
	v_mfma_f32_16x16x32_bf16 v[66:69], v[162:165], v[206:209], v[66:69]
	s_setprio 2
	s_barrier
	v_mfma_f32_16x16x32_bf16 v[70:73], v[150:153], v[202:205], v[70:73]
	v_mfma_f32_16x16x32_bf16 v[70:73], v[154:157], v[206:209], v[70:73]
	s_setprio 0
	ds_read_b128 v[166:169], v183 offset:49152
	ds_read_b128 v[170:173], v183 offset:50176
	ds_read_b128 v[186:189], v183 offset:51200
	ds_read_b128 v[190:193], v183 offset:52224
	ds_read_b128 v[194:197], v183 offset:53248
	ds_read_b128 v[198:201], v183 offset:54272
	ds_read_b128 v[202:205], v183 offset:55296
	ds_read_b128 v[206:209], v183 offset:56320
	s_add_u32 s24, s22, 0x40000
	s_addc_u32 s25, s23, 0
	s_mov_b32 s75, m0
	s_mov_b32 m0, s46
	s_nop 0
	global_load_lds_dwordx4 v176, s[24:25]
	s_mov_b32 m0, s75
	s_add_u32 s22, s22, 0x44000
	s_mov_b32 s75, m0
	s_mov_b32 m0, s47
	s_nop 0
	global_load_lds_dwordx4 v178, s[24:25]
	s_mov_b32 m0, s75
	s_addc_u32 s23, s23, 0
	s_mov_b32 s24, m0
	s_mov_b32 m0, s48
	s_nop 0
	global_load_lds_dwordx4 v176, s[22:23]
	s_mov_b32 m0, s24
	s_nop 0
	s_mov_b32 s24, m0
	s_mov_b32 m0, s49
	s_nop 0
	global_load_lds_dwordx4 v178, s[22:23]
	s_mov_b32 m0, s24
	s_waitcnt vmcnt(4)
	s_waitcnt lgkmcnt(0)
	s_barrier
	s_setprio 1
	.p2align 3
	v_mfma_f32_16x16x32_bf16 v[62:65], v[130:133], v[166:169], v[62:65]
	v_mfma_f32_16x16x32_bf16 v[62:65], v[134:137], v[170:173], v[62:65]
	v_mfma_f32_16x16x32_bf16 v[58:61], v[138:141], v[166:169], v[58:61]
	v_mfma_f32_16x16x32_bf16 v[58:61], v[142:145], v[170:173], v[58:61]
	v_mfma_f32_16x16x32_bf16 v[42:45], v[138:141], v[186:189], v[42:45]
	v_mfma_f32_16x16x32_bf16 v[42:45], v[142:145], v[190:193], v[42:45]
	v_mfma_f32_16x16x32_bf16 v[46:49], v[130:133], v[186:189], v[46:49]
	v_mfma_f32_16x16x32_bf16 v[46:49], v[134:137], v[190:193], v[46:49]
	v_mfma_f32_16x16x32_bf16 v[30:33], v[130:133], v[194:197], v[30:33]
	v_mfma_f32_16x16x32_bf16 v[30:33], v[134:137], v[198:201], v[30:33]
	v_mfma_f32_16x16x32_bf16 v[26:29], v[138:141], v[194:197], v[26:29]
	v_mfma_f32_16x16x32_bf16 v[26:29], v[142:145], v[198:201], v[26:29]
	v_mfma_f32_16x16x32_bf16 v[10:13], v[138:141], v[202:205], v[10:13]
	v_mfma_f32_16x16x32_bf16 v[10:13], v[142:145], v[206:209], v[10:13]
	v_mfma_f32_16x16x32_bf16 v[14:17], v[130:133], v[202:205], v[14:17]
	v_mfma_f32_16x16x32_bf16 v[14:17], v[134:137], v[206:209], v[14:17]
	v_mfma_f32_16x16x32_bf16 v[54:57], v[150:153], v[166:169], v[54:57]
	v_mfma_f32_16x16x32_bf16 v[54:57], v[154:157], v[170:173], v[54:57]
	v_mfma_f32_16x16x32_bf16 v[50:53], v[158:161], v[166:169], v[50:53]
	v_mfma_f32_16x16x32_bf16 v[50:53], v[162:165], v[170:173], v[50:53]
	v_mfma_f32_16x16x32_bf16 v[34:37], v[158:161], v[186:189], v[34:37]
	v_mfma_f32_16x16x32_bf16 v[34:37], v[162:165], v[190:193], v[34:37]
	v_mfma_f32_16x16x32_bf16 v[38:41], v[150:153], v[186:189], v[38:41]
	v_mfma_f32_16x16x32_bf16 v[38:41], v[154:157], v[190:193], v[38:41]
	v_mfma_f32_16x16x32_bf16 v[22:25], v[150:153], v[194:197], v[22:25]
	v_mfma_f32_16x16x32_bf16 v[22:25], v[154:157], v[198:201], v[22:25]
	v_mfma_f32_16x16x32_bf16 v[18:21], v[158:161], v[194:197], v[18:21]
	v_mfma_f32_16x16x32_bf16 v[18:21], v[162:165], v[198:201], v[18:21]
	v_mfma_f32_16x16x32_bf16 v[2:5], v[158:161], v[202:205], v[2:5]
	v_mfma_f32_16x16x32_bf16 v[2:5], v[162:165], v[206:209], v[2:5]
	s_setprio 2
	s_barrier
	v_mfma_f32_16x16x32_bf16 v[6:9], v[150:153], v[202:205], v[6:9]
	v_mfma_f32_16x16x32_bf16 v[6:9], v[154:157], v[206:209], v[6:9]
	s_setprio 0
	s_add_i32 s74, s74, 2
	s_add_u32 s67, s67, 0x80000
	s_addc_u32 s70, s70, 0
	s_add_u32 s20, s20, 0x400000
	s_addc_u32 s21, s21, 0
	s_add_u32 s71, s71, 0x400000
	s_addc_u32 s73, s73, 0
	s_cmpk_gt_u32 s74, 0x53
	s_cbranch_scc0 .LBB0_1952
	s_and_b64 vcc, exec, s[8:9]
	s_cbranch_vccz .LBB0_1955
	s_barrier

.LBB0_2145:
	s_ashr_i32 s25, s24, 31
	s_lshl_b64 s[26:27], s[24:25], 20
	s_add_u32 s26, s33, s26
	s_addc_u32 s27, s42, s27
	s_and_b64 s[28:29], s[2:3], exec
	s_cselect_b32 s5, s27, s37
	s_cselect_b32 s25, s26, s36
	s_ashr_i32 s23, s22, 31
	s_lshl_b64 s[28:29], s[22:23], 20
	s_add_u32 s28, s43, s28
	s_addc_u32 s29, s46, s29
	s_and_b64 s[40:41], s[2:3], exec
	s_cselect_b32 s23, s29, s35
	s_cselect_b32 s31, s28, s34
	s_add_u32 s77, s34, 0x100
	s_addc_u32 s78, s35, 0
	s_add_u32 s34, s36, 0x80080
	s_addc_u32 s35, s37, 0
	s_add_u32 s79, s36, 0x100
	s_addc_u32 s80, s37, 0
	s_mov_b32 s81, -2
	s_waitcnt vmcnt(25)
	s_waitcnt vmcnt(24)
	s_waitcnt vmcnt(4)
	s_waitcnt vmcnt(2)
	s_waitcnt vmcnt(1)
	s_waitcnt vmcnt(0)
	ds_read_b128 v[42:45], v181
	ds_read_b128 v[46:49], v181 offset:1024
	ds_read_b128 v[58:61], v181 offset:2048
	ds_read_b128 v[62:65], v181 offset:3072
	ds_read_b128 v[146:149], v182
	ds_read_b128 v[150:153], v182 offset:1024
	ds_read_b128 v[154:157], v182 offset:2048
	ds_read_b128 v[158:161], v182 offset:3072
	s_cmp_eq_u32 s81, 28
	s_cselect_b32 s37, s23, s78
	s_cselect_b32 s36, s31, s77
	s_cselect_b32 s41, s5, s80
	s_cselect_b32 s40, s25, s79
	ds_read_b128 v[170:173], v183
	ds_read_b128 v[188:191], v183 offset:1024
	ds_read_b128 v[192:195], v183 offset:2048
	ds_read_b128 v[196:199], v183 offset:3072
	ds_read_b128 v[200:203], v183 offset:4096
	ds_read_b128 v[204:207], v183 offset:5120
	ds_read_b128 v[208:211], v183 offset:6144
	ds_read_b128 v[212:215], v183 offset:7168
	s_add_u32 s82, s34, 0xfff80000
	s_addc_u32 s83, s35, -1
	s_mov_b32 s86, m0
	s_mov_b32 m0, s70
	s_nop 0
	global_load_lds_dwordx4 v1, s[82:83]
	s_mov_b32 m0, s86
	s_nop 0
	s_mov_b32 s86, m0
	s_mov_b32 m0, s73
	s_nop 0
	global_load_lds_dwordx4 v177, s[82:83]
	s_mov_b32 m0, s86
	s_mov_b32 s82, m0
	s_mov_b32 m0, s71
	s_nop 0
	global_load_lds_dwordx4 v1, s[34:35]
	s_mov_b32 m0, s82
	s_nop 0
	s_mov_b32 s82, m0
	s_mov_b32 m0, s74
	s_nop 0
	global_load_lds_dwordx4 v177, s[34:35]
	s_mov_b32 m0, s82
	s_waitcnt vmcnt(8)
	s_waitcnt lgkmcnt(0)
	s_barrier
	s_setprio 1
	.p2align 3
	v_mfma_f32_16x16x32_bf16 v[142:145], v[42:45], v[170:173], 0
	v_mfma_f32_16x16x32_bf16 v[142:145], v[46:49], v[188:191], v[142:145]
	v_mfma_f32_16x16x32_bf16 v[138:141], v[58:61], v[170:173], 0
	v_mfma_f32_16x16x32_bf16 v[138:141], v[62:65], v[188:191], v[138:141]
	v_mfma_f32_16x16x32_bf16 v[126:129], v[42:45], v[192:195], 0
	v_mfma_f32_16x16x32_bf16 v[126:129], v[46:49], v[196:199], v[126:129]
	v_mfma_f32_16x16x32_bf16 v[122:125], v[58:61], v[192:195], 0
	v_mfma_f32_16x16x32_bf16 v[122:125], v[62:65], v[196:199], v[122:125]
	v_mfma_f32_16x16x32_bf16 v[110:113], v[42:45], v[200:203], 0
	v_mfma_f32_16x16x32_bf16 v[110:113], v[46:49], v[204:207], v[110:113]
	v_mfma_f32_16x16x32_bf16 v[106:109], v[58:61], v[200:203], 0
	v_mfma_f32_16x16x32_bf16 v[106:109], v[62:65], v[204:207], v[106:109]
	v_mfma_f32_16x16x32_bf16 v[94:97], v[42:45], v[208:211], 0
	v_mfma_f32_16x16x32_bf16 v[94:97], v[46:49], v[212:215], v[94:97]
	v_mfma_f32_16x16x32_bf16 v[90:93], v[58:61], v[208:211], 0
	v_mfma_f32_16x16x32_bf16 v[90:93], v[62:65], v[212:215], v[90:93]
	v_mfma_f32_16x16x32_bf16 v[134:137], v[146:149], v[170:173], 0
	v_mfma_f32_16x16x32_bf16 v[134:137], v[150:153], v[188:191], v[134:137]
	v_mfma_f32_16x16x32_bf16 v[130:133], v[154:157], v[170:173], 0
	v_mfma_f32_16x16x32_bf16 v[130:133], v[158:161], v[188:191], v[130:133]
	v_mfma_f32_16x16x32_bf16 v[118:121], v[146:149], v[192:195], 0
	v_mfma_f32_16x16x32_bf16 v[118:121], v[150:153], v[196:199], v[118:121]
	v_mfma_f32_16x16x32_bf16 v[114:117], v[154:157], v[192:195], 0
	v_mfma_f32_16x16x32_bf16 v[114:117], v[158:161], v[196:199], v[114:117]
	v_mfma_f32_16x16x32_bf16 v[102:105], v[146:149], v[200:203], 0
	v_mfma_f32_16x16x32_bf16 v[102:105], v[150:153], v[204:207], v[102:105]
	v_mfma_f32_16x16x32_bf16 v[98:101], v[154:157], v[200:203], 0
	v_mfma_f32_16x16x32_bf16 v[98:101], v[158:161], v[204:207], v[98:101]
	v_mfma_f32_16x16x32_bf16 v[86:89], v[146:149], v[208:211], 0
	v_mfma_f32_16x16x32_bf16 v[86:89], v[150:153], v[212:215], v[86:89]
	s_setprio 2
	s_barrier
	v_mfma_f32_16x16x32_bf16 v[82:85], v[154:157], v[208:211], 0
	v_mfma_f32_16x16x32_bf16 v[82:85], v[158:161], v[212:215], v[82:85]
	s_setprio 0
	ds_read_b128 v[170:173], v183 offset:16384
	ds_read_b128 v[188:191], v183 offset:17408
	ds_read_b128 v[192:195], v183 offset:18432
	ds_read_b128 v[196:199], v183 offset:19456
	ds_read_b128 v[200:203], v183 offset:20480
	ds_read_b128 v[204:207], v183 offset:21504
	ds_read_b128 v[208:211], v183 offset:22528
	ds_read_b128 v[212:215], v183 offset:23552
	s_mov_b32 s82, m0
	s_mov_b32 m0, s49
	s_nop 0
	global_load_lds_dwordx4 v176, s[36:37]
	s_mov_b32 m0, s82
	s_nop 0
	s_mov_b32 s82, m0
	s_mov_b32 m0, s56
	s_nop 0
	global_load_lds_dwordx4 v178, s[36:37]
	s_mov_b32 m0, s82
	s_add_u32 s82, s36, 0x80000
	s_addc_u32 s83, s37, 0
	s_mov_b32 s86, m0
	s_mov_b32 m0, s57
	s_nop 0
	global_load_lds_dwordx4 v176, s[82:83]
	s_mov_b32 m0, s86
	s_nop 0
	s_mov_b32 s86, m0
	s_mov_b32 m0, s58
	s_nop 0
	global_load_lds_dwordx4 v178, s[82:83]
	s_mov_b32 m0, s86
	s_waitcnt vmcnt(4)
	s_waitcnt lgkmcnt(0)
	s_barrier
	s_setprio 1
	.p2align 3
	v_mfma_f32_16x16x32_bf16 v[78:81], v[42:45], v[170:173], 0
	v_mfma_f32_16x16x32_bf16 v[78:81], v[46:49], v[188:191], v[78:81]
	v_mfma_f32_16x16x32_bf16 v[74:77], v[58:61], v[170:173], 0
	v_mfma_f32_16x16x32_bf16 v[74:77], v[62:65], v[188:191], v[74:77]
	v_mfma_f32_16x16x32_bf16 v[54:57], v[42:45], v[192:195], 0
	v_mfma_f32_16x16x32_bf16 v[54:57], v[46:49], v[196:199], v[54:57]
	v_mfma_f32_16x16x32_bf16 v[50:53], v[58:61], v[192:195], 0
	v_mfma_f32_16x16x32_bf16 v[50:53], v[62:65], v[196:199], v[50:53]
	v_mfma_f32_16x16x32_bf16 v[30:33], v[42:45], v[200:203], 0
	v_mfma_f32_16x16x32_bf16 v[30:33], v[46:49], v[204:207], v[30:33]
	v_mfma_f32_16x16x32_bf16 v[26:29], v[58:61], v[200:203], 0
	v_mfma_f32_16x16x32_bf16 v[26:29], v[62:65], v[204:207], v[26:29]
	v_mfma_f32_16x16x32_bf16 v[14:17], v[42:45], v[208:211], 0
	v_mfma_f32_16x16x32_bf16 v[14:17], v[46:49], v[212:215], v[14:17]
	v_mfma_f32_16x16x32_bf16 v[10:13], v[58:61], v[208:211], 0
	v_mfma_f32_16x16x32_bf16 v[10:13], v[62:65], v[212:215], v[10:13]
	v_mfma_f32_16x16x32_bf16 v[38:41], v[146:149], v[192:195], 0
	v_mfma_f32_16x16x32_bf16 v[38:41], v[150:153], v[196:199], v[38:41]
	v_mfma_f32_16x16x32_bf16 v[34:37], v[154:157], v[192:195], 0
	v_mfma_f32_16x16x32_bf16 v[34:37], v[158:161], v[196:199], v[34:37]
	v_mfma_f32_16x16x32_bf16 v[22:25], v[146:149], v[200:203], 0
	v_mfma_f32_16x16x32_bf16 v[22:25], v[150:153], v[204:207], v[22:25]
	v_mfma_f32_16x16x32_bf16 v[18:21], v[154:157], v[200:203], 0
	v_mfma_f32_16x16x32_bf16 v[18:21], v[158:161], v[204:207], v[18:21]
	v_mfma_f32_16x16x32_bf16 v[6:9], v[146:149], v[208:211], 0
	v_mfma_f32_16x16x32_bf16 v[6:9], v[150:153], v[212:215], v[6:9]
	v_mfma_f32_16x16x32_bf16 v[2:5], v[154:157], v[208:211], 0
	v_mfma_f32_16x16x32_bf16 v[2:5], v[158:161], v[212:215], v[2:5]
	v_mfma_f32_16x16x32_bf16 v[42:45], v[146:149], v[170:173], 0
	v_mfma_f32_16x16x32_bf16 v[42:45], v[150:153], v[188:191], v[42:45]
	s_setprio 2
	s_barrier
	v_mfma_f32_16x16x32_bf16 v[46:49], v[154:157], v[170:173], 0
	v_mfma_f32_16x16x32_bf16 v[46:49], v[158:161], v[188:191], v[46:49]
	s_setprio 0
	ds_read_b128 v[58:61], v184
	ds_read_b128 v[62:65], v184 offset:1024
	ds_read_b128 v[66:69], v184 offset:2048
	ds_read_b128 v[70:73], v184 offset:3072
	ds_read_b128 v[146:149], v185
	ds_read_b128 v[150:153], v185 offset:1024
	ds_read_b128 v[154:157], v185 offset:2048
	ds_read_b128 v[158:161], v185 offset:3072
	ds_read_b128 v[170:173], v183 offset:32768
	ds_read_b128 v[188:191], v183 offset:33792
	ds_read_b128 v[192:195], v183 offset:34816
	ds_read_b128 v[196:199], v183 offset:35840
	ds_read_b128 v[200:203], v183 offset:36864
	ds_read_b128 v[204:207], v183 offset:37888
	ds_read_b128 v[208:211], v183 offset:38912
	ds_read_b128 v[212:215], v183 offset:39936
	s_mov_b32 s82, m0
	s_mov_b32 m0, s48
	s_nop 0
	global_load_lds_dwordx4 v1, s[40:41]
	s_mov_b32 m0, s82
	s_nop 0
	s_mov_b32 s82, m0
	s_mov_b32 m0, s59
	s_nop 0
	global_load_lds_dwordx4 v177, s[40:41]
	s_mov_b32 m0, s82
	s_add_u32 s40, s40, 0x80000
	s_addc_u32 s41, s41, 0
	s_mov_b32 s82, m0
	s_mov_b32 m0, s62
	s_nop 0
	global_load_lds_dwordx4 v1, s[40:41]
	s_mov_b32 m0, s82
	s_nop 0
	s_mov_b32 s82, m0
	s_mov_b32 m0, s63
	s_nop 0
	global_load_lds_dwordx4 v177, s[40:41]
	s_mov_b32 m0, s82
	s_waitcnt vmcnt(8)
	s_waitcnt lgkmcnt(0)
	s_barrier
	s_setprio 1
	.p2align 3
	v_mfma_f32_16x16x32_bf16 v[142:145], v[58:61], v[170:173], v[142:145]
	v_mfma_f32_16x16x32_bf16 v[142:145], v[62:65], v[188:191], v[142:145]
	v_mfma_f32_16x16x32_bf16 v[138:141], v[66:69], v[170:173], v[138:141]
	v_mfma_f32_16x16x32_bf16 v[138:141], v[70:73], v[188:191], v[138:141]
	v_mfma_f32_16x16x32_bf16 v[126:129], v[58:61], v[192:195], v[126:129]
	v_mfma_f32_16x16x32_bf16 v[126:129], v[62:65], v[196:199], v[126:129]
	v_mfma_f32_16x16x32_bf16 v[122:125], v[66:69], v[192:195], v[122:125]
	v_mfma_f32_16x16x32_bf16 v[122:125], v[70:73], v[196:199], v[122:125]
	v_mfma_f32_16x16x32_bf16 v[110:113], v[58:61], v[200:203], v[110:113]
	v_mfma_f32_16x16x32_bf16 v[110:113], v[62:65], v[204:207], v[110:113]
	v_mfma_f32_16x16x32_bf16 v[106:109], v[66:69], v[200:203], v[106:109]
	v_mfma_f32_16x16x32_bf16 v[106:109], v[70:73], v[204:207], v[106:109]
	v_mfma_f32_16x16x32_bf16 v[94:97], v[58:61], v[208:211], v[94:97]
	v_mfma_f32_16x16x32_bf16 v[94:97], v[62:65], v[212:215], v[94:97]
	v_mfma_f32_16x16x32_bf16 v[90:93], v[66:69], v[208:211], v[90:93]
	v_mfma_f32_16x16x32_bf16 v[90:93], v[70:73], v[212:215], v[90:93]
	v_mfma_f32_16x16x32_bf16 v[134:137], v[146:149], v[170:173], v[134:137]
	v_mfma_f32_16x16x32_bf16 v[134:137], v[150:153], v[188:191], v[134:137]
	v_mfma_f32_16x16x32_bf16 v[130:133], v[154:157], v[170:173], v[130:133]
	v_mfma_f32_16x16x32_bf16 v[130:133], v[158:161], v[188:191], v[130:133]
	v_mfma_f32_16x16x32_bf16 v[118:121], v[146:149], v[192:195], v[118:121]
	v_mfma_f32_16x16x32_bf16 v[118:121], v[150:153], v[196:199], v[118:121]
	v_mfma_f32_16x16x32_bf16 v[114:117], v[154:157], v[192:195], v[114:117]
	v_mfma_f32_16x16x32_bf16 v[114:117], v[158:161], v[196:199], v[114:117]
	v_mfma_f32_16x16x32_bf16 v[102:105], v[146:149], v[200:203], v[102:105]
	v_mfma_f32_16x16x32_bf16 v[102:105], v[150:153], v[204:207], v[102:105]
	v_mfma_f32_16x16x32_bf16 v[98:101], v[154:157], v[200:203], v[98:101]
	v_mfma_f32_16x16x32_bf16 v[98:101], v[158:161], v[204:207], v[98:101]
	v_mfma_f32_16x16x32_bf16 v[86:89], v[146:149], v[208:211], v[86:89]
	v_mfma_f32_16x16x32_bf16 v[86:89], v[150:153], v[212:215], v[86:89]
	s_setprio 2
	s_barrier
	v_mfma_f32_16x16x32_bf16 v[82:85], v[154:157], v[208:211], v[82:85]
	v_mfma_f32_16x16x32_bf16 v[82:85], v[158:161], v[212:215], v[82:85]
	s_setprio 0
	ds_read_b128 v[170:173], v183 offset:49152
	ds_read_b128 v[188:191], v183 offset:50176
	ds_read_b128 v[192:195], v183 offset:51200
	ds_read_b128 v[196:199], v183 offset:52224
	ds_read_b128 v[200:203], v183 offset:53248
	ds_read_b128 v[204:207], v183 offset:54272
	ds_read_b128 v[208:211], v183 offset:55296
	ds_read_b128 v[212:215], v183 offset:56320
	s_add_u32 s40, s36, 0x80
	s_addc_u32 s41, s37, 0
	s_mov_b32 s82, m0
	s_mov_b32 m0, s64
	s_nop 0
	global_load_lds_dwordx4 v176, s[40:41]
	s_mov_b32 m0, s82
	s_add_u32 s36, s36, 0x80080
	s_mov_b32 s82, m0
	s_mov_b32 m0, s65
	s_nop 0
	global_load_lds_dwordx4 v178, s[40:41]
	s_mov_b32 m0, s82
	s_addc_u32 s37, s37, 0
	s_mov_b32 s40, m0
	s_mov_b32 m0, s66
	s_nop 0
	global_load_lds_dwordx4 v176, s[36:37]
	s_mov_b32 m0, s40
	s_nop 0
	s_mov_b32 s40, m0
	s_mov_b32 m0, s67
	s_nop 0
	global_load_lds_dwordx4 v178, s[36:37]
	s_mov_b32 m0, s40
	s_waitcnt vmcnt(4)
	s_waitcnt lgkmcnt(0)
	s_barrier
	s_setprio 1
	.p2align 3
	v_mfma_f32_16x16x32_bf16 v[78:81], v[58:61], v[170:173], v[78:81]
	v_mfma_f32_16x16x32_bf16 v[78:81], v[62:65], v[188:191], v[78:81]
	v_mfma_f32_16x16x32_bf16 v[74:77], v[66:69], v[170:173], v[74:77]
	v_mfma_f32_16x16x32_bf16 v[74:77], v[70:73], v[188:191], v[74:77]
	v_mfma_f32_16x16x32_bf16 v[54:57], v[58:61], v[192:195], v[54:57]
	v_mfma_f32_16x16x32_bf16 v[54:57], v[62:65], v[196:199], v[54:57]
	v_mfma_f32_16x16x32_bf16 v[50:53], v[66:69], v[192:195], v[50:53]
	v_mfma_f32_16x16x32_bf16 v[50:53], v[70:73], v[196:199], v[50:53]
	v_mfma_f32_16x16x32_bf16 v[30:33], v[58:61], v[200:203], v[30:33]
	v_mfma_f32_16x16x32_bf16 v[30:33], v[62:65], v[204:207], v[30:33]
	v_mfma_f32_16x16x32_bf16 v[26:29], v[66:69], v[200:203], v[26:29]
	v_mfma_f32_16x16x32_bf16 v[26:29], v[70:73], v[204:207], v[26:29]
	v_mfma_f32_16x16x32_bf16 v[14:17], v[58:61], v[208:211], v[14:17]
	v_mfma_f32_16x16x32_bf16 v[14:17], v[62:65], v[212:215], v[14:17]
	v_mfma_f32_16x16x32_bf16 v[10:13], v[66:69], v[208:211], v[10:13]
	v_mfma_f32_16x16x32_bf16 v[10:13], v[70:73], v[212:215], v[10:13]
	v_mfma_f32_16x16x32_bf16 v[42:45], v[146:149], v[170:173], v[42:45]
	v_mfma_f32_16x16x32_bf16 v[70:73], v[150:153], v[188:191], v[42:45]
	v_mfma_f32_16x16x32_bf16 v[42:45], v[154:157], v[170:173], v[46:49]
	v_mfma_f32_16x16x32_bf16 v[66:69], v[158:161], v[188:191], v[42:45]
	v_mfma_f32_16x16x32_bf16 v[38:41], v[146:149], v[192:195], v[38:41]
	v_mfma_f32_16x16x32_bf16 v[38:41], v[150:153], v[196:199], v[38:41]
	v_mfma_f32_16x16x32_bf16 v[34:37], v[154:157], v[192:195], v[34:37]
	v_mfma_f32_16x16x32_bf16 v[34:37], v[158:161], v[196:199], v[34:37]
	v_mfma_f32_16x16x32_bf16 v[22:25], v[146:149], v[200:203], v[22:25]
	v_mfma_f32_16x16x32_bf16 v[22:25], v[150:153], v[204:207], v[22:25]
	v_mfma_f32_16x16x32_bf16 v[18:21], v[154:157], v[200:203], v[18:21]
	v_mfma_f32_16x16x32_bf16 v[18:21], v[158:161], v[204:207], v[18:21]
	v_mfma_f32_16x16x32_bf16 v[6:9], v[146:149], v[208:211], v[6:9]
	v_mfma_f32_16x16x32_bf16 v[6:9], v[150:153], v[212:215], v[6:9]
	s_setprio 2
	s_barrier
	v_mfma_f32_16x16x32_bf16 v[2:5], v[154:157], v[208:211], v[2:5]
	v_mfma_f32_16x16x32_bf16 v[2:5], v[158:161], v[212:215], v[2:5]
	s_setprio 0
	s_add_i32 s81, s81, 2
	s_add_u32 s77, s77, 0x100
	s_addc_u32 s78, s78, 0
	s_add_u32 s34, s34, 0x100
	s_addc_u32 s35, s35, 0
	s_add_u32 s79, s79, 0x100
	s_addc_u32 s80, s80, 0
	s_cmp_gt_u32 s81, 29
	.p2align 6
.LBB0_2146:
	ds_read_b128 v[42:45], v181
	ds_read_b128 v[46:49], v181 offset:1024
	ds_read_b128 v[58:61], v181 offset:2048
	ds_read_b128 v[62:65], v181 offset:3072
	ds_read_b128 v[146:149], v182
	ds_read_b128 v[150:153], v182 offset:1024
	ds_read_b128 v[154:157], v182 offset:2048
	ds_read_b128 v[158:161], v182 offset:3072
	s_cmp_eq_u32 s81, 28
	s_cselect_b32 s37, s23, s78
	s_cselect_b32 s36, s31, s77
	s_cselect_b32 s41, s5, s80
	s_cselect_b32 s40, s25, s79
	ds_read_b128 v[170:173], v183
	ds_read_b128 v[188:191], v183 offset:1024
	ds_read_b128 v[192:195], v183 offset:2048
	ds_read_b128 v[196:199], v183 offset:3072
	ds_read_b128 v[200:203], v183 offset:4096
	ds_read_b128 v[204:207], v183 offset:5120
	ds_read_b128 v[208:211], v183 offset:6144
	ds_read_b128 v[212:215], v183 offset:7168
	s_add_u32 s82, s34, 0xfff80000
	s_addc_u32 s83, s35, -1
	s_mov_b32 s86, m0
	s_mov_b32 m0, s70
	s_nop 0
	global_load_lds_dwordx4 v1, s[82:83]
	s_mov_b32 m0, s86
	s_nop 0
	s_mov_b32 s86, m0
	s_mov_b32 m0, s73
	s_nop 0
	global_load_lds_dwordx4 v177, s[82:83]
	s_mov_b32 m0, s86
	s_mov_b32 s82, m0
	s_mov_b32 m0, s71
	s_nop 0
	global_load_lds_dwordx4 v1, s[34:35]
	s_mov_b32 m0, s82
	s_nop 0
	s_mov_b32 s82, m0
	s_mov_b32 m0, s74
	s_nop 0
	global_load_lds_dwordx4 v177, s[34:35]
	s_mov_b32 m0, s82
	s_waitcnt vmcnt(8)
	s_waitcnt lgkmcnt(0)
	s_barrier
	s_setprio 1
	.p2align 3
	v_mfma_f32_16x16x32_bf16 v[142:145], v[42:45], v[170:173], v[142:145]
	v_mfma_f32_16x16x32_bf16 v[142:145], v[46:49], v[188:191], v[142:145]
	v_mfma_f32_16x16x32_bf16 v[138:141], v[58:61], v[170:173], v[138:141]
	v_mfma_f32_16x16x32_bf16 v[138:141], v[62:65], v[188:191], v[138:141]
	v_mfma_f32_16x16x32_bf16 v[126:129], v[42:45], v[192:195], v[126:129]
	v_mfma_f32_16x16x32_bf16 v[126:129], v[46:49], v[196:199], v[126:129]
	v_mfma_f32_16x16x32_bf16 v[122:125], v[58:61], v[192:195], v[122:125]
	v_mfma_f32_16x16x32_bf16 v[122:125], v[62:65], v[196:199], v[122:125]
	v_mfma_f32_16x16x32_bf16 v[110:113], v[42:45], v[200:203], v[110:113]
	v_mfma_f32_16x16x32_bf16 v[110:113], v[46:49], v[204:207], v[110:113]
	v_mfma_f32_16x16x32_bf16 v[106:109], v[58:61], v[200:203], v[106:109]
	v_mfma_f32_16x16x32_bf16 v[106:109], v[62:65], v[204:207], v[106:109]
	v_mfma_f32_16x16x32_bf16 v[94:97], v[42:45], v[208:211], v[94:97]
	v_mfma_f32_16x16x32_bf16 v[94:97], v[46:49], v[212:215], v[94:97]
	v_mfma_f32_16x16x32_bf16 v[90:93], v[58:61], v[208:211], v[90:93]
	v_mfma_f32_16x16x32_bf16 v[90:93], v[62:65], v[212:215], v[90:93]
	v_mfma_f32_16x16x32_bf16 v[134:137], v[146:149], v[170:173], v[134:137]
	v_mfma_f32_16x16x32_bf16 v[134:137], v[150:153], v[188:191], v[134:137]
	v_mfma_f32_16x16x32_bf16 v[130:133], v[154:157], v[170:173], v[130:133]
	v_mfma_f32_16x16x32_bf16 v[130:133], v[158:161], v[188:191], v[130:133]
	v_mfma_f32_16x16x32_bf16 v[118:121], v[146:149], v[192:195], v[118:121]
	v_mfma_f32_16x16x32_bf16 v[118:121], v[150:153], v[196:199], v[118:121]
	v_mfma_f32_16x16x32_bf16 v[114:117], v[154:157], v[192:195], v[114:117]
	v_mfma_f32_16x16x32_bf16 v[114:117], v[158:161], v[196:199], v[114:117]
	v_mfma_f32_16x16x32_bf16 v[102:105], v[146:149], v[200:203], v[102:105]
	v_mfma_f32_16x16x32_bf16 v[102:105], v[150:153], v[204:207], v[102:105]
	v_mfma_f32_16x16x32_bf16 v[98:101], v[154:157], v[200:203], v[98:101]
	v_mfma_f32_16x16x32_bf16 v[98:101], v[158:161], v[204:207], v[98:101]
	v_mfma_f32_16x16x32_bf16 v[86:89], v[146:149], v[208:211], v[86:89]
	v_mfma_f32_16x16x32_bf16 v[86:89], v[150:153], v[212:215], v[86:89]
	s_setprio 2
	s_barrier
	v_mfma_f32_16x16x32_bf16 v[82:85], v[154:157], v[208:211], v[82:85]
	v_mfma_f32_16x16x32_bf16 v[82:85], v[158:161], v[212:215], v[82:85]
	s_setprio 0
	ds_read_b128 v[170:173], v183 offset:16384
	ds_read_b128 v[188:191], v183 offset:17408
	ds_read_b128 v[192:195], v183 offset:18432
	ds_read_b128 v[196:199], v183 offset:19456
	ds_read_b128 v[200:203], v183 offset:20480
	ds_read_b128 v[204:207], v183 offset:21504
	ds_read_b128 v[208:211], v183 offset:22528
	ds_read_b128 v[212:215], v183 offset:23552
	s_mov_b32 s82, m0
	s_mov_b32 m0, s49
	s_nop 0
	global_load_lds_dwordx4 v176, s[36:37]
	s_mov_b32 m0, s82
	s_nop 0
	s_mov_b32 s82, m0
	s_mov_b32 m0, s56
	s_nop 0
	global_load_lds_dwordx4 v178, s[36:37]
	s_mov_b32 m0, s82
	s_add_u32 s82, s36, 0x80000
	s_addc_u32 s83, s37, 0
	s_mov_b32 s86, m0
	s_mov_b32 m0, s57
	s_nop 0
	global_load_lds_dwordx4 v176, s[82:83]
	s_mov_b32 m0, s86
	s_nop 0
	s_mov_b32 s86, m0
	s_mov_b32 m0, s58
	s_nop 0
	global_load_lds_dwordx4 v178, s[82:83]
	s_mov_b32 m0, s86
	s_waitcnt vmcnt(4)
	s_waitcnt lgkmcnt(0)
	s_barrier
	s_setprio 1
	.p2align 3
	v_mfma_f32_16x16x32_bf16 v[78:81], v[42:45], v[170:173], v[78:81]
	v_mfma_f32_16x16x32_bf16 v[78:81], v[46:49], v[188:191], v[78:81]
	v_mfma_f32_16x16x32_bf16 v[74:77], v[58:61], v[170:173], v[74:77]
	v_mfma_f32_16x16x32_bf16 v[74:77], v[62:65], v[188:191], v[74:77]
	v_mfma_f32_16x16x32_bf16 v[54:57], v[42:45], v[192:195], v[54:57]
	v_mfma_f32_16x16x32_bf16 v[54:57], v[46:49], v[196:199], v[54:57]
	v_mfma_f32_16x16x32_bf16 v[50:53], v[58:61], v[192:195], v[50:53]
	v_mfma_f32_16x16x32_bf16 v[50:53], v[62:65], v[196:199], v[50:53]
	v_mfma_f32_16x16x32_bf16 v[30:33], v[42:45], v[200:203], v[30:33]
	v_mfma_f32_16x16x32_bf16 v[30:33], v[46:49], v[204:207], v[30:33]
	v_mfma_f32_16x16x32_bf16 v[26:29], v[58:61], v[200:203], v[26:29]
	v_mfma_f32_16x16x32_bf16 v[26:29], v[62:65], v[204:207], v[26:29]
	v_mfma_f32_16x16x32_bf16 v[14:17], v[42:45], v[208:211], v[14:17]
	v_mfma_f32_16x16x32_bf16 v[14:17], v[46:49], v[212:215], v[14:17]
	v_mfma_f32_16x16x32_bf16 v[10:13], v[58:61], v[208:211], v[10:13]
	v_mfma_f32_16x16x32_bf16 v[10:13], v[62:65], v[212:215], v[10:13]
	v_mfma_f32_16x16x32_bf16 v[38:41], v[146:149], v[192:195], v[38:41]
	v_mfma_f32_16x16x32_bf16 v[38:41], v[150:153], v[196:199], v[38:41]
	v_mfma_f32_16x16x32_bf16 v[34:37], v[154:157], v[192:195], v[34:37]
	v_mfma_f32_16x16x32_bf16 v[34:37], v[158:161], v[196:199], v[34:37]
	v_mfma_f32_16x16x32_bf16 v[22:25], v[146:149], v[200:203], v[22:25]
	v_mfma_f32_16x16x32_bf16 v[22:25], v[150:153], v[204:207], v[22:25]
	v_mfma_f32_16x16x32_bf16 v[18:21], v[154:157], v[200:203], v[18:21]
	v_mfma_f32_16x16x32_bf16 v[18:21], v[158:161], v[204:207], v[18:21]
	v_mfma_f32_16x16x32_bf16 v[6:9], v[146:149], v[208:211], v[6:9]
	v_mfma_f32_16x16x32_bf16 v[6:9], v[150:153], v[212:215], v[6:9]
	v_mfma_f32_16x16x32_bf16 v[2:5], v[154:157], v[208:211], v[2:5]
	v_mfma_f32_16x16x32_bf16 v[2:5], v[158:161], v[212:215], v[2:5]
	v_mfma_f32_16x16x32_bf16 v[42:45], v[146:149], v[170:173], v[70:73]
	v_mfma_f32_16x16x32_bf16 v[42:45], v[150:153], v[188:191], v[42:45]
	s_setprio 2
	s_barrier
	v_mfma_f32_16x16x32_bf16 v[46:49], v[154:157], v[170:173], v[66:69]
	v_mfma_f32_16x16x32_bf16 v[46:49], v[158:161], v[188:191], v[46:49]
	s_setprio 0
	ds_read_b128 v[58:61], v184
	ds_read_b128 v[62:65], v184 offset:1024
	ds_read_b128 v[66:69], v184 offset:2048
	ds_read_b128 v[70:73], v184 offset:3072
	ds_read_b128 v[146:149], v185
	ds_read_b128 v[150:153], v185 offset:1024
	ds_read_b128 v[154:157], v185 offset:2048
	ds_read_b128 v[158:161], v185 offset:3072
	ds_read_b128 v[170:173], v183 offset:32768
	ds_read_b128 v[188:191], v183 offset:33792
	ds_read_b128 v[192:195], v183 offset:34816
	ds_read_b128 v[196:199], v183 offset:35840
	ds_read_b128 v[200:203], v183 offset:36864
	ds_read_b128 v[204:207], v183 offset:37888
	ds_read_b128 v[208:211], v183 offset:38912
	ds_read_b128 v[212:215], v183 offset:39936
	s_mov_b32 s82, m0
	s_mov_b32 m0, s48
	s_nop 0
	global_load_lds_dwordx4 v1, s[40:41]
	s_mov_b32 m0, s82
	s_nop 0
	s_mov_b32 s82, m0
	s_mov_b32 m0, s59
	s_nop 0
	global_load_lds_dwordx4 v177, s[40:41]
	s_mov_b32 m0, s82
	s_add_u32 s40, s40, 0x80000
	s_addc_u32 s41, s41, 0
	s_mov_b32 s82, m0
	s_mov_b32 m0, s62
	s_nop 0
	global_load_lds_dwordx4 v1, s[40:41]
	s_mov_b32 m0, s82
	s_nop 0
	s_mov_b32 s82, m0
	s_mov_b32 m0, s63
	s_nop 0
	global_load_lds_dwordx4 v177, s[40:41]
	s_mov_b32 m0, s82
	s_waitcnt vmcnt(8)
	s_waitcnt lgkmcnt(0)
	s_barrier
	s_setprio 1
	.p2align 3
	v_mfma_f32_16x16x32_bf16 v[142:145], v[58:61], v[170:173], v[142:145]
	v_mfma_f32_16x16x32_bf16 v[142:145], v[62:65], v[188:191], v[142:145]
	v_mfma_f32_16x16x32_bf16 v[138:141], v[66:69], v[170:173], v[138:141]
	v_mfma_f32_16x16x32_bf16 v[138:141], v[70:73], v[188:191], v[138:141]
	v_mfma_f32_16x16x32_bf16 v[126:129], v[58:61], v[192:195], v[126:129]
	v_mfma_f32_16x16x32_bf16 v[126:129], v[62:65], v[196:199], v[126:129]
	v_mfma_f32_16x16x32_bf16 v[122:125], v[66:69], v[192:195], v[122:125]
	v_mfma_f32_16x16x32_bf16 v[122:125], v[70:73], v[196:199], v[122:125]
	v_mfma_f32_16x16x32_bf16 v[110:113], v[58:61], v[200:203], v[110:113]
	v_mfma_f32_16x16x32_bf16 v[110:113], v[62:65], v[204:207], v[110:113]
	v_mfma_f32_16x16x32_bf16 v[106:109], v[66:69], v[200:203], v[106:109]
	v_mfma_f32_16x16x32_bf16 v[106:109], v[70:73], v[204:207], v[106:109]
	v_mfma_f32_16x16x32_bf16 v[94:97], v[58:61], v[208:211], v[94:97]
	v_mfma_f32_16x16x32_bf16 v[94:97], v[62:65], v[212:215], v[94:97]
	v_mfma_f32_16x16x32_bf16 v[90:93], v[66:69], v[208:211], v[90:93]
	v_mfma_f32_16x16x32_bf16 v[90:93], v[70:73], v[212:215], v[90:93]
	v_mfma_f32_16x16x32_bf16 v[134:137], v[146:149], v[170:173], v[134:137]
	v_mfma_f32_16x16x32_bf16 v[134:137], v[150:153], v[188:191], v[134:137]
	v_mfma_f32_16x16x32_bf16 v[130:133], v[154:157], v[170:173], v[130:133]
	v_mfma_f32_16x16x32_bf16 v[130:133], v[158:161], v[188:191], v[130:133]
	v_mfma_f32_16x16x32_bf16 v[118:121], v[146:149], v[192:195], v[118:121]
	v_mfma_f32_16x16x32_bf16 v[118:121], v[150:153], v[196:199], v[118:121]
	v_mfma_f32_16x16x32_bf16 v[114:117], v[154:157], v[192:195], v[114:117]
	v_mfma_f32_16x16x32_bf16 v[114:117], v[158:161], v[196:199], v[114:117]
	v_mfma_f32_16x16x32_bf16 v[102:105], v[146:149], v[200:203], v[102:105]
	v_mfma_f32_16x16x32_bf16 v[102:105], v[150:153], v[204:207], v[102:105]
	v_mfma_f32_16x16x32_bf16 v[98:101], v[154:157], v[200:203], v[98:101]
	v_mfma_f32_16x16x32_bf16 v[98:101], v[158:161], v[204:207], v[98:101]
	v_mfma_f32_16x16x32_bf16 v[86:89], v[146:149], v[208:211], v[86:89]
	v_mfma_f32_16x16x32_bf16 v[86:89], v[150:153], v[212:215], v[86:89]
	s_setprio 2
	s_barrier
	v_mfma_f32_16x16x32_bf16 v[82:85], v[154:157], v[208:211], v[82:85]
	v_mfma_f32_16x16x32_bf16 v[82:85], v[158:161], v[212:215], v[82:85]
	s_setprio 0
	ds_read_b128 v[170:173], v183 offset:49152
	ds_read_b128 v[188:191], v183 offset:50176
	ds_read_b128 v[192:195], v183 offset:51200
	ds_read_b128 v[196:199], v183 offset:52224
	ds_read_b128 v[200:203], v183 offset:53248
	ds_read_b128 v[204:207], v183 offset:54272
	ds_read_b128 v[208:211], v183 offset:55296
	ds_read_b128 v[212:215], v183 offset:56320
	s_add_u32 s40, s36, 0x80
	s_addc_u32 s41, s37, 0
	s_mov_b32 s82, m0
	s_mov_b32 m0, s64
	s_nop 0
	global_load_lds_dwordx4 v176, s[40:41]
	s_mov_b32 m0, s82
	s_add_u32 s36, s36, 0x80080
	s_mov_b32 s82, m0
	s_mov_b32 m0, s65
	s_nop 0
	global_load_lds_dwordx4 v178, s[40:41]
	s_mov_b32 m0, s82
	s_addc_u32 s37, s37, 0
	s_mov_b32 s40, m0
	s_mov_b32 m0, s66
	s_nop 0
	global_load_lds_dwordx4 v176, s[36:37]
	s_mov_b32 m0, s40
	s_nop 0
	s_mov_b32 s40, m0
	s_mov_b32 m0, s67
	s_nop 0
	global_load_lds_dwordx4 v178, s[36:37]
	s_mov_b32 m0, s40
	s_waitcnt vmcnt(4)
	s_waitcnt lgkmcnt(0)
	s_barrier
	s_setprio 1
	.p2align 3
	v_mfma_f32_16x16x32_bf16 v[78:81], v[58:61], v[170:173], v[78:81]
	v_mfma_f32_16x16x32_bf16 v[78:81], v[62:65], v[188:191], v[78:81]
	v_mfma_f32_16x16x32_bf16 v[74:77], v[66:69], v[170:173], v[74:77]
	v_mfma_f32_16x16x32_bf16 v[74:77], v[70:73], v[188:191], v[74:77]
	v_mfma_f32_16x16x32_bf16 v[54:57], v[58:61], v[192:195], v[54:57]
	v_mfma_f32_16x16x32_bf16 v[54:57], v[62:65], v[196:199], v[54:57]
	v_mfma_f32_16x16x32_bf16 v[50:53], v[66:69], v[192:195], v[50:53]
	v_mfma_f32_16x16x32_bf16 v[50:53], v[70:73], v[196:199], v[50:53]
	v_mfma_f32_16x16x32_bf16 v[30:33], v[58:61], v[200:203], v[30:33]
	v_mfma_f32_16x16x32_bf16 v[30:33], v[62:65], v[204:207], v[30:33]
	v_mfma_f32_16x16x32_bf16 v[26:29], v[66:69], v[200:203], v[26:29]
	v_mfma_f32_16x16x32_bf16 v[26:29], v[70:73], v[204:207], v[26:29]
	v_mfma_f32_16x16x32_bf16 v[14:17], v[58:61], v[208:211], v[14:17]
	v_mfma_f32_16x16x32_bf16 v[14:17], v[62:65], v[212:215], v[14:17]
	v_mfma_f32_16x16x32_bf16 v[10:13], v[66:69], v[208:211], v[10:13]
	v_mfma_f32_16x16x32_bf16 v[10:13], v[70:73], v[212:215], v[10:13]
	v_mfma_f32_16x16x32_bf16 v[42:45], v[146:149], v[170:173], v[42:45]
	v_mfma_f32_16x16x32_bf16 v[70:73], v[150:153], v[188:191], v[42:45]
	v_mfma_f32_16x16x32_bf16 v[42:45], v[154:157], v[170:173], v[46:49]
	v_mfma_f32_16x16x32_bf16 v[66:69], v[158:161], v[188:191], v[42:45]
	v_mfma_f32_16x16x32_bf16 v[38:41], v[146:149], v[192:195], v[38:41]
	v_mfma_f32_16x16x32_bf16 v[38:41], v[150:153], v[196:199], v[38:41]
	v_mfma_f32_16x16x32_bf16 v[34:37], v[154:157], v[192:195], v[34:37]
	v_mfma_f32_16x16x32_bf16 v[34:37], v[158:161], v[196:199], v[34:37]
	v_mfma_f32_16x16x32_bf16 v[22:25], v[146:149], v[200:203], v[22:25]
	v_mfma_f32_16x16x32_bf16 v[22:25], v[150:153], v[204:207], v[22:25]
	v_mfma_f32_16x16x32_bf16 v[18:21], v[154:157], v[200:203], v[18:21]
	v_mfma_f32_16x16x32_bf16 v[18:21], v[158:161], v[204:207], v[18:21]
	v_mfma_f32_16x16x32_bf16 v[6:9], v[146:149], v[208:211], v[6:9]
	v_mfma_f32_16x16x32_bf16 v[6:9], v[150:153], v[212:215], v[6:9]
	s_setprio 2
	s_barrier
	v_mfma_f32_16x16x32_bf16 v[2:5], v[154:157], v[208:211], v[2:5]
	v_mfma_f32_16x16x32_bf16 v[2:5], v[158:161], v[212:215], v[2:5]
	s_setprio 0
	s_add_i32 s81, s81, 2
	s_add_u32 s77, s77, 0x100
	s_addc_u32 s78, s78, 0
	s_add_u32 s34, s34, 0x100
	s_addc_u32 s35, s35, 0
	s_add_u32 s79, s79, 0x100
	s_addc_u32 s80, s80, 0
	s_cmp_gt_u32 s81, 29
	s_cbranch_scc0 .LBB0_2146
	s_and_b64 vcc, exec, s[14:15]
	s_cbranch_vccz .LBB0_2149
	s_barrier

.LBB0_2409:
	s_ashr_i32 s17, s16, 31
	s_lshl_b64 s[18:19], s[16:17], 20
	s_add_u32 s18, s33, s18
	s_addc_u32 s19, s34, s19
	s_and_b64 s[20:21], s[2:3], exec
	s_cselect_b32 s17, s19, s27
	s_cselect_b32 s71, s18, s26
	s_ashr_i32 s15, s14, 31
	s_lshl_b64 s[20:21], s[14:15], 20
	s_add_u32 s20, s35, s20
	s_addc_u32 s21, s36, s21
	s_and_b64 s[28:29], s[2:3], exec
	s_cselect_b32 s15, s21, s25
	s_cselect_b32 s73, s20, s24
	s_add_u32 s74, s24, 0x100
	s_addc_u32 s75, s25, 0
	s_add_u32 s24, s26, 0x80080
	s_addc_u32 s25, s27, 0
	s_add_u32 s76, s26, 0x100
	s_addc_u32 s77, s27, 0
	s_mov_b32 s78, -2
	s_waitcnt vmcnt(25)
	s_waitcnt vmcnt(24)
	s_waitcnt vmcnt(4)
	s_waitcnt vmcnt(2)
	s_waitcnt vmcnt(1)
	s_waitcnt vmcnt(0)
	ds_read_b128 v[130:133], v181
	ds_read_b128 v[134:137], v181 offset:1024
	ds_read_b128 v[138:141], v181 offset:2048
	ds_read_b128 v[142:145], v181 offset:3072
	ds_read_b128 v[146:149], v182
	ds_read_b128 v[150:153], v182 offset:1024
	ds_read_b128 v[154:157], v182 offset:2048
	ds_read_b128 v[158:161], v182 offset:3072
	s_cmp_eq_u32 s78, 28
	s_cselect_b32 s27, s15, s75
	s_cselect_b32 s26, s73, s74
	s_cselect_b32 s29, s17, s77
	s_cselect_b32 s28, s71, s76
	ds_read_b128 v[166:169], v183
	ds_read_b128 v[170:173], v183 offset:1024
	ds_read_b128 v[186:189], v183 offset:2048
	ds_read_b128 v[190:193], v183 offset:3072
	ds_read_b128 v[194:197], v183 offset:4096
	ds_read_b128 v[198:201], v183 offset:5120
	ds_read_b128 v[202:205], v183 offset:6144
	ds_read_b128 v[206:209], v183 offset:7168
	s_add_u32 s80, s24, 0xfff80000
	s_addc_u32 s81, s25, -1
	s_mov_b32 s79, m0
	s_mov_b32 m0, s64
	s_nop 0
	global_load_lds_dwordx4 v1, s[80:81]
	s_mov_b32 m0, s79
	s_nop 0
	s_mov_b32 s79, m0
	s_mov_b32 m0, s66
	s_nop 0
	global_load_lds_dwordx4 v177, s[80:81]
	s_mov_b32 m0, s79
	s_nop 0
	s_mov_b32 s79, m0
	s_mov_b32 m0, s65
	s_nop 0
	global_load_lds_dwordx4 v1, s[24:25]
	s_mov_b32 m0, s79
	s_nop 0
	s_mov_b32 s79, m0
	s_mov_b32 m0, s67
	s_nop 0
	global_load_lds_dwordx4 v177, s[24:25]
	s_mov_b32 m0, s79
	s_waitcnt vmcnt(8)
	s_waitcnt lgkmcnt(0)
	s_barrier
	s_setprio 1
	.p2align 3
	v_mfma_f32_16x16x32_bf16 v[126:129], v[130:133], v[166:169], 0
	v_mfma_f32_16x16x32_bf16 v[126:129], v[134:137], v[170:173], v[126:129]
	v_mfma_f32_16x16x32_bf16 v[122:125], v[138:141], v[166:169], 0
	v_mfma_f32_16x16x32_bf16 v[122:125], v[142:145], v[170:173], v[122:125]
	v_mfma_f32_16x16x32_bf16 v[114:117], v[138:141], v[186:189], 0
	v_mfma_f32_16x16x32_bf16 v[114:117], v[142:145], v[190:193], v[114:117]
	v_mfma_f32_16x16x32_bf16 v[118:121], v[130:133], v[186:189], 0
	v_mfma_f32_16x16x32_bf16 v[118:121], v[134:137], v[190:193], v[118:121]
	v_mfma_f32_16x16x32_bf16 v[94:97], v[130:133], v[194:197], 0
	v_mfma_f32_16x16x32_bf16 v[94:97], v[134:137], v[198:201], v[94:97]
	v_mfma_f32_16x16x32_bf16 v[90:93], v[138:141], v[194:197], 0
	v_mfma_f32_16x16x32_bf16 v[90:93], v[142:145], v[198:201], v[90:93]
	v_mfma_f32_16x16x32_bf16 v[78:81], v[138:141], v[202:205], 0
	v_mfma_f32_16x16x32_bf16 v[78:81], v[142:145], v[206:209], v[78:81]
	v_mfma_f32_16x16x32_bf16 v[86:89], v[130:133], v[202:205], 0
	v_mfma_f32_16x16x32_bf16 v[86:89], v[134:137], v[206:209], v[86:89]
	v_mfma_f32_16x16x32_bf16 v[110:113], v[146:149], v[166:169], 0
	v_mfma_f32_16x16x32_bf16 v[110:113], v[150:153], v[170:173], v[110:113]
	v_mfma_f32_16x16x32_bf16 v[106:109], v[154:157], v[166:169], 0
	v_mfma_f32_16x16x32_bf16 v[106:109], v[158:161], v[170:173], v[106:109]
	v_mfma_f32_16x16x32_bf16 v[98:101], v[154:157], v[186:189], 0
	v_mfma_f32_16x16x32_bf16 v[98:101], v[158:161], v[190:193], v[98:101]
	v_mfma_f32_16x16x32_bf16 v[102:105], v[146:149], v[186:189], 0
	v_mfma_f32_16x16x32_bf16 v[102:105], v[150:153], v[190:193], v[102:105]
	v_mfma_f32_16x16x32_bf16 v[82:85], v[146:149], v[194:197], 0
	v_mfma_f32_16x16x32_bf16 v[82:85], v[150:153], v[198:201], v[82:85]
	v_mfma_f32_16x16x32_bf16 v[74:77], v[154:157], v[194:197], 0
	v_mfma_f32_16x16x32_bf16 v[74:77], v[158:161], v[198:201], v[74:77]
	v_mfma_f32_16x16x32_bf16 v[66:69], v[154:157], v[202:205], 0
	v_mfma_f32_16x16x32_bf16 v[66:69], v[158:161], v[206:209], v[66:69]
	s_setprio 2
	s_barrier
	v_mfma_f32_16x16x32_bf16 v[70:73], v[146:149], v[202:205], 0
	v_mfma_f32_16x16x32_bf16 v[70:73], v[150:153], v[206:209], v[70:73]
	s_setprio 0
	ds_read_b128 v[166:169], v183 offset:16384
	ds_read_b128 v[170:173], v183 offset:17408
	ds_read_b128 v[186:189], v183 offset:18432
	ds_read_b128 v[190:193], v183 offset:19456
	ds_read_b128 v[194:197], v183 offset:20480
	ds_read_b128 v[198:201], v183 offset:21504
	ds_read_b128 v[202:205], v183 offset:22528
	ds_read_b128 v[206:209], v183 offset:23552
	s_mov_b32 s79, m0
	s_mov_b32 m0, s41
	s_nop 0
	global_load_lds_dwordx4 v176, s[26:27]
	s_mov_b32 m0, s79
	s_add_u32 s80, s26, 0x80000
	s_mov_b32 s79, m0
	s_mov_b32 m0, s42
	s_nop 0
	global_load_lds_dwordx4 v178, s[26:27]
	s_mov_b32 m0, s79
	s_addc_u32 s81, s27, 0
	s_mov_b32 s79, m0
	s_mov_b32 m0, s43
	s_nop 0
	global_load_lds_dwordx4 v176, s[80:81]
	s_mov_b32 m0, s79
	s_nop 0
	s_mov_b32 s79, m0
	s_mov_b32 m0, s46
	s_nop 0
	global_load_lds_dwordx4 v178, s[80:81]
	s_mov_b32 m0, s79
	s_waitcnt vmcnt(4)
	s_waitcnt lgkmcnt(0)
	s_barrier
	s_setprio 1
	.p2align 3
	v_mfma_f32_16x16x32_bf16 v[62:65], v[130:133], v[166:169], 0
	v_mfma_f32_16x16x32_bf16 v[62:65], v[134:137], v[170:173], v[62:65]
	v_mfma_f32_16x16x32_bf16 v[58:61], v[138:141], v[166:169], 0
	v_mfma_f32_16x16x32_bf16 v[58:61], v[142:145], v[170:173], v[58:61]
	v_mfma_f32_16x16x32_bf16 v[42:45], v[138:141], v[186:189], 0
	v_mfma_f32_16x16x32_bf16 v[42:45], v[142:145], v[190:193], v[42:45]
	v_mfma_f32_16x16x32_bf16 v[46:49], v[130:133], v[186:189], 0
	v_mfma_f32_16x16x32_bf16 v[46:49], v[134:137], v[190:193], v[46:49]
	v_mfma_f32_16x16x32_bf16 v[30:33], v[130:133], v[194:197], 0
	v_mfma_f32_16x16x32_bf16 v[30:33], v[134:137], v[198:201], v[30:33]
	v_mfma_f32_16x16x32_bf16 v[26:29], v[138:141], v[194:197], 0
	v_mfma_f32_16x16x32_bf16 v[26:29], v[142:145], v[198:201], v[26:29]
	v_mfma_f32_16x16x32_bf16 v[10:13], v[138:141], v[202:205], 0
	v_mfma_f32_16x16x32_bf16 v[10:13], v[142:145], v[206:209], v[10:13]
	v_mfma_f32_16x16x32_bf16 v[14:17], v[130:133], v[202:205], 0
	v_mfma_f32_16x16x32_bf16 v[14:17], v[134:137], v[206:209], v[14:17]
	v_mfma_f32_16x16x32_bf16 v[54:57], v[146:149], v[166:169], 0
	v_mfma_f32_16x16x32_bf16 v[54:57], v[150:153], v[170:173], v[54:57]
	v_mfma_f32_16x16x32_bf16 v[50:53], v[154:157], v[166:169], 0
	v_mfma_f32_16x16x32_bf16 v[50:53], v[158:161], v[170:173], v[50:53]
	v_mfma_f32_16x16x32_bf16 v[34:37], v[154:157], v[186:189], 0
	v_mfma_f32_16x16x32_bf16 v[34:37], v[158:161], v[190:193], v[34:37]
	v_mfma_f32_16x16x32_bf16 v[38:41], v[146:149], v[186:189], 0
	v_mfma_f32_16x16x32_bf16 v[38:41], v[150:153], v[190:193], v[38:41]
	v_mfma_f32_16x16x32_bf16 v[22:25], v[146:149], v[194:197], 0
	v_mfma_f32_16x16x32_bf16 v[22:25], v[150:153], v[198:201], v[22:25]
	v_mfma_f32_16x16x32_bf16 v[18:21], v[154:157], v[194:197], 0
	v_mfma_f32_16x16x32_bf16 v[18:21], v[158:161], v[198:201], v[18:21]
	v_mfma_f32_16x16x32_bf16 v[2:5], v[154:157], v[202:205], 0
	v_mfma_f32_16x16x32_bf16 v[2:5], v[158:161], v[206:209], v[2:5]
	s_setprio 2
	s_barrier
	v_mfma_f32_16x16x32_bf16 v[6:9], v[146:149], v[202:205], 0
	v_mfma_f32_16x16x32_bf16 v[6:9], v[150:153], v[206:209], v[6:9]
	s_setprio 0
	ds_read_b128 v[130:133], v184
	ds_read_b128 v[134:137], v184 offset:1024
	ds_read_b128 v[138:141], v184 offset:2048
	ds_read_b128 v[142:145], v184 offset:3072
	ds_read_b128 v[146:149], v185
	ds_read_b128 v[150:153], v185 offset:1024
	ds_read_b128 v[154:157], v185 offset:2048
	ds_read_b128 v[158:161], v185 offset:3072
	ds_read_b128 v[166:169], v183 offset:32768
	ds_read_b128 v[170:173], v183 offset:33792
	ds_read_b128 v[186:189], v183 offset:34816
	ds_read_b128 v[190:193], v183 offset:35840
	ds_read_b128 v[194:197], v183 offset:36864
	ds_read_b128 v[198:201], v183 offset:37888
	ds_read_b128 v[202:205], v183 offset:38912
	ds_read_b128 v[206:209], v183 offset:39936
	s_mov_b32 s79, m0
	s_mov_b32 m0, s40
	s_nop 0
	global_load_lds_dwordx4 v1, s[28:29]
	s_mov_b32 m0, s79
	s_nop 0
	s_mov_b32 s79, m0
	s_mov_b32 m0, s47
	s_nop 0
	global_load_lds_dwordx4 v177, s[28:29]
	s_mov_b32 m0, s79
	s_add_u32 s28, s28, 0x80000
	s_addc_u32 s29, s29, 0
	s_mov_b32 s79, m0
	s_mov_b32 m0, s48
	s_nop 0
	global_load_lds_dwordx4 v1, s[28:29]
	s_mov_b32 m0, s79
	s_nop 0
	s_mov_b32 s79, m0
	s_mov_b32 m0, s49
	s_nop 0
	global_load_lds_dwordx4 v177, s[28:29]
	s_mov_b32 m0, s79
	s_waitcnt vmcnt(8)
	s_waitcnt lgkmcnt(0)
	s_barrier
	s_setprio 1
	.p2align 3
	v_mfma_f32_16x16x32_bf16 v[126:129], v[130:133], v[166:169], v[126:129]
	v_mfma_f32_16x16x32_bf16 v[126:129], v[134:137], v[170:173], v[126:129]
	v_mfma_f32_16x16x32_bf16 v[122:125], v[138:141], v[166:169], v[122:125]
	v_mfma_f32_16x16x32_bf16 v[122:125], v[142:145], v[170:173], v[122:125]
	v_mfma_f32_16x16x32_bf16 v[114:117], v[138:141], v[186:189], v[114:117]
	v_mfma_f32_16x16x32_bf16 v[114:117], v[142:145], v[190:193], v[114:117]
	v_mfma_f32_16x16x32_bf16 v[118:121], v[130:133], v[186:189], v[118:121]
	v_mfma_f32_16x16x32_bf16 v[118:121], v[134:137], v[190:193], v[118:121]
	v_mfma_f32_16x16x32_bf16 v[94:97], v[130:133], v[194:197], v[94:97]
	v_mfma_f32_16x16x32_bf16 v[94:97], v[134:137], v[198:201], v[94:97]
	v_mfma_f32_16x16x32_bf16 v[90:93], v[138:141], v[194:197], v[90:93]
	v_mfma_f32_16x16x32_bf16 v[90:93], v[142:145], v[198:201], v[90:93]
	v_mfma_f32_16x16x32_bf16 v[78:81], v[138:141], v[202:205], v[78:81]
	v_mfma_f32_16x16x32_bf16 v[78:81], v[142:145], v[206:209], v[78:81]
	v_mfma_f32_16x16x32_bf16 v[86:89], v[130:133], v[202:205], v[86:89]
	v_mfma_f32_16x16x32_bf16 v[86:89], v[134:137], v[206:209], v[86:89]
	v_mfma_f32_16x16x32_bf16 v[110:113], v[146:149], v[166:169], v[110:113]
	v_mfma_f32_16x16x32_bf16 v[110:113], v[150:153], v[170:173], v[110:113]
	v_mfma_f32_16x16x32_bf16 v[106:109], v[154:157], v[166:169], v[106:109]
	v_mfma_f32_16x16x32_bf16 v[106:109], v[158:161], v[170:173], v[106:109]
	v_mfma_f32_16x16x32_bf16 v[98:101], v[154:157], v[186:189], v[98:101]
	v_mfma_f32_16x16x32_bf16 v[98:101], v[158:161], v[190:193], v[98:101]
	v_mfma_f32_16x16x32_bf16 v[102:105], v[146:149], v[186:189], v[102:105]
	v_mfma_f32_16x16x32_bf16 v[102:105], v[150:153], v[190:193], v[102:105]
	v_mfma_f32_16x16x32_bf16 v[82:85], v[146:149], v[194:197], v[82:85]
	v_mfma_f32_16x16x32_bf16 v[82:85], v[150:153], v[198:201], v[82:85]
	v_mfma_f32_16x16x32_bf16 v[74:77], v[154:157], v[194:197], v[74:77]
	v_mfma_f32_16x16x32_bf16 v[74:77], v[158:161], v[198:201], v[74:77]
	v_mfma_f32_16x16x32_bf16 v[66:69], v[154:157], v[202:205], v[66:69]
	v_mfma_f32_16x16x32_bf16 v[66:69], v[158:161], v[206:209], v[66:69]
	s_setprio 2
	s_barrier
	v_mfma_f32_16x16x32_bf16 v[70:73], v[146:149], v[202:205], v[70:73]
	v_mfma_f32_16x16x32_bf16 v[70:73], v[150:153], v[206:209], v[70:73]
	s_setprio 0
	ds_read_b128 v[166:169], v183 offset:49152
	ds_read_b128 v[170:173], v183 offset:50176
	ds_read_b128 v[186:189], v183 offset:51200
	ds_read_b128 v[190:193], v183 offset:52224
	ds_read_b128 v[194:197], v183 offset:53248
	ds_read_b128 v[198:201], v183 offset:54272
	ds_read_b128 v[202:205], v183 offset:55296
	ds_read_b128 v[206:209], v183 offset:56320
	s_add_u32 s28, s26, 0x80
	s_addc_u32 s29, s27, 0
	s_mov_b32 s79, m0
	s_mov_b32 m0, s56
	s_nop 0
	global_load_lds_dwordx4 v176, s[28:29]
	s_mov_b32 m0, s79
	s_add_u32 s26, s26, 0x80080
	s_mov_b32 s79, m0
	s_mov_b32 m0, s57
	s_nop 0
	global_load_lds_dwordx4 v178, s[28:29]
	s_mov_b32 m0, s79
	s_addc_u32 s27, s27, 0
	s_mov_b32 s28, m0
	s_mov_b32 m0, s58
	s_nop 0
	global_load_lds_dwordx4 v176, s[26:27]
	s_mov_b32 m0, s28
	s_nop 0
	s_mov_b32 s28, m0
	s_mov_b32 m0, s59
	s_nop 0
	global_load_lds_dwordx4 v178, s[26:27]
	s_mov_b32 m0, s28
	s_waitcnt vmcnt(4)
	s_waitcnt lgkmcnt(0)
	s_barrier
	s_setprio 1
	.p2align 3
	v_mfma_f32_16x16x32_bf16 v[62:65], v[130:133], v[166:169], v[62:65]
	v_mfma_f32_16x16x32_bf16 v[62:65], v[134:137], v[170:173], v[62:65]
	v_mfma_f32_16x16x32_bf16 v[58:61], v[138:141], v[166:169], v[58:61]
	v_mfma_f32_16x16x32_bf16 v[58:61], v[142:145], v[170:173], v[58:61]
	v_mfma_f32_16x16x32_bf16 v[42:45], v[138:141], v[186:189], v[42:45]
	v_mfma_f32_16x16x32_bf16 v[42:45], v[142:145], v[190:193], v[42:45]
	v_mfma_f32_16x16x32_bf16 v[46:49], v[130:133], v[186:189], v[46:49]
	v_mfma_f32_16x16x32_bf16 v[46:49], v[134:137], v[190:193], v[46:49]
	v_mfma_f32_16x16x32_bf16 v[30:33], v[130:133], v[194:197], v[30:33]
	v_mfma_f32_16x16x32_bf16 v[30:33], v[134:137], v[198:201], v[30:33]
	v_mfma_f32_16x16x32_bf16 v[26:29], v[138:141], v[194:197], v[26:29]
	v_mfma_f32_16x16x32_bf16 v[26:29], v[142:145], v[198:201], v[26:29]
	v_mfma_f32_16x16x32_bf16 v[10:13], v[138:141], v[202:205], v[10:13]
	v_mfma_f32_16x16x32_bf16 v[10:13], v[142:145], v[206:209], v[10:13]
	v_mfma_f32_16x16x32_bf16 v[14:17], v[130:133], v[202:205], v[14:17]
	v_mfma_f32_16x16x32_bf16 v[14:17], v[134:137], v[206:209], v[14:17]
	v_mfma_f32_16x16x32_bf16 v[54:57], v[146:149], v[166:169], v[54:57]
	v_mfma_f32_16x16x32_bf16 v[54:57], v[150:153], v[170:173], v[54:57]
	v_mfma_f32_16x16x32_bf16 v[50:53], v[154:157], v[166:169], v[50:53]
	v_mfma_f32_16x16x32_bf16 v[50:53], v[158:161], v[170:173], v[50:53]
	v_mfma_f32_16x16x32_bf16 v[34:37], v[154:157], v[186:189], v[34:37]
	v_mfma_f32_16x16x32_bf16 v[34:37], v[158:161], v[190:193], v[34:37]
	v_mfma_f32_16x16x32_bf16 v[38:41], v[146:149], v[186:189], v[38:41]
	v_mfma_f32_16x16x32_bf16 v[38:41], v[150:153], v[190:193], v[38:41]
	v_mfma_f32_16x16x32_bf16 v[22:25], v[146:149], v[194:197], v[22:25]
	v_mfma_f32_16x16x32_bf16 v[22:25], v[150:153], v[198:201], v[22:25]
	v_mfma_f32_16x16x32_bf16 v[18:21], v[154:157], v[194:197], v[18:21]
	v_mfma_f32_16x16x32_bf16 v[18:21], v[158:161], v[198:201], v[18:21]
	v_mfma_f32_16x16x32_bf16 v[2:5], v[154:157], v[202:205], v[2:5]
	v_mfma_f32_16x16x32_bf16 v[2:5], v[158:161], v[206:209], v[2:5]
	s_setprio 2
	s_barrier
	v_mfma_f32_16x16x32_bf16 v[6:9], v[146:149], v[202:205], v[6:9]
	v_mfma_f32_16x16x32_bf16 v[6:9], v[150:153], v[206:209], v[6:9]
	s_setprio 0
	s_add_i32 s78, s78, 2
	s_add_u32 s74, s74, 0x100
	s_addc_u32 s75, s75, 0
	s_add_u32 s24, s24, 0x100
	s_addc_u32 s25, s25, 0
	s_add_u32 s76, s76, 0x100
	s_addc_u32 s77, s77, 0
	s_cmp_gt_u32 s78, 29
	.p2align 6
.LBB0_2410:
	ds_read_b128 v[130:133], v181
	ds_read_b128 v[134:137], v181 offset:1024
	ds_read_b128 v[138:141], v181 offset:2048
	ds_read_b128 v[142:145], v181 offset:3072
	ds_read_b128 v[146:149], v182
	ds_read_b128 v[150:153], v182 offset:1024
	ds_read_b128 v[154:157], v182 offset:2048
	ds_read_b128 v[158:161], v182 offset:3072
	s_cmp_eq_u32 s78, 28
	s_cselect_b32 s27, s15, s75
	s_cselect_b32 s26, s73, s74
	s_cselect_b32 s29, s17, s77
	s_cselect_b32 s28, s71, s76
	ds_read_b128 v[166:169], v183
	ds_read_b128 v[170:173], v183 offset:1024
	ds_read_b128 v[186:189], v183 offset:2048
	ds_read_b128 v[190:193], v183 offset:3072
	ds_read_b128 v[194:197], v183 offset:4096
	ds_read_b128 v[198:201], v183 offset:5120
	ds_read_b128 v[202:205], v183 offset:6144
	ds_read_b128 v[206:209], v183 offset:7168
	s_add_u32 s80, s24, 0xfff80000
	s_addc_u32 s81, s25, -1
	s_mov_b32 s79, m0
	s_mov_b32 m0, s64
	s_nop 0
	global_load_lds_dwordx4 v1, s[80:81]
	s_mov_b32 m0, s79
	s_nop 0
	s_mov_b32 s79, m0
	s_mov_b32 m0, s66
	s_nop 0
	global_load_lds_dwordx4 v177, s[80:81]
	s_mov_b32 m0, s79
	s_nop 0
	s_mov_b32 s79, m0
	s_mov_b32 m0, s65
	s_nop 0
	global_load_lds_dwordx4 v1, s[24:25]
	s_mov_b32 m0, s79
	s_nop 0
	s_mov_b32 s79, m0
	s_mov_b32 m0, s67
	s_nop 0
	global_load_lds_dwordx4 v177, s[24:25]
	s_mov_b32 m0, s79
	s_waitcnt vmcnt(8)
	s_waitcnt lgkmcnt(0)
	s_barrier
	s_setprio 1
	.p2align 3
	v_mfma_f32_16x16x32_bf16 v[126:129], v[130:133], v[166:169], v[126:129]
	v_mfma_f32_16x16x32_bf16 v[126:129], v[134:137], v[170:173], v[126:129]
	v_mfma_f32_16x16x32_bf16 v[122:125], v[138:141], v[166:169], v[122:125]
	v_mfma_f32_16x16x32_bf16 v[122:125], v[142:145], v[170:173], v[122:125]
	v_mfma_f32_16x16x32_bf16 v[114:117], v[138:141], v[186:189], v[114:117]
	v_mfma_f32_16x16x32_bf16 v[114:117], v[142:145], v[190:193], v[114:117]
	v_mfma_f32_16x16x32_bf16 v[118:121], v[130:133], v[186:189], v[118:121]
	v_mfma_f32_16x16x32_bf16 v[118:121], v[134:137], v[190:193], v[118:121]
	v_mfma_f32_16x16x32_bf16 v[94:97], v[130:133], v[194:197], v[94:97]
	v_mfma_f32_16x16x32_bf16 v[94:97], v[134:137], v[198:201], v[94:97]
	v_mfma_f32_16x16x32_bf16 v[90:93], v[138:141], v[194:197], v[90:93]
	v_mfma_f32_16x16x32_bf16 v[90:93], v[142:145], v[198:201], v[90:93]
	v_mfma_f32_16x16x32_bf16 v[78:81], v[138:141], v[202:205], v[78:81]
	v_mfma_f32_16x16x32_bf16 v[78:81], v[142:145], v[206:209], v[78:81]
	v_mfma_f32_16x16x32_bf16 v[86:89], v[130:133], v[202:205], v[86:89]
	v_mfma_f32_16x16x32_bf16 v[86:89], v[134:137], v[206:209], v[86:89]
	v_mfma_f32_16x16x32_bf16 v[110:113], v[146:149], v[166:169], v[110:113]
	v_mfma_f32_16x16x32_bf16 v[110:113], v[150:153], v[170:173], v[110:113]
	v_mfma_f32_16x16x32_bf16 v[106:109], v[154:157], v[166:169], v[106:109]
	v_mfma_f32_16x16x32_bf16 v[106:109], v[158:161], v[170:173], v[106:109]
	v_mfma_f32_16x16x32_bf16 v[98:101], v[154:157], v[186:189], v[98:101]
	v_mfma_f32_16x16x32_bf16 v[98:101], v[158:161], v[190:193], v[98:101]
	v_mfma_f32_16x16x32_bf16 v[102:105], v[146:149], v[186:189], v[102:105]
	v_mfma_f32_16x16x32_bf16 v[102:105], v[150:153], v[190:193], v[102:105]
	v_mfma_f32_16x16x32_bf16 v[82:85], v[146:149], v[194:197], v[82:85]
	v_mfma_f32_16x16x32_bf16 v[82:85], v[150:153], v[198:201], v[82:85]
	v_mfma_f32_16x16x32_bf16 v[74:77], v[154:157], v[194:197], v[74:77]
	v_mfma_f32_16x16x32_bf16 v[74:77], v[158:161], v[198:201], v[74:77]
	v_mfma_f32_16x16x32_bf16 v[66:69], v[154:157], v[202:205], v[66:69]
	v_mfma_f32_16x16x32_bf16 v[66:69], v[158:161], v[206:209], v[66:69]
	s_setprio 2
	s_barrier
	v_mfma_f32_16x16x32_bf16 v[70:73], v[146:149], v[202:205], v[70:73]
	v_mfma_f32_16x16x32_bf16 v[70:73], v[150:153], v[206:209], v[70:73]
	s_setprio 0
	ds_read_b128 v[166:169], v183 offset:16384
	ds_read_b128 v[170:173], v183 offset:17408
	ds_read_b128 v[186:189], v183 offset:18432
	ds_read_b128 v[190:193], v183 offset:19456
	ds_read_b128 v[194:197], v183 offset:20480
	ds_read_b128 v[198:201], v183 offset:21504
	ds_read_b128 v[202:205], v183 offset:22528
	ds_read_b128 v[206:209], v183 offset:23552
	s_mov_b32 s79, m0
	s_mov_b32 m0, s41
	s_nop 0
	global_load_lds_dwordx4 v176, s[26:27]
	s_mov_b32 m0, s79
	s_add_u32 s80, s26, 0x80000
	s_mov_b32 s79, m0
	s_mov_b32 m0, s42
	s_nop 0
	global_load_lds_dwordx4 v178, s[26:27]
	s_mov_b32 m0, s79
	s_addc_u32 s81, s27, 0
	s_mov_b32 s79, m0
	s_mov_b32 m0, s43
	s_nop 0
	global_load_lds_dwordx4 v176, s[80:81]
	s_mov_b32 m0, s79
	s_nop 0
	s_mov_b32 s79, m0
	s_mov_b32 m0, s46
	s_nop 0
	global_load_lds_dwordx4 v178, s[80:81]
	s_mov_b32 m0, s79
	s_waitcnt vmcnt(4)
	s_waitcnt lgkmcnt(0)
	s_barrier
	s_setprio 1
	.p2align 3
	v_mfma_f32_16x16x32_bf16 v[62:65], v[130:133], v[166:169], v[62:65]
	v_mfma_f32_16x16x32_bf16 v[62:65], v[134:137], v[170:173], v[62:65]
	v_mfma_f32_16x16x32_bf16 v[58:61], v[138:141], v[166:169], v[58:61]
	v_mfma_f32_16x16x32_bf16 v[58:61], v[142:145], v[170:173], v[58:61]
	v_mfma_f32_16x16x32_bf16 v[42:45], v[138:141], v[186:189], v[42:45]
	v_mfma_f32_16x16x32_bf16 v[42:45], v[142:145], v[190:193], v[42:45]
	v_mfma_f32_16x16x32_bf16 v[46:49], v[130:133], v[186:189], v[46:49]
	v_mfma_f32_16x16x32_bf16 v[46:49], v[134:137], v[190:193], v[46:49]
	v_mfma_f32_16x16x32_bf16 v[30:33], v[130:133], v[194:197], v[30:33]
	v_mfma_f32_16x16x32_bf16 v[30:33], v[134:137], v[198:201], v[30:33]
	v_mfma_f32_16x16x32_bf16 v[26:29], v[138:141], v[194:197], v[26:29]
	v_mfma_f32_16x16x32_bf16 v[26:29], v[142:145], v[198:201], v[26:29]
	v_mfma_f32_16x16x32_bf16 v[10:13], v[138:141], v[202:205], v[10:13]
	v_mfma_f32_16x16x32_bf16 v[10:13], v[142:145], v[206:209], v[10:13]
	v_mfma_f32_16x16x32_bf16 v[14:17], v[130:133], v[202:205], v[14:17]
	v_mfma_f32_16x16x32_bf16 v[14:17], v[134:137], v[206:209], v[14:17]
	v_mfma_f32_16x16x32_bf16 v[54:57], v[146:149], v[166:169], v[54:57]
	v_mfma_f32_16x16x32_bf16 v[54:57], v[150:153], v[170:173], v[54:57]
	v_mfma_f32_16x16x32_bf16 v[50:53], v[154:157], v[166:169], v[50:53]
	v_mfma_f32_16x16x32_bf16 v[50:53], v[158:161], v[170:173], v[50:53]
	v_mfma_f32_16x16x32_bf16 v[34:37], v[154:157], v[186:189], v[34:37]
	v_mfma_f32_16x16x32_bf16 v[34:37], v[158:161], v[190:193], v[34:37]
	v_mfma_f32_16x16x32_bf16 v[38:41], v[146:149], v[186:189], v[38:41]
	v_mfma_f32_16x16x32_bf16 v[38:41], v[150:153], v[190:193], v[38:41]
	v_mfma_f32_16x16x32_bf16 v[22:25], v[146:149], v[194:197], v[22:25]
	v_mfma_f32_16x16x32_bf16 v[22:25], v[150:153], v[198:201], v[22:25]
	v_mfma_f32_16x16x32_bf16 v[18:21], v[154:157], v[194:197], v[18:21]
	v_mfma_f32_16x16x32_bf16 v[18:21], v[158:161], v[198:201], v[18:21]
	v_mfma_f32_16x16x32_bf16 v[2:5], v[154:157], v[202:205], v[2:5]
	v_mfma_f32_16x16x32_bf16 v[2:5], v[158:161], v[206:209], v[2:5]
	s_setprio 2
	s_barrier
	v_mfma_f32_16x16x32_bf16 v[6:9], v[146:149], v[202:205], v[6:9]
	v_mfma_f32_16x16x32_bf16 v[6:9], v[150:153], v[206:209], v[6:9]
	s_setprio 0
	ds_read_b128 v[130:133], v184
	ds_read_b128 v[134:137], v184 offset:1024
	ds_read_b128 v[138:141], v184 offset:2048
	ds_read_b128 v[142:145], v184 offset:3072
	ds_read_b128 v[146:149], v185
	ds_read_b128 v[150:153], v185 offset:1024
	ds_read_b128 v[154:157], v185 offset:2048
	ds_read_b128 v[158:161], v185 offset:3072
	ds_read_b128 v[166:169], v183 offset:32768
	ds_read_b128 v[170:173], v183 offset:33792
	ds_read_b128 v[186:189], v183 offset:34816
	ds_read_b128 v[190:193], v183 offset:35840
	ds_read_b128 v[194:197], v183 offset:36864
	ds_read_b128 v[198:201], v183 offset:37888
	ds_read_b128 v[202:205], v183 offset:38912
	ds_read_b128 v[206:209], v183 offset:39936
	s_mov_b32 s79, m0
	s_mov_b32 m0, s40
	s_nop 0
	global_load_lds_dwordx4 v1, s[28:29]
	s_mov_b32 m0, s79
	s_nop 0
	s_mov_b32 s79, m0
	s_mov_b32 m0, s47
	s_nop 0
	global_load_lds_dwordx4 v177, s[28:29]
	s_mov_b32 m0, s79
	s_add_u32 s28, s28, 0x80000
	s_addc_u32 s29, s29, 0
	s_mov_b32 s79, m0
	s_mov_b32 m0, s48
	s_nop 0
	global_load_lds_dwordx4 v1, s[28:29]
	s_mov_b32 m0, s79
	s_nop 0
	s_mov_b32 s79, m0
	s_mov_b32 m0, s49
	s_nop 0
	global_load_lds_dwordx4 v177, s[28:29]
	s_mov_b32 m0, s79
	s_waitcnt vmcnt(8)
	s_waitcnt lgkmcnt(0)
	s_barrier
	s_setprio 1
	.p2align 3
	v_mfma_f32_16x16x32_bf16 v[126:129], v[130:133], v[166:169], v[126:129]
	v_mfma_f32_16x16x32_bf16 v[126:129], v[134:137], v[170:173], v[126:129]
	v_mfma_f32_16x16x32_bf16 v[122:125], v[138:141], v[166:169], v[122:125]
	v_mfma_f32_16x16x32_bf16 v[122:125], v[142:145], v[170:173], v[122:125]
	v_mfma_f32_16x16x32_bf16 v[114:117], v[138:141], v[186:189], v[114:117]
	v_mfma_f32_16x16x32_bf16 v[114:117], v[142:145], v[190:193], v[114:117]
	v_mfma_f32_16x16x32_bf16 v[118:121], v[130:133], v[186:189], v[118:121]
	v_mfma_f32_16x16x32_bf16 v[118:121], v[134:137], v[190:193], v[118:121]
	v_mfma_f32_16x16x32_bf16 v[94:97], v[130:133], v[194:197], v[94:97]
	v_mfma_f32_16x16x32_bf16 v[94:97], v[134:137], v[198:201], v[94:97]
	v_mfma_f32_16x16x32_bf16 v[90:93], v[138:141], v[194:197], v[90:93]
	v_mfma_f32_16x16x32_bf16 v[90:93], v[142:145], v[198:201], v[90:93]
	v_mfma_f32_16x16x32_bf16 v[78:81], v[138:141], v[202:205], v[78:81]
	v_mfma_f32_16x16x32_bf16 v[78:81], v[142:145], v[206:209], v[78:81]
	v_mfma_f32_16x16x32_bf16 v[86:89], v[130:133], v[202:205], v[86:89]
	v_mfma_f32_16x16x32_bf16 v[86:89], v[134:137], v[206:209], v[86:89]
	v_mfma_f32_16x16x32_bf16 v[110:113], v[146:149], v[166:169], v[110:113]
	v_mfma_f32_16x16x32_bf16 v[110:113], v[150:153], v[170:173], v[110:113]
	v_mfma_f32_16x16x32_bf16 v[106:109], v[154:157], v[166:169], v[106:109]
	v_mfma_f32_16x16x32_bf16 v[106:109], v[158:161], v[170:173], v[106:109]
	v_mfma_f32_16x16x32_bf16 v[98:101], v[154:157], v[186:189], v[98:101]
	v_mfma_f32_16x16x32_bf16 v[98:101], v[158:161], v[190:193], v[98:101]
	v_mfma_f32_16x16x32_bf16 v[102:105], v[146:149], v[186:189], v[102:105]
	v_mfma_f32_16x16x32_bf16 v[102:105], v[150:153], v[190:193], v[102:105]
	v_mfma_f32_16x16x32_bf16 v[82:85], v[146:149], v[194:197], v[82:85]
	v_mfma_f32_16x16x32_bf16 v[82:85], v[150:153], v[198:201], v[82:85]
	v_mfma_f32_16x16x32_bf16 v[74:77], v[154:157], v[194:197], v[74:77]
	v_mfma_f32_16x16x32_bf16 v[74:77], v[158:161], v[198:201], v[74:77]
	v_mfma_f32_16x16x32_bf16 v[66:69], v[154:157], v[202:205], v[66:69]
	v_mfma_f32_16x16x32_bf16 v[66:69], v[158:161], v[206:209], v[66:69]
	s_setprio 2
	s_barrier
	v_mfma_f32_16x16x32_bf16 v[70:73], v[146:149], v[202:205], v[70:73]
	v_mfma_f32_16x16x32_bf16 v[70:73], v[150:153], v[206:209], v[70:73]
	s_setprio 0
	ds_read_b128 v[166:169], v183 offset:49152
	ds_read_b128 v[170:173], v183 offset:50176
	ds_read_b128 v[186:189], v183 offset:51200
	ds_read_b128 v[190:193], v183 offset:52224
	ds_read_b128 v[194:197], v183 offset:53248
	ds_read_b128 v[198:201], v183 offset:54272
	ds_read_b128 v[202:205], v183 offset:55296
	ds_read_b128 v[206:209], v183 offset:56320
	s_add_u32 s28, s26, 0x80
	s_addc_u32 s29, s27, 0
	s_mov_b32 s79, m0
	s_mov_b32 m0, s56
	s_nop 0
	global_load_lds_dwordx4 v176, s[28:29]
	s_mov_b32 m0, s79
	s_add_u32 s26, s26, 0x80080
	s_mov_b32 s79, m0
	s_mov_b32 m0, s57
	s_nop 0
	global_load_lds_dwordx4 v178, s[28:29]
	s_mov_b32 m0, s79
	s_addc_u32 s27, s27, 0
	s_mov_b32 s28, m0
	s_mov_b32 m0, s58
	s_nop 0
	global_load_lds_dwordx4 v176, s[26:27]
	s_mov_b32 m0, s28
	s_nop 0
	s_mov_b32 s28, m0
	s_mov_b32 m0, s59
	s_nop 0
	global_load_lds_dwordx4 v178, s[26:27]
	s_mov_b32 m0, s28
	s_waitcnt vmcnt(4)
	s_waitcnt lgkmcnt(0)
	s_barrier
	s_setprio 1
	.p2align 3
	v_mfma_f32_16x16x32_bf16 v[62:65], v[130:133], v[166:169], v[62:65]
	v_mfma_f32_16x16x32_bf16 v[62:65], v[134:137], v[170:173], v[62:65]
	v_mfma_f32_16x16x32_bf16 v[58:61], v[138:141], v[166:169], v[58:61]
	v_mfma_f32_16x16x32_bf16 v[58:61], v[142:145], v[170:173], v[58:61]
	v_mfma_f32_16x16x32_bf16 v[42:45], v[138:141], v[186:189], v[42:45]
	v_mfma_f32_16x16x32_bf16 v[42:45], v[142:145], v[190:193], v[42:45]
	v_mfma_f32_16x16x32_bf16 v[46:49], v[130:133], v[186:189], v[46:49]
	v_mfma_f32_16x16x32_bf16 v[46:49], v[134:137], v[190:193], v[46:49]
	v_mfma_f32_16x16x32_bf16 v[30:33], v[130:133], v[194:197], v[30:33]
	v_mfma_f32_16x16x32_bf16 v[30:33], v[134:137], v[198:201], v[30:33]
	v_mfma_f32_16x16x32_bf16 v[26:29], v[138:141], v[194:197], v[26:29]
	v_mfma_f32_16x16x32_bf16 v[26:29], v[142:145], v[198:201], v[26:29]
	v_mfma_f32_16x16x32_bf16 v[10:13], v[138:141], v[202:205], v[10:13]
	v_mfma_f32_16x16x32_bf16 v[10:13], v[142:145], v[206:209], v[10:13]
	v_mfma_f32_16x16x32_bf16 v[14:17], v[130:133], v[202:205], v[14:17]
	v_mfma_f32_16x16x32_bf16 v[14:17], v[134:137], v[206:209], v[14:17]
	v_mfma_f32_16x16x32_bf16 v[54:57], v[146:149], v[166:169], v[54:57]
	v_mfma_f32_16x16x32_bf16 v[54:57], v[150:153], v[170:173], v[54:57]
	v_mfma_f32_16x16x32_bf16 v[50:53], v[154:157], v[166:169], v[50:53]
	v_mfma_f32_16x16x32_bf16 v[50:53], v[158:161], v[170:173], v[50:53]
	v_mfma_f32_16x16x32_bf16 v[34:37], v[154:157], v[186:189], v[34:37]
	v_mfma_f32_16x16x32_bf16 v[34:37], v[158:161], v[190:193], v[34:37]
	v_mfma_f32_16x16x32_bf16 v[38:41], v[146:149], v[186:189], v[38:41]
	v_mfma_f32_16x16x32_bf16 v[38:41], v[150:153], v[190:193], v[38:41]
	v_mfma_f32_16x16x32_bf16 v[22:25], v[146:149], v[194:197], v[22:25]
	v_mfma_f32_16x16x32_bf16 v[22:25], v[150:153], v[198:201], v[22:25]
	v_mfma_f32_16x16x32_bf16 v[18:21], v[154:157], v[194:197], v[18:21]
	v_mfma_f32_16x16x32_bf16 v[18:21], v[158:161], v[198:201], v[18:21]
	v_mfma_f32_16x16x32_bf16 v[2:5], v[154:157], v[202:205], v[2:5]
	v_mfma_f32_16x16x32_bf16 v[2:5], v[158:161], v[206:209], v[2:5]
	s_setprio 2
	s_barrier
	v_mfma_f32_16x16x32_bf16 v[6:9], v[146:149], v[202:205], v[6:9]
	v_mfma_f32_16x16x32_bf16 v[6:9], v[150:153], v[206:209], v[6:9]
	s_setprio 0
	s_add_i32 s78, s78, 2
	s_add_u32 s74, s74, 0x100
	s_addc_u32 s75, s75, 0
	s_add_u32 s24, s24, 0x100
	s_addc_u32 s25, s25, 0
	s_add_u32 s76, s76, 0x100
	s_addc_u32 s77, s77, 0
	s_cmp_gt_u32 s78, 29
	s_cbranch_scc0 .LBB0_2410
	s_and_b64 vcc, exec, s[8:9]
	s_cbranch_vccz .LBB0_2413
	s_barrier

.LBB0_2593:
	s_ashr_i32 s11, s10, 31
	s_lshl_b64 s[12:13], s[10:11], 20
	s_add_u32 s12, s26, s12
	s_addc_u32 s13, s27, s13
	s_and_b64 s[14:15], s[2:3], exec
	s_cselect_b32 s11, s13, s21
	s_cselect_b32 s62, s12, s20
	s_ashr_i32 s9, s8, 31
	s_lshl_b64 s[14:15], s[8:9], 20
	s_add_u32 s14, s28, s14
	s_addc_u32 s15, s29, s15
	s_and_b64 s[22:23], s[2:3], exec
	s_cselect_b32 s9, s15, s19
	s_cselect_b32 s63, s14, s18
	s_add_u32 s64, s18, 0x100
	s_addc_u32 s65, s19, 0
	s_add_u32 s18, s20, 0x80080
	s_addc_u32 s19, s21, 0
	s_add_u32 s66, s20, 0x100
	s_addc_u32 s67, s21, 0
	s_mov_b32 s70, -2
	ds_read_b128 v[148:151], v143
	ds_read_b128 v[152:155], v143 offset:1024
	ds_read_b128 v[156:159], v143 offset:2048
	ds_read_b128 v[160:163], v143 offset:3072
	ds_read_b128 v[164:167], v144
	ds_read_b128 v[168:171], v144 offset:1024
	ds_read_b128 v[172:175], v144 offset:2048
	ds_read_b128 v[176:179], v144 offset:3072
	s_cmp_eq_u32 s70, 28
	s_cselect_b32 s21, s9, s65
	s_cselect_b32 s20, s63, s64
	s_cselect_b32 s23, s11, s67
	s_cselect_b32 s22, s62, s66
	ds_read_b128 v[180:183], v145
	ds_read_b128 v[184:187], v145 offset:1024
	ds_read_b128 v[188:191], v145 offset:2048
	ds_read_b128 v[192:195], v145 offset:3072
	ds_read_b128 v[196:199], v145 offset:4096
	ds_read_b128 v[200:203], v145 offset:5120
	ds_read_b128 v[204:207], v145 offset:6144
	ds_read_b128 v[208:211], v145 offset:7168
	s_add_u32 s74, s18, 0xfff80000
	s_addc_u32 s75, s19, -1
	s_mov_b32 s71, m0
	s_mov_b32 m0, s48
	s_nop 0
	global_load_lds_dwordx4 v138, s[74:75]
	s_mov_b32 m0, s71
	s_nop 0
	s_mov_b32 s71, m0
	s_mov_b32 m0, s57
	s_nop 0
	global_load_lds_dwordx4 v140, s[74:75]
	s_mov_b32 m0, s71
	s_nop 0
	s_mov_b32 s71, m0
	s_mov_b32 m0, s49
	s_nop 0
	global_load_lds_dwordx4 v138, s[18:19]
	s_mov_b32 m0, s71
	s_nop 0
	s_mov_b32 s71, m0
	s_mov_b32 m0, s58
	s_nop 0
	global_load_lds_dwordx4 v140, s[18:19]
	s_mov_b32 m0, s71
	s_waitcnt vmcnt(8)
	s_waitcnt lgkmcnt(0)
	s_barrier
	s_setprio 1
	.p2align 3
	v_mfma_f32_16x16x32_bf16 v[126:129], v[148:151], v[180:183], 0
	v_mfma_f32_16x16x32_bf16 v[126:129], v[152:155], v[184:187], v[126:129]
	v_mfma_f32_16x16x32_bf16 v[122:125], v[156:159], v[180:183], 0
	v_mfma_f32_16x16x32_bf16 v[122:125], v[160:163], v[184:187], v[122:125]
	v_mfma_f32_16x16x32_bf16 v[106:109], v[156:159], v[188:191], 0
	v_mfma_f32_16x16x32_bf16 v[106:109], v[160:163], v[192:195], v[106:109]
	v_mfma_f32_16x16x32_bf16 v[110:113], v[148:151], v[188:191], 0
	v_mfma_f32_16x16x32_bf16 v[110:113], v[152:155], v[192:195], v[110:113]
	v_mfma_f32_16x16x32_bf16 v[94:97], v[148:151], v[196:199], 0
	v_mfma_f32_16x16x32_bf16 v[94:97], v[152:155], v[200:203], v[94:97]
	v_mfma_f32_16x16x32_bf16 v[90:93], v[156:159], v[196:199], 0
	v_mfma_f32_16x16x32_bf16 v[90:93], v[160:163], v[200:203], v[90:93]
	v_mfma_f32_16x16x32_bf16 v[74:77], v[156:159], v[204:207], 0
	v_mfma_f32_16x16x32_bf16 v[74:77], v[160:163], v[208:211], v[74:77]
	v_mfma_f32_16x16x32_bf16 v[78:81], v[148:151], v[204:207], 0
	v_mfma_f32_16x16x32_bf16 v[78:81], v[152:155], v[208:211], v[78:81]
	v_mfma_f32_16x16x32_bf16 v[118:121], v[164:167], v[180:183], 0
	v_mfma_f32_16x16x32_bf16 v[118:121], v[168:171], v[184:187], v[118:121]
	v_mfma_f32_16x16x32_bf16 v[114:117], v[172:175], v[180:183], 0
	v_mfma_f32_16x16x32_bf16 v[114:117], v[176:179], v[184:187], v[114:117]
	v_mfma_f32_16x16x32_bf16 v[98:101], v[172:175], v[188:191], 0
	v_mfma_f32_16x16x32_bf16 v[98:101], v[176:179], v[192:195], v[98:101]
	v_mfma_f32_16x16x32_bf16 v[102:105], v[164:167], v[188:191], 0
	v_mfma_f32_16x16x32_bf16 v[102:105], v[168:171], v[192:195], v[102:105]
	v_mfma_f32_16x16x32_bf16 v[86:89], v[164:167], v[196:199], 0
	v_mfma_f32_16x16x32_bf16 v[86:89], v[168:171], v[200:203], v[86:89]
	v_mfma_f32_16x16x32_bf16 v[82:85], v[172:175], v[196:199], 0
	v_mfma_f32_16x16x32_bf16 v[82:85], v[176:179], v[200:203], v[82:85]
	v_mfma_f32_16x16x32_bf16 v[66:69], v[172:175], v[204:207], 0
	v_mfma_f32_16x16x32_bf16 v[66:69], v[176:179], v[208:211], v[66:69]
	s_setprio 2
	s_barrier
	v_mfma_f32_16x16x32_bf16 v[70:73], v[164:167], v[204:207], 0
	v_mfma_f32_16x16x32_bf16 v[70:73], v[168:171], v[208:211], v[70:73]
	s_setprio 0
	ds_read_b128 v[180:183], v145 offset:16384
	ds_read_b128 v[184:187], v145 offset:17408
	ds_read_b128 v[188:191], v145 offset:18432
	ds_read_b128 v[192:195], v145 offset:19456
	ds_read_b128 v[196:199], v145 offset:20480
	ds_read_b128 v[200:203], v145 offset:21504
	ds_read_b128 v[204:207], v145 offset:22528
	ds_read_b128 v[208:211], v145 offset:23552
	s_mov_b32 s71, m0
	s_mov_b32 m0, s35
	s_nop 0
	global_load_lds_dwordx4 v139, s[20:21]
	s_mov_b32 m0, s71
	s_add_u32 s74, s20, 0x80000
	s_mov_b32 s71, m0
	s_mov_b32 m0, s36
	s_nop 0
	global_load_lds_dwordx4 v141, s[20:21]
	s_mov_b32 m0, s71
	s_addc_u32 s75, s21, 0
	s_mov_b32 s71, m0
	s_mov_b32 m0, s37
	s_nop 0
	global_load_lds_dwordx4 v139, s[74:75]
	s_mov_b32 m0, s71
	s_nop 0
	s_mov_b32 s71, m0
	s_mov_b32 m0, s40
	s_nop 0
	global_load_lds_dwordx4 v141, s[74:75]
	s_mov_b32 m0, s71
	s_waitcnt vmcnt(4)
	s_waitcnt lgkmcnt(0)
	s_barrier
	s_setprio 1
	.p2align 3
	v_mfma_f32_16x16x32_bf16 v[62:65], v[148:151], v[180:183], 0
	v_mfma_f32_16x16x32_bf16 v[62:65], v[152:155], v[184:187], v[62:65]
	v_mfma_f32_16x16x32_bf16 v[58:61], v[156:159], v[180:183], 0
	v_mfma_f32_16x16x32_bf16 v[58:61], v[160:163], v[184:187], v[58:61]
	v_mfma_f32_16x16x32_bf16 v[42:45], v[156:159], v[188:191], 0
	v_mfma_f32_16x16x32_bf16 v[42:45], v[160:163], v[192:195], v[42:45]
	v_mfma_f32_16x16x32_bf16 v[46:49], v[148:151], v[188:191], 0
	v_mfma_f32_16x16x32_bf16 v[46:49], v[152:155], v[192:195], v[46:49]
	v_mfma_f32_16x16x32_bf16 v[30:33], v[148:151], v[196:199], 0
	v_mfma_f32_16x16x32_bf16 v[30:33], v[152:155], v[200:203], v[30:33]
	v_mfma_f32_16x16x32_bf16 v[26:29], v[156:159], v[196:199], 0
	v_mfma_f32_16x16x32_bf16 v[26:29], v[160:163], v[200:203], v[26:29]
	v_mfma_f32_16x16x32_bf16 v[10:13], v[156:159], v[204:207], 0
	v_mfma_f32_16x16x32_bf16 v[10:13], v[160:163], v[208:211], v[10:13]
	v_mfma_f32_16x16x32_bf16 v[14:17], v[148:151], v[204:207], 0
	v_mfma_f32_16x16x32_bf16 v[14:17], v[152:155], v[208:211], v[14:17]
	v_mfma_f32_16x16x32_bf16 v[54:57], v[164:167], v[180:183], 0
	v_mfma_f32_16x16x32_bf16 v[54:57], v[168:171], v[184:187], v[54:57]
	v_mfma_f32_16x16x32_bf16 v[50:53], v[172:175], v[180:183], 0
	v_mfma_f32_16x16x32_bf16 v[50:53], v[176:179], v[184:187], v[50:53]
	v_mfma_f32_16x16x32_bf16 v[34:37], v[172:175], v[188:191], 0
	v_mfma_f32_16x16x32_bf16 v[34:37], v[176:179], v[192:195], v[34:37]
	v_mfma_f32_16x16x32_bf16 v[38:41], v[164:167], v[188:191], 0
	v_mfma_f32_16x16x32_bf16 v[38:41], v[168:171], v[192:195], v[38:41]
	v_mfma_f32_16x16x32_bf16 v[22:25], v[164:167], v[196:199], 0
	v_mfma_f32_16x16x32_bf16 v[22:25], v[168:171], v[200:203], v[22:25]
	v_mfma_f32_16x16x32_bf16 v[18:21], v[172:175], v[196:199], 0
	v_mfma_f32_16x16x32_bf16 v[18:21], v[176:179], v[200:203], v[18:21]
	v_mfma_f32_16x16x32_bf16 v[2:5], v[172:175], v[204:207], 0
	v_mfma_f32_16x16x32_bf16 v[2:5], v[176:179], v[208:211], v[2:5]
	s_setprio 2
	s_barrier
	v_mfma_f32_16x16x32_bf16 v[6:9], v[164:167], v[204:207], 0
	v_mfma_f32_16x16x32_bf16 v[6:9], v[168:171], v[208:211], v[6:9]
	s_setprio 0
	ds_read_b128 v[148:151], v146
	ds_read_b128 v[152:155], v146 offset:1024
	ds_read_b128 v[156:159], v146 offset:2048
	ds_read_b128 v[160:163], v146 offset:3072
	ds_read_b128 v[164:167], v147
	ds_read_b128 v[168:171], v147 offset:1024
	ds_read_b128 v[172:175], v147 offset:2048
	ds_read_b128 v[176:179], v147 offset:3072
	ds_read_b128 v[180:183], v145 offset:32768
	ds_read_b128 v[184:187], v145 offset:33792
	ds_read_b128 v[188:191], v145 offset:34816
	ds_read_b128 v[192:195], v145 offset:35840
	ds_read_b128 v[196:199], v145 offset:36864
	ds_read_b128 v[200:203], v145 offset:37888
	ds_read_b128 v[204:207], v145 offset:38912
	ds_read_b128 v[208:211], v145 offset:39936
	s_mov_b32 s71, m0
	s_mov_b32 m0, s31
	s_nop 0
	global_load_lds_dwordx4 v138, s[22:23]
	s_mov_b32 m0, s71
	s_nop 0
	s_mov_b32 s71, m0
	s_mov_b32 m0, s41
	s_nop 0
	global_load_lds_dwordx4 v140, s[22:23]
	s_mov_b32 m0, s71
	s_add_u32 s22, s22, 0x80000
	s_addc_u32 s23, s23, 0
	s_mov_b32 s71, m0
	s_mov_b32 m0, s42
	s_nop 0
	global_load_lds_dwordx4 v138, s[22:23]
	s_mov_b32 m0, s71
	s_nop 0
	s_mov_b32 s71, m0
	s_mov_b32 m0, s43
	s_nop 0
	global_load_lds_dwordx4 v140, s[22:23]
	s_mov_b32 m0, s71
	s_waitcnt vmcnt(8)
	s_waitcnt lgkmcnt(0)
	s_barrier
	s_setprio 1
	.p2align 3
	v_mfma_f32_16x16x32_bf16 v[126:129], v[148:151], v[180:183], v[126:129]
	v_mfma_f32_16x16x32_bf16 v[126:129], v[152:155], v[184:187], v[126:129]
	v_mfma_f32_16x16x32_bf16 v[122:125], v[156:159], v[180:183], v[122:125]
	v_mfma_f32_16x16x32_bf16 v[122:125], v[160:163], v[184:187], v[122:125]
	v_mfma_f32_16x16x32_bf16 v[106:109], v[156:159], v[188:191], v[106:109]
	v_mfma_f32_16x16x32_bf16 v[106:109], v[160:163], v[192:195], v[106:109]
	v_mfma_f32_16x16x32_bf16 v[110:113], v[148:151], v[188:191], v[110:113]
	v_mfma_f32_16x16x32_bf16 v[110:113], v[152:155], v[192:195], v[110:113]
	v_mfma_f32_16x16x32_bf16 v[94:97], v[148:151], v[196:199], v[94:97]
	v_mfma_f32_16x16x32_bf16 v[94:97], v[152:155], v[200:203], v[94:97]
	v_mfma_f32_16x16x32_bf16 v[90:93], v[156:159], v[196:199], v[90:93]
	v_mfma_f32_16x16x32_bf16 v[90:93], v[160:163], v[200:203], v[90:93]
	v_mfma_f32_16x16x32_bf16 v[74:77], v[156:159], v[204:207], v[74:77]
	v_mfma_f32_16x16x32_bf16 v[74:77], v[160:163], v[208:211], v[74:77]
	v_mfma_f32_16x16x32_bf16 v[78:81], v[148:151], v[204:207], v[78:81]
	v_mfma_f32_16x16x32_bf16 v[78:81], v[152:155], v[208:211], v[78:81]
	v_mfma_f32_16x16x32_bf16 v[118:121], v[164:167], v[180:183], v[118:121]
	v_mfma_f32_16x16x32_bf16 v[118:121], v[168:171], v[184:187], v[118:121]
	v_mfma_f32_16x16x32_bf16 v[114:117], v[172:175], v[180:183], v[114:117]
	v_mfma_f32_16x16x32_bf16 v[114:117], v[176:179], v[184:187], v[114:117]
	v_mfma_f32_16x16x32_bf16 v[98:101], v[172:175], v[188:191], v[98:101]
	v_mfma_f32_16x16x32_bf16 v[98:101], v[176:179], v[192:195], v[98:101]
	v_mfma_f32_16x16x32_bf16 v[102:105], v[164:167], v[188:191], v[102:105]
	v_mfma_f32_16x16x32_bf16 v[102:105], v[168:171], v[192:195], v[102:105]
	v_mfma_f32_16x16x32_bf16 v[86:89], v[164:167], v[196:199], v[86:89]
	v_mfma_f32_16x16x32_bf16 v[86:89], v[168:171], v[200:203], v[86:89]
	v_mfma_f32_16x16x32_bf16 v[82:85], v[172:175], v[196:199], v[82:85]
	v_mfma_f32_16x16x32_bf16 v[82:85], v[176:179], v[200:203], v[82:85]
	v_mfma_f32_16x16x32_bf16 v[66:69], v[172:175], v[204:207], v[66:69]
	v_mfma_f32_16x16x32_bf16 v[66:69], v[176:179], v[208:211], v[66:69]
	s_setprio 2
	s_barrier
	v_mfma_f32_16x16x32_bf16 v[70:73], v[164:167], v[204:207], v[70:73]
	v_mfma_f32_16x16x32_bf16 v[70:73], v[168:171], v[208:211], v[70:73]
	s_setprio 0
	ds_read_b128 v[180:183], v145 offset:49152
	ds_read_b128 v[184:187], v145 offset:50176
	ds_read_b128 v[188:191], v145 offset:51200
	ds_read_b128 v[192:195], v145 offset:52224
	ds_read_b128 v[196:199], v145 offset:53248
	ds_read_b128 v[200:203], v145 offset:54272
	ds_read_b128 v[204:207], v145 offset:55296
	ds_read_b128 v[208:211], v145 offset:56320
	s_add_u32 s22, s20, 0x80
	s_addc_u32 s23, s21, 0
	s_mov_b32 s71, m0
	s_mov_b32 m0, s44
	s_nop 0
	global_load_lds_dwordx4 v139, s[22:23]
	s_mov_b32 m0, s71
	s_add_u32 s20, s20, 0x80080
	s_mov_b32 s71, m0
	s_mov_b32 m0, s45
	s_nop 0
	global_load_lds_dwordx4 v141, s[22:23]
	s_mov_b32 m0, s71
	s_addc_u32 s21, s21, 0
	s_mov_b32 s22, m0
	s_mov_b32 m0, s46
	s_nop 0
	global_load_lds_dwordx4 v139, s[20:21]
	s_mov_b32 m0, s22
	s_nop 0
	s_mov_b32 s22, m0
	s_mov_b32 m0, s47
	s_nop 0
	global_load_lds_dwordx4 v141, s[20:21]
	s_mov_b32 m0, s22
	s_waitcnt vmcnt(4)
	s_waitcnt lgkmcnt(0)
	s_barrier
	s_setprio 1
	.p2align 3
	v_mfma_f32_16x16x32_bf16 v[62:65], v[148:151], v[180:183], v[62:65]
	v_mfma_f32_16x16x32_bf16 v[62:65], v[152:155], v[184:187], v[62:65]
	v_mfma_f32_16x16x32_bf16 v[58:61], v[156:159], v[180:183], v[58:61]
	v_mfma_f32_16x16x32_bf16 v[58:61], v[160:163], v[184:187], v[58:61]
	v_mfma_f32_16x16x32_bf16 v[42:45], v[156:159], v[188:191], v[42:45]
	v_mfma_f32_16x16x32_bf16 v[42:45], v[160:163], v[192:195], v[42:45]
	v_mfma_f32_16x16x32_bf16 v[46:49], v[148:151], v[188:191], v[46:49]
	v_mfma_f32_16x16x32_bf16 v[46:49], v[152:155], v[192:195], v[46:49]
	v_mfma_f32_16x16x32_bf16 v[30:33], v[148:151], v[196:199], v[30:33]
	v_mfma_f32_16x16x32_bf16 v[30:33], v[152:155], v[200:203], v[30:33]
	v_mfma_f32_16x16x32_bf16 v[26:29], v[156:159], v[196:199], v[26:29]
	v_mfma_f32_16x16x32_bf16 v[26:29], v[160:163], v[200:203], v[26:29]
	v_mfma_f32_16x16x32_bf16 v[10:13], v[156:159], v[204:207], v[10:13]
	v_mfma_f32_16x16x32_bf16 v[10:13], v[160:163], v[208:211], v[10:13]
	v_mfma_f32_16x16x32_bf16 v[14:17], v[148:151], v[204:207], v[14:17]
	v_mfma_f32_16x16x32_bf16 v[14:17], v[152:155], v[208:211], v[14:17]
	v_mfma_f32_16x16x32_bf16 v[54:57], v[164:167], v[180:183], v[54:57]
	v_mfma_f32_16x16x32_bf16 v[54:57], v[168:171], v[184:187], v[54:57]
	v_mfma_f32_16x16x32_bf16 v[50:53], v[172:175], v[180:183], v[50:53]
	v_mfma_f32_16x16x32_bf16 v[50:53], v[176:179], v[184:187], v[50:53]
	v_mfma_f32_16x16x32_bf16 v[34:37], v[172:175], v[188:191], v[34:37]
	v_mfma_f32_16x16x32_bf16 v[34:37], v[176:179], v[192:195], v[34:37]
	v_mfma_f32_16x16x32_bf16 v[38:41], v[164:167], v[188:191], v[38:41]
	v_mfma_f32_16x16x32_bf16 v[38:41], v[168:171], v[192:195], v[38:41]
	v_mfma_f32_16x16x32_bf16 v[22:25], v[164:167], v[196:199], v[22:25]
	v_mfma_f32_16x16x32_bf16 v[22:25], v[168:171], v[200:203], v[22:25]
	v_mfma_f32_16x16x32_bf16 v[18:21], v[172:175], v[196:199], v[18:21]
	v_mfma_f32_16x16x32_bf16 v[18:21], v[176:179], v[200:203], v[18:21]
	v_mfma_f32_16x16x32_bf16 v[2:5], v[172:175], v[204:207], v[2:5]
	v_mfma_f32_16x16x32_bf16 v[2:5], v[176:179], v[208:211], v[2:5]
	s_setprio 2
	s_barrier
	v_mfma_f32_16x16x32_bf16 v[6:9], v[164:167], v[204:207], v[6:9]
	v_mfma_f32_16x16x32_bf16 v[6:9], v[168:171], v[208:211], v[6:9]
	s_setprio 0
	s_add_i32 s70, s70, 2
	s_add_u32 s64, s64, 0x100
	s_addc_u32 s65, s65, 0
	s_add_u32 s18, s18, 0x100
	s_addc_u32 s19, s19, 0
	s_add_u32 s66, s66, 0x100
	s_addc_u32 s67, s67, 0
	s_cmp_gt_u32 s70, 29
	.p2align 6
.LBB0_2594:
	ds_read_b128 v[148:151], v143
	ds_read_b128 v[152:155], v143 offset:1024
	ds_read_b128 v[156:159], v143 offset:2048
	ds_read_b128 v[160:163], v143 offset:3072
	ds_read_b128 v[164:167], v144
	ds_read_b128 v[168:171], v144 offset:1024
	ds_read_b128 v[172:175], v144 offset:2048
	ds_read_b128 v[176:179], v144 offset:3072
	s_cmp_eq_u32 s70, 28
	s_cselect_b32 s21, s9, s65
	s_cselect_b32 s20, s63, s64
	s_cselect_b32 s23, s11, s67
	s_cselect_b32 s22, s62, s66
	ds_read_b128 v[180:183], v145
	ds_read_b128 v[184:187], v145 offset:1024
	ds_read_b128 v[188:191], v145 offset:2048
	ds_read_b128 v[192:195], v145 offset:3072
	ds_read_b128 v[196:199], v145 offset:4096
	ds_read_b128 v[200:203], v145 offset:5120
	ds_read_b128 v[204:207], v145 offset:6144
	ds_read_b128 v[208:211], v145 offset:7168
	s_add_u32 s74, s18, 0xfff80000
	s_addc_u32 s75, s19, -1
	s_mov_b32 s71, m0
	s_mov_b32 m0, s48
	s_nop 0
	global_load_lds_dwordx4 v138, s[74:75]
	s_mov_b32 m0, s71
	s_nop 0
	s_mov_b32 s71, m0
	s_mov_b32 m0, s57
	s_nop 0
	global_load_lds_dwordx4 v140, s[74:75]
	s_mov_b32 m0, s71
	s_nop 0
	s_mov_b32 s71, m0
	s_mov_b32 m0, s49
	s_nop 0
	global_load_lds_dwordx4 v138, s[18:19]
	s_mov_b32 m0, s71
	s_nop 0
	s_mov_b32 s71, m0
	s_mov_b32 m0, s58
	s_nop 0
	global_load_lds_dwordx4 v140, s[18:19]
	s_mov_b32 m0, s71
	s_waitcnt vmcnt(8)
	s_waitcnt lgkmcnt(0)
	s_barrier
	s_setprio 1
	.p2align 3
	v_mfma_f32_16x16x32_bf16 v[126:129], v[148:151], v[180:183], v[126:129]
	v_mfma_f32_16x16x32_bf16 v[126:129], v[152:155], v[184:187], v[126:129]
	v_mfma_f32_16x16x32_bf16 v[122:125], v[156:159], v[180:183], v[122:125]
	v_mfma_f32_16x16x32_bf16 v[122:125], v[160:163], v[184:187], v[122:125]
	v_mfma_f32_16x16x32_bf16 v[106:109], v[156:159], v[188:191], v[106:109]
	v_mfma_f32_16x16x32_bf16 v[106:109], v[160:163], v[192:195], v[106:109]
	v_mfma_f32_16x16x32_bf16 v[110:113], v[148:151], v[188:191], v[110:113]
	v_mfma_f32_16x16x32_bf16 v[110:113], v[152:155], v[192:195], v[110:113]
	v_mfma_f32_16x16x32_bf16 v[94:97], v[148:151], v[196:199], v[94:97]
	v_mfma_f32_16x16x32_bf16 v[94:97], v[152:155], v[200:203], v[94:97]
	v_mfma_f32_16x16x32_bf16 v[90:93], v[156:159], v[196:199], v[90:93]
	v_mfma_f32_16x16x32_bf16 v[90:93], v[160:163], v[200:203], v[90:93]
	v_mfma_f32_16x16x32_bf16 v[74:77], v[156:159], v[204:207], v[74:77]
	v_mfma_f32_16x16x32_bf16 v[74:77], v[160:163], v[208:211], v[74:77]
	v_mfma_f32_16x16x32_bf16 v[78:81], v[148:151], v[204:207], v[78:81]
	v_mfma_f32_16x16x32_bf16 v[78:81], v[152:155], v[208:211], v[78:81]
	v_mfma_f32_16x16x32_bf16 v[118:121], v[164:167], v[180:183], v[118:121]
	v_mfma_f32_16x16x32_bf16 v[118:121], v[168:171], v[184:187], v[118:121]
	v_mfma_f32_16x16x32_bf16 v[114:117], v[172:175], v[180:183], v[114:117]
	v_mfma_f32_16x16x32_bf16 v[114:117], v[176:179], v[184:187], v[114:117]
	v_mfma_f32_16x16x32_bf16 v[98:101], v[172:175], v[188:191], v[98:101]
	v_mfma_f32_16x16x32_bf16 v[98:101], v[176:179], v[192:195], v[98:101]
	v_mfma_f32_16x16x32_bf16 v[102:105], v[164:167], v[188:191], v[102:105]
	v_mfma_f32_16x16x32_bf16 v[102:105], v[168:171], v[192:195], v[102:105]
	v_mfma_f32_16x16x32_bf16 v[86:89], v[164:167], v[196:199], v[86:89]
	v_mfma_f32_16x16x32_bf16 v[86:89], v[168:171], v[200:203], v[86:89]
	v_mfma_f32_16x16x32_bf16 v[82:85], v[172:175], v[196:199], v[82:85]
	v_mfma_f32_16x16x32_bf16 v[82:85], v[176:179], v[200:203], v[82:85]
	v_mfma_f32_16x16x32_bf16 v[66:69], v[172:175], v[204:207], v[66:69]
	v_mfma_f32_16x16x32_bf16 v[66:69], v[176:179], v[208:211], v[66:69]
	s_setprio 2
	s_barrier
	v_mfma_f32_16x16x32_bf16 v[70:73], v[164:167], v[204:207], v[70:73]
	v_mfma_f32_16x16x32_bf16 v[70:73], v[168:171], v[208:211], v[70:73]
	s_setprio 0
	ds_read_b128 v[180:183], v145 offset:16384
	ds_read_b128 v[184:187], v145 offset:17408
	ds_read_b128 v[188:191], v145 offset:18432
	ds_read_b128 v[192:195], v145 offset:19456
	ds_read_b128 v[196:199], v145 offset:20480
	ds_read_b128 v[200:203], v145 offset:21504
	ds_read_b128 v[204:207], v145 offset:22528
	ds_read_b128 v[208:211], v145 offset:23552
	s_mov_b32 s71, m0
	s_mov_b32 m0, s35
	s_nop 0
	global_load_lds_dwordx4 v139, s[20:21]
	s_mov_b32 m0, s71
	s_add_u32 s74, s20, 0x80000
	s_mov_b32 s71, m0
	s_mov_b32 m0, s36
	s_nop 0
	global_load_lds_dwordx4 v141, s[20:21]
	s_mov_b32 m0, s71
	s_addc_u32 s75, s21, 0
	s_mov_b32 s71, m0
	s_mov_b32 m0, s37
	s_nop 0
	global_load_lds_dwordx4 v139, s[74:75]
	s_mov_b32 m0, s71
	s_nop 0
	s_mov_b32 s71, m0
	s_mov_b32 m0, s40
	s_nop 0
	global_load_lds_dwordx4 v141, s[74:75]
	s_mov_b32 m0, s71
	s_waitcnt vmcnt(4)
	s_waitcnt lgkmcnt(0)
	s_barrier
	s_setprio 1
	.p2align 3
	v_mfma_f32_16x16x32_bf16 v[62:65], v[148:151], v[180:183], v[62:65]
	v_mfma_f32_16x16x32_bf16 v[62:65], v[152:155], v[184:187], v[62:65]
	v_mfma_f32_16x16x32_bf16 v[58:61], v[156:159], v[180:183], v[58:61]
	v_mfma_f32_16x16x32_bf16 v[58:61], v[160:163], v[184:187], v[58:61]
	v_mfma_f32_16x16x32_bf16 v[42:45], v[156:159], v[188:191], v[42:45]
	v_mfma_f32_16x16x32_bf16 v[42:45], v[160:163], v[192:195], v[42:45]
	v_mfma_f32_16x16x32_bf16 v[46:49], v[148:151], v[188:191], v[46:49]
	v_mfma_f32_16x16x32_bf16 v[46:49], v[152:155], v[192:195], v[46:49]
	v_mfma_f32_16x16x32_bf16 v[30:33], v[148:151], v[196:199], v[30:33]
	v_mfma_f32_16x16x32_bf16 v[30:33], v[152:155], v[200:203], v[30:33]
	v_mfma_f32_16x16x32_bf16 v[26:29], v[156:159], v[196:199], v[26:29]
	v_mfma_f32_16x16x32_bf16 v[26:29], v[160:163], v[200:203], v[26:29]
	v_mfma_f32_16x16x32_bf16 v[10:13], v[156:159], v[204:207], v[10:13]
	v_mfma_f32_16x16x32_bf16 v[10:13], v[160:163], v[208:211], v[10:13]
	v_mfma_f32_16x16x32_bf16 v[14:17], v[148:151], v[204:207], v[14:17]
	v_mfma_f32_16x16x32_bf16 v[14:17], v[152:155], v[208:211], v[14:17]
	v_mfma_f32_16x16x32_bf16 v[54:57], v[164:167], v[180:183], v[54:57]
	v_mfma_f32_16x16x32_bf16 v[54:57], v[168:171], v[184:187], v[54:57]
	v_mfma_f32_16x16x32_bf16 v[50:53], v[172:175], v[180:183], v[50:53]
	v_mfma_f32_16x16x32_bf16 v[50:53], v[176:179], v[184:187], v[50:53]
	v_mfma_f32_16x16x32_bf16 v[34:37], v[172:175], v[188:191], v[34:37]
	v_mfma_f32_16x16x32_bf16 v[34:37], v[176:179], v[192:195], v[34:37]
	v_mfma_f32_16x16x32_bf16 v[38:41], v[164:167], v[188:191], v[38:41]
	v_mfma_f32_16x16x32_bf16 v[38:41], v[168:171], v[192:195], v[38:41]
	v_mfma_f32_16x16x32_bf16 v[22:25], v[164:167], v[196:199], v[22:25]
	v_mfma_f32_16x16x32_bf16 v[22:25], v[168:171], v[200:203], v[22:25]
	v_mfma_f32_16x16x32_bf16 v[18:21], v[172:175], v[196:199], v[18:21]
	v_mfma_f32_16x16x32_bf16 v[18:21], v[176:179], v[200:203], v[18:21]
	v_mfma_f32_16x16x32_bf16 v[2:5], v[172:175], v[204:207], v[2:5]
	v_mfma_f32_16x16x32_bf16 v[2:5], v[176:179], v[208:211], v[2:5]
	s_setprio 2
	s_barrier
	v_mfma_f32_16x16x32_bf16 v[6:9], v[164:167], v[204:207], v[6:9]
	v_mfma_f32_16x16x32_bf16 v[6:9], v[168:171], v[208:211], v[6:9]
	s_setprio 0
	ds_read_b128 v[148:151], v146
	ds_read_b128 v[152:155], v146 offset:1024
	ds_read_b128 v[156:159], v146 offset:2048
	ds_read_b128 v[160:163], v146 offset:3072
	ds_read_b128 v[164:167], v147
	ds_read_b128 v[168:171], v147 offset:1024
	ds_read_b128 v[172:175], v147 offset:2048
	ds_read_b128 v[176:179], v147 offset:3072
	ds_read_b128 v[180:183], v145 offset:32768
	ds_read_b128 v[184:187], v145 offset:33792
	ds_read_b128 v[188:191], v145 offset:34816
	ds_read_b128 v[192:195], v145 offset:35840
	ds_read_b128 v[196:199], v145 offset:36864
	ds_read_b128 v[200:203], v145 offset:37888
	ds_read_b128 v[204:207], v145 offset:38912
	ds_read_b128 v[208:211], v145 offset:39936
	s_mov_b32 s71, m0
	s_mov_b32 m0, s31
	s_nop 0
	global_load_lds_dwordx4 v138, s[22:23]
	s_mov_b32 m0, s71
	s_nop 0
	s_mov_b32 s71, m0
	s_mov_b32 m0, s41
	s_nop 0
	global_load_lds_dwordx4 v140, s[22:23]
	s_mov_b32 m0, s71
	s_add_u32 s22, s22, 0x80000
	s_addc_u32 s23, s23, 0
	s_mov_b32 s71, m0
	s_mov_b32 m0, s42
	s_nop 0
	global_load_lds_dwordx4 v138, s[22:23]
	s_mov_b32 m0, s71
	s_nop 0
	s_mov_b32 s71, m0
	s_mov_b32 m0, s43
	s_nop 0
	global_load_lds_dwordx4 v140, s[22:23]
	s_mov_b32 m0, s71
	s_waitcnt vmcnt(8)
	s_waitcnt lgkmcnt(0)
	s_barrier
	s_setprio 1
	.p2align 3
	v_mfma_f32_16x16x32_bf16 v[126:129], v[148:151], v[180:183], v[126:129]
	v_mfma_f32_16x16x32_bf16 v[126:129], v[152:155], v[184:187], v[126:129]
	v_mfma_f32_16x16x32_bf16 v[122:125], v[156:159], v[180:183], v[122:125]
	v_mfma_f32_16x16x32_bf16 v[122:125], v[160:163], v[184:187], v[122:125]
	v_mfma_f32_16x16x32_bf16 v[106:109], v[156:159], v[188:191], v[106:109]
	v_mfma_f32_16x16x32_bf16 v[106:109], v[160:163], v[192:195], v[106:109]
	v_mfma_f32_16x16x32_bf16 v[110:113], v[148:151], v[188:191], v[110:113]
	v_mfma_f32_16x16x32_bf16 v[110:113], v[152:155], v[192:195], v[110:113]
	v_mfma_f32_16x16x32_bf16 v[94:97], v[148:151], v[196:199], v[94:97]
	v_mfma_f32_16x16x32_bf16 v[94:97], v[152:155], v[200:203], v[94:97]
	v_mfma_f32_16x16x32_bf16 v[90:93], v[156:159], v[196:199], v[90:93]
	v_mfma_f32_16x16x32_bf16 v[90:93], v[160:163], v[200:203], v[90:93]
	v_mfma_f32_16x16x32_bf16 v[74:77], v[156:159], v[204:207], v[74:77]
	v_mfma_f32_16x16x32_bf16 v[74:77], v[160:163], v[208:211], v[74:77]
	v_mfma_f32_16x16x32_bf16 v[78:81], v[148:151], v[204:207], v[78:81]
	v_mfma_f32_16x16x32_bf16 v[78:81], v[152:155], v[208:211], v[78:81]
	v_mfma_f32_16x16x32_bf16 v[118:121], v[164:167], v[180:183], v[118:121]
	v_mfma_f32_16x16x32_bf16 v[118:121], v[168:171], v[184:187], v[118:121]
	v_mfma_f32_16x16x32_bf16 v[114:117], v[172:175], v[180:183], v[114:117]
	v_mfma_f32_16x16x32_bf16 v[114:117], v[176:179], v[184:187], v[114:117]
	v_mfma_f32_16x16x32_bf16 v[98:101], v[172:175], v[188:191], v[98:101]
	v_mfma_f32_16x16x32_bf16 v[98:101], v[176:179], v[192:195], v[98:101]
	v_mfma_f32_16x16x32_bf16 v[102:105], v[164:167], v[188:191], v[102:105]
	v_mfma_f32_16x16x32_bf16 v[102:105], v[168:171], v[192:195], v[102:105]
	v_mfma_f32_16x16x32_bf16 v[86:89], v[164:167], v[196:199], v[86:89]
	v_mfma_f32_16x16x32_bf16 v[86:89], v[168:171], v[200:203], v[86:89]
	v_mfma_f32_16x16x32_bf16 v[82:85], v[172:175], v[196:199], v[82:85]
	v_mfma_f32_16x16x32_bf16 v[82:85], v[176:179], v[200:203], v[82:85]
	v_mfma_f32_16x16x32_bf16 v[66:69], v[172:175], v[204:207], v[66:69]
	v_mfma_f32_16x16x32_bf16 v[66:69], v[176:179], v[208:211], v[66:69]
	s_setprio 2
	s_barrier
	v_mfma_f32_16x16x32_bf16 v[70:73], v[164:167], v[204:207], v[70:73]
	v_mfma_f32_16x16x32_bf16 v[70:73], v[168:171], v[208:211], v[70:73]
	s_setprio 0
	ds_read_b128 v[180:183], v145 offset:49152
	ds_read_b128 v[184:187], v145 offset:50176
	ds_read_b128 v[188:191], v145 offset:51200
	ds_read_b128 v[192:195], v145 offset:52224
	ds_read_b128 v[196:199], v145 offset:53248
	ds_read_b128 v[200:203], v145 offset:54272
	ds_read_b128 v[204:207], v145 offset:55296
	ds_read_b128 v[208:211], v145 offset:56320
	s_add_u32 s22, s20, 0x80
	s_addc_u32 s23, s21, 0
	s_mov_b32 s71, m0
	s_mov_b32 m0, s44
	s_nop 0
	global_load_lds_dwordx4 v139, s[22:23]
	s_mov_b32 m0, s71
	s_add_u32 s20, s20, 0x80080
	s_mov_b32 s71, m0
	s_mov_b32 m0, s45
	s_nop 0
	global_load_lds_dwordx4 v141, s[22:23]
	s_mov_b32 m0, s71
	s_addc_u32 s21, s21, 0
	s_mov_b32 s22, m0
	s_mov_b32 m0, s46
	s_nop 0
	global_load_lds_dwordx4 v139, s[20:21]
	s_mov_b32 m0, s22
	s_nop 0
	s_mov_b32 s22, m0
	s_mov_b32 m0, s47
	s_nop 0
	global_load_lds_dwordx4 v141, s[20:21]
	s_mov_b32 m0, s22
	s_waitcnt vmcnt(4)
	s_waitcnt lgkmcnt(0)
	s_barrier
	s_setprio 1
	.p2align 3
	v_mfma_f32_16x16x32_bf16 v[62:65], v[148:151], v[180:183], v[62:65]
	v_mfma_f32_16x16x32_bf16 v[62:65], v[152:155], v[184:187], v[62:65]
	v_mfma_f32_16x16x32_bf16 v[58:61], v[156:159], v[180:183], v[58:61]
	v_mfma_f32_16x16x32_bf16 v[58:61], v[160:163], v[184:187], v[58:61]
	v_mfma_f32_16x16x32_bf16 v[42:45], v[156:159], v[188:191], v[42:45]
	v_mfma_f32_16x16x32_bf16 v[42:45], v[160:163], v[192:195], v[42:45]
	v_mfma_f32_16x16x32_bf16 v[46:49], v[148:151], v[188:191], v[46:49]
	v_mfma_f32_16x16x32_bf16 v[46:49], v[152:155], v[192:195], v[46:49]
	v_mfma_f32_16x16x32_bf16 v[30:33], v[148:151], v[196:199], v[30:33]
	v_mfma_f32_16x16x32_bf16 v[30:33], v[152:155], v[200:203], v[30:33]
	v_mfma_f32_16x16x32_bf16 v[26:29], v[156:159], v[196:199], v[26:29]
	v_mfma_f32_16x16x32_bf16 v[26:29], v[160:163], v[200:203], v[26:29]
	v_mfma_f32_16x16x32_bf16 v[10:13], v[156:159], v[204:207], v[10:13]
	v_mfma_f32_16x16x32_bf16 v[10:13], v[160:163], v[208:211], v[10:13]
	v_mfma_f32_16x16x32_bf16 v[14:17], v[148:151], v[204:207], v[14:17]
	v_mfma_f32_16x16x32_bf16 v[14:17], v[152:155], v[208:211], v[14:17]
	v_mfma_f32_16x16x32_bf16 v[54:57], v[164:167], v[180:183], v[54:57]
	v_mfma_f32_16x16x32_bf16 v[54:57], v[168:171], v[184:187], v[54:57]
	v_mfma_f32_16x16x32_bf16 v[50:53], v[172:175], v[180:183], v[50:53]
	v_mfma_f32_16x16x32_bf16 v[50:53], v[176:179], v[184:187], v[50:53]
	v_mfma_f32_16x16x32_bf16 v[34:37], v[172:175], v[188:191], v[34:37]
	v_mfma_f32_16x16x32_bf16 v[34:37], v[176:179], v[192:195], v[34:37]
	v_mfma_f32_16x16x32_bf16 v[38:41], v[164:167], v[188:191], v[38:41]
	v_mfma_f32_16x16x32_bf16 v[38:41], v[168:171], v[192:195], v[38:41]
	v_mfma_f32_16x16x32_bf16 v[22:25], v[164:167], v[196:199], v[22:25]
	v_mfma_f32_16x16x32_bf16 v[22:25], v[168:171], v[200:203], v[22:25]
	v_mfma_f32_16x16x32_bf16 v[18:21], v[172:175], v[196:199], v[18:21]
	v_mfma_f32_16x16x32_bf16 v[18:21], v[176:179], v[200:203], v[18:21]
	v_mfma_f32_16x16x32_bf16 v[2:5], v[172:175], v[204:207], v[2:5]
	v_mfma_f32_16x16x32_bf16 v[2:5], v[176:179], v[208:211], v[2:5]
	s_setprio 2
	s_barrier
	v_mfma_f32_16x16x32_bf16 v[6:9], v[164:167], v[204:207], v[6:9]
	v_mfma_f32_16x16x32_bf16 v[6:9], v[168:171], v[208:211], v[6:9]
	s_setprio 0
	s_add_i32 s70, s70, 2
	s_add_u32 s64, s64, 0x100
	s_addc_u32 s65, s65, 0
	s_add_u32 s18, s18, 0x100
	s_addc_u32 s19, s19, 0
	s_add_u32 s66, s66, 0x100
	s_addc_u32 s67, s67, 0
	s_cmp_gt_u32 s70, 29
	s_cbranch_scc0 .LBB0_2594
	s_and_b64 vcc, exec, s[6:7]
	s_cbranch_vccz .LBB0_2597
	s_barrier

.LBB0_2791:
	s_ashr_i32 s21, s20, 31
	s_lshl_b64 s[22:23], s[20:21], 15
	s_add_u32 s22, s37, s22
	s_addc_u32 s23, s40, s23
	s_and_b64 s[24:25], s[2:3], exec
	s_cselect_b32 s21, s23, s31
	s_cselect_b32 s63, s22, s30
	s_ashr_i32 s19, s18, 31
	s_lshl_b64 s[24:25], s[18:19], 15
	s_add_u32 s24, s41, s24
	s_addc_u32 s25, s42, s25
	s_and_b64 s[34:35], s[2:3], exec
	s_cselect_b32 s19, s25, s29
	s_cselect_b32 s64, s24, s28
	s_add_u32 s65, s28, 0x80000
	s_addc_u32 s66, s29, 0
	s_add_u32 s28, s30, 0x204000
	s_addc_u32 s29, s31, 0
	s_add_u32 s67, s30, 0x400000
	s_addc_u32 s68, s31, 0
	s_mov_b32 s69, -2
	s_waitcnt vmcnt(25)
	s_waitcnt vmcnt(24)
	s_waitcnt vmcnt(4)
	s_waitcnt vmcnt(2)
	s_waitcnt vmcnt(1)
	s_waitcnt vmcnt(0)
	ds_read_b128 v[130:133], v181
	ds_read_b128 v[134:137], v181 offset:1024
	ds_read_b128 v[138:141], v181 offset:2048
	ds_read_b128 v[142:145], v181 offset:3072
	ds_read_b128 v[150:153], v182
	ds_read_b128 v[154:157], v182 offset:1024
	ds_read_b128 v[158:161], v182 offset:2048
	ds_read_b128 v[162:165], v182 offset:3072
	s_cmpk_eq_i32 s69, 0x52
	s_cselect_b32 s31, s19, s66
	s_cselect_b32 s30, s64, s65
	s_cselect_b32 s35, s21, s68
	s_cselect_b32 s34, s63, s67
	ds_read_b128 v[166:169], v183
	ds_read_b128 v[170:173], v183 offset:1024
	ds_read_b128 v[186:189], v183 offset:2048
	ds_read_b128 v[190:193], v183 offset:3072
	ds_read_b128 v[194:197], v183 offset:4096
	ds_read_b128 v[198:201], v183 offset:5120
	ds_read_b128 v[202:205], v183 offset:6144
	ds_read_b128 v[206:209], v183 offset:7168
	s_add_u32 s70, s28, 0xffffc000
	s_addc_u32 s71, s29, -1
	s_mov_b32 s73, m0
	s_mov_b32 m0, s57
	s_nop 0
	global_load_lds_dwordx4 v1, s[70:71]
	s_mov_b32 m0, s73
	s_nop 0
	s_mov_b32 s73, m0
	s_mov_b32 m0, s59
	s_nop 0
	global_load_lds_dwordx4 v177, s[70:71]
	s_mov_b32 m0, s73
	s_mov_b32 s70, m0
	s_mov_b32 m0, s58
	s_nop 0
	global_load_lds_dwordx4 v1, s[28:29]
	s_mov_b32 m0, s70
	s_nop 0
	s_mov_b32 s70, m0
	s_mov_b32 m0, s60
	s_nop 0
	global_load_lds_dwordx4 v177, s[28:29]
	s_mov_b32 m0, s70
	s_waitcnt vmcnt(8)
	s_waitcnt lgkmcnt(0)
	s_barrier
	s_setprio 1
	.p2align 3
	v_mfma_f32_16x16x32_bf16 v[126:129], v[130:133], v[166:169], 0
	v_mfma_f32_16x16x32_bf16 v[126:129], v[134:137], v[170:173], v[126:129]
	v_mfma_f32_16x16x32_bf16 v[122:125], v[138:141], v[166:169], 0
	v_mfma_f32_16x16x32_bf16 v[122:125], v[142:145], v[170:173], v[122:125]
	v_mfma_f32_16x16x32_bf16 v[110:113], v[138:141], v[186:189], 0
	v_mfma_f32_16x16x32_bf16 v[110:113], v[142:145], v[190:193], v[110:113]
	v_mfma_f32_16x16x32_bf16 v[118:121], v[130:133], v[186:189], 0
	v_mfma_f32_16x16x32_bf16 v[118:121], v[134:137], v[190:193], v[118:121]
	v_mfma_f32_16x16x32_bf16 v[94:97], v[130:133], v[194:197], 0
	v_mfma_f32_16x16x32_bf16 v[94:97], v[134:137], v[198:201], v[94:97]
	v_mfma_f32_16x16x32_bf16 v[90:93], v[138:141], v[194:197], 0
	v_mfma_f32_16x16x32_bf16 v[90:93], v[142:145], v[198:201], v[90:93]
	v_mfma_f32_16x16x32_bf16 v[78:81], v[138:141], v[202:205], 0
	v_mfma_f32_16x16x32_bf16 v[78:81], v[142:145], v[206:209], v[78:81]
	v_mfma_f32_16x16x32_bf16 v[86:89], v[130:133], v[202:205], 0
	v_mfma_f32_16x16x32_bf16 v[86:89], v[134:137], v[206:209], v[86:89]
	v_mfma_f32_16x16x32_bf16 v[114:117], v[150:153], v[166:169], 0
	v_mfma_f32_16x16x32_bf16 v[114:117], v[154:157], v[170:173], v[114:117]
	v_mfma_f32_16x16x32_bf16 v[106:109], v[158:161], v[166:169], 0
	v_mfma_f32_16x16x32_bf16 v[106:109], v[162:165], v[170:173], v[106:109]
	v_mfma_f32_16x16x32_bf16 v[98:101], v[158:161], v[186:189], 0
	v_mfma_f32_16x16x32_bf16 v[98:101], v[162:165], v[190:193], v[98:101]
	v_mfma_f32_16x16x32_bf16 v[102:105], v[150:153], v[186:189], 0
	v_mfma_f32_16x16x32_bf16 v[102:105], v[154:157], v[190:193], v[102:105]
	v_mfma_f32_16x16x32_bf16 v[82:85], v[150:153], v[194:197], 0
	v_mfma_f32_16x16x32_bf16 v[82:85], v[154:157], v[198:201], v[82:85]
	v_mfma_f32_16x16x32_bf16 v[74:77], v[158:161], v[194:197], 0
	v_mfma_f32_16x16x32_bf16 v[74:77], v[162:165], v[198:201], v[74:77]
	v_mfma_f32_16x16x32_bf16 v[66:69], v[158:161], v[202:205], 0
	v_mfma_f32_16x16x32_bf16 v[66:69], v[162:165], v[206:209], v[66:69]
	s_setprio 2
	s_barrier
	v_mfma_f32_16x16x32_bf16 v[70:73], v[150:153], v[202:205], 0
	v_mfma_f32_16x16x32_bf16 v[70:73], v[154:157], v[206:209], v[70:73]
	s_setprio 0
	ds_read_b128 v[166:169], v183 offset:16384
	ds_read_b128 v[170:173], v183 offset:17408
	ds_read_b128 v[186:189], v183 offset:18432
	ds_read_b128 v[190:193], v183 offset:19456
	ds_read_b128 v[194:197], v183 offset:20480
	ds_read_b128 v[198:201], v183 offset:21504
	ds_read_b128 v[202:205], v183 offset:22528
	ds_read_b128 v[206:209], v183 offset:23552
	s_mov_b32 s70, m0
	s_mov_b32 m0, s27
	s_nop 0
	global_load_lds_dwordx4 v176, s[30:31]
	s_mov_b32 m0, s70
	s_nop 0
	s_mov_b32 s70, m0
	s_mov_b32 m0, s45
	s_nop 0
	global_load_lds_dwordx4 v178, s[30:31]
	s_mov_b32 m0, s70
	s_add_u32 s70, s30, 0x4000
	s_addc_u32 s71, s31, 0
	s_mov_b32 s73, m0
	s_mov_b32 m0, s46
	s_nop 0
	global_load_lds_dwordx4 v176, s[70:71]
	s_mov_b32 m0, s73
	s_nop 0
	s_mov_b32 s73, m0
	s_mov_b32 m0, s47
	s_nop 0
	global_load_lds_dwordx4 v178, s[70:71]
	s_mov_b32 m0, s73
	s_waitcnt vmcnt(4)
	s_waitcnt lgkmcnt(0)
	s_barrier
	s_setprio 1
	.p2align 3
	v_mfma_f32_16x16x32_bf16 v[62:65], v[130:133], v[166:169], 0
	v_mfma_f32_16x16x32_bf16 v[62:65], v[134:137], v[170:173], v[62:65]
	v_mfma_f32_16x16x32_bf16 v[58:61], v[138:141], v[166:169], 0
	v_mfma_f32_16x16x32_bf16 v[58:61], v[142:145], v[170:173], v[58:61]
	v_mfma_f32_16x16x32_bf16 v[42:45], v[138:141], v[186:189], 0
	v_mfma_f32_16x16x32_bf16 v[42:45], v[142:145], v[190:193], v[42:45]
	v_mfma_f32_16x16x32_bf16 v[46:49], v[130:133], v[186:189], 0
	v_mfma_f32_16x16x32_bf16 v[46:49], v[134:137], v[190:193], v[46:49]
	v_mfma_f32_16x16x32_bf16 v[30:33], v[130:133], v[194:197], 0
	v_mfma_f32_16x16x32_bf16 v[30:33], v[134:137], v[198:201], v[30:33]
	v_mfma_f32_16x16x32_bf16 v[26:29], v[138:141], v[194:197], 0
	v_mfma_f32_16x16x32_bf16 v[26:29], v[142:145], v[198:201], v[26:29]
	v_mfma_f32_16x16x32_bf16 v[10:13], v[138:141], v[202:205], 0
	v_mfma_f32_16x16x32_bf16 v[10:13], v[142:145], v[206:209], v[10:13]
	v_mfma_f32_16x16x32_bf16 v[14:17], v[130:133], v[202:205], 0
	v_mfma_f32_16x16x32_bf16 v[14:17], v[134:137], v[206:209], v[14:17]
	v_mfma_f32_16x16x32_bf16 v[54:57], v[150:153], v[166:169], 0
	v_mfma_f32_16x16x32_bf16 v[54:57], v[154:157], v[170:173], v[54:57]
	v_mfma_f32_16x16x32_bf16 v[50:53], v[158:161], v[166:169], 0
	v_mfma_f32_16x16x32_bf16 v[50:53], v[162:165], v[170:173], v[50:53]
	v_mfma_f32_16x16x32_bf16 v[34:37], v[158:161], v[186:189], 0
	v_mfma_f32_16x16x32_bf16 v[34:37], v[162:165], v[190:193], v[34:37]
	v_mfma_f32_16x16x32_bf16 v[38:41], v[150:153], v[186:189], 0
	v_mfma_f32_16x16x32_bf16 v[38:41], v[154:157], v[190:193], v[38:41]
	v_mfma_f32_16x16x32_bf16 v[22:25], v[150:153], v[194:197], 0
	v_mfma_f32_16x16x32_bf16 v[22:25], v[154:157], v[198:201], v[22:25]
	v_mfma_f32_16x16x32_bf16 v[18:21], v[158:161], v[194:197], 0
	v_mfma_f32_16x16x32_bf16 v[18:21], v[162:165], v[198:201], v[18:21]
	v_mfma_f32_16x16x32_bf16 v[2:5], v[158:161], v[202:205], 0
	v_mfma_f32_16x16x32_bf16 v[2:5], v[162:165], v[206:209], v[2:5]
	s_setprio 2
	s_barrier
	v_mfma_f32_16x16x32_bf16 v[6:9], v[150:153], v[202:205], 0
	v_mfma_f32_16x16x32_bf16 v[6:9], v[154:157], v[206:209], v[6:9]
	s_setprio 0
	ds_read_b128 v[130:133], v184
	ds_read_b128 v[134:137], v184 offset:1024
	ds_read_b128 v[138:141], v184 offset:2048
	ds_read_b128 v[142:145], v184 offset:3072
	ds_read_b128 v[150:153], v185
	ds_read_b128 v[154:157], v185 offset:1024
	ds_read_b128 v[158:161], v185 offset:2048
	ds_read_b128 v[162:165], v185 offset:3072
	ds_read_b128 v[166:169], v183 offset:32768
	ds_read_b128 v[170:173], v183 offset:33792
	ds_read_b128 v[186:189], v183 offset:34816
	ds_read_b128 v[190:193], v183 offset:35840
	ds_read_b128 v[194:197], v183 offset:36864
	ds_read_b128 v[198:201], v183 offset:37888
	ds_read_b128 v[202:205], v183 offset:38912
	ds_read_b128 v[206:209], v183 offset:39936
	s_mov_b32 s70, m0
	s_mov_b32 m0, s44
	s_nop 0
	global_load_lds_dwordx4 v1, s[34:35]
	s_mov_b32 m0, s70
	s_nop 0
	s_mov_b32 s70, m0
	s_mov_b32 m0, s48
	s_nop 0
	global_load_lds_dwordx4 v177, s[34:35]
	s_mov_b32 m0, s70
	s_add_u32 s34, s34, 0x4000
	s_addc_u32 s35, s35, 0
	s_mov_b32 s70, m0
	s_mov_b32 m0, s49
	s_nop 0
	global_load_lds_dwordx4 v1, s[34:35]
	s_mov_b32 m0, s70
	s_nop 0
	s_mov_b32 s70, m0
	s_mov_b32 m0, s50
	s_nop 0
	global_load_lds_dwordx4 v177, s[34:35]
	s_mov_b32 m0, s70
	s_waitcnt vmcnt(8)
	s_waitcnt lgkmcnt(0)
	s_barrier
	s_setprio 1
	.p2align 3
	v_mfma_f32_16x16x32_bf16 v[126:129], v[130:133], v[166:169], v[126:129]
	v_mfma_f32_16x16x32_bf16 v[126:129], v[134:137], v[170:173], v[126:129]
	v_mfma_f32_16x16x32_bf16 v[122:125], v[138:141], v[166:169], v[122:125]
	v_mfma_f32_16x16x32_bf16 v[122:125], v[142:145], v[170:173], v[122:125]
	v_mfma_f32_16x16x32_bf16 v[110:113], v[138:141], v[186:189], v[110:113]
	v_mfma_f32_16x16x32_bf16 v[110:113], v[142:145], v[190:193], v[110:113]
	v_mfma_f32_16x16x32_bf16 v[118:121], v[130:133], v[186:189], v[118:121]
	v_mfma_f32_16x16x32_bf16 v[118:121], v[134:137], v[190:193], v[118:121]
	v_mfma_f32_16x16x32_bf16 v[94:97], v[130:133], v[194:197], v[94:97]
	v_mfma_f32_16x16x32_bf16 v[94:97], v[134:137], v[198:201], v[94:97]
	v_mfma_f32_16x16x32_bf16 v[90:93], v[138:141], v[194:197], v[90:93]
	v_mfma_f32_16x16x32_bf16 v[90:93], v[142:145], v[198:201], v[90:93]
	v_mfma_f32_16x16x32_bf16 v[78:81], v[138:141], v[202:205], v[78:81]
	v_mfma_f32_16x16x32_bf16 v[78:81], v[142:145], v[206:209], v[78:81]
	v_mfma_f32_16x16x32_bf16 v[86:89], v[130:133], v[202:205], v[86:89]
	v_mfma_f32_16x16x32_bf16 v[86:89], v[134:137], v[206:209], v[86:89]
	v_mfma_f32_16x16x32_bf16 v[114:117], v[150:153], v[166:169], v[114:117]
	v_mfma_f32_16x16x32_bf16 v[114:117], v[154:157], v[170:173], v[114:117]
	v_mfma_f32_16x16x32_bf16 v[106:109], v[158:161], v[166:169], v[106:109]
	v_mfma_f32_16x16x32_bf16 v[106:109], v[162:165], v[170:173], v[106:109]
	v_mfma_f32_16x16x32_bf16 v[98:101], v[158:161], v[186:189], v[98:101]
	v_mfma_f32_16x16x32_bf16 v[98:101], v[162:165], v[190:193], v[98:101]
	v_mfma_f32_16x16x32_bf16 v[102:105], v[150:153], v[186:189], v[102:105]
	v_mfma_f32_16x16x32_bf16 v[102:105], v[154:157], v[190:193], v[102:105]
	v_mfma_f32_16x16x32_bf16 v[82:85], v[150:153], v[194:197], v[82:85]
	v_mfma_f32_16x16x32_bf16 v[82:85], v[154:157], v[198:201], v[82:85]
	v_mfma_f32_16x16x32_bf16 v[74:77], v[158:161], v[194:197], v[74:77]
	v_mfma_f32_16x16x32_bf16 v[74:77], v[162:165], v[198:201], v[74:77]
	v_mfma_f32_16x16x32_bf16 v[66:69], v[158:161], v[202:205], v[66:69]
	v_mfma_f32_16x16x32_bf16 v[66:69], v[162:165], v[206:209], v[66:69]
	s_setprio 2
	s_barrier
	v_mfma_f32_16x16x32_bf16 v[70:73], v[150:153], v[202:205], v[70:73]
	v_mfma_f32_16x16x32_bf16 v[70:73], v[154:157], v[206:209], v[70:73]
	s_setprio 0
	ds_read_b128 v[166:169], v183 offset:49152
	ds_read_b128 v[170:173], v183 offset:50176
	ds_read_b128 v[186:189], v183 offset:51200
	ds_read_b128 v[190:193], v183 offset:52224
	ds_read_b128 v[194:197], v183 offset:53248
	ds_read_b128 v[198:201], v183 offset:54272
	ds_read_b128 v[202:205], v183 offset:55296
	ds_read_b128 v[206:209], v183 offset:56320
	s_add_u32 s34, s30, 0x40000
	s_addc_u32 s35, s31, 0
	s_mov_b32 s70, m0
	s_mov_b32 m0, s51
	s_nop 0
	global_load_lds_dwordx4 v176, s[34:35]
	s_mov_b32 m0, s70
	s_add_u32 s30, s30, 0x44000
	s_mov_b32 s70, m0
	s_mov_b32 m0, s52
	s_nop 0
	global_load_lds_dwordx4 v178, s[34:35]
	s_mov_b32 m0, s70
	s_addc_u32 s31, s31, 0
	s_mov_b32 s34, m0
	s_mov_b32 m0, s53
	s_nop 0
	global_load_lds_dwordx4 v176, s[30:31]
	s_mov_b32 m0, s34
	s_nop 0
	s_mov_b32 s34, m0
	s_mov_b32 m0, s54
	s_nop 0
	global_load_lds_dwordx4 v178, s[30:31]
	s_mov_b32 m0, s34
	s_waitcnt vmcnt(4)
	s_waitcnt lgkmcnt(0)
	s_barrier
	s_setprio 1
	.p2align 3
	v_mfma_f32_16x16x32_bf16 v[62:65], v[130:133], v[166:169], v[62:65]
	v_mfma_f32_16x16x32_bf16 v[62:65], v[134:137], v[170:173], v[62:65]
	v_mfma_f32_16x16x32_bf16 v[58:61], v[138:141], v[166:169], v[58:61]
	v_mfma_f32_16x16x32_bf16 v[58:61], v[142:145], v[170:173], v[58:61]
	v_mfma_f32_16x16x32_bf16 v[42:45], v[138:141], v[186:189], v[42:45]
	v_mfma_f32_16x16x32_bf16 v[42:45], v[142:145], v[190:193], v[42:45]
	v_mfma_f32_16x16x32_bf16 v[46:49], v[130:133], v[186:189], v[46:49]
	v_mfma_f32_16x16x32_bf16 v[46:49], v[134:137], v[190:193], v[46:49]
	v_mfma_f32_16x16x32_bf16 v[30:33], v[130:133], v[194:197], v[30:33]
	v_mfma_f32_16x16x32_bf16 v[30:33], v[134:137], v[198:201], v[30:33]
	v_mfma_f32_16x16x32_bf16 v[26:29], v[138:141], v[194:197], v[26:29]
	v_mfma_f32_16x16x32_bf16 v[26:29], v[142:145], v[198:201], v[26:29]
	v_mfma_f32_16x16x32_bf16 v[10:13], v[138:141], v[202:205], v[10:13]
	v_mfma_f32_16x16x32_bf16 v[10:13], v[142:145], v[206:209], v[10:13]
	v_mfma_f32_16x16x32_bf16 v[14:17], v[130:133], v[202:205], v[14:17]
	v_mfma_f32_16x16x32_bf16 v[14:17], v[134:137], v[206:209], v[14:17]
	v_mfma_f32_16x16x32_bf16 v[54:57], v[150:153], v[166:169], v[54:57]
	v_mfma_f32_16x16x32_bf16 v[54:57], v[154:157], v[170:173], v[54:57]
	v_mfma_f32_16x16x32_bf16 v[50:53], v[158:161], v[166:169], v[50:53]
	v_mfma_f32_16x16x32_bf16 v[50:53], v[162:165], v[170:173], v[50:53]
	v_mfma_f32_16x16x32_bf16 v[34:37], v[158:161], v[186:189], v[34:37]
	v_mfma_f32_16x16x32_bf16 v[34:37], v[162:165], v[190:193], v[34:37]
	v_mfma_f32_16x16x32_bf16 v[38:41], v[150:153], v[186:189], v[38:41]
	v_mfma_f32_16x16x32_bf16 v[38:41], v[154:157], v[190:193], v[38:41]
	v_mfma_f32_16x16x32_bf16 v[22:25], v[150:153], v[194:197], v[22:25]
	v_mfma_f32_16x16x32_bf16 v[22:25], v[154:157], v[198:201], v[22:25]
	v_mfma_f32_16x16x32_bf16 v[18:21], v[158:161], v[194:197], v[18:21]
	v_mfma_f32_16x16x32_bf16 v[18:21], v[162:165], v[198:201], v[18:21]
	v_mfma_f32_16x16x32_bf16 v[2:5], v[158:161], v[202:205], v[2:5]
	v_mfma_f32_16x16x32_bf16 v[2:5], v[162:165], v[206:209], v[2:5]
	s_setprio 2
	s_barrier
	v_mfma_f32_16x16x32_bf16 v[6:9], v[150:153], v[202:205], v[6:9]
	v_mfma_f32_16x16x32_bf16 v[6:9], v[154:157], v[206:209], v[6:9]
	s_setprio 0
	s_add_i32 s69, s69, 2
	s_add_u32 s65, s65, 0x80000
	s_addc_u32 s66, s66, 0
	s_add_u32 s28, s28, 0x400000
	s_addc_u32 s29, s29, 0
	s_add_u32 s67, s67, 0x400000
	s_addc_u32 s68, s68, 0
	s_cmpk_gt_u32 s69, 0x53
	.p2align 6
.LBB0_2792:
	ds_read_b128 v[130:133], v181
	ds_read_b128 v[134:137], v181 offset:1024
	ds_read_b128 v[138:141], v181 offset:2048
	ds_read_b128 v[142:145], v181 offset:3072
	ds_read_b128 v[150:153], v182
	ds_read_b128 v[154:157], v182 offset:1024
	ds_read_b128 v[158:161], v182 offset:2048
	ds_read_b128 v[162:165], v182 offset:3072
	s_cmpk_eq_i32 s69, 0x52
	s_cselect_b32 s31, s19, s66
	s_cselect_b32 s30, s64, s65
	s_cselect_b32 s35, s21, s68
	s_cselect_b32 s34, s63, s67
	ds_read_b128 v[166:169], v183
	ds_read_b128 v[170:173], v183 offset:1024
	ds_read_b128 v[186:189], v183 offset:2048
	ds_read_b128 v[190:193], v183 offset:3072
	ds_read_b128 v[194:197], v183 offset:4096
	ds_read_b128 v[198:201], v183 offset:5120
	ds_read_b128 v[202:205], v183 offset:6144
	ds_read_b128 v[206:209], v183 offset:7168
	s_add_u32 s70, s28, 0xffffc000
	s_addc_u32 s71, s29, -1
	s_mov_b32 s73, m0
	s_mov_b32 m0, s57
	s_nop 0
	global_load_lds_dwordx4 v1, s[70:71]
	s_mov_b32 m0, s73
	s_nop 0
	s_mov_b32 s73, m0
	s_mov_b32 m0, s59
	s_nop 0
	global_load_lds_dwordx4 v177, s[70:71]
	s_mov_b32 m0, s73
	s_mov_b32 s70, m0
	s_mov_b32 m0, s58
	s_nop 0
	global_load_lds_dwordx4 v1, s[28:29]
	s_mov_b32 m0, s70
	s_nop 0
	s_mov_b32 s70, m0
	s_mov_b32 m0, s60
	s_nop 0
	global_load_lds_dwordx4 v177, s[28:29]
	s_mov_b32 m0, s70
	s_waitcnt vmcnt(8)
	s_waitcnt lgkmcnt(0)
	s_barrier
	s_setprio 1
	.p2align 3
	v_mfma_f32_16x16x32_bf16 v[126:129], v[130:133], v[166:169], v[126:129]
	v_mfma_f32_16x16x32_bf16 v[126:129], v[134:137], v[170:173], v[126:129]
	v_mfma_f32_16x16x32_bf16 v[122:125], v[138:141], v[166:169], v[122:125]
	v_mfma_f32_16x16x32_bf16 v[122:125], v[142:145], v[170:173], v[122:125]
	v_mfma_f32_16x16x32_bf16 v[110:113], v[138:141], v[186:189], v[110:113]
	v_mfma_f32_16x16x32_bf16 v[110:113], v[142:145], v[190:193], v[110:113]
	v_mfma_f32_16x16x32_bf16 v[118:121], v[130:133], v[186:189], v[118:121]
	v_mfma_f32_16x16x32_bf16 v[118:121], v[134:137], v[190:193], v[118:121]
	v_mfma_f32_16x16x32_bf16 v[94:97], v[130:133], v[194:197], v[94:97]
	v_mfma_f32_16x16x32_bf16 v[94:97], v[134:137], v[198:201], v[94:97]
	v_mfma_f32_16x16x32_bf16 v[90:93], v[138:141], v[194:197], v[90:93]
	v_mfma_f32_16x16x32_bf16 v[90:93], v[142:145], v[198:201], v[90:93]
	v_mfma_f32_16x16x32_bf16 v[78:81], v[138:141], v[202:205], v[78:81]
	v_mfma_f32_16x16x32_bf16 v[78:81], v[142:145], v[206:209], v[78:81]
	v_mfma_f32_16x16x32_bf16 v[86:89], v[130:133], v[202:205], v[86:89]
	v_mfma_f32_16x16x32_bf16 v[86:89], v[134:137], v[206:209], v[86:89]
	v_mfma_f32_16x16x32_bf16 v[114:117], v[150:153], v[166:169], v[114:117]
	v_mfma_f32_16x16x32_bf16 v[114:117], v[154:157], v[170:173], v[114:117]
	v_mfma_f32_16x16x32_bf16 v[106:109], v[158:161], v[166:169], v[106:109]
	v_mfma_f32_16x16x32_bf16 v[106:109], v[162:165], v[170:173], v[106:109]
	v_mfma_f32_16x16x32_bf16 v[98:101], v[158:161], v[186:189], v[98:101]
	v_mfma_f32_16x16x32_bf16 v[98:101], v[162:165], v[190:193], v[98:101]
	v_mfma_f32_16x16x32_bf16 v[102:105], v[150:153], v[186:189], v[102:105]
	v_mfma_f32_16x16x32_bf16 v[102:105], v[154:157], v[190:193], v[102:105]
	v_mfma_f32_16x16x32_bf16 v[82:85], v[150:153], v[194:197], v[82:85]
	v_mfma_f32_16x16x32_bf16 v[82:85], v[154:157], v[198:201], v[82:85]
	v_mfma_f32_16x16x32_bf16 v[74:77], v[158:161], v[194:197], v[74:77]
	v_mfma_f32_16x16x32_bf16 v[74:77], v[162:165], v[198:201], v[74:77]
	v_mfma_f32_16x16x32_bf16 v[66:69], v[158:161], v[202:205], v[66:69]
	v_mfma_f32_16x16x32_bf16 v[66:69], v[162:165], v[206:209], v[66:69]
	s_setprio 2
	s_barrier
	v_mfma_f32_16x16x32_bf16 v[70:73], v[150:153], v[202:205], v[70:73]
	v_mfma_f32_16x16x32_bf16 v[70:73], v[154:157], v[206:209], v[70:73]
	s_setprio 0
	ds_read_b128 v[166:169], v183 offset:16384
	ds_read_b128 v[170:173], v183 offset:17408
	ds_read_b128 v[186:189], v183 offset:18432
	ds_read_b128 v[190:193], v183 offset:19456
	ds_read_b128 v[194:197], v183 offset:20480
	ds_read_b128 v[198:201], v183 offset:21504
	ds_read_b128 v[202:205], v183 offset:22528
	ds_read_b128 v[206:209], v183 offset:23552
	s_mov_b32 s70, m0
	s_mov_b32 m0, s27
	s_nop 0
	global_load_lds_dwordx4 v176, s[30:31]
	s_mov_b32 m0, s70
	s_nop 0
	s_mov_b32 s70, m0
	s_mov_b32 m0, s45
	s_nop 0
	global_load_lds_dwordx4 v178, s[30:31]
	s_mov_b32 m0, s70
	s_add_u32 s70, s30, 0x4000
	s_addc_u32 s71, s31, 0
	s_mov_b32 s73, m0
	s_mov_b32 m0, s46
	s_nop 0
	global_load_lds_dwordx4 v176, s[70:71]
	s_mov_b32 m0, s73
	s_nop 0
	s_mov_b32 s73, m0
	s_mov_b32 m0, s47
	s_nop 0
	global_load_lds_dwordx4 v178, s[70:71]
	s_mov_b32 m0, s73
	s_waitcnt vmcnt(4)
	s_waitcnt lgkmcnt(0)
	s_barrier
	s_setprio 1
	.p2align 3
	v_mfma_f32_16x16x32_bf16 v[62:65], v[130:133], v[166:169], v[62:65]
	v_mfma_f32_16x16x32_bf16 v[62:65], v[134:137], v[170:173], v[62:65]
	v_mfma_f32_16x16x32_bf16 v[58:61], v[138:141], v[166:169], v[58:61]
	v_mfma_f32_16x16x32_bf16 v[58:61], v[142:145], v[170:173], v[58:61]
	v_mfma_f32_16x16x32_bf16 v[42:45], v[138:141], v[186:189], v[42:45]
	v_mfma_f32_16x16x32_bf16 v[42:45], v[142:145], v[190:193], v[42:45]
	v_mfma_f32_16x16x32_bf16 v[46:49], v[130:133], v[186:189], v[46:49]
	v_mfma_f32_16x16x32_bf16 v[46:49], v[134:137], v[190:193], v[46:49]
	v_mfma_f32_16x16x32_bf16 v[30:33], v[130:133], v[194:197], v[30:33]
	v_mfma_f32_16x16x32_bf16 v[30:33], v[134:137], v[198:201], v[30:33]
	v_mfma_f32_16x16x32_bf16 v[26:29], v[138:141], v[194:197], v[26:29]
	v_mfma_f32_16x16x32_bf16 v[26:29], v[142:145], v[198:201], v[26:29]
	v_mfma_f32_16x16x32_bf16 v[10:13], v[138:141], v[202:205], v[10:13]
	v_mfma_f32_16x16x32_bf16 v[10:13], v[142:145], v[206:209], v[10:13]
	v_mfma_f32_16x16x32_bf16 v[14:17], v[130:133], v[202:205], v[14:17]
	v_mfma_f32_16x16x32_bf16 v[14:17], v[134:137], v[206:209], v[14:17]
	v_mfma_f32_16x16x32_bf16 v[54:57], v[150:153], v[166:169], v[54:57]
	v_mfma_f32_16x16x32_bf16 v[54:57], v[154:157], v[170:173], v[54:57]
	v_mfma_f32_16x16x32_bf16 v[50:53], v[158:161], v[166:169], v[50:53]
	v_mfma_f32_16x16x32_bf16 v[50:53], v[162:165], v[170:173], v[50:53]
	v_mfma_f32_16x16x32_bf16 v[34:37], v[158:161], v[186:189], v[34:37]
	v_mfma_f32_16x16x32_bf16 v[34:37], v[162:165], v[190:193], v[34:37]
	v_mfma_f32_16x16x32_bf16 v[38:41], v[150:153], v[186:189], v[38:41]
	v_mfma_f32_16x16x32_bf16 v[38:41], v[154:157], v[190:193], v[38:41]
	v_mfma_f32_16x16x32_bf16 v[22:25], v[150:153], v[194:197], v[22:25]
	v_mfma_f32_16x16x32_bf16 v[22:25], v[154:157], v[198:201], v[22:25]
	v_mfma_f32_16x16x32_bf16 v[18:21], v[158:161], v[194:197], v[18:21]
	v_mfma_f32_16x16x32_bf16 v[18:21], v[162:165], v[198:201], v[18:21]
	v_mfma_f32_16x16x32_bf16 v[2:5], v[158:161], v[202:205], v[2:5]
	v_mfma_f32_16x16x32_bf16 v[2:5], v[162:165], v[206:209], v[2:5]
	s_setprio 2
	s_barrier
	v_mfma_f32_16x16x32_bf16 v[6:9], v[150:153], v[202:205], v[6:9]
	v_mfma_f32_16x16x32_bf16 v[6:9], v[154:157], v[206:209], v[6:9]
	s_setprio 0
	ds_read_b128 v[130:133], v184
	ds_read_b128 v[134:137], v184 offset:1024
	ds_read_b128 v[138:141], v184 offset:2048
	ds_read_b128 v[142:145], v184 offset:3072
	ds_read_b128 v[150:153], v185
	ds_read_b128 v[154:157], v185 offset:1024
	ds_read_b128 v[158:161], v185 offset:2048
	ds_read_b128 v[162:165], v185 offset:3072
	ds_read_b128 v[166:169], v183 offset:32768
	ds_read_b128 v[170:173], v183 offset:33792
	ds_read_b128 v[186:189], v183 offset:34816
	ds_read_b128 v[190:193], v183 offset:35840
	ds_read_b128 v[194:197], v183 offset:36864
	ds_read_b128 v[198:201], v183 offset:37888
	ds_read_b128 v[202:205], v183 offset:38912
	ds_read_b128 v[206:209], v183 offset:39936
	s_mov_b32 s70, m0
	s_mov_b32 m0, s44
	s_nop 0
	global_load_lds_dwordx4 v1, s[34:35]
	s_mov_b32 m0, s70
	s_nop 0
	s_mov_b32 s70, m0
	s_mov_b32 m0, s48
	s_nop 0
	global_load_lds_dwordx4 v177, s[34:35]
	s_mov_b32 m0, s70
	s_add_u32 s34, s34, 0x4000
	s_addc_u32 s35, s35, 0
	s_mov_b32 s70, m0
	s_mov_b32 m0, s49
	s_nop 0
	global_load_lds_dwordx4 v1, s[34:35]
	s_mov_b32 m0, s70
	s_nop 0
	s_mov_b32 s70, m0
	s_mov_b32 m0, s50
	s_nop 0
	global_load_lds_dwordx4 v177, s[34:35]
	s_mov_b32 m0, s70
	s_waitcnt vmcnt(8)
	s_waitcnt lgkmcnt(0)
	s_barrier
	s_setprio 1
	.p2align 3
	v_mfma_f32_16x16x32_bf16 v[126:129], v[130:133], v[166:169], v[126:129]
	v_mfma_f32_16x16x32_bf16 v[126:129], v[134:137], v[170:173], v[126:129]
	v_mfma_f32_16x16x32_bf16 v[122:125], v[138:141], v[166:169], v[122:125]
	v_mfma_f32_16x16x32_bf16 v[122:125], v[142:145], v[170:173], v[122:125]
	v_mfma_f32_16x16x32_bf16 v[110:113], v[138:141], v[186:189], v[110:113]
	v_mfma_f32_16x16x32_bf16 v[110:113], v[142:145], v[190:193], v[110:113]
	v_mfma_f32_16x16x32_bf16 v[118:121], v[130:133], v[186:189], v[118:121]
	v_mfma_f32_16x16x32_bf16 v[118:121], v[134:137], v[190:193], v[118:121]
	v_mfma_f32_16x16x32_bf16 v[94:97], v[130:133], v[194:197], v[94:97]
	v_mfma_f32_16x16x32_bf16 v[94:97], v[134:137], v[198:201], v[94:97]
	v_mfma_f32_16x16x32_bf16 v[90:93], v[138:141], v[194:197], v[90:93]
	v_mfma_f32_16x16x32_bf16 v[90:93], v[142:145], v[198:201], v[90:93]
	v_mfma_f32_16x16x32_bf16 v[78:81], v[138:141], v[202:205], v[78:81]
	v_mfma_f32_16x16x32_bf16 v[78:81], v[142:145], v[206:209], v[78:81]
	v_mfma_f32_16x16x32_bf16 v[86:89], v[130:133], v[202:205], v[86:89]
	v_mfma_f32_16x16x32_bf16 v[86:89], v[134:137], v[206:209], v[86:89]
	v_mfma_f32_16x16x32_bf16 v[114:117], v[150:153], v[166:169], v[114:117]
	v_mfma_f32_16x16x32_bf16 v[114:117], v[154:157], v[170:173], v[114:117]
	v_mfma_f32_16x16x32_bf16 v[106:109], v[158:161], v[166:169], v[106:109]
	v_mfma_f32_16x16x32_bf16 v[106:109], v[162:165], v[170:173], v[106:109]
	v_mfma_f32_16x16x32_bf16 v[98:101], v[158:161], v[186:189], v[98:101]
	v_mfma_f32_16x16x32_bf16 v[98:101], v[162:165], v[190:193], v[98:101]
	v_mfma_f32_16x16x32_bf16 v[102:105], v[150:153], v[186:189], v[102:105]
	v_mfma_f32_16x16x32_bf16 v[102:105], v[154:157], v[190:193], v[102:105]
	v_mfma_f32_16x16x32_bf16 v[82:85], v[150:153], v[194:197], v[82:85]
	v_mfma_f32_16x16x32_bf16 v[82:85], v[154:157], v[198:201], v[82:85]
	v_mfma_f32_16x16x32_bf16 v[74:77], v[158:161], v[194:197], v[74:77]
	v_mfma_f32_16x16x32_bf16 v[74:77], v[162:165], v[198:201], v[74:77]
	v_mfma_f32_16x16x32_bf16 v[66:69], v[158:161], v[202:205], v[66:69]
	v_mfma_f32_16x16x32_bf16 v[66:69], v[162:165], v[206:209], v[66:69]
	s_setprio 2
	s_barrier
	v_mfma_f32_16x16x32_bf16 v[70:73], v[150:153], v[202:205], v[70:73]
	v_mfma_f32_16x16x32_bf16 v[70:73], v[154:157], v[206:209], v[70:73]
	s_setprio 0
	ds_read_b128 v[166:169], v183 offset:49152
	ds_read_b128 v[170:173], v183 offset:50176
	ds_read_b128 v[186:189], v183 offset:51200
	ds_read_b128 v[190:193], v183 offset:52224
	ds_read_b128 v[194:197], v183 offset:53248
	ds_read_b128 v[198:201], v183 offset:54272
	ds_read_b128 v[202:205], v183 offset:55296
	ds_read_b128 v[206:209], v183 offset:56320
	s_add_u32 s34, s30, 0x40000
	s_addc_u32 s35, s31, 0
	s_mov_b32 s70, m0
	s_mov_b32 m0, s51
	s_nop 0
	global_load_lds_dwordx4 v176, s[34:35]
	s_mov_b32 m0, s70
	s_add_u32 s30, s30, 0x44000
	s_mov_b32 s70, m0
	s_mov_b32 m0, s52
	s_nop 0
	global_load_lds_dwordx4 v178, s[34:35]
	s_mov_b32 m0, s70
	s_addc_u32 s31, s31, 0
	s_mov_b32 s34, m0
	s_mov_b32 m0, s53
	s_nop 0
	global_load_lds_dwordx4 v176, s[30:31]
	s_mov_b32 m0, s34
	s_nop 0
	s_mov_b32 s34, m0
	s_mov_b32 m0, s54
	s_nop 0
	global_load_lds_dwordx4 v178, s[30:31]
	s_mov_b32 m0, s34
	s_waitcnt vmcnt(4)
	s_waitcnt lgkmcnt(0)
	s_barrier
	s_setprio 1
	.p2align 3
	v_mfma_f32_16x16x32_bf16 v[62:65], v[130:133], v[166:169], v[62:65]
	v_mfma_f32_16x16x32_bf16 v[62:65], v[134:137], v[170:173], v[62:65]
	v_mfma_f32_16x16x32_bf16 v[58:61], v[138:141], v[166:169], v[58:61]
	v_mfma_f32_16x16x32_bf16 v[58:61], v[142:145], v[170:173], v[58:61]
	v_mfma_f32_16x16x32_bf16 v[42:45], v[138:141], v[186:189], v[42:45]
	v_mfma_f32_16x16x32_bf16 v[42:45], v[142:145], v[190:193], v[42:45]
	v_mfma_f32_16x16x32_bf16 v[46:49], v[130:133], v[186:189], v[46:49]
	v_mfma_f32_16x16x32_bf16 v[46:49], v[134:137], v[190:193], v[46:49]
	v_mfma_f32_16x16x32_bf16 v[30:33], v[130:133], v[194:197], v[30:33]
	v_mfma_f32_16x16x32_bf16 v[30:33], v[134:137], v[198:201], v[30:33]
	v_mfma_f32_16x16x32_bf16 v[26:29], v[138:141], v[194:197], v[26:29]
	v_mfma_f32_16x16x32_bf16 v[26:29], v[142:145], v[198:201], v[26:29]
	v_mfma_f32_16x16x32_bf16 v[10:13], v[138:141], v[202:205], v[10:13]
	v_mfma_f32_16x16x32_bf16 v[10:13], v[142:145], v[206:209], v[10:13]
	v_mfma_f32_16x16x32_bf16 v[14:17], v[130:133], v[202:205], v[14:17]
	v_mfma_f32_16x16x32_bf16 v[14:17], v[134:137], v[206:209], v[14:17]
	v_mfma_f32_16x16x32_bf16 v[54:57], v[150:153], v[166:169], v[54:57]
	v_mfma_f32_16x16x32_bf16 v[54:57], v[154:157], v[170:173], v[54:57]
	v_mfma_f32_16x16x32_bf16 v[50:53], v[158:161], v[166:169], v[50:53]
	v_mfma_f32_16x16x32_bf16 v[50:53], v[162:165], v[170:173], v[50:53]
	v_mfma_f32_16x16x32_bf16 v[34:37], v[158:161], v[186:189], v[34:37]
	v_mfma_f32_16x16x32_bf16 v[34:37], v[162:165], v[190:193], v[34:37]
	v_mfma_f32_16x16x32_bf16 v[38:41], v[150:153], v[186:189], v[38:41]
	v_mfma_f32_16x16x32_bf16 v[38:41], v[154:157], v[190:193], v[38:41]
	v_mfma_f32_16x16x32_bf16 v[22:25], v[150:153], v[194:197], v[22:25]
	v_mfma_f32_16x16x32_bf16 v[22:25], v[154:157], v[198:201], v[22:25]
	v_mfma_f32_16x16x32_bf16 v[18:21], v[158:161], v[194:197], v[18:21]
	v_mfma_f32_16x16x32_bf16 v[18:21], v[162:165], v[198:201], v[18:21]
	v_mfma_f32_16x16x32_bf16 v[2:5], v[158:161], v[202:205], v[2:5]
	v_mfma_f32_16x16x32_bf16 v[2:5], v[162:165], v[206:209], v[2:5]
	s_setprio 2
	s_barrier
	v_mfma_f32_16x16x32_bf16 v[6:9], v[150:153], v[202:205], v[6:9]
	v_mfma_f32_16x16x32_bf16 v[6:9], v[154:157], v[206:209], v[6:9]
	s_setprio 0
	s_add_i32 s69, s69, 2
	s_add_u32 s65, s65, 0x80000
	s_addc_u32 s66, s66, 0
	s_add_u32 s28, s28, 0x400000
	s_addc_u32 s29, s29, 0
	s_add_u32 s67, s67, 0x400000
	s_addc_u32 s68, s68, 0
	s_cmpk_gt_u32 s69, 0x53
	s_cbranch_scc0 .LBB0_2792
	s_and_b64 vcc, exec, s[8:9]
	s_cbranch_vccz .LBB0_2795
	s_barrier
